# v9
# speedup vs baseline: 1.0115x; 1.0115x over previous
; #define PG8_STAGE4(b, pa, pb) do { PG8_STAGE(PG8_SB(b, 0), (pb), voffB); PG8_STAGE(PG8_SA(b, 0), (pa), voffA); PG8_STAGE(PG8_SB(b, 1), (pb) + hstep, voffB); PG8_STAGE(PG8_SA(b, 1), (pa) + hstep, voffA); } while (0)
; #define PG8_SYNC() do { asm volatile("s_waitcnt vmcnt(0) lgkmcnt(0)" ::: "memory"); __builtin_amdgcn_s_barrier(); asm volatile("" ::: "memory"); } while (0)
; template <class Epi, class Sched>
; __device__ __forceinline__ void gemm_simple(PG8_LAS unsigned char* lds, const Gemm g, const Sched& S, const Epi& E, int wave_s) {
;     ...
;     for (int i = 0; i < 2; ++i) { int R, C; stage_rc(tid * 16 + i * 8192, R, C); const int Rb = Epi::PERM ? ((R & ~31) + perm32(R & 31)) : R;
;         voffA[i] = (unsigned)(R * K + C) * 2u; voffB[i] = (unsigned)(Rb * K + C) * 2u; }
;     const size_t kstep = (size_t)(BK * 2), hstep = (size_t)HALF * K * 2, tstep = 2 * hstep;
;     const unsigned ldsw = (unsigned)wid * 1024u; const unsigned lds_u = (unsigned)(__UINTPTR_TYPE__)lds;
;     const int aoff = lds_byte(wr * 64 + fr, fq * 8), boff = lds_byte(wc * 32 + fr, fq * 8);
;     ...
;     const char* cA = (const char*)g.A + (size_t)cur.pm * tstep; const char* cB = (const char*)g.Bt + (size_t)cur.pn * tstep;
;     PG8_SYNC();
;     PG8_STAGE4(0, cA, cB);
.LBB0_44:
	s_andn2_b64 vcc, exec, s[4:5]
	s_cbranch_vccnz .LBB0_83
	v_ashrrev_i32_e32 v4, 31, v2
	v_lshrrev_b32_e32 v4, 26, v4
	v_lshlrev_b32_e32 v3, 4, v2
	v_add_u32_e32 v4, v2, v4
	v_bfe_i32 v2, v2, 27, 1
	v_lshrrev_b32_e32 v2, 22, v2
	v_add_u32_e32 v2, v3, v2
	v_and_b32_e32 v2, 0xfffffc00, v2
	v_sub_u32_e32 v2, v3, v2
	v_lshrrev_b32_e32 v5, 4, v2
	v_bitop3_b32 v2, v5, v2, 32 bitop3:0x6c
	v_ashrrev_i32_e32 v6, 31, v2
	v_lshrrev_b32_e32 v6, 26, v6
	v_ashrrev_i32_e32 v4, 6, v4
	v_add_u32_e32 v6, v2, v6
	v_lshlrev_b32_e32 v5, 3, v4
	v_ashrrev_i32_e32 v7, 6, v6
	v_and_b32_e32 v6, 0xc0, v6
	v_and_b32_e32 v5, -16, v5
	v_lshlrev_b32_e32 v4, 5, v4
	v_sub_u32_e32 v2, v2, v6
	v_add_u32_e32 v5, v7, v5
	v_and_b32_e32 v4, 32, v4
	v_ashrrev_i16_sdwa v2, v166, sext(v2) dst_sel:DWORD dst_unused:UNUSED_PAD src0_sel:DWORD src1_sel:BYTE_0
	v_add_u32_sdwa v2, v4, sext(v2) dst_sel:DWORD dst_unused:UNUSED_PAD src0_sel:DWORD src1_sel:WORD_0
	v_lshlrev_b32_e32 v4, 1, v5
	v_lshrrev_b32_e32 v6, 2, v5
	v_and_b32_e32 v7, 3, v7
	s_mov_b32 s5, 0x7fffe0
	v_and_b32_e32 v4, 24, v4
	v_and_b32_e32 v6, 4, v6
	v_and_or_b32 v7, v5, s5, v7
	v_or3_b32 v4, v7, v6, v4
	s_movk_i32 s6, 0x1600
	v_mul_lo_u32 v5, v5, s6
	v_mul_u32_u24_e32 v4, 0x1600, v4
	v_add_lshl_u32 v138, v2, v5, 1
	v_add_lshl_u32 v139, v4, v2, 1
	v_add_u32_e32 v2, 0x2000, v3
	v_ashrrev_i32_e32 v3, 31, v2
	v_lshrrev_b32_e32 v3, 22, v3
	v_add_u32_e32 v3, v2, v3
	v_ashrrev_i32_e32 v3, 10, v3
	v_mul_i32_i24_e32 v4, 0x400, v3
	v_sub_u32_e32 v2, v2, v4
	v_lshrrev_b32_e32 v4, 4, v2
	v_bitop3_b32 v2, v4, v2, 32 bitop3:0x6c
	v_ashrrev_i32_e32 v5, 31, v2
	v_lshrrev_b32_e32 v5, 26, v5
	v_add_u32_e32 v5, v2, v5
	v_lshlrev_b32_e32 v4, 3, v3
	v_ashrrev_i32_e32 v6, 6, v5
	v_and_b32_e32 v5, 0xc0, v5
	v_and_b32_e32 v4, -16, v4
	v_lshlrev_b32_e32 v3, 5, v3
	v_sub_u32_e32 v2, v2, v5
	v_add_u32_e32 v4, v6, v4
	v_and_b32_e32 v3, 32, v3
	v_ashrrev_i16_sdwa v2, v166, sext(v2) dst_sel:DWORD dst_unused:UNUSED_PAD src0_sel:DWORD src1_sel:BYTE_0
	v_add_u32_sdwa v2, v3, sext(v2) dst_sel:DWORD dst_unused:UNUSED_PAD src0_sel:DWORD src1_sel:WORD_0
	v_lshlrev_b32_e32 v3, 1, v4
	v_lshrrev_b32_e32 v5, 2, v4
	v_and_b32_e32 v6, 3, v6
	v_readlane_b32 s4, v254, 57
	v_and_b32_e32 v3, 24, v3
	v_and_b32_e32 v5, 4, v5
	v_and_or_b32 v6, v4, s5, v6
	s_add_u32 s20, s4, 0x6400000
	v_readlane_b32 s4, v254, 58
	v_or3_b32 v3, v6, v5, v3
	s_addc_u32 s21, s4, 0
	v_mul_lo_u32 v4, v4, s6
	v_mul_u32_u24_e32 v3, 0x1600, v3
	s_ashr_i32 s23, s8, 2
	s_ashr_i32 s4, s8, 6
	v_add_lshl_u32 v140, v2, v4, 1
	v_add_lshl_u32 v152, v3, v2, 1
	s_andn2_b32 s23, s23, 63
	v_and_b32_e32 v2, 48, v1
	v_lshlrev_b32_e32 v3, 6, v1
	s_movk_i32 s5, 0x3c0
	v_lshlrev_b32_e32 v1, 2, v1
	s_and_b32 s22, s4, 3
	s_lshl_b32 s25, s4, 10
	s_lshl_b32 s4, s23, 7
	v_and_or_b32 v2, v3, s5, v2
	v_and_b32_e32 v1, 32, v1
	v_bitop3_b32 v4, v2, s4, v1 bitop3:0xde
	s_lshl_b32 s24, s22, 5
	s_lshl_b32 s4, s22, 12
	s_mul_i32 s7, s35, 0x2c0000
	s_mul_hi_i32 s6, s35, 0x2c0000
	s_add_u32 s16, s20, s7
	s_addc_u32 s17, s21, s6
	s_waitcnt vmcnt(0) lgkmcnt(0)
	s_barrier
	s_add_i32 s25, s25, 0
	s_mul_i32 s5, s52, 0x2c0000
	s_add_i32 s26, s25, 0x10000
	s_mov_b32 m0, s26
	s_nop 0
	global_load_lds_dwordx4 v139, s[16:17]
	s_add_i32 s27, s25, 0x12000
	v_bitop3_b32 v5, s4, v2, v1 bitop3:0xf6
	s_mul_hi_i32 s4, s52, 0x2c0000
	s_mov_b32 m0, s27
	s_nop 0
	global_load_lds_dwordx4 v152, s[16:17]
	s_add_u32 s18, s2, s5
	s_addc_u32 s19, s3, s4
	s_mov_b32 m0, s25
	s_nop 0
	global_load_lds_dwordx4 v138, s[18:19]
	s_add_i32 s28, s25, 0x2000
	s_mov_b32 m0, s28
	s_nop 0
	global_load_lds_dwordx4 v140, s[18:19]
	s_add_u32 s4, s16, 0x160000
	s_addc_u32 s5, s17, 0
	s_add_i32 s29, s25, 0x14000
	s_mov_b32 m0, s29
	s_nop 0
	global_load_lds_dwordx4 v139, s[4:5]
	s_add_i32 s36, s25, 0x16000
	s_mov_b32 m0, s36
	s_nop 0
	global_load_lds_dwordx4 v152, s[4:5]
	s_add_u32 s4, s18, 0x160000
	s_addc_u32 s5, s19, 0
	s_add_i32 s37, s25, 0x4000
	s_mov_b32 m0, s37
	s_nop 0
	global_load_lds_dwordx4 v138, s[4:5]
	s_add_i32 s38, s25, 0x6000
	s_mov_b32 m0, s38
	s_nop 0
	global_load_lds_dwordx4 v140, s[4:5]
	v_mov_b32_e32 v1, v0
	v_mov_b32_e32 v2, v0
	v_mov_b32_e32 v3, v0
	s_add_i32 s39, s25, 0x18000
	s_add_i32 s40, s25, 0x8000
	s_add_i32 s41, s25, 0x1c000
	s_add_i32 s42, s25, 0xc000
	s_add_i32 s43, s25, 0x1a000
	s_add_i32 s44, s25, 0xa000
	s_add_i32 s45, s25, 0x1e000
	s_add_i32 s46, s25, 0xe000
	s_ashr_i32 s47, s34, 31
	s_ashr_i32 s48, s31, 31
	s_mov_b32 s53, 0
	v_add_u32_e32 v153, 0, v5
	v_add_u32_e32 v154, 0, v4
	s_branch .LBB0_50

; template <class Epi, class Sched>
; __device__ __forceinline__ void gemm_simple(PG8_LAS unsigned char* lds, const Gemm g, const Sched& S, const Epi& E, int wave_s) {
;     ...
;         if (ui > 0) {
;             if constexpr (Epi::NST >= 16) PG8_TILE_W(0, cA + kstep, cB + kstep, "18", "20"); else PG8_TILE_W(0, cA + kstep, cB + kstep, "10", "12");
;             PG8_TILE_W(1, cA + 2 * kstep, cB + 2 * kstep, "2", "4");
;             t = 2;
.LBB0_60:
	s_waitcnt lgkmcnt(0)
	v_mov_b64_e32 v[6:7], v[2:3]
	v_mov_b64_e32 v[10:11], v[2:3]
	v_mov_b64_e32 v[22:23], v[2:3]
	v_mov_b64_e32 v[26:27], v[2:3]
	v_mov_b64_e32 v[38:39], v[2:3]
	v_mov_b64_e32 v[42:43], v[2:3]
	v_mov_b64_e32 v[54:55], v[2:3]
	v_mov_b64_e32 v[58:59], v[2:3]
	v_mov_b64_e32 v[14:15], v[2:3]
	v_mov_b64_e32 v[18:19], v[2:3]
	v_mov_b64_e32 v[30:31], v[2:3]
	v_mov_b64_e32 v[34:35], v[2:3]
	v_mov_b64_e32 v[46:47], v[2:3]
	v_mov_b64_e32 v[50:51], v[2:3]
	v_mov_b64_e32 v[62:63], v[2:3]
	v_mov_b64_e32 v[66:67], v[2:3]
	v_mov_b64_e32 v[70:71], v[2:3]
	v_mov_b64_e32 v[74:75], v[2:3]
	v_mov_b64_e32 v[86:87], v[2:3]
	v_mov_b64_e32 v[90:91], v[2:3]
	v_mov_b64_e32 v[102:103], v[2:3]
	v_mov_b64_e32 v[106:107], v[2:3]
	v_mov_b64_e32 v[118:119], v[2:3]
	v_mov_b64_e32 v[122:123], v[2:3]
	v_mov_b64_e32 v[78:79], v[2:3]
	v_mov_b64_e32 v[82:83], v[2:3]
	v_mov_b64_e32 v[94:95], v[2:3]
	v_mov_b64_e32 v[98:99], v[2:3]
	v_mov_b64_e32 v[110:111], v[2:3]
	v_mov_b64_e32 v[114:115], v[2:3]
	v_mov_b64_e32 v[126:127], v[2:3]
	v_mov_b64_e32 v[130:131], v[2:3]
	s_mov_b32 s10, 0
	s_cmp_eq_u32 s53, 0
	v_add_u32_e32 v132, 0x10000, v153
	v_add_u32_e32 v133, 0x14000, v153
	v_add_u32_e32 v134, 0x18000, v153
	v_add_u32_e32 v135, 0x1c000, v153
	v_mov_b64_e32 v[4:5], v[0:1]
	v_mov_b64_e32 v[8:9], v[0:1]
	v_mov_b64_e32 v[20:21], v[0:1]
	v_mov_b64_e32 v[24:25], v[0:1]
	v_mov_b64_e32 v[36:37], v[0:1]
	v_mov_b64_e32 v[40:41], v[0:1]
	v_mov_b64_e32 v[52:53], v[0:1]
	v_mov_b64_e32 v[56:57], v[0:1]
	v_mov_b64_e32 v[12:13], v[0:1]
	v_mov_b64_e32 v[16:17], v[0:1]
	v_mov_b64_e32 v[28:29], v[0:1]
	v_mov_b64_e32 v[32:33], v[0:1]
	v_mov_b64_e32 v[44:45], v[0:1]
	v_mov_b64_e32 v[48:49], v[0:1]
	v_mov_b64_e32 v[60:61], v[0:1]
	v_mov_b64_e32 v[64:65], v[0:1]
	v_mov_b64_e32 v[68:69], v[0:1]
	v_mov_b64_e32 v[72:73], v[0:1]
	v_mov_b64_e32 v[84:85], v[0:1]
	v_mov_b64_e32 v[88:89], v[0:1]
	v_mov_b64_e32 v[100:101], v[0:1]
	v_mov_b64_e32 v[104:105], v[0:1]
	v_mov_b64_e32 v[116:117], v[0:1]
	v_mov_b64_e32 v[120:121], v[0:1]
	v_mov_b64_e32 v[76:77], v[0:1]
	v_mov_b64_e32 v[80:81], v[0:1]
	v_mov_b64_e32 v[92:93], v[0:1]
	v_mov_b64_e32 v[96:97], v[0:1]
	v_mov_b64_e32 v[108:109], v[0:1]
	v_mov_b64_e32 v[112:113], v[0:1]
	v_mov_b64_e32 v[124:125], v[0:1]
	v_mov_b64_e32 v[128:129], v[0:1]
	s_cbranch_scc1 .LBB0_62
	s_waitcnt vmcnt(18) lgkmcnt(0)
	s_barrier
	ds_read_b128 v[4:7], v132
	ds_read_b128 v[8:11], v132 offset:1024
	ds_read_b128 v[12:15], v132 offset:2048
	ds_read_b128 v[16:19], v132 offset:3072
	ds_read_b128 v[20:23], v154
	ds_read_b128 v[24:27], v154 offset:1024
	ds_read_b128 v[28:31], v154 offset:2048
	ds_read_b128 v[32:35], v154 offset:3072
	ds_read_b128 v[36:39], v154 offset:4096
	ds_read_b128 v[40:43], v154 offset:5120
	ds_read_b128 v[44:47], v154 offset:6144
	ds_read_b128 v[48:51], v154 offset:7168
	ds_read_b128 v[52:55], v133
	ds_read_b128 v[56:59], v133 offset:1024
	ds_read_b128 v[60:63], v133 offset:2048
	ds_read_b128 v[64:67], v133 offset:3072
	s_add_u32 s10, s16, 0x80
	s_addc_u32 s11, s17, 0
	s_mov_b32 m0, s39
	s_nop 0
	global_load_lds_dwordx4 v139, s[10:11]
	s_mov_b32 m0, s43
	s_nop 0
	global_load_lds_dwordx4 v152, s[10:11]
	s_waitcnt lgkmcnt(5)
	v_mfma_f32_16x16x32_bf16 v[92:95], v[4:7], v[44:47], v[0:3]
	v_mfma_f32_16x16x32_bf16 v[68:71], v[4:7], v[20:23], v[0:3]
	v_mfma_f32_16x16x32_bf16 v[72:75], v[12:15], v[20:23], v[0:3]
	v_mfma_f32_16x16x32_bf16 v[76:79], v[4:7], v[28:31], v[0:3]
	v_mfma_f32_16x16x32_bf16 v[80:83], v[12:15], v[28:31], v[0:3]
	v_mfma_f32_16x16x32_bf16 v[84:87], v[4:7], v[36:39], v[0:3]
	v_mfma_f32_16x16x32_bf16 v[88:91], v[12:15], v[36:39], v[0:3]
	s_waitcnt lgkmcnt(4)
	v_mfma_f32_16x16x32_bf16 v[100:103], v[8:11], v[48:51], v[92:95]
	v_mfma_f32_16x16x32_bf16 v[92:95], v[12:15], v[44:47], v[0:3]
	v_mfma_f32_16x16x32_bf16 v[68:71], v[8:11], v[24:27], v[68:71]
	v_mfma_f32_16x16x32_bf16 v[72:75], v[16:19], v[24:27], v[72:75]
	v_mfma_f32_16x16x32_bf16 v[76:79], v[8:11], v[32:35], v[76:79]
	v_mfma_f32_16x16x32_bf16 v[80:83], v[16:19], v[32:35], v[80:83]
	v_mfma_f32_16x16x32_bf16 v[84:87], v[8:11], v[40:43], v[84:87]
	v_mfma_f32_16x16x32_bf16 v[88:91], v[16:19], v[40:43], v[88:91]
	v_mfma_f32_16x16x32_bf16 v[104:107], v[16:19], v[48:51], v[92:95]
	s_add_u32 s10, s18, 0x80
	s_addc_u32 s11, s19, 0
	s_mov_b32 m0, s40
	s_nop 0
	global_load_lds_dwordx4 v138, s[10:11]
	s_mov_b32 m0, s44
	s_nop 0
	global_load_lds_dwordx4 v140, s[10:11]
	s_waitcnt lgkmcnt(3)
	v_mfma_f32_16x16x32_bf16 v[92:95], v[52:55], v[20:23], v[0:3]
	s_waitcnt lgkmcnt(1)
	v_mfma_f32_16x16x32_bf16 v[20:23], v[60:63], v[20:23], v[0:3]
	v_mfma_f32_16x16x32_bf16 v[116:119], v[56:59], v[24:27], v[92:95]
	s_waitcnt lgkmcnt(0)
	v_mfma_f32_16x16x32_bf16 v[20:23], v[64:67], v[24:27], v[20:23]
	v_mfma_f32_16x16x32_bf16 v[24:27], v[52:55], v[28:31], v[0:3]
	v_mfma_f32_16x16x32_bf16 v[28:31], v[60:63], v[28:31], v[0:3]
	v_mfma_f32_16x16x32_bf16 v[24:27], v[56:59], v[32:35], v[24:27]
	v_mfma_f32_16x16x32_bf16 v[28:31], v[64:67], v[32:35], v[28:31]
	v_mfma_f32_16x16x32_bf16 v[32:35], v[52:55], v[36:39], v[0:3]
	v_mfma_f32_16x16x32_bf16 v[36:39], v[60:63], v[36:39], v[0:3]
	v_mfma_f32_16x16x32_bf16 v[32:35], v[56:59], v[40:43], v[32:35]
	v_mfma_f32_16x16x32_bf16 v[36:39], v[64:67], v[40:43], v[36:39]
	v_mfma_f32_16x16x32_bf16 v[40:43], v[52:55], v[44:47], v[0:3]
	v_mfma_f32_16x16x32_bf16 v[44:47], v[60:63], v[44:47], v[0:3]
	v_mfma_f32_16x16x32_bf16 v[40:43], v[56:59], v[48:51], v[40:43]
	v_mfma_f32_16x16x32_bf16 v[44:47], v[64:67], v[48:51], v[44:47]
	s_waitcnt vmcnt(20) lgkmcnt(0)
	s_barrier
	ds_read_b128 v[48:51], v154 offset:16384
	ds_read_b128 v[92:95], v154 offset:17408
	ds_read_b128 v[96:99], v154 offset:18432
	ds_read_b128 v[108:111], v154 offset:19456
	ds_read_b128 v[112:115], v154 offset:20480
	ds_read_b128 v[120:123], v154 offset:21504
	ds_read_b128 v[124:127], v154 offset:22528
	ds_read_b128 v[128:131], v154 offset:23552
	s_add_u32 s10, s16, 0x160080
	s_addc_u32 s11, s17, 0
	s_mov_b32 m0, s41
	s_nop 0
	global_load_lds_dwordx4 v139, s[10:11]
	s_mov_b32 m0, s45
	s_nop 0
	global_load_lds_dwordx4 v152, s[10:11]
	s_waitcnt lgkmcnt(7)
	v_mfma_f32_16x16x32_bf16 v[142:145], v[4:7], v[48:51], v[0:3]
	s_waitcnt lgkmcnt(5)
	v_mfma_f32_16x16x32_bf16 v[156:159], v[4:7], v[96:99], v[0:3]
	s_waitcnt lgkmcnt(3)
	v_mfma_f32_16x16x32_bf16 v[170:173], v[4:7], v[112:115], v[0:3]
	s_waitcnt lgkmcnt(1)
	v_mfma_f32_16x16x32_bf16 v[4:7], v[4:7], v[124:127], v[0:3]
	v_mfma_f32_16x16x32_bf16 v[142:145], v[8:11], v[92:95], v[142:145]
	v_mfma_f32_16x16x32_bf16 v[156:159], v[8:11], v[108:111], v[156:159]
	v_mfma_f32_16x16x32_bf16 v[170:173], v[8:11], v[120:123], v[170:173]
	s_waitcnt lgkmcnt(0)
	v_mfma_f32_16x16x32_bf16 v[4:7], v[8:11], v[128:131], v[4:7]
	v_mfma_f32_16x16x32_bf16 v[8:11], v[12:15], v[124:127], v[0:3]
	v_mfma_f32_16x16x32_bf16 v[146:149], v[12:15], v[48:51], v[0:3]
	v_mfma_f32_16x16x32_bf16 v[160:163], v[12:15], v[96:99], v[0:3]
	v_mfma_f32_16x16x32_bf16 v[174:177], v[12:15], v[112:115], v[0:3]
	v_mfma_f32_16x16x32_bf16 v[8:11], v[16:19], v[128:131], v[8:11]
	v_mfma_f32_16x16x32_bf16 v[146:149], v[16:19], v[92:95], v[146:149]
	v_mfma_f32_16x16x32_bf16 v[160:163], v[16:19], v[108:111], v[160:163]
	v_mfma_f32_16x16x32_bf16 v[174:177], v[16:19], v[120:123], v[174:177]
	s_add_u32 s10, s18, 0x160080
	s_addc_u32 s11, s19, 0
	s_mov_b32 m0, s42
	s_nop 0
	global_load_lds_dwordx4 v138, s[10:11]
	s_mov_b32 m0, s46
	s_nop 0
	global_load_lds_dwordx4 v140, s[10:11]
	v_mfma_f32_16x16x32_bf16 v[12:15], v[52:55], v[48:51], v[0:3]
	v_mfma_f32_16x16x32_bf16 v[178:181], v[56:59], v[92:95], v[12:15]
	v_mfma_f32_16x16x32_bf16 v[12:15], v[60:63], v[48:51], v[0:3]
	v_mfma_f32_16x16x32_bf16 v[182:185], v[64:67], v[92:95], v[12:15]
	v_mfma_f32_16x16x32_bf16 v[12:15], v[52:55], v[96:99], v[0:3]
	v_mfma_f32_16x16x32_bf16 v[186:189], v[56:59], v[108:111], v[12:15]
	v_mfma_f32_16x16x32_bf16 v[12:15], v[60:63], v[96:99], v[0:3]
	v_mfma_f32_16x16x32_bf16 v[190:193], v[64:67], v[108:111], v[12:15]
	v_mfma_f32_16x16x32_bf16 v[12:15], v[52:55], v[112:115], v[0:3]
	v_mfma_f32_16x16x32_bf16 v[194:197], v[56:59], v[120:123], v[12:15]
	v_mfma_f32_16x16x32_bf16 v[12:15], v[60:63], v[112:115], v[0:3]
	v_mfma_f32_16x16x32_bf16 v[198:201], v[64:67], v[120:123], v[12:15]
	v_mfma_f32_16x16x32_bf16 v[12:15], v[52:55], v[124:127], v[0:3]
	v_mfma_f32_16x16x32_bf16 v[202:205], v[56:59], v[128:131], v[12:15]
	v_mfma_f32_16x16x32_bf16 v[12:15], v[60:63], v[124:127], v[0:3]
	v_mfma_f32_16x16x32_bf16 v[206:209], v[64:67], v[128:131], v[12:15]
	s_waitcnt vmcnt(2) lgkmcnt(0)
	s_barrier
	s_nop 5
	ds_read_b128 v[12:15], v134
	ds_read_b128 v[16:19], v134 offset:1024
	ds_read_b128 v[52:55], v134 offset:2048
	ds_read_b128 v[56:59], v134 offset:3072
	ds_read_b128 v[48:51], v154 offset:32768
	ds_read_b128 v[60:63], v154 offset:33792
	ds_read_b128 v[64:67], v154 offset:34816
	ds_read_b128 v[210:213], v154 offset:35840
	ds_read_b128 v[214:217], v154 offset:36864
	ds_read_b128 v[218:221], v154 offset:37888
	ds_read_b128 v[222:225], v154 offset:38912
	ds_read_b128 v[226:229], v154 offset:39936
	ds_read_b128 v[230:233], v135
	ds_read_b128 v[234:237], v135 offset:1024
	ds_read_b128 v[238:241], v135 offset:2048
	ds_read_b128 v[242:245], v135 offset:3072
	s_add_u32 s10, s16, 0x100
	s_addc_u32 s11, s17, 0
	s_mov_b32 m0, s26
	s_nop 0
	global_load_lds_dwordx4 v139, s[10:11]
	s_mov_b32 m0, s27
	s_nop 0
	global_load_lds_dwordx4 v152, s[10:11]
	s_waitcnt lgkmcnt(11)
	v_mfma_f32_16x16x32_bf16 v[68:71], v[12:15], v[48:51], v[68:71]
	s_waitcnt lgkmcnt(10)
	v_mfma_f32_16x16x32_bf16 v[128:131], v[16:19], v[60:63], v[68:71]
	v_mfma_f32_16x16x32_bf16 v[68:71], v[52:55], v[48:51], v[72:75]
	v_mfma_f32_16x16x32_bf16 v[124:127], v[56:59], v[60:63], v[68:71]
	s_waitcnt lgkmcnt(9)
	v_mfma_f32_16x16x32_bf16 v[68:71], v[12:15], v[64:67], v[76:79]
	s_waitcnt lgkmcnt(8)
	v_mfma_f32_16x16x32_bf16 v[112:115], v[16:19], v[210:213], v[68:71]
	v_mfma_f32_16x16x32_bf16 v[68:71], v[52:55], v[64:67], v[80:83]
	v_mfma_f32_16x16x32_bf16 v[108:111], v[56:59], v[210:213], v[68:71]
	s_waitcnt lgkmcnt(7)
	v_mfma_f32_16x16x32_bf16 v[68:71], v[12:15], v[214:217], v[84:87]
	s_waitcnt lgkmcnt(6)
	v_mfma_f32_16x16x32_bf16 v[96:99], v[16:19], v[218:221], v[68:71]
	v_mfma_f32_16x16x32_bf16 v[68:71], v[52:55], v[214:217], v[88:91]
	v_mfma_f32_16x16x32_bf16 v[92:95], v[56:59], v[218:221], v[68:71]
	s_waitcnt lgkmcnt(5)
	v_mfma_f32_16x16x32_bf16 v[68:71], v[12:15], v[222:225], v[100:103]
	s_waitcnt lgkmcnt(4)
	v_mfma_f32_16x16x32_bf16 v[80:83], v[16:19], v[226:229], v[68:71]
	v_mfma_f32_16x16x32_bf16 v[68:71], v[52:55], v[222:225], v[104:107]
	v_mfma_f32_16x16x32_bf16 v[76:79], v[56:59], v[226:229], v[68:71]
	s_add_u32 s10, s18, 0x100
	s_addc_u32 s11, s19, 0
	s_mov_b32 m0, s25
	s_nop 0
	global_load_lds_dwordx4 v138, s[10:11]
	s_mov_b32 m0, s28
	s_nop 0
	global_load_lds_dwordx4 v140, s[10:11]
	s_waitcnt lgkmcnt(1)
	v_mfma_f32_16x16x32_bf16 v[20:23], v[238:241], v[48:51], v[20:23]
	v_mfma_f32_16x16x32_bf16 v[68:71], v[230:233], v[48:51], v[116:119]
	s_waitcnt lgkmcnt(0)
	v_mfma_f32_16x16x32_bf16 v[116:119], v[242:245], v[60:63], v[20:23]
	v_mfma_f32_16x16x32_bf16 v[20:23], v[230:233], v[64:67], v[24:27]
	v_mfma_f32_16x16x32_bf16 v[104:107], v[234:237], v[210:213], v[20:23]
	v_mfma_f32_16x16x32_bf16 v[20:23], v[238:241], v[64:67], v[28:31]
	v_mfma_f32_16x16x32_bf16 v[100:103], v[242:245], v[210:213], v[20:23]
	v_mfma_f32_16x16x32_bf16 v[20:23], v[230:233], v[214:217], v[32:35]
	v_mfma_f32_16x16x32_bf16 v[88:91], v[234:237], v[218:221], v[20:23]
	v_mfma_f32_16x16x32_bf16 v[20:23], v[238:241], v[214:217], v[36:39]
	v_mfma_f32_16x16x32_bf16 v[84:87], v[242:245], v[218:221], v[20:23]
	v_mfma_f32_16x16x32_bf16 v[20:23], v[230:233], v[222:225], v[40:43]
	v_mfma_f32_16x16x32_bf16 v[72:75], v[234:237], v[226:229], v[20:23]
	v_mfma_f32_16x16x32_bf16 v[20:23], v[238:241], v[222:225], v[44:47]
	v_mfma_f32_16x16x32_bf16 v[120:123], v[234:237], v[60:63], v[68:71]
	v_mfma_f32_16x16x32_bf16 v[68:71], v[242:245], v[226:229], v[20:23]
	s_waitcnt vmcnt(4) lgkmcnt(0)
	s_barrier
	s_nop 4
	ds_read_b128 v[20:23], v154 offset:49152
	ds_read_b128 v[24:27], v154 offset:50176
	ds_read_b128 v[36:39], v154 offset:51200
	ds_read_b128 v[210:213], v154 offset:52224
	ds_read_b128 v[214:217], v154 offset:53248
	ds_read_b128 v[218:221], v154 offset:54272
	ds_read_b128 v[222:225], v154 offset:55296
	ds_read_b128 v[226:229], v154 offset:56320
	s_add_u32 s10, s16, 0x160100
	s_addc_u32 s11, s17, 0
	s_mov_b32 m0, s29
	s_nop 0
	global_load_lds_dwordx4 v139, s[10:11]
	s_mov_b32 m0, s36
	s_nop 0
	global_load_lds_dwordx4 v152, s[10:11]
	s_waitcnt lgkmcnt(7)
	v_mfma_f32_16x16x32_bf16 v[28:31], v[12:15], v[20:23], v[142:145]
	s_waitcnt lgkmcnt(6)
	v_mfma_f32_16x16x32_bf16 v[64:67], v[16:19], v[24:27], v[28:31]
	v_mfma_f32_16x16x32_bf16 v[28:31], v[52:55], v[20:23], v[146:149]
	v_mfma_f32_16x16x32_bf16 v[60:63], v[56:59], v[24:27], v[28:31]
	s_waitcnt lgkmcnt(5)
	v_mfma_f32_16x16x32_bf16 v[28:31], v[12:15], v[36:39], v[156:159]
	s_waitcnt lgkmcnt(4)
	v_mfma_f32_16x16x32_bf16 v[48:51], v[16:19], v[210:213], v[28:31]
	v_mfma_f32_16x16x32_bf16 v[28:31], v[52:55], v[36:39], v[160:163]
	v_mfma_f32_16x16x32_bf16 v[44:47], v[56:59], v[210:213], v[28:31]
	s_waitcnt lgkmcnt(3)
	v_mfma_f32_16x16x32_bf16 v[28:31], v[12:15], v[214:217], v[170:173]
	s_waitcnt lgkmcnt(1)
	v_mfma_f32_16x16x32_bf16 v[4:7], v[12:15], v[222:225], v[4:7]
	v_mfma_f32_16x16x32_bf16 v[32:35], v[16:19], v[218:221], v[28:31]
	v_mfma_f32_16x16x32_bf16 v[28:31], v[52:55], v[214:217], v[174:177]
	s_waitcnt lgkmcnt(0)
	v_mfma_f32_16x16x32_bf16 v[16:19], v[16:19], v[226:229], v[4:7]
	v_mfma_f32_16x16x32_bf16 v[4:7], v[52:55], v[222:225], v[8:11]
	v_mfma_f32_16x16x32_bf16 v[28:31], v[56:59], v[218:221], v[28:31]
	v_mfma_f32_16x16x32_bf16 v[12:15], v[56:59], v[226:229], v[4:7]
	s_add_u32 s10, s18, 0x160100
	s_addc_u32 s11, s19, 0
	s_mov_b32 m0, s37
	s_nop 0
	global_load_lds_dwordx4 v138, s[10:11]
	s_mov_b32 m0, s38
	s_nop 0
	global_load_lds_dwordx4 v140, s[10:11]
	v_mfma_f32_16x16x32_bf16 v[4:7], v[230:233], v[20:23], v[178:181]
	s_mov_b32 s10, 2
	v_mfma_f32_16x16x32_bf16 v[56:59], v[234:237], v[24:27], v[4:7]
	v_mfma_f32_16x16x32_bf16 v[4:7], v[238:241], v[20:23], v[182:185]
	v_mfma_f32_16x16x32_bf16 v[52:55], v[242:245], v[24:27], v[4:7]
	v_mfma_f32_16x16x32_bf16 v[4:7], v[230:233], v[36:39], v[186:189]
	v_mfma_f32_16x16x32_bf16 v[40:43], v[234:237], v[210:213], v[4:7]
	v_mfma_f32_16x16x32_bf16 v[4:7], v[238:241], v[36:39], v[190:193]
	v_mfma_f32_16x16x32_bf16 v[36:39], v[242:245], v[210:213], v[4:7]
	v_mfma_f32_16x16x32_bf16 v[4:7], v[230:233], v[214:217], v[194:197]
	v_mfma_f32_16x16x32_bf16 v[24:27], v[234:237], v[218:221], v[4:7]
	v_mfma_f32_16x16x32_bf16 v[4:7], v[238:241], v[214:217], v[198:201]
	v_mfma_f32_16x16x32_bf16 v[20:23], v[242:245], v[218:221], v[4:7]
	v_mfma_f32_16x16x32_bf16 v[4:7], v[230:233], v[222:225], v[202:205]
	v_mfma_f32_16x16x32_bf16 v[8:11], v[234:237], v[226:229], v[4:7]
	v_mfma_f32_16x16x32_bf16 v[4:7], v[238:241], v[222:225], v[206:209]
	v_mfma_f32_16x16x32_bf16 v[4:7], v[242:245], v[226:229], v[4:7]

; template <class Epi, class Sched>
; __device__ __forceinline__ void gemm_simple(PG8_LAS unsigned char* lds, const Gemm g, const Sched& S, const Epi& E, int wave_s) {
;     ...
;         for (; t < nt; t += 2) {
;             const bool last = (t == nt - 2);
;             PG8_TILE(0, cA + (size_t)(t + 1) * kstep, cB + (size_t)(t + 1) * kstep, true);
.LBB0_63:
	s_waitcnt vmcnt(2) lgkmcnt(0)
	s_barrier
	ds_read_b128 v[142:145], v132
	ds_read_b128 v[170:173], v154
	ds_read_b128 v[156:159], v132 offset:2048
	ds_read_b128 v[178:181], v154 offset:2048
	ds_read_b128 v[186:189], v154 offset:4096
	ds_read_b128 v[194:197], v154 offset:6144
	ds_read_b128 v[146:149], v132 offset:1024
	ds_read_b128 v[174:177], v154 offset:1024
	ds_read_b128 v[160:163], v132 offset:3072
	ds_read_b128 v[182:185], v154 offset:3072
	ds_read_b128 v[190:193], v154 offset:5120
	ds_read_b128 v[198:201], v154 offset:7168
	ds_read_b128 v[202:205], v133
	ds_read_b128 v[210:213], v133 offset:2048
	ds_read_b128 v[206:209], v133 offset:1024
	ds_read_b128 v[214:217], v133 offset:3072
	s_add_u32 s16, s63, s54
	s_addc_u32 s17, s64, 0
	s_mov_b32 m0, s39
	s_nop 0
	global_load_lds_dwordx4 v139, s[16:17]
	s_mov_b32 m0, s43
	s_nop 0
	global_load_lds_dwordx4 v152, s[16:17]
	s_waitcnt lgkmcnt(14)
	v_mfma_f32_16x16x32_bf16 v[128:131], v[142:145], v[170:173], v[128:131]
	s_waitcnt lgkmcnt(13)
	v_mfma_f32_16x16x32_bf16 v[124:127], v[156:159], v[170:173], v[124:127]
	s_waitcnt lgkmcnt(12)
	v_mfma_f32_16x16x32_bf16 v[112:115], v[142:145], v[178:181], v[112:115]
	v_mfma_f32_16x16x32_bf16 v[108:111], v[156:159], v[178:181], v[108:111]
	s_waitcnt lgkmcnt(11)
	v_mfma_f32_16x16x32_bf16 v[96:99], v[142:145], v[186:189], v[96:99]
	v_mfma_f32_16x16x32_bf16 v[92:95], v[156:159], v[186:189], v[92:95]
	s_waitcnt lgkmcnt(10)
	v_mfma_f32_16x16x32_bf16 v[80:83], v[142:145], v[194:197], v[80:83]
	v_mfma_f32_16x16x32_bf16 v[76:79], v[156:159], v[194:197], v[76:79]
	s_waitcnt lgkmcnt(8)
	v_mfma_f32_16x16x32_bf16 v[128:131], v[146:149], v[174:177], v[128:131]
	s_waitcnt lgkmcnt(7)
	v_mfma_f32_16x16x32_bf16 v[124:127], v[160:163], v[174:177], v[124:127]
	s_waitcnt lgkmcnt(6)
	v_mfma_f32_16x16x32_bf16 v[112:115], v[146:149], v[182:185], v[112:115]
	v_mfma_f32_16x16x32_bf16 v[108:111], v[160:163], v[182:185], v[108:111]
	s_waitcnt lgkmcnt(5)
	v_mfma_f32_16x16x32_bf16 v[96:99], v[146:149], v[190:193], v[96:99]
	v_mfma_f32_16x16x32_bf16 v[92:95], v[160:163], v[190:193], v[92:95]
	s_waitcnt lgkmcnt(4)
	v_mfma_f32_16x16x32_bf16 v[80:83], v[146:149], v[198:201], v[80:83]
	v_mfma_f32_16x16x32_bf16 v[76:79], v[160:163], v[198:201], v[76:79]
	s_add_u32 s16, s18, s54
	s_addc_u32 s17, s19, 0
	s_mov_b32 m0, s40
	s_nop 0
	global_load_lds_dwordx4 v138, s[16:17]
	s_mov_b32 m0, s44
	s_nop 0
	global_load_lds_dwordx4 v140, s[16:17]
	s_waitcnt lgkmcnt(3)
	v_mfma_f32_16x16x32_bf16 v[120:123], v[202:205], v[170:173], v[120:123]
	s_waitcnt lgkmcnt(2)
	v_mfma_f32_16x16x32_bf16 v[116:119], v[210:213], v[170:173], v[116:119]
	v_mfma_f32_16x16x32_bf16 v[104:107], v[202:205], v[178:181], v[104:107]
	v_mfma_f32_16x16x32_bf16 v[100:103], v[210:213], v[178:181], v[100:103]
	v_mfma_f32_16x16x32_bf16 v[88:91], v[202:205], v[186:189], v[88:91]
	v_mfma_f32_16x16x32_bf16 v[84:87], v[210:213], v[186:189], v[84:87]
	v_mfma_f32_16x16x32_bf16 v[72:75], v[202:205], v[194:197], v[72:75]
	v_mfma_f32_16x16x32_bf16 v[68:71], v[210:213], v[194:197], v[68:71]
	s_waitcnt lgkmcnt(1)
	v_mfma_f32_16x16x32_bf16 v[120:123], v[206:209], v[174:177], v[120:123]
	s_waitcnt lgkmcnt(0)
	v_mfma_f32_16x16x32_bf16 v[116:119], v[214:217], v[174:177], v[116:119]
	v_mfma_f32_16x16x32_bf16 v[104:107], v[206:209], v[182:185], v[104:107]
	v_mfma_f32_16x16x32_bf16 v[100:103], v[214:217], v[182:185], v[100:103]
	v_mfma_f32_16x16x32_bf16 v[88:91], v[206:209], v[190:193], v[88:91]
	v_mfma_f32_16x16x32_bf16 v[84:87], v[214:217], v[190:193], v[84:87]
	v_mfma_f32_16x16x32_bf16 v[72:75], v[206:209], v[198:201], v[72:75]
	v_mfma_f32_16x16x32_bf16 v[68:71], v[214:217], v[198:201], v[68:71]
	s_waitcnt vmcnt(4) lgkmcnt(0)
	s_barrier
	ds_read_b128 v[170:173], v154 offset:16384
	ds_read_b128 v[178:181], v154 offset:18432
	ds_read_b128 v[186:189], v154 offset:20480
	ds_read_b128 v[194:197], v154 offset:22528
	ds_read_b128 v[174:177], v154 offset:17408
	ds_read_b128 v[182:185], v154 offset:19456
	ds_read_b128 v[190:193], v154 offset:21504
	ds_read_b128 v[198:201], v154 offset:23552
	s_add_u32 s16, s61, s54
	s_addc_u32 s17, s62, 0
	s_mov_b32 m0, s41
	s_nop 0
	global_load_lds_dwordx4 v139, s[16:17]
	s_mov_b32 m0, s45
	s_nop 0
	global_load_lds_dwordx4 v152, s[16:17]
	s_waitcnt lgkmcnt(7)
	v_mfma_f32_16x16x32_bf16 v[64:67], v[142:145], v[170:173], v[64:67]
	v_mfma_f32_16x16x32_bf16 v[60:63], v[156:159], v[170:173], v[60:63]
	s_waitcnt lgkmcnt(6)
	v_mfma_f32_16x16x32_bf16 v[48:51], v[142:145], v[178:181], v[48:51]
	v_mfma_f32_16x16x32_bf16 v[44:47], v[156:159], v[178:181], v[44:47]
	s_waitcnt lgkmcnt(5)
	v_mfma_f32_16x16x32_bf16 v[32:35], v[142:145], v[186:189], v[32:35]
	v_mfma_f32_16x16x32_bf16 v[28:31], v[156:159], v[186:189], v[28:31]
	s_waitcnt lgkmcnt(4)
	v_mfma_f32_16x16x32_bf16 v[16:19], v[142:145], v[194:197], v[16:19]
	v_mfma_f32_16x16x32_bf16 v[12:15], v[156:159], v[194:197], v[12:15]
	s_waitcnt lgkmcnt(3)
	v_mfma_f32_16x16x32_bf16 v[64:67], v[146:149], v[174:177], v[64:67]
	v_mfma_f32_16x16x32_bf16 v[60:63], v[160:163], v[174:177], v[60:63]
	s_waitcnt lgkmcnt(2)
	v_mfma_f32_16x16x32_bf16 v[48:51], v[146:149], v[182:185], v[48:51]
	v_mfma_f32_16x16x32_bf16 v[44:47], v[160:163], v[182:185], v[44:47]
	s_waitcnt lgkmcnt(1)
	v_mfma_f32_16x16x32_bf16 v[32:35], v[146:149], v[190:193], v[32:35]
	v_mfma_f32_16x16x32_bf16 v[28:31], v[160:163], v[190:193], v[28:31]
	s_waitcnt lgkmcnt(0)
	v_mfma_f32_16x16x32_bf16 v[16:19], v[146:149], v[198:201], v[16:19]
	v_mfma_f32_16x16x32_bf16 v[12:15], v[160:163], v[198:201], v[12:15]
	s_add_u32 s16, s59, s54
	s_addc_u32 s17, s60, 0
	s_mov_b32 m0, s42
	s_nop 0
	global_load_lds_dwordx4 v138, s[16:17]
	s_mov_b32 m0, s46
	s_nop 0
	global_load_lds_dwordx4 v140, s[16:17]
	v_mfma_f32_16x16x32_bf16 v[56:59], v[202:205], v[170:173], v[56:59]
	s_add_u32 s16, s57, s54
	s_addc_u32 s17, s58, 0
	s_add_u32 s65, s55, s54
	v_mfma_f32_16x16x32_bf16 v[52:55], v[210:213], v[170:173], v[52:55]
	s_addc_u32 s66, s56, 0
	v_mfma_f32_16x16x32_bf16 v[40:43], v[202:205], v[178:181], v[40:43]
	v_mfma_f32_16x16x32_bf16 v[36:39], v[210:213], v[178:181], v[36:39]
	v_mfma_f32_16x16x32_bf16 v[24:27], v[202:205], v[186:189], v[24:27]
	v_mfma_f32_16x16x32_bf16 v[20:23], v[210:213], v[186:189], v[20:23]
	v_mfma_f32_16x16x32_bf16 v[8:11], v[202:205], v[194:197], v[8:11]
	v_mfma_f32_16x16x32_bf16 v[4:7], v[210:213], v[194:197], v[4:7]
	v_mfma_f32_16x16x32_bf16 v[56:59], v[206:209], v[174:177], v[56:59]
	v_mfma_f32_16x16x32_bf16 v[52:55], v[214:217], v[174:177], v[52:55]
	v_mfma_f32_16x16x32_bf16 v[40:43], v[206:209], v[182:185], v[40:43]
	v_mfma_f32_16x16x32_bf16 v[36:39], v[214:217], v[182:185], v[36:39]
	v_mfma_f32_16x16x32_bf16 v[24:27], v[206:209], v[190:193], v[24:27]
	v_mfma_f32_16x16x32_bf16 v[20:23], v[214:217], v[190:193], v[20:23]
	v_mfma_f32_16x16x32_bf16 v[8:11], v[206:209], v[198:201], v[8:11]
	v_mfma_f32_16x16x32_bf16 v[4:7], v[214:217], v[198:201], v[4:7]
	s_waitcnt vmcnt(2) lgkmcnt(0)
	s_barrier
; template <class Epi, class Sched>
; __device__ __forceinline__ void gemm_simple(PG8_LAS unsigned char* lds, const Gemm g, const Sched& S, const Epi& E, int wave_s) {
;     ...
;             const bool last = (t == nt - 2);
;             PG8_TILE(0, cA + (size_t)(t + 1) * kstep, cB + (size_t)(t + 1) * kstep, true);
;             const char* a2 = last ? nA : cA + (size_t)(t + 2) * kstep; const char* b2 = last ? nB : cB + (size_t)(t + 2) * kstep;
;             PG8_TILE(1, a2, b2, (!last || has_next));
	ds_read_b128 v[142:145], v134
	ds_read_b128 v[170:173], v154 offset:32768
	ds_read_b128 v[156:159], v134 offset:2048
	ds_read_b128 v[178:181], v154 offset:34816
	ds_read_b128 v[186:189], v154 offset:36864
	ds_read_b128 v[194:197], v154 offset:38912
	ds_read_b128 v[146:149], v134 offset:1024
	ds_read_b128 v[174:177], v154 offset:33792
	ds_read_b128 v[160:163], v134 offset:3072
	ds_read_b128 v[182:185], v154 offset:35840
	ds_read_b128 v[190:193], v154 offset:37888
	ds_read_b128 v[198:201], v154 offset:39936
	ds_read_b128 v[202:205], v135
	ds_read_b128 v[210:213], v135 offset:2048
	ds_read_b128 v[206:209], v135 offset:1024
	ds_read_b128 v[214:217], v135 offset:3072
	s_cmp_eq_u32 s54, s10
	s_cselect_b32 s17, s5, s17
	s_cselect_b32 s16, s4, s16
	s_cselect_b32 s67, s9, s66
	s_cselect_b32 s66, s8, s65
	s_mov_b32 m0, s26
	s_nop 0
	global_load_lds_dwordx4 v139, s[66:67]
	s_mov_b32 m0, s27
	s_nop 0
	global_load_lds_dwordx4 v152, s[66:67]
	s_waitcnt lgkmcnt(14)
	v_mfma_f32_16x16x32_bf16 v[128:131], v[142:145], v[170:173], v[128:131]
	s_waitcnt lgkmcnt(13)
	v_mfma_f32_16x16x32_bf16 v[124:127], v[156:159], v[170:173], v[124:127]
	s_waitcnt lgkmcnt(12)
	v_mfma_f32_16x16x32_bf16 v[112:115], v[142:145], v[178:181], v[112:115]
	v_mfma_f32_16x16x32_bf16 v[108:111], v[156:159], v[178:181], v[108:111]
	s_waitcnt lgkmcnt(11)
	v_mfma_f32_16x16x32_bf16 v[96:99], v[142:145], v[186:189], v[96:99]
	v_mfma_f32_16x16x32_bf16 v[92:95], v[156:159], v[186:189], v[92:95]
	s_waitcnt lgkmcnt(10)
	v_mfma_f32_16x16x32_bf16 v[80:83], v[142:145], v[194:197], v[80:83]
	v_mfma_f32_16x16x32_bf16 v[76:79], v[156:159], v[194:197], v[76:79]
	s_waitcnt lgkmcnt(8)
	v_mfma_f32_16x16x32_bf16 v[128:131], v[146:149], v[174:177], v[128:131]
	s_waitcnt lgkmcnt(7)
	v_mfma_f32_16x16x32_bf16 v[124:127], v[160:163], v[174:177], v[124:127]
	s_waitcnt lgkmcnt(6)
	v_mfma_f32_16x16x32_bf16 v[112:115], v[146:149], v[182:185], v[112:115]
	v_mfma_f32_16x16x32_bf16 v[108:111], v[160:163], v[182:185], v[108:111]
	s_waitcnt lgkmcnt(5)
	v_mfma_f32_16x16x32_bf16 v[96:99], v[146:149], v[190:193], v[96:99]
	v_mfma_f32_16x16x32_bf16 v[92:95], v[160:163], v[190:193], v[92:95]
	s_waitcnt lgkmcnt(4)
	v_mfma_f32_16x16x32_bf16 v[80:83], v[146:149], v[198:201], v[80:83]
	v_mfma_f32_16x16x32_bf16 v[76:79], v[160:163], v[198:201], v[76:79]
	s_mov_b32 m0, s25
	s_nop 0
	global_load_lds_dwordx4 v138, s[16:17]
	s_mov_b32 m0, s28
	s_nop 0
	global_load_lds_dwordx4 v140, s[16:17]
	s_waitcnt lgkmcnt(3)
	v_mfma_f32_16x16x32_bf16 v[120:123], v[202:205], v[170:173], v[120:123]
	s_waitcnt lgkmcnt(2)
	v_mfma_f32_16x16x32_bf16 v[116:119], v[210:213], v[170:173], v[116:119]
	v_mfma_f32_16x16x32_bf16 v[104:107], v[202:205], v[178:181], v[104:107]
	v_mfma_f32_16x16x32_bf16 v[100:103], v[210:213], v[178:181], v[100:103]
	v_mfma_f32_16x16x32_bf16 v[88:91], v[202:205], v[186:189], v[88:91]
	v_mfma_f32_16x16x32_bf16 v[84:87], v[210:213], v[186:189], v[84:87]
	v_mfma_f32_16x16x32_bf16 v[72:75], v[202:205], v[194:197], v[72:75]
	v_mfma_f32_16x16x32_bf16 v[68:71], v[210:213], v[194:197], v[68:71]
	s_waitcnt lgkmcnt(1)
	v_mfma_f32_16x16x32_bf16 v[120:123], v[206:209], v[174:177], v[120:123]
	s_waitcnt lgkmcnt(0)
	v_mfma_f32_16x16x32_bf16 v[116:119], v[214:217], v[174:177], v[116:119]
	v_mfma_f32_16x16x32_bf16 v[104:107], v[206:209], v[182:185], v[104:107]
	v_mfma_f32_16x16x32_bf16 v[100:103], v[214:217], v[182:185], v[100:103]
	v_mfma_f32_16x16x32_bf16 v[88:91], v[206:209], v[190:193], v[88:91]
	v_mfma_f32_16x16x32_bf16 v[84:87], v[214:217], v[190:193], v[84:87]
	v_mfma_f32_16x16x32_bf16 v[72:75], v[206:209], v[198:201], v[72:75]
	v_mfma_f32_16x16x32_bf16 v[68:71], v[214:217], v[198:201], v[68:71]
	s_waitcnt vmcnt(4) lgkmcnt(0)
	s_barrier
	ds_read_b128 v[170:173], v154 offset:49152
	ds_read_b128 v[178:181], v154 offset:51200
	ds_read_b128 v[186:189], v154 offset:53248
	ds_read_b128 v[194:197], v154 offset:55296
	ds_read_b128 v[174:177], v154 offset:50176
	ds_read_b128 v[182:185], v154 offset:52224
	ds_read_b128 v[190:193], v154 offset:54272
	ds_read_b128 v[198:201], v154 offset:56320
	s_add_u32 s66, s66, 0x160000
	s_addc_u32 s67, s67, 0
	s_mov_b32 m0, s29
	s_nop 0
	global_load_lds_dwordx4 v139, s[66:67]
	s_mov_b32 m0, s36
	s_nop 0
	global_load_lds_dwordx4 v152, s[66:67]
	s_waitcnt lgkmcnt(7)
	v_mfma_f32_16x16x32_bf16 v[64:67], v[142:145], v[170:173], v[64:67]
	v_mfma_f32_16x16x32_bf16 v[60:63], v[156:159], v[170:173], v[60:63]
	s_waitcnt lgkmcnt(6)
	v_mfma_f32_16x16x32_bf16 v[48:51], v[142:145], v[178:181], v[48:51]
	v_mfma_f32_16x16x32_bf16 v[44:47], v[156:159], v[178:181], v[44:47]
	s_waitcnt lgkmcnt(5)
	v_mfma_f32_16x16x32_bf16 v[32:35], v[142:145], v[186:189], v[32:35]
	v_mfma_f32_16x16x32_bf16 v[28:31], v[156:159], v[186:189], v[28:31]
	s_waitcnt lgkmcnt(4)
	v_mfma_f32_16x16x32_bf16 v[16:19], v[142:145], v[194:197], v[16:19]
	v_mfma_f32_16x16x32_bf16 v[12:15], v[156:159], v[194:197], v[12:15]
	s_waitcnt lgkmcnt(3)
	v_mfma_f32_16x16x32_bf16 v[64:67], v[146:149], v[174:177], v[64:67]
	v_mfma_f32_16x16x32_bf16 v[60:63], v[160:163], v[174:177], v[60:63]
	s_waitcnt lgkmcnt(2)
	v_mfma_f32_16x16x32_bf16 v[48:51], v[146:149], v[182:185], v[48:51]
	v_mfma_f32_16x16x32_bf16 v[44:47], v[160:163], v[182:185], v[44:47]
	s_waitcnt lgkmcnt(1)
	v_mfma_f32_16x16x32_bf16 v[32:35], v[146:149], v[190:193], v[32:35]
	v_mfma_f32_16x16x32_bf16 v[28:31], v[160:163], v[190:193], v[28:31]
	s_waitcnt lgkmcnt(0)
; template <class Epi, class Sched>
; __device__ __forceinline__ void gemm_simple(PG8_LAS unsigned char* lds, const Gemm g, const Sched& S, const Epi& E, int wave_s) {
;     ...
;             const bool last = (t == nt - 2);
;             PG8_TILE(0, cA + (size_t)(t + 1) * kstep, cB + (size_t)(t + 1) * kstep, true);
;             const char* a2 = last ? nA : cA + (size_t)(t + 2) * kstep; const char* b2 = last ? nB : cB + (size_t)(t + 2) * kstep;
;             PG8_TILE(1, a2, b2, (!last || has_next));
;     __device__ __forceinline__ void operator()(const f32x4 (&acc)[2][2][4][2], const Unit& u, int wr, int wc, int fr, int fq, const LAS float* rt) const {
;         const int row0 = u.pm * 256 + wr * 64 + fr, col0 = u.pn * 256 + wc * 32 + 8 * fq, lane = fq * 16 + fr;
; #pragma unroll
;         for (int ai = 0; ai < 2; ++ai)
; #pragma unroll
;             for (int m = 0; m < 4; ++m) { const size_t row = (size_t)(row0 + ai * 128 + m * 16); const float rs = (MODE == 1) ? rt[ai * 128 + wr * 64 + m * 16 + fr] : 1.0f; float ss = 0.f;
; #pragma unroll
;                 for (int bj = 0; bj < 2; ++bj) { const size_t o = row * DM + col0 + bj * 128; const u32x4 xv = *(const u32x4*)(xin + o);
;                     f32x4 v0 = acc[ai][bj][m][0], v1 = acc[ai][bj][m][1];
;                     if (MODE == 1) { const u32x4 p = *(const u32x4*)(pe + o);
;                         v0[0] = sigmoidf_(v0[0] * rs) * bflo(p.x); v0[1] = sigmoidf_(v0[1] * rs) * bfhi(p.x); v0[2] = sigmoidf_(v0[2] * rs) * bflo(p.y); v0[3] = sigmoidf_(v0[3] * rs) * bfhi(p.y);
;                         v1[0] = sigmoidf_(v1[0] * rs) * bflo(p.z); v1[1] = sigmoidf_(v1[1] * rs) * bfhi(p.z); v1[2] = sigmoidf_(v1[2] * rs) * bflo(p.w); v1[3] = sigmoidf_(v1[3] * rs) * bfhi(p.w); }
;                     v0[0] += bflo(xv.x); v0[1] += bfhi(xv.x); v0[2] += bflo(xv.y); v0[3] += bfhi(xv.y); v1[0] += bflo(xv.z); v1[1] += bfhi(xv.z); v1[2] += bflo(xv.w); v1[3] += bfhi(xv.w);
;                     ss += (v0[0] * v0[0] + v0[1] * v0[1]) + (v0[2] * v0[2] + v0[3] * v0[3]) + (v1[0] * v1[0] + v1[1] * v1[1]) + (v1[2] * v1[2] + v1[3] * v1[3]);
;                     u32x4 w; w.x = cvt_pk_bf16(v0[0], v0[1]); w.y = cvt_pk_bf16(v0[2], v0[3]); w.z = cvt_pk_bf16(v1[0], v1[1]); w.w = cvt_pk_bf16(v1[2], v1[3]);
;                     __builtin_nontemporal_store(w, (u32x4*)(xout + o)); }
	v_mfma_f32_16x16x32_bf16 v[16:19], v[146:149], v[198:201], v[16:19]
	v_mfma_f32_16x16x32_bf16 v[12:15], v[160:163], v[198:201], v[12:15]
	s_add_u32 s16, s16, 0x160000
	s_addc_u32 s17, s17, 0
	s_mov_b32 m0, s37
	s_nop 0
	global_load_lds_dwordx4 v138, s[16:17]
	s_mov_b32 m0, s38
	s_nop 0
	global_load_lds_dwordx4 v140, s[16:17]
	s_add_i32 s53, s53, 2
	s_add_u32 s10, s10, 0xffffff00
	s_addc_u32 s11, s11, -1
	s_add_u32 s55, s55, 0x100
	s_addc_u32 s56, s56, 0
	s_add_u32 s57, s57, 0x100
	s_addc_u32 s58, s58, 0
	s_add_u32 s59, s59, 0x100
	v_mfma_f32_16x16x32_bf16 v[56:59], v[202:205], v[170:173], v[56:59]
	s_addc_u32 s60, s60, 0
	s_add_u32 s61, s61, 0x100
	s_addc_u32 s62, s62, 0
	v_mfma_f32_16x16x32_bf16 v[52:55], v[210:213], v[170:173], v[52:55]
	s_add_u32 s18, s18, 0x100
	s_addc_u32 s19, s19, 0
	s_add_u32 s63, s63, 0x100
	v_mfma_f32_16x16x32_bf16 v[40:43], v[202:205], v[178:181], v[40:43]
	s_addc_u32 s64, s64, 0
	s_cmpk_lt_u32 s53, 0x56
	v_mfma_f32_16x16x32_bf16 v[36:39], v[210:213], v[178:181], v[36:39]
	v_mfma_f32_16x16x32_bf16 v[24:27], v[202:205], v[186:189], v[24:27]
	v_mfma_f32_16x16x32_bf16 v[20:23], v[210:213], v[186:189], v[20:23]
	v_mfma_f32_16x16x32_bf16 v[8:11], v[202:205], v[194:197], v[8:11]
	v_mfma_f32_16x16x32_bf16 v[4:7], v[210:213], v[194:197], v[4:7]
	v_mfma_f32_16x16x32_bf16 v[56:59], v[206:209], v[174:177], v[56:59]
	v_mfma_f32_16x16x32_bf16 v[52:55], v[214:217], v[174:177], v[52:55]
	v_mfma_f32_16x16x32_bf16 v[40:43], v[206:209], v[182:185], v[40:43]
	v_mfma_f32_16x16x32_bf16 v[36:39], v[214:217], v[182:185], v[36:39]
	v_mfma_f32_16x16x32_bf16 v[24:27], v[206:209], v[190:193], v[24:27]
	v_mfma_f32_16x16x32_bf16 v[20:23], v[214:217], v[190:193], v[20:23]
	v_mfma_f32_16x16x32_bf16 v[8:11], v[206:209], v[198:201], v[8:11]
	v_mfma_f32_16x16x32_bf16 v[4:7], v[214:217], v[198:201], v[4:7]
	s_cbranch_scc1 .LBB0_63
	v_mov_b32_e32 v132, v141
	s_lshl_b32 s10, s52, 8
	v_mbcnt_lo_u32_b32 v132, -1, v132
	v_mbcnt_hi_u32_b32 v135, -1, v132
	v_and_b32_e32 v136, 15, v135
	s_add_i32 s10, s10, s23
	v_or_b32_e32 v134, s10, v136
	s_lshl_b32 s10, s35, 8
	v_ashrrev_i32_e32 v137, 4, v135
	s_or_b32 s10, s10, s24
	v_lshl_add_u32 v132, v137, 3, s10
	v_lshlrev_b32_e32 v137, 6, v137
	v_lshlrev_b32_e32 v136, 2, v136
	s_movk_i32 s10, 0x80
	v_cmp_gt_u32_e32 vcc, 16, v135
	v_ashrrev_i32_e32 v135, 31, v134
	v_bitop3_b32 v156, v137, 64, v136 bitop3:0x36
	v_bitop3_b32 v155, v137, s10, v136 bitop3:0x36
	v_lshlrev_b64 v[136:137], 12, v[134:135]
	v_ashrrev_i32_e32 v133, 31, v132
	v_lshl_add_u64 v[136:137], s[94:95], 0, v[136:137]
	v_lshl_add_u64 v[136:137], v[132:133], 1, v[136:137]
	v_lshlrev_b32_e32 v236, 12, v134
	v_lshl_add_u32 v236, v132, 1, v236
	global_load_dwordx4 v[172:175], v236, s[94:95]
	global_load_dwordx4 v[176:179], v236, s[94:95] offset:256
	v_add_u32_e32 v237, 0x10000, v236
	global_load_dwordx4 v[180:183], v237, s[94:95]
	global_load_dwordx4 v[184:187], v237, s[94:95] offset:256
	v_add_u32_e32 v237, 0x20000, v236
	global_load_dwordx4 v[188:191], v237, s[94:95]
	global_load_dwordx4 v[192:195], v237, s[94:95] offset:256
	v_add_u32_e32 v237, 0x30000, v236
	global_load_dwordx4 v[196:199], v237, s[94:95]
	global_load_dwordx4 v[200:203], v237, s[94:95] offset:256
	v_add_u32_e32 v237, 0x80000, v236
	global_load_dwordx4 v[204:207], v237, s[94:95]
	global_load_dwordx4 v[208:211], v237, s[94:95] offset:256
	v_add_u32_e32 v237, 0x90000, v236
	global_load_dwordx4 v[212:215], v237, s[94:95]
	global_load_dwordx4 v[216:219], v237, s[94:95] offset:256
	v_add_u32_e32 v237, 0xa0000, v236
	global_load_dwordx4 v[220:223], v237, s[94:95]
	global_load_dwordx4 v[224:227], v237, s[94:95] offset:256
	v_add_u32_e32 v237, 0xb0000, v236
	global_load_dwordx4 v[228:231], v237, s[94:95]
	global_load_dwordx4 v[232:235], v237, s[94:95] offset:256
	s_lshl_b32 s10, s35, 2
	s_ashr_i32 s11, s10, 31
	s_waitcnt vmcnt(15)
	s_nop 1
	v_mov_b64_e32 v[142:143], v[172:173]
	v_mov_b64_e32 v[144:145], v[174:175]
	v_lshlrev_b32_e32 v146, 16, v142
	v_and_b32_e32 v142, 0xffff0000, v142
	v_add_f32_e32 v129, v129, v142
	v_lshlrev_b32_e32 v142, 16, v143
	v_add_f32_e32 v130, v130, v142
	v_and_b32_e32 v142, 0xffff0000, v143
	v_add_f32_e32 v131, v131, v142
	v_lshlrev_b32_e32 v142, 16, v144
	v_add_f32_e32 v142, v124, v142
	v_and_b32_e32 v124, 0xffff0000, v144
	v_add_f32_e32 v143, v125, v124
	v_lshlrev_b32_e32 v124, 16, v145
	v_add_f32_e32 v144, v126, v124
	v_and_b32_e32 v124, 0xffff0000, v145
	v_add_f32_e32 v128, v128, v146
	v_add_f32_e32 v127, v127, v124
	v_mul_f32_e32 v124, v129, v129
	v_mul_f32_e32 v125, v131, v131
	v_fmac_f32_e32 v124, v128, v128
	v_fmac_f32_e32 v125, v130, v130
	v_add_f32_e32 v124, v124, v125
	v_mul_f32_e32 v125, v143, v143
	v_fmac_f32_e32 v125, v142, v142
	v_add_f32_e32 v124, v125, v124
	v_mul_f32_e32 v125, v127, v127
	v_fmac_f32_e32 v125, v144, v144
	v_add_f32_e32 v145, v125, v124
	v_cvt_pk_bf16_f32 v124, v128, v129
	v_cvt_pk_bf16_f32 v125, v130, v131
	v_cvt_pk_bf16_f32 v126, v142, v143
	v_cvt_pk_bf16_f32 v127, v144, v127
	global_store_dwordx4 v[136:137], v[124:127], off nt
	s_waitcnt vmcnt(15)
	s_nop 1
	v_mov_b64_e32 v[124:125], v[176:177]
	v_mov_b64_e32 v[126:127], v[178:179]
	v_lshlrev_b32_e32 v128, 16, v124
	v_and_b32_e32 v124, 0xffff0000, v124
	v_add_f32_e32 v121, v121, v124
	v_lshlrev_b32_e32 v124, 16, v125
	v_add_f32_e32 v122, v122, v124
	v_and_b32_e32 v124, 0xffff0000, v125
	v_add_f32_e32 v123, v123, v124
	v_lshlrev_b32_e32 v124, 16, v126
	v_add_f32_e32 v124, v116, v124
	v_and_b32_e32 v116, 0xffff0000, v126
	v_add_f32_e32 v125, v117, v116
	v_lshlrev_b32_e32 v116, 16, v127
	v_add_f32_e32 v126, v118, v116
	v_and_b32_e32 v116, 0xffff0000, v127
	v_add_f32_e32 v120, v120, v128
	v_add_f32_e32 v119, v119, v116
	v_mul_f32_e32 v116, v121, v121
	v_mul_f32_e32 v117, v123, v123
	v_fmac_f32_e32 v116, v120, v120
	v_fmac_f32_e32 v117, v122, v122
	v_add_f32_e32 v116, v116, v117
	v_mul_f32_e32 v117, v125, v125
	v_fmac_f32_e32 v117, v124, v124
	v_add_f32_e32 v116, v117, v116
	v_mul_f32_e32 v117, v119, v119
	v_fmac_f32_e32 v117, v126, v126
	v_add_f32_e32 v116, v117, v116
	v_add_f32_e32 v127, v145, v116
	v_cvt_pk_bf16_f32 v116, v120, v121
	v_cvt_pk_bf16_f32 v117, v122, v123
	v_cvt_pk_bf16_f32 v118, v124, v125
	v_cvt_pk_bf16_f32 v119, v126, v119
	global_store_dwordx4 v[136:137], v[116:119], off offset:256 nt
	ds_bpermute_b32 v116, v156, v127
	s_waitcnt lgkmcnt(0)
	v_add_f32_e32 v116, v127, v116
	ds_bpermute_b32 v117, v155, v116
	s_and_saveexec_b64 s[16:17], vcc
	s_cbranch_execz .LBB0_66
	v_readlane_b32 s18, v255, 2
	v_lshlrev_b64 v[118:119], 7, v[134:135]
	v_readlane_b32 s19, v255, 3
	s_lshl_b32 s84, s22, 2
	s_mov_b32 s69, 0xf800000
	v_lshl_add_u64 v[118:119], s[18:19], 0, v[118:119]
	v_lshl_add_u64 v[118:119], s[10:11], 2, v[118:119]
	v_lshl_add_u64 v[118:119], v[118:119], 0, s[84:85]
	s_waitcnt lgkmcnt(0)
	v_add_f32_e32 v116, v116, v117
	global_store_dword v[118:119], v116, off

; #define LAS __attribute__((address_space(3)))
; template <class Epi, class Sched>
; __device__ __forceinline__ void gemm_simple(PG8_LAS unsigned char* lds, const Gemm g, const Sched& S, const Epi& E, int wave_s) {
;     ...
;     for (int i = 0; i < 2; ++i) { int R, C; stage_rc(tid * 16 + i * 8192, R, C); const int Rb = Epi::PERM ? ((R & ~31) + perm32(R & 31)) : R;
;         voffA[i] = (unsigned)(R * K + C) * 2u; voffB[i] = (unsigned)(Rb * K + C) * 2u; }
;     const size_t kstep = (size_t)(BK * 2), hstep = (size_t)HALF * K * 2, tstep = 2 * hstep;
;     const unsigned ldsw = (unsigned)wid * 1024u; const unsigned lds_u = (unsigned)(__UINTPTR_TYPE__)lds;
;     const int aoff = lds_byte(wr * 64 + fr, fq * 8), boff = lds_byte(wc * 32 + fr, fq * 8);
; __device__ __forceinline__ void rstd_table(const float* ssq, LAS unsigned char* lds, const Unit& u, int tid, int par) {
;     if (tid < 256) { const f32x4* p = (const f32x4*)(ssq + (size_t)(u.pm * 256 + tid) * 32); f32x4 a = p[0];
; #pragma unroll
;         for (int i = 1; i < 8; ++i) a += p[i];
;         ((LAS float*)(lds + 131072 + par * 1024))[tid] = 1.0f / sqrtf(((a[0] + a[1]) + (a[2] + a[3])) * (1.0f / DM) + 1e-6f); }
.LBB0_85:
	v_mov_b32_e32 v0, v141
	s_cmpk_gt_i32 s31, 0x15ff
	v_mbcnt_lo_u32_b32 v0, -1, v0
	v_mbcnt_hi_u32_b32 v4, -1, v0
	v_add_u32_e32 v138, s75, v4
	v_mov_b32_e32 v0, v141
	v_readfirstlane_b32 s18, v138
	s_cbranch_scc1 .LBB0_99
	v_bfe_i32 v3, v138, 27, 1
	v_lshlrev_b32_e32 v1, 4, v138
	v_lshrrev_b32_e32 v3, 22, v3
	v_add_u32_e32 v3, v1, v3
	v_and_b32_e32 v3, 0xfffffc00, v3
	v_sub_u32_e32 v3, v1, v3
	v_ashrrev_i32_e32 v2, 31, v138
	s_waitcnt lgkmcnt(0)
	v_lshrrev_b32_e32 v5, 4, v3
	v_lshrrev_b32_e32 v2, 26, v2
	v_bitop3_b32 v3, v5, v3, 32 bitop3:0x6c
	v_add_u32_e32 v2, v138, v2
	v_ashrrev_i32_e32 v6, 31, v3
	v_ashrrev_i32_e32 v2, 6, v2
	v_lshrrev_b32_e32 v6, 26, v6
	v_lshlrev_b32_e32 v5, 3, v2
	v_add_u32_e32 v6, v3, v6
	v_readlane_b32 s4, v254, 57
	v_and_b32_e32 v5, -16, v5
	v_ashrrev_i32_e32 v7, 6, v6
	v_and_b32_e32 v6, 0xc0, v6
	s_add_u32 s36, s4, 0x3800000
	v_readlane_b32 s4, v254, 58
	v_add_u32_e32 v5, v7, v5
	v_sub_u32_e32 v3, v3, v6
	s_addc_u32 s37, s4, 0
	v_lshlrev_b32_e32 v2, 5, v2
	v_ashrrev_i16_sdwa v3, v166, sext(v3) dst_sel:DWORD dst_unused:UNUSED_PAD src0_sel:DWORD src1_sel:BYTE_0
	v_lshlrev_b32_e32 v6, 1, v5
	v_lshrrev_b32_e32 v8, 2, v5
	v_and_b32_e32 v7, 3, v7
	s_mov_b32 s4, 0xfffe0
	v_and_b32_e32 v2, 32, v2
	v_bfe_i32 v3, v3, 0, 16
	v_and_b32_e32 v6, 24, v6
	v_and_b32_e32 v8, 4, v8
	v_and_or_b32 v7, v5, s4, v7
	v_or3_b32 v6, v7, v8, v6
	v_add_lshl_u32 v2, v2, v3, 1
	v_add_u32_e32 v1, 0x2000, v1
	v_lshl_add_u32 v139, v5, 12, v2
	v_lshl_add_u32 v140, v6, 12, v2
	v_ashrrev_i32_e32 v2, 31, v1
	v_lshrrev_b32_e32 v2, 22, v2
	v_add_u32_e32 v2, v1, v2
	v_ashrrev_i32_e32 v2, 10, v2
	v_mul_i32_i24_e32 v3, 0x400, v2
	v_sub_u32_e32 v1, v1, v3
	v_lshrrev_b32_e32 v3, 4, v1
	v_bitop3_b32 v1, v3, v1, 32 bitop3:0x6c
	v_ashrrev_i32_e32 v5, 31, v1
	v_lshrrev_b32_e32 v5, 26, v5
	v_lshlrev_b32_e32 v3, 3, v2
	v_add_u32_e32 v5, v1, v5
	v_and_b32_e32 v3, -16, v3
	v_ashrrev_i32_e32 v6, 6, v5
	v_add_u32_e32 v3, v6, v3
	v_and_b32_e32 v6, 3, v6
	s_ashr_i32 s38, s31, 31
	v_and_or_b32 v6, v3, s4, v6
	s_lshr_b32 s4, s38, 29
	s_add_i32 s4, s31, s4
	s_ashr_i32 s5, s18, 6
	s_ashr_i32 s6, s4, 3
	s_and_b32 s4, s4, -8
	s_lshl_b32 s16, s5, 10
	s_sub_i32 s4, s31, s4
	s_cmp_lt_i32 s4, 0
	s_movk_i32 s7, 0x2c1
	s_cselect_b32 s7, s7, 0x2c0
	s_mul_i32 s4, s4, s7
	s_add_i32 s4, s4, s6
	s_mul_hi_i32 s6, s4, 0x2e8ba2e9
	s_lshr_b32 s7, s6, 31
	s_ashr_i32 s6, s6, 5
	s_add_i32 s6, s6, s7
	s_lshl_b32 s7, s6, 2
	s_mulk_i32 s6, 0xb0
	s_sub_i32 s6, s4, s6
	s_bfe_u32 s4, s6, 0x2001d
	s_add_i32 s8, s6, s4
	s_sext_i32_i16 s4, s8
	s_and_b32 s8, s8, 0xfffc
	s_sub_i32 s6, s6, s8
	s_sext_i32_i16 s6, s6
	s_lshr_b32 s4, s4, 2
	s_add_i32 s22, s7, s6
	v_and_b32_e32 v5, 0xc0, v5
	s_ashr_i32 s23, s22, 31
	s_bfe_i64 s[8:9], s[4:5], 0x100000
	v_sub_u32_e32 v1, v1, v5
	s_lshl_b64 s[6:7], s[22:23], 20
	s_lshl_b64 s[8:9], s[8:9], 20
	v_lshlrev_b32_e32 v2, 5, v2
	v_ashrrev_i16_sdwa v1, v166, sext(v1) dst_sel:DWORD dst_unused:UNUSED_PAD src0_sel:DWORD src1_sel:BYTE_0
	v_lshlrev_b32_e32 v5, 1, v3
	v_lshrrev_b32_e32 v7, 2, v3
	s_add_u32 s10, s36, s8
	v_and_b32_e32 v2, 32, v2
	v_bfe_i32 v1, v1, 0, 16
	v_and_b32_e32 v5, 24, v5
	v_and_b32_e32 v7, 4, v7
	s_addc_u32 s11, s37, s9
	s_waitcnt vmcnt(0) lgkmcnt(0)
	s_barrier
	s_add_i32 s23, s16, 0
	v_or3_b32 v5, v6, v7, v5
	v_add_lshl_u32 v1, v2, v1, 1
	s_add_i32 s35, s23, 0x10000
	s_mov_b32 m0, s35
	s_nop 0
	global_load_lds_dwordx4 v140, s[10:11]
	s_add_i32 s39, s23, 0x12000
	v_lshl_add_u32 v153, v5, 12, v1
	s_mov_b32 m0, s39
	s_nop 0
	global_load_lds_dwordx4 v153, s[10:11]
	s_add_u32 s24, s94, s6
	s_addc_u32 s25, s95, s7
	s_mov_b32 m0, s23
	s_nop 0
	global_load_lds_dwordx4 v139, s[24:25]
	v_lshl_add_u32 v152, v3, 12, v1
	s_add_i32 s40, s23, 0x2000
	s_mov_b32 m0, s40
	s_nop 0
	global_load_lds_dwordx4 v152, s[24:25]
	s_add_u32 s6, s10, 0x80000
	s_addc_u32 s7, s11, 0
	s_add_i32 s41, s23, 0x14000
	s_mov_b32 m0, s41
	s_nop 0
	global_load_lds_dwordx4 v140, s[6:7]
	s_add_i32 s42, s23, 0x16000
	s_mov_b32 m0, s42
	s_nop 0
	global_load_lds_dwordx4 v153, s[6:7]
	s_add_u32 s6, s24, 0x80000
	s_addc_u32 s7, s25, 0
	s_add_i32 s43, s23, 0x4000
	s_mov_b32 m0, s43
	s_nop 0
	global_load_lds_dwordx4 v139, s[6:7]
	s_add_i32 s44, s23, 0x6000
	s_mov_b32 m0, s44
	s_nop 0
	global_load_lds_dwordx4 v152, s[6:7]
	s_movk_i32 s6, 0xff
	s_movk_i32 s8, 0x100
	v_cmp_lt_i32_e64 s[6:7], s6, v138
	v_cmp_gt_i32_e32 vcc, s8, v138
	s_and_saveexec_b64 s[16:17], vcc
	s_cbranch_execz .LBB0_88
	v_lshl_add_u32 v2, s22, 8, v138
	v_ashrrev_i32_e32 v3, 31, v2
	v_lshlrev_b64 v[2:3], 7, v[2:3]
	v_lshl_add_u64 v[2:3], s[0:1], 0, v[2:3]
	global_load_dwordx4 v[6:9], v[2:3], off offset:48
	global_load_dwordx4 v[10:13], v[2:3], off offset:32
	global_load_dwordx4 v[14:17], v[2:3], off
	global_load_dwordx4 v[18:21], v[2:3], off offset:16
	s_waitcnt vmcnt(0)
	v_pk_add_f32 v[16:17], v[16:17], v[20:21]
	v_pk_add_f32 v[14:15], v[14:15], v[18:19]
	v_pk_add_f32 v[12:13], v[16:17], v[12:13]
	v_pk_add_f32 v[10:11], v[14:15], v[10:11]
	v_pk_add_f32 v[22:23], v[12:13], v[8:9]
	v_pk_add_f32 v[24:25], v[10:11], v[6:7]
	global_load_dwordx4 v[6:9], v[2:3], off offset:112
	global_load_dwordx4 v[10:13], v[2:3], off offset:96
	global_load_dwordx4 v[14:17], v[2:3], off offset:80
	global_load_dwordx4 v[18:21], v[2:3], off offset:64
	s_waitcnt vmcnt(0)
	v_pk_add_f32 v[2:3], v[22:23], v[20:21]
	v_pk_add_f32 v[18:19], v[24:25], v[18:19]
	v_pk_add_f32 v[2:3], v[2:3], v[16:17]
	v_pk_add_f32 v[14:15], v[18:19], v[14:15]
	v_pk_add_f32 v[2:3], v[2:3], v[12:13]
	v_pk_add_f32 v[10:11], v[14:15], v[10:11]
	v_pk_add_f32 v[2:3], v[2:3], v[8:9]
	v_pk_add_f32 v[6:7], v[10:11], v[6:7]
	s_nop 0
	v_pk_mov_b32 v[8:9], v[6:7], v[2:3] op_sel:[1,0]
	v_mov_b32_e32 v7, v3
	v_pk_add_f32 v[2:3], v[8:9], v[6:7]
	s_nop 0
	v_add_f32_e32 v1, v2, v3
	v_fmamk_f32 v1, v1, 0x3a000000, v164
	v_cmp_gt_f32_e32 vcc, s69, v1
	v_mul_f32_e32 v2, 0x4f800000, v1
	s_nop 0
	v_cndmask_b32_e32 v1, v1, v2, vcc
	v_sqrt_f32_e32 v2, v1
	s_nop 0
	v_add_u32_e32 v3, -1, v2
	v_fma_f32 v5, -v3, v2, v1
	v_cmp_ge_f32_e64 s[8:9], 0, v5
	v_add_u32_e32 v5, 1, v2
	s_nop 0
	v_cndmask_b32_e64 v3, v2, v3, s[8:9]
	v_fma_f32 v2, -v5, v2, v1
	v_cmp_lt_f32_e64 s[8:9], 0, v2
	s_nop 1
	v_cndmask_b32_e64 v2, v3, v5, s[8:9]
	v_mul_f32_e32 v3, 0x37800000, v2
	v_cndmask_b32_e32 v2, v2, v3, vcc
	v_cmp_class_f32_e32 vcc, v1, v165
	s_nop 1
	v_cndmask_b32_e32 v1, v2, v1, vcc
	v_div_scale_f32 v2, s[8:9], v1, v1, 1.0
	v_rcp_f32_e32 v3, v2
	s_nop 0
	v_fma_f32 v5, -v2, v3, 1.0
	v_fmac_f32_e32 v3, v5, v3
	v_div_scale_f32 v5, vcc, 1.0, v1, 1.0
	v_mul_f32_e32 v6, v5, v3
	v_fma_f32 v7, -v2, v6, v5
	v_fmac_f32_e32 v6, v7, v3
	v_fma_f32 v2, -v2, v6, v5
	v_div_fmas_f32 v2, v2, v3, v6
	v_div_fixup_f32 v1, v2, v1, 1.0
	v_lshl_add_u32 v2, v138, 2, 0
	v_add_u32_e32 v2, 0x20000, v2
	ds_write_b32 v2, v1

; template <class Epi, class Sched>
; __device__ __forceinline__ void gemm_simple(PG8_LAS unsigned char* lds, const Gemm g, const Sched& S, const Epi& E, int wave_s) {
;     ...
;         if (ui > 0) {
;             if constexpr (Epi::NST >= 16) PG8_TILE_W(0, cA + kstep, cB + kstep, "18", "20"); else PG8_TILE_W(0, cA + kstep, cB + kstep, "10", "12");
;             PG8_TILE_W(1, cA + 2 * kstep, cB + 2 * kstep, "2", "4");
;             t = 2;
.LBB0_92:
	v_mov_b64_e32 v[14:15], v[2:3]
	v_mov_b64_e32 v[18:19], v[2:3]
	v_mov_b64_e32 v[26:27], v[2:3]
	v_mov_b64_e32 v[34:35], v[2:3]
	v_mov_b64_e32 v[42:43], v[2:3]
	v_mov_b64_e32 v[50:51], v[2:3]
	v_mov_b64_e32 v[58:59], v[2:3]
	v_mov_b64_e32 v[66:67], v[2:3]
	v_mov_b64_e32 v[6:7], v[2:3]
	v_mov_b64_e32 v[10:11], v[2:3]
	v_mov_b64_e32 v[22:23], v[2:3]
	v_mov_b64_e32 v[30:31], v[2:3]
	v_mov_b64_e32 v[38:39], v[2:3]
	v_mov_b64_e32 v[46:47], v[2:3]
	v_mov_b64_e32 v[54:55], v[2:3]
	v_mov_b64_e32 v[62:63], v[2:3]
	v_mov_b64_e32 v[74:75], v[2:3]
	v_mov_b64_e32 v[82:83], v[2:3]
	v_mov_b64_e32 v[90:91], v[2:3]
	v_mov_b64_e32 v[98:99], v[2:3]
	v_mov_b64_e32 v[106:107], v[2:3]
	v_mov_b64_e32 v[114:115], v[2:3]
	v_mov_b64_e32 v[122:123], v[2:3]
	v_mov_b64_e32 v[130:131], v[2:3]
	v_mov_b64_e32 v[70:71], v[2:3]
	v_mov_b64_e32 v[78:79], v[2:3]
	v_mov_b64_e32 v[86:87], v[2:3]
	v_mov_b64_e32 v[94:95], v[2:3]
	v_mov_b64_e32 v[102:103], v[2:3]
	v_mov_b64_e32 v[110:111], v[2:3]
	v_mov_b64_e32 v[118:119], v[2:3]
	v_mov_b64_e32 v[126:127], v[2:3]
	s_mov_b32 s26, 0
	s_cmp_eq_u32 s59, 0
	v_add_u32_e32 v132, 0x10000, v155
	v_add_u32_e32 v133, 0x14000, v155
	v_add_u32_e32 v134, 0x18000, v155
	v_add_u32_e32 v135, 0x1c000, v155
	v_mov_b64_e32 v[12:13], v[0:1]
	v_mov_b64_e32 v[16:17], v[0:1]
	v_mov_b64_e32 v[24:25], v[0:1]
	v_mov_b64_e32 v[32:33], v[0:1]
	v_mov_b64_e32 v[40:41], v[0:1]
	v_mov_b64_e32 v[48:49], v[0:1]
	v_mov_b64_e32 v[56:57], v[0:1]
	v_mov_b64_e32 v[64:65], v[0:1]
	v_mov_b64_e32 v[4:5], v[0:1]
	v_mov_b64_e32 v[8:9], v[0:1]
	v_mov_b64_e32 v[20:21], v[0:1]
	v_mov_b64_e32 v[28:29], v[0:1]
	v_mov_b64_e32 v[36:37], v[0:1]
	v_mov_b64_e32 v[44:45], v[0:1]
	v_mov_b64_e32 v[52:53], v[0:1]
	v_mov_b64_e32 v[60:61], v[0:1]
	v_mov_b64_e32 v[72:73], v[0:1]
	v_mov_b64_e32 v[80:81], v[0:1]
	v_mov_b64_e32 v[88:89], v[0:1]
	v_mov_b64_e32 v[96:97], v[0:1]
	v_mov_b64_e32 v[104:105], v[0:1]
	v_mov_b64_e32 v[112:113], v[0:1]
	v_mov_b64_e32 v[120:121], v[0:1]
	v_mov_b64_e32 v[128:129], v[0:1]
	v_mov_b64_e32 v[68:69], v[0:1]
	v_mov_b64_e32 v[76:77], v[0:1]
	v_mov_b64_e32 v[84:85], v[0:1]
	v_mov_b64_e32 v[92:93], v[0:1]
	v_mov_b64_e32 v[100:101], v[0:1]
	v_mov_b64_e32 v[108:109], v[0:1]
	v_mov_b64_e32 v[116:117], v[0:1]
	v_mov_b64_e32 v[124:125], v[0:1]
	s_cbranch_scc1 .LBB0_94
	s_waitcnt vmcnt(10) lgkmcnt(0)
	s_barrier
	ds_read_b128 v[4:7], v132
	ds_read_b128 v[8:11], v132 offset:1024
	ds_read_b128 v[12:15], v132 offset:2048
	ds_read_b128 v[16:19], v132 offset:3072
	ds_read_b128 v[20:23], v156
	ds_read_b128 v[24:27], v156 offset:1024
	ds_read_b128 v[28:31], v156 offset:2048
	ds_read_b128 v[32:35], v156 offset:3072
	ds_read_b128 v[36:39], v156 offset:4096
	ds_read_b128 v[40:43], v156 offset:5120
	ds_read_b128 v[44:47], v156 offset:6144
	ds_read_b128 v[48:51], v156 offset:7168
	ds_read_b128 v[52:55], v133
	ds_read_b128 v[56:59], v133 offset:1024
	ds_read_b128 v[60:63], v133 offset:2048
	ds_read_b128 v[64:67], v133 offset:3072
	s_add_u32 s18, s10, 0x80
	s_addc_u32 s19, s11, 0
	s_mov_b32 m0, s48
	s_nop 0
	global_load_lds_dwordx4 v140, s[18:19]
	s_mov_b32 m0, s52
	s_nop 0
	global_load_lds_dwordx4 v153, s[18:19]
	s_waitcnt lgkmcnt(5)
	v_mfma_f32_16x16x32_bf16 v[92:95], v[4:7], v[44:47], v[0:3]
	v_mfma_f32_16x16x32_bf16 v[68:71], v[4:7], v[20:23], v[0:3]
	v_mfma_f32_16x16x32_bf16 v[72:75], v[12:15], v[20:23], v[0:3]
	v_mfma_f32_16x16x32_bf16 v[76:79], v[4:7], v[28:31], v[0:3]
	v_mfma_f32_16x16x32_bf16 v[80:83], v[12:15], v[28:31], v[0:3]
	v_mfma_f32_16x16x32_bf16 v[84:87], v[4:7], v[36:39], v[0:3]
	v_mfma_f32_16x16x32_bf16 v[88:91], v[12:15], v[36:39], v[0:3]
	s_waitcnt lgkmcnt(4)
	v_mfma_f32_16x16x32_bf16 v[96:99], v[8:11], v[48:51], v[92:95]
	v_mfma_f32_16x16x32_bf16 v[92:95], v[12:15], v[44:47], v[0:3]
	v_mfma_f32_16x16x32_bf16 v[68:71], v[8:11], v[24:27], v[68:71]
	v_mfma_f32_16x16x32_bf16 v[72:75], v[16:19], v[24:27], v[72:75]
	v_mfma_f32_16x16x32_bf16 v[76:79], v[8:11], v[32:35], v[76:79]
	v_mfma_f32_16x16x32_bf16 v[80:83], v[16:19], v[32:35], v[80:83]
	v_mfma_f32_16x16x32_bf16 v[84:87], v[8:11], v[40:43], v[84:87]
	v_mfma_f32_16x16x32_bf16 v[88:91], v[16:19], v[40:43], v[88:91]
	v_mfma_f32_16x16x32_bf16 v[104:107], v[16:19], v[48:51], v[92:95]
	s_add_u32 s18, s24, 0x80
	s_addc_u32 s19, s25, 0
	s_mov_b32 m0, s49
	s_nop 0
	global_load_lds_dwordx4 v139, s[18:19]
	s_mov_b32 m0, s53
	s_nop 0
	global_load_lds_dwordx4 v152, s[18:19]
	s_waitcnt lgkmcnt(3)
	v_mfma_f32_16x16x32_bf16 v[92:95], v[52:55], v[20:23], v[0:3]
	s_waitcnt lgkmcnt(1)
	v_mfma_f32_16x16x32_bf16 v[20:23], v[60:63], v[20:23], v[0:3]
	v_mfma_f32_16x16x32_bf16 v[112:115], v[56:59], v[24:27], v[92:95]
	s_waitcnt lgkmcnt(0)
	v_mfma_f32_16x16x32_bf16 v[20:23], v[64:67], v[24:27], v[20:23]
	v_mfma_f32_16x16x32_bf16 v[24:27], v[52:55], v[28:31], v[0:3]
	v_mfma_f32_16x16x32_bf16 v[28:31], v[60:63], v[28:31], v[0:3]
	v_mfma_f32_16x16x32_bf16 v[24:27], v[56:59], v[32:35], v[24:27]
	v_mfma_f32_16x16x32_bf16 v[28:31], v[64:67], v[32:35], v[28:31]
	v_mfma_f32_16x16x32_bf16 v[32:35], v[52:55], v[36:39], v[0:3]
	v_mfma_f32_16x16x32_bf16 v[36:39], v[60:63], v[36:39], v[0:3]
	v_mfma_f32_16x16x32_bf16 v[32:35], v[56:59], v[40:43], v[32:35]
	v_mfma_f32_16x16x32_bf16 v[36:39], v[64:67], v[40:43], v[36:39]
	v_mfma_f32_16x16x32_bf16 v[40:43], v[52:55], v[44:47], v[0:3]
	v_mfma_f32_16x16x32_bf16 v[44:47], v[60:63], v[44:47], v[0:3]
	v_mfma_f32_16x16x32_bf16 v[40:43], v[56:59], v[48:51], v[40:43]
	v_mfma_f32_16x16x32_bf16 v[44:47], v[64:67], v[48:51], v[44:47]
	s_waitcnt vmcnt(12) lgkmcnt(0)
	s_barrier
	ds_read_b128 v[48:51], v156 offset:16384
	ds_read_b128 v[92:95], v156 offset:17408
	ds_read_b128 v[100:103], v156 offset:18432
	ds_read_b128 v[108:111], v156 offset:19456
	ds_read_b128 v[116:119], v156 offset:20480
	ds_read_b128 v[120:123], v156 offset:21504
	ds_read_b128 v[124:127], v156 offset:22528
	ds_read_b128 v[128:131], v156 offset:23552
	s_add_u32 s18, s10, 0x80080
	s_addc_u32 s19, s11, 0
	s_mov_b32 m0, s50
	s_nop 0
	global_load_lds_dwordx4 v140, s[18:19]
	s_mov_b32 m0, s54
	s_nop 0
	global_load_lds_dwordx4 v153, s[18:19]
	s_waitcnt lgkmcnt(7)
	v_mfma_f32_16x16x32_bf16 v[142:145], v[4:7], v[48:51], v[0:3]
	s_waitcnt lgkmcnt(5)
	v_mfma_f32_16x16x32_bf16 v[158:161], v[4:7], v[100:103], v[0:3]
	s_waitcnt lgkmcnt(3)
	v_mfma_f32_16x16x32_bf16 v[174:177], v[4:7], v[116:119], v[0:3]
	s_waitcnt lgkmcnt(1)
	v_mfma_f32_16x16x32_bf16 v[4:7], v[4:7], v[124:127], v[0:3]
	v_mfma_f32_16x16x32_bf16 v[142:145], v[8:11], v[92:95], v[142:145]
	v_mfma_f32_16x16x32_bf16 v[158:161], v[8:11], v[108:111], v[158:161]
	v_mfma_f32_16x16x32_bf16 v[174:177], v[8:11], v[120:123], v[174:177]
	s_waitcnt lgkmcnt(0)
	v_mfma_f32_16x16x32_bf16 v[4:7], v[8:11], v[128:131], v[4:7]
	v_mfma_f32_16x16x32_bf16 v[8:11], v[12:15], v[124:127], v[0:3]
	v_mfma_f32_16x16x32_bf16 v[146:149], v[12:15], v[48:51], v[0:3]
	v_mfma_f32_16x16x32_bf16 v[170:173], v[12:15], v[100:103], v[0:3]
	v_mfma_f32_16x16x32_bf16 v[178:181], v[12:15], v[116:119], v[0:3]
	v_mfma_f32_16x16x32_bf16 v[12:15], v[16:19], v[128:131], v[8:11]
	v_mfma_f32_16x16x32_bf16 v[146:149], v[16:19], v[92:95], v[146:149]
	v_mfma_f32_16x16x32_bf16 v[170:173], v[16:19], v[108:111], v[170:173]
	v_mfma_f32_16x16x32_bf16 v[178:181], v[16:19], v[120:123], v[178:181]
	s_add_u32 s18, s24, 0x80080
	s_addc_u32 s19, s25, 0
	s_mov_b32 m0, s51
	s_nop 0
	global_load_lds_dwordx4 v139, s[18:19]
	s_mov_b32 m0, s55
	s_nop 0
	global_load_lds_dwordx4 v152, s[18:19]
	v_mfma_f32_16x16x32_bf16 v[8:11], v[52:55], v[48:51], v[0:3]
	v_mfma_f32_16x16x32_bf16 v[16:19], v[56:59], v[92:95], v[8:11]
	v_mfma_f32_16x16x32_bf16 v[8:11], v[60:63], v[48:51], v[0:3]
	v_mfma_f32_16x16x32_bf16 v[48:51], v[64:67], v[92:95], v[8:11]
	v_mfma_f32_16x16x32_bf16 v[8:11], v[52:55], v[100:103], v[0:3]
	v_mfma_f32_16x16x32_bf16 v[182:185], v[56:59], v[108:111], v[8:11]
	v_mfma_f32_16x16x32_bf16 v[8:11], v[60:63], v[100:103], v[0:3]
	v_mfma_f32_16x16x32_bf16 v[186:189], v[64:67], v[108:111], v[8:11]
	v_mfma_f32_16x16x32_bf16 v[8:11], v[52:55], v[116:119], v[0:3]
	v_mfma_f32_16x16x32_bf16 v[190:193], v[56:59], v[120:123], v[8:11]
	v_mfma_f32_16x16x32_bf16 v[8:11], v[60:63], v[116:119], v[0:3]
	v_mfma_f32_16x16x32_bf16 v[194:197], v[64:67], v[120:123], v[8:11]
	v_mfma_f32_16x16x32_bf16 v[8:11], v[52:55], v[124:127], v[0:3]
	v_mfma_f32_16x16x32_bf16 v[198:201], v[56:59], v[128:131], v[8:11]
	v_mfma_f32_16x16x32_bf16 v[8:11], v[60:63], v[124:127], v[0:3]
	v_mfma_f32_16x16x32_bf16 v[202:205], v[64:67], v[128:131], v[8:11]
	s_waitcnt vmcnt(2) lgkmcnt(0)
	s_barrier
	s_nop 5
	ds_read_b128 v[8:11], v134
	ds_read_b128 v[56:59], v134 offset:1024
	ds_read_b128 v[64:67], v134 offset:2048
	ds_read_b128 v[206:209], v134 offset:3072
	ds_read_b128 v[52:55], v156 offset:32768
	ds_read_b128 v[60:63], v156 offset:33792
	ds_read_b128 v[210:213], v156 offset:34816
	ds_read_b128 v[214:217], v156 offset:35840
	ds_read_b128 v[218:221], v156 offset:36864
	ds_read_b128 v[222:225], v156 offset:37888
	ds_read_b128 v[226:229], v156 offset:38912
	ds_read_b128 v[230:233], v156 offset:39936
	ds_read_b128 v[234:237], v135
	ds_read_b128 v[238:241], v135 offset:1024
	ds_read_b128 v[242:245], v135 offset:2048
	ds_read_b128 v[246:249], v135 offset:3072
	s_add_u32 s18, s10, 0x100
	s_addc_u32 s19, s11, 0
	s_mov_b32 m0, s35
	s_nop 0
	global_load_lds_dwordx4 v140, s[18:19]
	s_mov_b32 m0, s39
	s_nop 0
	global_load_lds_dwordx4 v153, s[18:19]
	s_waitcnt lgkmcnt(11)
	v_mfma_f32_16x16x32_bf16 v[68:71], v[8:11], v[52:55], v[68:71]
	s_waitcnt lgkmcnt(10)
	v_mfma_f32_16x16x32_bf16 v[124:127], v[56:59], v[60:63], v[68:71]
	v_mfma_f32_16x16x32_bf16 v[68:71], v[64:67], v[52:55], v[72:75]
	v_mfma_f32_16x16x32_bf16 v[116:119], v[206:209], v[60:63], v[68:71]
	s_waitcnt lgkmcnt(9)
	v_mfma_f32_16x16x32_bf16 v[68:71], v[8:11], v[210:213], v[76:79]
	s_waitcnt lgkmcnt(8)
	v_mfma_f32_16x16x32_bf16 v[108:111], v[56:59], v[214:217], v[68:71]
	v_mfma_f32_16x16x32_bf16 v[68:71], v[64:67], v[210:213], v[80:83]
	v_mfma_f32_16x16x32_bf16 v[100:103], v[206:209], v[214:217], v[68:71]
	s_waitcnt lgkmcnt(7)
	v_mfma_f32_16x16x32_bf16 v[68:71], v[8:11], v[218:221], v[84:87]
	s_waitcnt lgkmcnt(6)
	v_mfma_f32_16x16x32_bf16 v[92:95], v[56:59], v[222:225], v[68:71]
	v_mfma_f32_16x16x32_bf16 v[68:71], v[64:67], v[218:221], v[88:91]
	v_mfma_f32_16x16x32_bf16 v[84:87], v[206:209], v[222:225], v[68:71]
	s_waitcnt lgkmcnt(5)
	v_mfma_f32_16x16x32_bf16 v[68:71], v[8:11], v[226:229], v[96:99]
	s_waitcnt lgkmcnt(4)
	v_mfma_f32_16x16x32_bf16 v[76:79], v[56:59], v[230:233], v[68:71]
	v_mfma_f32_16x16x32_bf16 v[68:71], v[64:67], v[226:229], v[104:107]
	v_mfma_f32_16x16x32_bf16 v[68:71], v[206:209], v[230:233], v[68:71]
	s_add_u32 s18, s24, 0x100
	s_addc_u32 s19, s25, 0
	s_mov_b32 m0, s23
	s_nop 0
	global_load_lds_dwordx4 v139, s[18:19]
	s_mov_b32 m0, s40
	s_nop 0
	global_load_lds_dwordx4 v152, s[18:19]
	s_waitcnt lgkmcnt(1)
	v_mfma_f32_16x16x32_bf16 v[20:23], v[242:245], v[52:55], v[20:23]
	s_waitcnt lgkmcnt(0)
	v_mfma_f32_16x16x32_bf16 v[120:123], v[246:249], v[60:63], v[20:23]
	v_mfma_f32_16x16x32_bf16 v[20:23], v[234:237], v[210:213], v[24:27]
	v_mfma_f32_16x16x32_bf16 v[72:75], v[234:237], v[52:55], v[112:115]
	v_mfma_f32_16x16x32_bf16 v[112:115], v[238:241], v[214:217], v[20:23]
	v_mfma_f32_16x16x32_bf16 v[20:23], v[242:245], v[210:213], v[28:31]
	v_mfma_f32_16x16x32_bf16 v[104:107], v[246:249], v[214:217], v[20:23]
	v_mfma_f32_16x16x32_bf16 v[20:23], v[234:237], v[218:221], v[32:35]
	v_mfma_f32_16x16x32_bf16 v[96:99], v[238:241], v[222:225], v[20:23]
	v_mfma_f32_16x16x32_bf16 v[20:23], v[242:245], v[218:221], v[36:39]
	v_mfma_f32_16x16x32_bf16 v[88:91], v[246:249], v[222:225], v[20:23]
	v_mfma_f32_16x16x32_bf16 v[20:23], v[234:237], v[226:229], v[40:43]
	v_mfma_f32_16x16x32_bf16 v[80:83], v[238:241], v[230:233], v[20:23]
	v_mfma_f32_16x16x32_bf16 v[20:23], v[242:245], v[226:229], v[44:47]
	v_mfma_f32_16x16x32_bf16 v[128:131], v[238:241], v[60:63], v[72:75]
	v_mfma_f32_16x16x32_bf16 v[72:75], v[246:249], v[230:233], v[20:23]
	s_waitcnt vmcnt(4) lgkmcnt(0)
	s_barrier
	ds_read_b128 v[24:27], v156 offset:49152
	ds_read_b128 v[32:35], v156 offset:50176
	ds_read_b128 v[40:43], v156 offset:51200
	ds_read_b128 v[210:213], v156 offset:52224
	ds_read_b128 v[214:217], v156 offset:53248
	ds_read_b128 v[218:221], v156 offset:54272
	ds_read_b128 v[222:225], v156 offset:55296
	ds_read_b128 v[226:229], v156 offset:56320
	s_add_u32 s18, s10, 0x80100
	s_addc_u32 s19, s11, 0
	s_mov_b32 m0, s41
	s_nop 0
	global_load_lds_dwordx4 v140, s[18:19]
	s_mov_b32 m0, s42
	s_nop 0
	global_load_lds_dwordx4 v153, s[18:19]
	s_waitcnt lgkmcnt(7)
	v_mfma_f32_16x16x32_bf16 v[20:23], v[8:11], v[24:27], v[142:145]
	s_waitcnt lgkmcnt(6)
	v_mfma_f32_16x16x32_bf16 v[60:63], v[56:59], v[32:35], v[20:23]
	v_mfma_f32_16x16x32_bf16 v[20:23], v[64:67], v[24:27], v[146:149]
	v_mfma_f32_16x16x32_bf16 v[52:55], v[206:209], v[32:35], v[20:23]
	s_waitcnt lgkmcnt(5)
	v_mfma_f32_16x16x32_bf16 v[20:23], v[8:11], v[40:43], v[158:161]
	s_waitcnt lgkmcnt(4)
	v_mfma_f32_16x16x32_bf16 v[44:47], v[56:59], v[210:213], v[20:23]
	v_mfma_f32_16x16x32_bf16 v[20:23], v[64:67], v[40:43], v[170:173]
	v_mfma_f32_16x16x32_bf16 v[36:39], v[206:209], v[210:213], v[20:23]
	s_waitcnt lgkmcnt(3)
	v_mfma_f32_16x16x32_bf16 v[20:23], v[8:11], v[214:217], v[174:177]
	s_waitcnt lgkmcnt(1)
	v_mfma_f32_16x16x32_bf16 v[4:7], v[8:11], v[222:225], v[4:7]
	v_mfma_f32_16x16x32_bf16 v[28:31], v[56:59], v[218:221], v[20:23]
	v_mfma_f32_16x16x32_bf16 v[20:23], v[64:67], v[214:217], v[178:181]
	s_waitcnt lgkmcnt(0)
	v_mfma_f32_16x16x32_bf16 v[8:11], v[56:59], v[226:229], v[4:7]
	v_mfma_f32_16x16x32_bf16 v[4:7], v[64:67], v[222:225], v[12:15]
	v_mfma_f32_16x16x32_bf16 v[20:23], v[206:209], v[218:221], v[20:23]
	v_mfma_f32_16x16x32_bf16 v[4:7], v[206:209], v[226:229], v[4:7]
	s_add_u32 s18, s24, 0x80100
	s_addc_u32 s19, s25, 0
	s_mov_b32 m0, s43
	s_nop 0
	global_load_lds_dwordx4 v139, s[18:19]
	s_mov_b32 m0, s44
	s_nop 0
	global_load_lds_dwordx4 v152, s[18:19]
	v_mfma_f32_16x16x32_bf16 v[12:15], v[234:237], v[24:27], v[16:19]
	s_mov_b32 s26, 2
	v_mfma_f32_16x16x32_bf16 v[64:67], v[238:241], v[32:35], v[12:15]
	v_mfma_f32_16x16x32_bf16 v[12:15], v[242:245], v[24:27], v[48:51]
	v_mfma_f32_16x16x32_bf16 v[56:59], v[246:249], v[32:35], v[12:15]
	v_mfma_f32_16x16x32_bf16 v[12:15], v[234:237], v[40:43], v[182:185]
	v_mfma_f32_16x16x32_bf16 v[48:51], v[238:241], v[210:213], v[12:15]
	v_mfma_f32_16x16x32_bf16 v[12:15], v[242:245], v[40:43], v[186:189]
	v_mfma_f32_16x16x32_bf16 v[40:43], v[246:249], v[210:213], v[12:15]
	v_mfma_f32_16x16x32_bf16 v[12:15], v[234:237], v[214:217], v[190:193]
	v_mfma_f32_16x16x32_bf16 v[32:35], v[238:241], v[218:221], v[12:15]
	v_mfma_f32_16x16x32_bf16 v[12:15], v[242:245], v[214:217], v[194:197]
	v_mfma_f32_16x16x32_bf16 v[24:27], v[246:249], v[218:221], v[12:15]
	v_mfma_f32_16x16x32_bf16 v[12:15], v[234:237], v[222:225], v[198:201]
	v_mfma_f32_16x16x32_bf16 v[16:19], v[238:241], v[226:229], v[12:15]
	v_mfma_f32_16x16x32_bf16 v[12:15], v[242:245], v[222:225], v[202:205]
	v_mfma_f32_16x16x32_bf16 v[12:15], v[246:249], v[226:229], v[12:15]

; template <class Epi, class Sched>
; __device__ __forceinline__ void gemm_simple(PG8_LAS unsigned char* lds, const Gemm g, const Sched& S, const Epi& E, int wave_s) {
;     ...
;         for (; t < nt; t += 2) {
;             const bool last = (t == nt - 2);
;             PG8_TILE(0, cA + (size_t)(t + 1) * kstep, cB + (size_t)(t + 1) * kstep, true);
.LBB0_95:
	s_waitcnt vmcnt(2) lgkmcnt(0)
	s_barrier
	ds_read_b128 v[142:145], v132
	ds_read_b128 v[174:177], v156
	ds_read_b128 v[158:161], v132 offset:2048
	ds_read_b128 v[182:185], v156 offset:2048
	ds_read_b128 v[190:193], v156 offset:4096
	ds_read_b128 v[198:201], v156 offset:6144
	ds_read_b128 v[146:149], v132 offset:1024
	ds_read_b128 v[178:181], v156 offset:1024
	ds_read_b128 v[170:173], v132 offset:3072
	ds_read_b128 v[186:189], v156 offset:3072
	ds_read_b128 v[194:197], v156 offset:5120
	ds_read_b128 v[202:205], v156 offset:7168
	ds_read_b128 v[206:209], v133
	ds_read_b128 v[214:217], v133 offset:2048
	ds_read_b128 v[210:213], v133 offset:1024
	ds_read_b128 v[218:221], v133 offset:3072
	s_add_u32 s64, s10, s63
	s_addc_u32 s65, s11, 0
	s_add_u32 s28, s64, 0x80
	s_addc_u32 s29, s65, 0
	s_mov_b32 m0, s48
	s_nop 0
	global_load_lds_dwordx4 v140, s[28:29]
	s_mov_b32 m0, s52
	s_nop 0
	global_load_lds_dwordx4 v153, s[28:29]
	s_waitcnt lgkmcnt(14)
	v_mfma_f32_16x16x32_bf16 v[124:127], v[142:145], v[174:177], v[124:127]
	s_waitcnt lgkmcnt(13)
	v_mfma_f32_16x16x32_bf16 v[116:119], v[158:161], v[174:177], v[116:119]
	s_waitcnt lgkmcnt(12)
	v_mfma_f32_16x16x32_bf16 v[108:111], v[142:145], v[182:185], v[108:111]
	v_mfma_f32_16x16x32_bf16 v[100:103], v[158:161], v[182:185], v[100:103]
	s_waitcnt lgkmcnt(11)
	v_mfma_f32_16x16x32_bf16 v[92:95], v[142:145], v[190:193], v[92:95]
	v_mfma_f32_16x16x32_bf16 v[84:87], v[158:161], v[190:193], v[84:87]
	s_waitcnt lgkmcnt(10)
	v_mfma_f32_16x16x32_bf16 v[76:79], v[142:145], v[198:201], v[76:79]
	v_mfma_f32_16x16x32_bf16 v[68:71], v[158:161], v[198:201], v[68:71]
	s_waitcnt lgkmcnt(8)
	v_mfma_f32_16x16x32_bf16 v[124:127], v[146:149], v[178:181], v[124:127]
	s_waitcnt lgkmcnt(7)
	v_mfma_f32_16x16x32_bf16 v[116:119], v[170:173], v[178:181], v[116:119]
	s_waitcnt lgkmcnt(6)
	v_mfma_f32_16x16x32_bf16 v[108:111], v[146:149], v[186:189], v[108:111]
	v_mfma_f32_16x16x32_bf16 v[100:103], v[170:173], v[186:189], v[100:103]
	s_waitcnt lgkmcnt(5)
	v_mfma_f32_16x16x32_bf16 v[92:95], v[146:149], v[194:197], v[92:95]
	v_mfma_f32_16x16x32_bf16 v[84:87], v[170:173], v[194:197], v[84:87]
	s_waitcnt lgkmcnt(4)
	v_mfma_f32_16x16x32_bf16 v[76:79], v[146:149], v[202:205], v[76:79]
	v_mfma_f32_16x16x32_bf16 v[68:71], v[170:173], v[202:205], v[68:71]
	s_add_u32 s66, s24, s63
	s_addc_u32 s67, s25, 0
	s_add_u32 s28, s66, 0x80
	s_addc_u32 s29, s67, 0
	s_mov_b32 m0, s49
	s_nop 0
	global_load_lds_dwordx4 v139, s[28:29]
	s_mov_b32 m0, s53
	s_nop 0
	global_load_lds_dwordx4 v152, s[28:29]
	s_waitcnt lgkmcnt(3)
	v_mfma_f32_16x16x32_bf16 v[128:131], v[206:209], v[174:177], v[128:131]
	s_waitcnt lgkmcnt(2)
	v_mfma_f32_16x16x32_bf16 v[120:123], v[214:217], v[174:177], v[120:123]
	v_mfma_f32_16x16x32_bf16 v[112:115], v[206:209], v[182:185], v[112:115]
	v_mfma_f32_16x16x32_bf16 v[104:107], v[214:217], v[182:185], v[104:107]
	v_mfma_f32_16x16x32_bf16 v[96:99], v[206:209], v[190:193], v[96:99]
	v_mfma_f32_16x16x32_bf16 v[88:91], v[214:217], v[190:193], v[88:91]
	v_mfma_f32_16x16x32_bf16 v[80:83], v[206:209], v[198:201], v[80:83]
	v_mfma_f32_16x16x32_bf16 v[72:75], v[214:217], v[198:201], v[72:75]
	s_waitcnt lgkmcnt(1)
	v_mfma_f32_16x16x32_bf16 v[128:131], v[210:213], v[178:181], v[128:131]
	s_waitcnt lgkmcnt(0)
	v_mfma_f32_16x16x32_bf16 v[120:123], v[218:221], v[178:181], v[120:123]
	v_mfma_f32_16x16x32_bf16 v[112:115], v[210:213], v[186:189], v[112:115]
	v_mfma_f32_16x16x32_bf16 v[104:107], v[218:221], v[186:189], v[104:107]
	v_mfma_f32_16x16x32_bf16 v[96:99], v[210:213], v[194:197], v[96:99]
	v_mfma_f32_16x16x32_bf16 v[88:91], v[218:221], v[194:197], v[88:91]
	v_mfma_f32_16x16x32_bf16 v[80:83], v[210:213], v[202:205], v[80:83]
	v_mfma_f32_16x16x32_bf16 v[72:75], v[218:221], v[202:205], v[72:75]
	s_waitcnt vmcnt(4) lgkmcnt(0)
	s_barrier
	ds_read_b128 v[174:177], v156 offset:16384
	ds_read_b128 v[182:185], v156 offset:18432
	ds_read_b128 v[190:193], v156 offset:20480
	ds_read_b128 v[198:201], v156 offset:22528
	ds_read_b128 v[178:181], v156 offset:17408
	ds_read_b128 v[186:189], v156 offset:19456
	ds_read_b128 v[194:197], v156 offset:21504
	ds_read_b128 v[202:205], v156 offset:23552
	s_add_u32 s28, s64, 0x80080
	s_addc_u32 s29, s65, 0
	s_mov_b32 m0, s50
	s_nop 0
	global_load_lds_dwordx4 v140, s[28:29]
	s_mov_b32 m0, s54
	s_nop 0
	global_load_lds_dwordx4 v153, s[28:29]
	s_waitcnt lgkmcnt(7)
	v_mfma_f32_16x16x32_bf16 v[60:63], v[142:145], v[174:177], v[60:63]
	v_mfma_f32_16x16x32_bf16 v[52:55], v[158:161], v[174:177], v[52:55]
	s_waitcnt lgkmcnt(6)
	v_mfma_f32_16x16x32_bf16 v[44:47], v[142:145], v[182:185], v[44:47]
	v_mfma_f32_16x16x32_bf16 v[36:39], v[158:161], v[182:185], v[36:39]
	s_waitcnt lgkmcnt(5)
	v_mfma_f32_16x16x32_bf16 v[28:31], v[142:145], v[190:193], v[28:31]
	v_mfma_f32_16x16x32_bf16 v[20:23], v[158:161], v[190:193], v[20:23]
	s_waitcnt lgkmcnt(4)
	v_mfma_f32_16x16x32_bf16 v[8:11], v[142:145], v[198:201], v[8:11]
	v_mfma_f32_16x16x32_bf16 v[4:7], v[158:161], v[198:201], v[4:7]
	s_waitcnt lgkmcnt(3)
	v_mfma_f32_16x16x32_bf16 v[60:63], v[146:149], v[178:181], v[60:63]
	v_mfma_f32_16x16x32_bf16 v[52:55], v[170:173], v[178:181], v[52:55]
	s_waitcnt lgkmcnt(2)
	v_mfma_f32_16x16x32_bf16 v[44:47], v[146:149], v[186:189], v[44:47]
	v_mfma_f32_16x16x32_bf16 v[36:39], v[170:173], v[186:189], v[36:39]
	s_waitcnt lgkmcnt(1)
	v_mfma_f32_16x16x32_bf16 v[28:31], v[146:149], v[194:197], v[28:31]
	v_mfma_f32_16x16x32_bf16 v[20:23], v[170:173], v[194:197], v[20:23]
	s_waitcnt lgkmcnt(0)
	v_mfma_f32_16x16x32_bf16 v[8:11], v[146:149], v[202:205], v[8:11]
	v_mfma_f32_16x16x32_bf16 v[4:7], v[170:173], v[202:205], v[4:7]
	s_add_u32 s28, s66, 0x80080
	s_addc_u32 s29, s67, 0
	s_mov_b32 m0, s51
	s_nop 0
	global_load_lds_dwordx4 v139, s[28:29]
	s_mov_b32 m0, s55
	s_nop 0
	global_load_lds_dwordx4 v152, s[28:29]
	v_mfma_f32_16x16x32_bf16 v[64:67], v[206:209], v[174:177], v[64:67]
	s_add_u32 s28, s66, 0x100
	s_addc_u32 s29, s67, 0
	s_add_u32 s64, s64, 0x100
	v_mfma_f32_16x16x32_bf16 v[56:59], v[214:217], v[174:177], v[56:59]
	s_addc_u32 s65, s65, 0
	v_mfma_f32_16x16x32_bf16 v[48:51], v[206:209], v[182:185], v[48:51]
	v_mfma_f32_16x16x32_bf16 v[40:43], v[214:217], v[182:185], v[40:43]
	v_mfma_f32_16x16x32_bf16 v[32:35], v[206:209], v[190:193], v[32:35]
	v_mfma_f32_16x16x32_bf16 v[24:27], v[214:217], v[190:193], v[24:27]
	v_mfma_f32_16x16x32_bf16 v[16:19], v[206:209], v[198:201], v[16:19]
	v_mfma_f32_16x16x32_bf16 v[12:15], v[214:217], v[198:201], v[12:15]
	v_mfma_f32_16x16x32_bf16 v[64:67], v[210:213], v[178:181], v[64:67]
	v_mfma_f32_16x16x32_bf16 v[56:59], v[218:221], v[178:181], v[56:59]
	v_mfma_f32_16x16x32_bf16 v[48:51], v[210:213], v[186:189], v[48:51]
	v_mfma_f32_16x16x32_bf16 v[40:43], v[218:221], v[186:189], v[40:43]
	v_mfma_f32_16x16x32_bf16 v[32:35], v[210:213], v[194:197], v[32:35]
	v_mfma_f32_16x16x32_bf16 v[24:27], v[218:221], v[194:197], v[24:27]
	v_mfma_f32_16x16x32_bf16 v[16:19], v[210:213], v[202:205], v[16:19]
	v_mfma_f32_16x16x32_bf16 v[12:15], v[218:221], v[202:205], v[12:15]
	s_waitcnt vmcnt(2) lgkmcnt(0)
	s_barrier
; template <class Epi, class Sched>
; __device__ __forceinline__ void gemm_simple(PG8_LAS unsigned char* lds, const Gemm g, const Sched& S, const Epi& E, int wave_s) {
;     ...
;             const bool last = (t == nt - 2);
;             PG8_TILE(0, cA + (size_t)(t + 1) * kstep, cB + (size_t)(t + 1) * kstep, true);
;             const char* a2 = last ? nA : cA + (size_t)(t + 2) * kstep; const char* b2 = last ? nB : cB + (size_t)(t + 2) * kstep;
;             PG8_TILE(1, a2, b2, (!last || has_next));
	ds_read_b128 v[142:145], v134
	ds_read_b128 v[174:177], v156 offset:32768
	ds_read_b128 v[158:161], v134 offset:2048
	ds_read_b128 v[182:185], v156 offset:34816
	ds_read_b128 v[190:193], v156 offset:36864
	ds_read_b128 v[198:201], v156 offset:38912
	ds_read_b128 v[146:149], v134 offset:1024
	ds_read_b128 v[178:181], v156 offset:33792
	ds_read_b128 v[170:173], v134 offset:3072
	ds_read_b128 v[186:189], v156 offset:35840
	ds_read_b128 v[194:197], v156 offset:37888
	ds_read_b128 v[202:205], v156 offset:39936
	ds_read_b128 v[206:209], v135
	ds_read_b128 v[214:217], v135 offset:2048
	ds_read_b128 v[210:213], v135 offset:1024
	ds_read_b128 v[218:221], v135 offset:3072
	s_cmp_eq_u32 s63, s26
	s_cselect_b32 s29, s17, s29
	s_cselect_b32 s28, s60, s28
	s_cselect_b32 s65, s5, s65
	s_cselect_b32 s64, s61, s64
	s_mov_b32 m0, s35
	s_nop 0
	global_load_lds_dwordx4 v140, s[64:65]
	s_mov_b32 m0, s39
	s_nop 0
	global_load_lds_dwordx4 v153, s[64:65]
	s_waitcnt lgkmcnt(14)
	v_mfma_f32_16x16x32_bf16 v[124:127], v[142:145], v[174:177], v[124:127]
	s_waitcnt lgkmcnt(13)
	v_mfma_f32_16x16x32_bf16 v[116:119], v[158:161], v[174:177], v[116:119]
	s_waitcnt lgkmcnt(12)
	v_mfma_f32_16x16x32_bf16 v[108:111], v[142:145], v[182:185], v[108:111]
	v_mfma_f32_16x16x32_bf16 v[100:103], v[158:161], v[182:185], v[100:103]
	s_waitcnt lgkmcnt(11)
	v_mfma_f32_16x16x32_bf16 v[92:95], v[142:145], v[190:193], v[92:95]
	v_mfma_f32_16x16x32_bf16 v[84:87], v[158:161], v[190:193], v[84:87]
	s_waitcnt lgkmcnt(10)
	v_mfma_f32_16x16x32_bf16 v[76:79], v[142:145], v[198:201], v[76:79]
	v_mfma_f32_16x16x32_bf16 v[68:71], v[158:161], v[198:201], v[68:71]
	s_waitcnt lgkmcnt(8)
	v_mfma_f32_16x16x32_bf16 v[124:127], v[146:149], v[178:181], v[124:127]
	s_waitcnt lgkmcnt(7)
	v_mfma_f32_16x16x32_bf16 v[116:119], v[170:173], v[178:181], v[116:119]
	s_waitcnt lgkmcnt(6)
	v_mfma_f32_16x16x32_bf16 v[108:111], v[146:149], v[186:189], v[108:111]
	v_mfma_f32_16x16x32_bf16 v[100:103], v[170:173], v[186:189], v[100:103]
	s_waitcnt lgkmcnt(5)
	v_mfma_f32_16x16x32_bf16 v[92:95], v[146:149], v[194:197], v[92:95]
	v_mfma_f32_16x16x32_bf16 v[84:87], v[170:173], v[194:197], v[84:87]
	s_waitcnt lgkmcnt(4)
	v_mfma_f32_16x16x32_bf16 v[76:79], v[146:149], v[202:205], v[76:79]
	v_mfma_f32_16x16x32_bf16 v[68:71], v[170:173], v[202:205], v[68:71]
	s_mov_b32 m0, s23
	s_nop 0
	global_load_lds_dwordx4 v139, s[28:29]
	s_mov_b32 m0, s40
	s_nop 0
	global_load_lds_dwordx4 v152, s[28:29]
	s_waitcnt lgkmcnt(3)
	v_mfma_f32_16x16x32_bf16 v[128:131], v[206:209], v[174:177], v[128:131]
	s_waitcnt lgkmcnt(2)
	v_mfma_f32_16x16x32_bf16 v[120:123], v[214:217], v[174:177], v[120:123]
	v_mfma_f32_16x16x32_bf16 v[112:115], v[206:209], v[182:185], v[112:115]
	v_mfma_f32_16x16x32_bf16 v[104:107], v[214:217], v[182:185], v[104:107]
	v_mfma_f32_16x16x32_bf16 v[96:99], v[206:209], v[190:193], v[96:99]
	v_mfma_f32_16x16x32_bf16 v[88:91], v[214:217], v[190:193], v[88:91]
	v_mfma_f32_16x16x32_bf16 v[80:83], v[206:209], v[198:201], v[80:83]
	v_mfma_f32_16x16x32_bf16 v[72:75], v[214:217], v[198:201], v[72:75]
	s_waitcnt lgkmcnt(1)
	v_mfma_f32_16x16x32_bf16 v[128:131], v[210:213], v[178:181], v[128:131]
	s_waitcnt lgkmcnt(0)
	v_mfma_f32_16x16x32_bf16 v[120:123], v[218:221], v[178:181], v[120:123]
	v_mfma_f32_16x16x32_bf16 v[112:115], v[210:213], v[186:189], v[112:115]
	v_mfma_f32_16x16x32_bf16 v[104:107], v[218:221], v[186:189], v[104:107]
	v_mfma_f32_16x16x32_bf16 v[96:99], v[210:213], v[194:197], v[96:99]
	v_mfma_f32_16x16x32_bf16 v[88:91], v[218:221], v[194:197], v[88:91]
	v_mfma_f32_16x16x32_bf16 v[80:83], v[210:213], v[202:205], v[80:83]
	v_mfma_f32_16x16x32_bf16 v[72:75], v[218:221], v[202:205], v[72:75]
	s_waitcnt vmcnt(4) lgkmcnt(0)
	s_barrier
; #define LAS __attribute__((address_space(3)))
; __device__ __forceinline__ void rstd_table(const float* ssq, LAS unsigned char* lds, const Unit& u, int tid, int par) {
;     if (tid < 256) { const f32x4* p = (const f32x4*)(ssq + (size_t)(u.pm * 256 + tid) * 32); f32x4 a = p[0];
; #pragma unroll
;         for (int i = 1; i < 8; ++i) a += p[i];
;         ((LAS float*)(lds + 131072 + par * 1024))[tid] = 1.0f / sqrtf(((a[0] + a[1]) + (a[2] + a[3])) * (1.0f / DM) + 1e-6f); }
	ds_read_b128 v[174:177], v156 offset:49152
	ds_read_b128 v[182:185], v156 offset:51200
	ds_read_b128 v[190:193], v156 offset:53248
	ds_read_b128 v[198:201], v156 offset:55296
	ds_read_b128 v[178:181], v156 offset:50176
	ds_read_b128 v[186:189], v156 offset:52224
	ds_read_b128 v[194:197], v156 offset:54272
	ds_read_b128 v[202:205], v156 offset:56320
	s_add_u32 s64, s64, 0x80000
	s_addc_u32 s65, s65, 0
	s_mov_b32 m0, s41
	s_nop 0
	global_load_lds_dwordx4 v140, s[64:65]
	s_mov_b32 m0, s42
	s_nop 0
	global_load_lds_dwordx4 v153, s[64:65]
	s_waitcnt lgkmcnt(7)
	v_mfma_f32_16x16x32_bf16 v[60:63], v[142:145], v[174:177], v[60:63]
	v_mfma_f32_16x16x32_bf16 v[52:55], v[158:161], v[174:177], v[52:55]
	s_waitcnt lgkmcnt(6)
	v_mfma_f32_16x16x32_bf16 v[44:47], v[142:145], v[182:185], v[44:47]
	v_mfma_f32_16x16x32_bf16 v[36:39], v[158:161], v[182:185], v[36:39]
	s_waitcnt lgkmcnt(5)
	v_mfma_f32_16x16x32_bf16 v[28:31], v[142:145], v[190:193], v[28:31]
	v_mfma_f32_16x16x32_bf16 v[20:23], v[158:161], v[190:193], v[20:23]
	s_waitcnt lgkmcnt(4)
	v_mfma_f32_16x16x32_bf16 v[8:11], v[142:145], v[198:201], v[8:11]
	v_mfma_f32_16x16x32_bf16 v[4:7], v[158:161], v[198:201], v[4:7]
	s_waitcnt lgkmcnt(3)
	v_mfma_f32_16x16x32_bf16 v[60:63], v[146:149], v[178:181], v[60:63]
	v_mfma_f32_16x16x32_bf16 v[52:55], v[170:173], v[178:181], v[52:55]
	s_waitcnt lgkmcnt(2)
	v_mfma_f32_16x16x32_bf16 v[44:47], v[146:149], v[186:189], v[44:47]
	v_mfma_f32_16x16x32_bf16 v[36:39], v[170:173], v[186:189], v[36:39]
	s_waitcnt lgkmcnt(1)
	v_mfma_f32_16x16x32_bf16 v[28:31], v[146:149], v[194:197], v[28:31]
	v_mfma_f32_16x16x32_bf16 v[20:23], v[170:173], v[194:197], v[20:23]
	s_waitcnt lgkmcnt(0)
	v_mfma_f32_16x16x32_bf16 v[8:11], v[146:149], v[202:205], v[8:11]
	v_mfma_f32_16x16x32_bf16 v[4:7], v[170:173], v[202:205], v[4:7]
	s_add_u32 s28, s28, 0x80000
	s_addc_u32 s29, s29, 0
	s_mov_b32 m0, s43
	s_nop 0
	global_load_lds_dwordx4 v139, s[28:29]
	s_mov_b32 m0, s44
	s_nop 0
	global_load_lds_dwordx4 v152, s[28:29]
	v_mfma_f32_16x16x32_bf16 v[64:67], v[206:209], v[174:177], v[64:67]
	s_add_i32 s62, s62, 2
	s_add_u32 s26, s26, 0xffffff00
	s_addc_u32 s27, s27, -1
	v_mfma_f32_16x16x32_bf16 v[56:59], v[214:217], v[174:177], v[56:59]
	s_add_u32 s24, s24, 0x100
	s_addc_u32 s25, s25, 0
	s_add_u32 s10, s10, 0x100
	v_mfma_f32_16x16x32_bf16 v[48:51], v[206:209], v[182:185], v[48:51]
	s_addc_u32 s11, s11, 0
	s_cmp_lt_u32 s62, 30
	v_mfma_f32_16x16x32_bf16 v[40:43], v[214:217], v[182:185], v[40:43]
	v_mfma_f32_16x16x32_bf16 v[32:35], v[206:209], v[190:193], v[32:35]
	v_mfma_f32_16x16x32_bf16 v[24:27], v[214:217], v[190:193], v[24:27]
	v_mfma_f32_16x16x32_bf16 v[16:19], v[206:209], v[198:201], v[16:19]
	v_mfma_f32_16x16x32_bf16 v[12:15], v[214:217], v[198:201], v[12:15]
	v_mfma_f32_16x16x32_bf16 v[64:67], v[210:213], v[178:181], v[64:67]
	v_mfma_f32_16x16x32_bf16 v[56:59], v[218:221], v[178:181], v[56:59]
	v_mfma_f32_16x16x32_bf16 v[48:51], v[210:213], v[186:189], v[48:51]
	v_mfma_f32_16x16x32_bf16 v[40:43], v[218:221], v[186:189], v[40:43]
	v_mfma_f32_16x16x32_bf16 v[32:35], v[210:213], v[194:197], v[32:35]
	v_mfma_f32_16x16x32_bf16 v[24:27], v[218:221], v[194:197], v[24:27]
	v_mfma_f32_16x16x32_bf16 v[16:19], v[210:213], v[202:205], v[16:19]
	v_mfma_f32_16x16x32_bf16 v[12:15], v[218:221], v[202:205], v[12:15]
	s_cbranch_scc1 .LBB0_95
	s_nor_b64 s[10:11], s[6:7], s[8:9]
	s_and_saveexec_b64 s[24:25], s[10:11]
	s_cbranch_execz .LBB0_89
	v_lshl_add_u32 v132, s16, 8, v138
	v_ashrrev_i32_e32 v133, 31, v132
	v_lshlrev_b64 v[132:133], 7, v[132:133]
	v_lshl_add_u64 v[136:137], s[0:1], 0, v[132:133]
	global_load_dwordx4 v[132:135], v[136:137], off offset:48
	global_load_dwordx4 v[142:145], v[136:137], off offset:32
	global_load_dwordx4 v[146:149], v[136:137], off
	global_load_dwordx4 v[158:161], v[136:137], off offset:16
	s_lshl_b32 s5, s57, 10
	s_and_b32 s5, s5, 0x400
	s_waitcnt vmcnt(0)
	v_pk_add_f32 v[148:149], v[148:149], v[160:161]
	v_pk_add_f32 v[146:147], v[146:147], v[158:159]
	v_pk_add_f32 v[144:145], v[148:149], v[144:145]
	v_pk_add_f32 v[142:143], v[146:147], v[142:143]
	v_pk_add_f32 v[162:163], v[144:145], v[134:135]
	v_pk_add_f32 v[170:171], v[142:143], v[132:133]
	global_load_dwordx4 v[132:135], v[136:137], off offset:112
	global_load_dwordx4 v[142:145], v[136:137], off offset:96
	global_load_dwordx4 v[146:149], v[136:137], off offset:80
	global_load_dwordx4 v[158:161], v[136:137], off offset:64
	s_waitcnt vmcnt(0)
	v_pk_add_f32 v[136:137], v[162:163], v[160:161]
	v_pk_add_f32 v[158:159], v[170:171], v[158:159]
	v_pk_add_f32 v[136:137], v[136:137], v[148:149]
	v_pk_add_f32 v[146:147], v[158:159], v[146:147]
	v_pk_add_f32 v[136:137], v[136:137], v[144:145]
	v_pk_add_f32 v[142:143], v[146:147], v[142:143]
	v_pk_add_f32 v[134:135], v[136:137], v[134:135]
	v_pk_add_f32 v[132:133], v[142:143], v[132:133]
	s_nop 0
	v_pk_mov_b32 v[136:137], v[132:133], v[134:135] op_sel:[1,0]
	v_mov_b32_e32 v133, v135
	v_pk_add_f32 v[132:133], v[136:137], v[132:133]
	s_nop 0
	v_add_f32_e32 v132, v132, v133
	v_fmamk_f32 v132, v132, 0x3a000000, v164
	v_cmp_gt_f32_e32 vcc, s69, v132
	v_mul_f32_e32 v133, 0x4f800000, v132
	s_nop 0
	v_cndmask_b32_e32 v132, v132, v133, vcc
	v_sqrt_f32_e32 v133, v132
	s_nop 0
	v_add_u32_e32 v134, -1, v133
	v_fma_f32 v135, -v134, v133, v132
	v_cmp_ge_f32_e64 s[10:11], 0, v135
	v_add_u32_e32 v135, 1, v133
	s_nop 0
	v_cndmask_b32_e64 v134, v133, v134, s[10:11]
	v_fma_f32 v133, -v135, v133, v132
	v_cmp_lt_f32_e64 s[10:11], 0, v133
	s_nop 1
	v_cndmask_b32_e64 v133, v134, v135, s[10:11]
	v_mul_f32_e32 v134, 0x37800000, v133
	v_cndmask_b32_e32 v133, v133, v134, vcc
	v_cmp_class_f32_e32 vcc, v132, v165
	s_nop 1
	v_cndmask_b32_e32 v132, v133, v132, vcc
	v_div_scale_f32 v133, s[10:11], v132, v132, 1.0
	v_rcp_f32_e32 v134, v133
	s_nop 0
	v_fma_f32 v135, -v133, v134, 1.0
	v_fmac_f32_e32 v134, v135, v134
	v_div_scale_f32 v135, vcc, 1.0, v132, 1.0
	v_mul_f32_e32 v136, v135, v134
	v_fma_f32 v137, -v133, v136, v135
	v_fmac_f32_e32 v136, v137, v134
	v_fma_f32 v133, -v133, v136, v135
	v_div_fmas_f32 v133, v133, v134, v136
	v_div_fixup_f32 v132, v133, v132, 1.0
	v_add_u32_e32 v133, s5, v154
	ds_write_b32 v133, v132
	s_branch .LBB0_89

; #define PG8_STAGE4(b, pa, pb) do { PG8_STAGE(PG8_SB(b, 0), (pb), voffB); PG8_STAGE(PG8_SA(b, 0), (pa), voffA); PG8_STAGE(PG8_SB(b, 1), (pb) + hstep, voffB); PG8_STAGE(PG8_SA(b, 1), (pa) + hstep, voffA); } while (0)
; #define PG8_SYNC() do { asm volatile("s_waitcnt vmcnt(0) lgkmcnt(0)" ::: "memory"); __builtin_amdgcn_s_barrier(); asm volatile("" ::: "memory"); } while (0)
; template <class Epi, class Sched>
; __device__ __forceinline__ void gemm_simple(PG8_LAS unsigned char* lds, const Gemm g, const Sched& S, const Epi& E, int wave_s) {
;     ...
;     for (int i = 0; i < 2; ++i) { int R, C; stage_rc(tid * 16 + i * 8192, R, C); const int Rb = Epi::PERM ? ((R & ~31) + perm32(R & 31)) : R;
;         voffA[i] = (unsigned)(R * K + C) * 2u; voffB[i] = (unsigned)(Rb * K + C) * 2u; }
;     const size_t kstep = (size_t)(BK * 2), hstep = (size_t)HALF * K * 2, tstep = 2 * hstep;
;     const unsigned ldsw = (unsigned)wid * 1024u; const unsigned lds_u = (unsigned)(__UINTPTR_TYPE__)lds;
;     const int aoff = lds_byte(wr * 64 + fr, fq * 8), boff = lds_byte(wc * 32 + fr, fq * 8);
;     ...
;     const char* cA = (const char*)g.A + (size_t)cur.pm * tstep; const char* cB = (const char*)g.Bt + (size_t)cur.pn * tstep;
;     PG8_SYNC();
;     PG8_STAGE4(0, cA, cB);
.LBB0_107:
	v_cndmask_b32_e64 v3, 0, 1, s[4:5]
	v_cmp_ne_u32_e64 s[6:7], 1, v3
	s_andn2_b64 vcc, exec, s[4:5]
	s_cbranch_vccnz .LBB0_137
	v_ashrrev_i32_e32 v4, 31, v2
	v_lshrrev_b32_e32 v4, 26, v4
	v_lshlrev_b32_e32 v3, 4, v2
	v_add_u32_e32 v4, v2, v4
	v_bfe_i32 v2, v2, 27, 1
	v_lshrrev_b32_e32 v2, 22, v2
	v_add_u32_e32 v2, v3, v2
	v_and_b32_e32 v2, 0xfffffc00, v2
	v_sub_u32_e32 v2, v3, v2
	s_waitcnt lgkmcnt(0)
	v_lshrrev_b32_e32 v5, 4, v2
	v_bitop3_b32 v2, v5, v2, 32 bitop3:0x6c
	v_ashrrev_i32_e32 v6, 31, v2
	v_ashrrev_i32_e32 v4, 6, v4
	v_lshrrev_b32_e32 v6, 26, v6
	v_lshlrev_b32_e32 v5, 3, v4
	v_add_u32_e32 v6, v2, v6
	v_and_b32_e32 v5, -16, v5
	v_ashrrev_i32_e32 v7, 6, v6
	v_and_b32_e32 v6, 0xc0, v6
	v_add_u32_e32 v5, v7, v5
	v_sub_u32_e32 v2, v2, v6
	v_lshlrev_b32_e32 v4, 5, v4
	v_ashrrev_i16_sdwa v2, v166, sext(v2) dst_sel:DWORD dst_unused:UNUSED_PAD src0_sel:DWORD src1_sel:BYTE_0
	v_lshlrev_b32_e32 v6, 1, v5
	v_lshrrev_b32_e32 v8, 2, v5
	v_and_b32_e32 v7, 3, v7
	s_mov_b32 s5, 0xfffe0
	v_and_b32_e32 v4, 32, v4
	v_bfe_i32 v2, v2, 0, 16
	v_and_b32_e32 v6, 24, v6
	v_and_b32_e32 v8, 4, v8
	v_and_or_b32 v7, v5, s5, v7
	v_or3_b32 v6, v7, v8, v6
	v_add_lshl_u32 v2, v4, v2, 1
	v_lshl_add_u32 v138, v5, 12, v2
	v_lshl_add_u32 v139, v6, 12, v2
	v_add_u32_e32 v2, 0x2000, v3
	v_ashrrev_i32_e32 v3, 31, v2
	v_lshrrev_b32_e32 v3, 22, v3
	v_add_u32_e32 v3, v2, v3
	v_ashrrev_i32_e32 v3, 10, v3
	v_mul_i32_i24_e32 v4, 0x400, v3
	v_sub_u32_e32 v2, v2, v4
	v_lshrrev_b32_e32 v4, 4, v2
	v_bitop3_b32 v2, v4, v2, 32 bitop3:0x6c
	v_ashrrev_i32_e32 v5, 31, v2
	v_lshrrev_b32_e32 v5, 26, v5
	v_lshlrev_b32_e32 v4, 3, v3
	v_add_u32_e32 v5, v2, v5
	v_and_b32_e32 v4, -16, v4
	v_ashrrev_i32_e32 v6, 6, v5
	v_and_b32_e32 v5, 0xc0, v5
	v_add_u32_e32 v4, v6, v4
	v_sub_u32_e32 v2, v2, v5
	v_readlane_b32 s4, v254, 57
	v_lshlrev_b32_e32 v3, 5, v3
	v_ashrrev_i16_sdwa v2, v166, sext(v2) dst_sel:DWORD dst_unused:UNUSED_PAD src0_sel:DWORD src1_sel:BYTE_0
	v_lshlrev_b32_e32 v5, 1, v4
	v_lshrrev_b32_e32 v7, 2, v4
	v_and_b32_e32 v6, 3, v6
	s_add_u32 s28, s4, 0x3000000
	v_readlane_b32 s4, v254, 58
	v_and_b32_e32 v3, 32, v3
	v_bfe_i32 v2, v2, 0, 16
	v_and_b32_e32 v5, 24, v5
	v_and_b32_e32 v7, 4, v7
	v_and_or_b32 v6, v4, s5, v6
	s_addc_u32 s29, s4, 0
	v_or3_b32 v5, v6, v7, v5
	v_add_lshl_u32 v2, v3, v2, 1
	s_ashr_i32 s37, s8, 2
	s_ashr_i32 s4, s8, 6
	v_lshl_add_u32 v140, v4, 12, v2
	v_lshl_add_u32 v152, v5, 12, v2
	s_andn2_b32 s37, s37, 63
	v_and_b32_e32 v2, 48, v1
	v_lshlrev_b32_e32 v3, 6, v1
	s_movk_i32 s5, 0x3c0
	v_lshlrev_b32_e32 v1, 2, v1
	s_and_b32 s36, s4, 3
	s_lshl_b32 s10, s4, 10
	s_lshl_b32 s4, s37, 7
	v_and_or_b32 v2, v3, s5, v2
	v_and_b32_e32 v1, 32, v1
	v_bitop3_b32 v4, v2, s4, v1 bitop3:0xde
	s_lshl_b32 s4, s36, 12
	s_ashr_i32 s23, s22, 31
	s_ashr_i32 s21, s20, 31
	s_lshl_b32 s38, s36, 5
	v_bitop3_b32 v5, s4, v2, v1 bitop3:0xf6
	s_lshl_b64 s[4:5], s[22:23], 20
	s_lshl_b64 s[8:9], s[20:21], 20
	s_add_u32 s24, s28, s8
	s_addc_u32 s25, s29, s9
	s_waitcnt vmcnt(0) lgkmcnt(0)
	s_barrier
	s_add_i32 s39, s10, 0
	s_add_i32 s40, s39, 0x10000
	s_mov_b32 m0, s40
	s_nop 0
	global_load_lds_dwordx4 v139, s[24:25]
	s_add_i32 s41, s39, 0x12000
	s_mov_b32 m0, s41
	s_nop 0
	global_load_lds_dwordx4 v152, s[24:25]
	s_add_u32 s26, s12, s4
	s_addc_u32 s27, s13, s5
	s_mov_b32 m0, s39
	s_nop 0
	global_load_lds_dwordx4 v138, s[26:27]
	s_add_i32 s42, s39, 0x2000
	s_mov_b32 m0, s42
	s_nop 0
	global_load_lds_dwordx4 v140, s[26:27]
	s_add_u32 s4, s24, 0x80000
	s_addc_u32 s5, s25, 0
	s_add_i32 s43, s39, 0x14000
	s_mov_b32 m0, s43
	s_nop 0
	global_load_lds_dwordx4 v139, s[4:5]
	s_add_i32 s44, s39, 0x16000
	s_mov_b32 m0, s44
	s_nop 0
	global_load_lds_dwordx4 v152, s[4:5]
	s_add_u32 s4, s26, 0x80000
	s_addc_u32 s5, s27, 0
	s_add_i32 s45, s39, 0x4000
	s_mov_b32 m0, s45
	s_nop 0
	global_load_lds_dwordx4 v138, s[4:5]
	s_add_i32 s46, s39, 0x6000
	s_mov_b32 m0, s46
	s_nop 0
	global_load_lds_dwordx4 v140, s[4:5]
	v_mov_b32_e32 v1, v0
	v_mov_b32_e32 v2, v0
	v_mov_b32_e32 v3, v0
	s_add_i32 s47, s39, 0x18000
	s_add_i32 s48, s39, 0x8000
	s_add_i32 s49, s39, 0x1c000
	s_add_i32 s50, s39, 0xc000
	s_add_i32 s51, s39, 0x1a000
	s_add_i32 s52, s39, 0xa000
	s_add_i32 s53, s39, 0x1e000
	s_add_i32 s54, s39, 0xe000
	s_ashr_i32 s55, s34, 31
	s_ashr_i32 s56, s31, 31
	s_mov_b32 s11, 0
	v_add_u32_e32 v153, 0, v5
	v_add_u32_e32 v154, 0, v4
	s_branch .LBB0_110

; template <class Epi, class Sched>
; __device__ __forceinline__ void gemm_simple(PG8_LAS unsigned char* lds, const Gemm g, const Sched& S, const Epi& E, int wave_s) {
;     ...
;         if (ui > 0) {
;             if constexpr (Epi::NST >= 16) PG8_TILE_W(0, cA + kstep, cB + kstep, "18", "20"); else PG8_TILE_W(0, cA + kstep, cB + kstep, "10", "12");
;             PG8_TILE_W(1, cA + 2 * kstep, cB + 2 * kstep, "2", "4");
;             t = 2;
.LBB0_116:
	s_waitcnt lgkmcnt(0)
	v_mov_b64_e32 v[6:7], v[2:3]
	v_mov_b64_e32 v[10:11], v[2:3]
	v_mov_b64_e32 v[22:23], v[2:3]
	v_mov_b64_e32 v[26:27], v[2:3]
	v_mov_b64_e32 v[38:39], v[2:3]
	v_mov_b64_e32 v[42:43], v[2:3]
	v_mov_b64_e32 v[54:55], v[2:3]
	v_mov_b64_e32 v[58:59], v[2:3]
	v_mov_b64_e32 v[14:15], v[2:3]
	v_mov_b64_e32 v[18:19], v[2:3]
	v_mov_b64_e32 v[30:31], v[2:3]
	v_mov_b64_e32 v[34:35], v[2:3]
	v_mov_b64_e32 v[46:47], v[2:3]
	v_mov_b64_e32 v[50:51], v[2:3]
	v_mov_b64_e32 v[62:63], v[2:3]
	v_mov_b64_e32 v[66:67], v[2:3]
	v_mov_b64_e32 v[70:71], v[2:3]
	v_mov_b64_e32 v[74:75], v[2:3]
	v_mov_b64_e32 v[86:87], v[2:3]
	v_mov_b64_e32 v[90:91], v[2:3]
	v_mov_b64_e32 v[102:103], v[2:3]
	v_mov_b64_e32 v[106:107], v[2:3]
	v_mov_b64_e32 v[118:119], v[2:3]
	v_mov_b64_e32 v[122:123], v[2:3]
	v_mov_b64_e32 v[78:79], v[2:3]
	v_mov_b64_e32 v[82:83], v[2:3]
	v_mov_b64_e32 v[94:95], v[2:3]
	v_mov_b64_e32 v[98:99], v[2:3]
	v_mov_b64_e32 v[110:111], v[2:3]
	v_mov_b64_e32 v[114:115], v[2:3]
	v_mov_b64_e32 v[126:127], v[2:3]
	v_mov_b64_e32 v[130:131], v[2:3]
	v_cmp_lt_i64_e32 vcc, s[16:17], v[168:169]
	s_mov_b32 s58, 0
	s_cmp_eq_u32 s11, 0
	v_add_u32_e32 v132, 0x10000, v153
	v_add_u32_e32 v133, 0x14000, v153
	v_add_u32_e32 v134, 0x18000, v153
	v_add_u32_e32 v135, 0x1c000, v153
	v_mov_b64_e32 v[4:5], v[0:1]
	v_mov_b64_e32 v[8:9], v[0:1]
	v_mov_b64_e32 v[20:21], v[0:1]
	v_mov_b64_e32 v[24:25], v[0:1]
	v_mov_b64_e32 v[36:37], v[0:1]
	v_mov_b64_e32 v[40:41], v[0:1]
	v_mov_b64_e32 v[52:53], v[0:1]
	v_mov_b64_e32 v[56:57], v[0:1]
	v_mov_b64_e32 v[12:13], v[0:1]
	v_mov_b64_e32 v[16:17], v[0:1]
	v_mov_b64_e32 v[28:29], v[0:1]
	v_mov_b64_e32 v[32:33], v[0:1]
	v_mov_b64_e32 v[44:45], v[0:1]
	v_mov_b64_e32 v[48:49], v[0:1]
	v_mov_b64_e32 v[60:61], v[0:1]
	v_mov_b64_e32 v[64:65], v[0:1]
	v_mov_b64_e32 v[68:69], v[0:1]
	v_mov_b64_e32 v[72:73], v[0:1]
	v_mov_b64_e32 v[84:85], v[0:1]
	v_mov_b64_e32 v[88:89], v[0:1]
	v_mov_b64_e32 v[100:101], v[0:1]
	v_mov_b64_e32 v[104:105], v[0:1]
	v_mov_b64_e32 v[116:117], v[0:1]
	v_mov_b64_e32 v[120:121], v[0:1]
	v_mov_b64_e32 v[76:77], v[0:1]
	v_mov_b64_e32 v[80:81], v[0:1]
	v_mov_b64_e32 v[92:93], v[0:1]
	v_mov_b64_e32 v[96:97], v[0:1]
	v_mov_b64_e32 v[108:109], v[0:1]
	v_mov_b64_e32 v[112:113], v[0:1]
	v_mov_b64_e32 v[124:125], v[0:1]
	v_mov_b64_e32 v[128:129], v[0:1]
	s_cbranch_scc1 .LBB0_118
	s_waitcnt vmcnt(18) lgkmcnt(0)
	s_barrier
	ds_read_b128 v[4:7], v132
	ds_read_b128 v[8:11], v132 offset:1024
	ds_read_b128 v[12:15], v132 offset:2048
	ds_read_b128 v[16:19], v132 offset:3072
	ds_read_b128 v[20:23], v154
	ds_read_b128 v[24:27], v154 offset:1024
	ds_read_b128 v[28:31], v154 offset:2048
	ds_read_b128 v[32:35], v154 offset:3072
	ds_read_b128 v[36:39], v154 offset:4096
	ds_read_b128 v[40:43], v154 offset:5120
	ds_read_b128 v[44:47], v154 offset:6144
	ds_read_b128 v[48:51], v154 offset:7168
	ds_read_b128 v[52:55], v133
	ds_read_b128 v[56:59], v133 offset:1024
	ds_read_b128 v[60:63], v133 offset:2048
	ds_read_b128 v[64:67], v133 offset:3072
	s_add_u32 s16, s24, 0x80
	s_addc_u32 s17, s25, 0
	s_mov_b32 m0, s47
	s_nop 0
	global_load_lds_dwordx4 v139, s[16:17]
	s_mov_b32 m0, s51
	s_nop 0
	global_load_lds_dwordx4 v152, s[16:17]
	s_waitcnt lgkmcnt(5)
	v_mfma_f32_16x16x32_bf16 v[92:95], v[4:7], v[44:47], v[0:3]
	v_mfma_f32_16x16x32_bf16 v[68:71], v[4:7], v[20:23], v[0:3]
	v_mfma_f32_16x16x32_bf16 v[72:75], v[12:15], v[20:23], v[0:3]
	v_mfma_f32_16x16x32_bf16 v[76:79], v[4:7], v[28:31], v[0:3]
	v_mfma_f32_16x16x32_bf16 v[80:83], v[12:15], v[28:31], v[0:3]
	v_mfma_f32_16x16x32_bf16 v[84:87], v[4:7], v[36:39], v[0:3]
	v_mfma_f32_16x16x32_bf16 v[88:91], v[12:15], v[36:39], v[0:3]
	s_waitcnt lgkmcnt(4)
	v_mfma_f32_16x16x32_bf16 v[100:103], v[8:11], v[48:51], v[92:95]
	v_mfma_f32_16x16x32_bf16 v[92:95], v[12:15], v[44:47], v[0:3]
	v_mfma_f32_16x16x32_bf16 v[68:71], v[8:11], v[24:27], v[68:71]
	v_mfma_f32_16x16x32_bf16 v[72:75], v[16:19], v[24:27], v[72:75]
	v_mfma_f32_16x16x32_bf16 v[76:79], v[8:11], v[32:35], v[76:79]
	v_mfma_f32_16x16x32_bf16 v[80:83], v[16:19], v[32:35], v[80:83]
	v_mfma_f32_16x16x32_bf16 v[84:87], v[8:11], v[40:43], v[84:87]
	v_mfma_f32_16x16x32_bf16 v[88:91], v[16:19], v[40:43], v[88:91]
	v_mfma_f32_16x16x32_bf16 v[104:107], v[16:19], v[48:51], v[92:95]
	s_add_u32 s16, s26, 0x80
	s_addc_u32 s17, s27, 0
	s_mov_b32 m0, s48
	s_nop 0
	global_load_lds_dwordx4 v138, s[16:17]
	s_mov_b32 m0, s52
	s_nop 0
	global_load_lds_dwordx4 v140, s[16:17]
	s_waitcnt lgkmcnt(3)
	v_mfma_f32_16x16x32_bf16 v[92:95], v[52:55], v[20:23], v[0:3]
	s_waitcnt lgkmcnt(1)
	v_mfma_f32_16x16x32_bf16 v[20:23], v[60:63], v[20:23], v[0:3]
	v_mfma_f32_16x16x32_bf16 v[116:119], v[56:59], v[24:27], v[92:95]
	s_waitcnt lgkmcnt(0)
	v_mfma_f32_16x16x32_bf16 v[20:23], v[64:67], v[24:27], v[20:23]
	v_mfma_f32_16x16x32_bf16 v[24:27], v[52:55], v[28:31], v[0:3]
	v_mfma_f32_16x16x32_bf16 v[28:31], v[60:63], v[28:31], v[0:3]
	v_mfma_f32_16x16x32_bf16 v[24:27], v[56:59], v[32:35], v[24:27]
	v_mfma_f32_16x16x32_bf16 v[28:31], v[64:67], v[32:35], v[28:31]
	v_mfma_f32_16x16x32_bf16 v[32:35], v[52:55], v[36:39], v[0:3]
	v_mfma_f32_16x16x32_bf16 v[36:39], v[60:63], v[36:39], v[0:3]
	v_mfma_f32_16x16x32_bf16 v[32:35], v[56:59], v[40:43], v[32:35]
	v_mfma_f32_16x16x32_bf16 v[36:39], v[64:67], v[40:43], v[36:39]
	v_mfma_f32_16x16x32_bf16 v[40:43], v[52:55], v[44:47], v[0:3]
	v_mfma_f32_16x16x32_bf16 v[44:47], v[60:63], v[44:47], v[0:3]
	v_mfma_f32_16x16x32_bf16 v[40:43], v[56:59], v[48:51], v[40:43]
	v_mfma_f32_16x16x32_bf16 v[44:47], v[64:67], v[48:51], v[44:47]
	s_waitcnt vmcnt(20) lgkmcnt(0)
	s_barrier
	ds_read_b128 v[48:51], v154 offset:16384
	ds_read_b128 v[92:95], v154 offset:17408
	ds_read_b128 v[96:99], v154 offset:18432
	ds_read_b128 v[108:111], v154 offset:19456
	ds_read_b128 v[112:115], v154 offset:20480
	ds_read_b128 v[120:123], v154 offset:21504
	ds_read_b128 v[124:127], v154 offset:22528
	ds_read_b128 v[128:131], v154 offset:23552
	s_add_u32 s16, s24, 0x80080
	s_addc_u32 s17, s25, 0
	s_mov_b32 m0, s49
	s_nop 0
	global_load_lds_dwordx4 v139, s[16:17]
	s_mov_b32 m0, s53
	s_nop 0
	global_load_lds_dwordx4 v152, s[16:17]
	s_waitcnt lgkmcnt(7)
	v_mfma_f32_16x16x32_bf16 v[146:149], v[4:7], v[48:51], v[0:3]
	s_waitcnt lgkmcnt(5)
	v_mfma_f32_16x16x32_bf16 v[160:163], v[4:7], v[96:99], v[0:3]
	s_waitcnt lgkmcnt(3)
	v_mfma_f32_16x16x32_bf16 v[174:177], v[4:7], v[112:115], v[0:3]
	s_waitcnt lgkmcnt(1)
	v_mfma_f32_16x16x32_bf16 v[4:7], v[4:7], v[124:127], v[0:3]
	v_mfma_f32_16x16x32_bf16 v[146:149], v[8:11], v[92:95], v[146:149]
	v_mfma_f32_16x16x32_bf16 v[160:163], v[8:11], v[108:111], v[160:163]
	v_mfma_f32_16x16x32_bf16 v[174:177], v[8:11], v[120:123], v[174:177]
	s_waitcnt lgkmcnt(0)
	v_mfma_f32_16x16x32_bf16 v[4:7], v[8:11], v[128:131], v[4:7]
	v_mfma_f32_16x16x32_bf16 v[8:11], v[12:15], v[124:127], v[0:3]
	v_mfma_f32_16x16x32_bf16 v[156:159], v[12:15], v[48:51], v[0:3]
	v_mfma_f32_16x16x32_bf16 v[170:173], v[12:15], v[96:99], v[0:3]
	v_mfma_f32_16x16x32_bf16 v[178:181], v[12:15], v[112:115], v[0:3]
	v_mfma_f32_16x16x32_bf16 v[8:11], v[16:19], v[128:131], v[8:11]
	v_mfma_f32_16x16x32_bf16 v[156:159], v[16:19], v[92:95], v[156:159]
	v_mfma_f32_16x16x32_bf16 v[170:173], v[16:19], v[108:111], v[170:173]
	v_mfma_f32_16x16x32_bf16 v[178:181], v[16:19], v[120:123], v[178:181]
	s_add_u32 s16, s26, 0x80080
	s_addc_u32 s17, s27, 0
	s_mov_b32 m0, s50
	s_nop 0
	global_load_lds_dwordx4 v138, s[16:17]
	s_mov_b32 m0, s54
	s_nop 0
	global_load_lds_dwordx4 v140, s[16:17]
	v_mfma_f32_16x16x32_bf16 v[12:15], v[52:55], v[48:51], v[0:3]
	v_mfma_f32_16x16x32_bf16 v[182:185], v[56:59], v[92:95], v[12:15]
	v_mfma_f32_16x16x32_bf16 v[12:15], v[60:63], v[48:51], v[0:3]
	v_mfma_f32_16x16x32_bf16 v[186:189], v[64:67], v[92:95], v[12:15]
	v_mfma_f32_16x16x32_bf16 v[12:15], v[52:55], v[96:99], v[0:3]
	v_mfma_f32_16x16x32_bf16 v[190:193], v[56:59], v[108:111], v[12:15]
	v_mfma_f32_16x16x32_bf16 v[12:15], v[60:63], v[96:99], v[0:3]
	v_mfma_f32_16x16x32_bf16 v[194:197], v[64:67], v[108:111], v[12:15]
	v_mfma_f32_16x16x32_bf16 v[12:15], v[52:55], v[112:115], v[0:3]
	v_mfma_f32_16x16x32_bf16 v[198:201], v[56:59], v[120:123], v[12:15]
	v_mfma_f32_16x16x32_bf16 v[12:15], v[60:63], v[112:115], v[0:3]
	v_mfma_f32_16x16x32_bf16 v[202:205], v[64:67], v[120:123], v[12:15]
	v_mfma_f32_16x16x32_bf16 v[12:15], v[52:55], v[124:127], v[0:3]
	v_mfma_f32_16x16x32_bf16 v[206:209], v[56:59], v[128:131], v[12:15]
	v_mfma_f32_16x16x32_bf16 v[12:15], v[60:63], v[124:127], v[0:3]
	v_mfma_f32_16x16x32_bf16 v[210:213], v[64:67], v[128:131], v[12:15]
	s_waitcnt vmcnt(2) lgkmcnt(0)
	s_barrier
	s_nop 5
	ds_read_b128 v[12:15], v134
	ds_read_b128 v[16:19], v134 offset:1024
	ds_read_b128 v[52:55], v134 offset:2048
	ds_read_b128 v[56:59], v134 offset:3072
	ds_read_b128 v[48:51], v154 offset:32768
	ds_read_b128 v[60:63], v154 offset:33792
	ds_read_b128 v[64:67], v154 offset:34816
	ds_read_b128 v[214:217], v154 offset:35840
	ds_read_b128 v[218:221], v154 offset:36864
	ds_read_b128 v[222:225], v154 offset:37888
	ds_read_b128 v[226:229], v154 offset:38912
	ds_read_b128 v[230:233], v154 offset:39936
	ds_read_b128 v[234:237], v135
	ds_read_b128 v[238:241], v135 offset:1024
	ds_read_b128 v[242:245], v135 offset:2048
	ds_read_b128 v[246:249], v135 offset:3072
	s_add_u32 s16, s24, 0x100
	s_addc_u32 s17, s25, 0
	s_mov_b32 m0, s40
	s_nop 0
	global_load_lds_dwordx4 v139, s[16:17]
	s_mov_b32 m0, s41
	s_nop 0
	global_load_lds_dwordx4 v152, s[16:17]
	s_waitcnt lgkmcnt(11)
	v_mfma_f32_16x16x32_bf16 v[68:71], v[12:15], v[48:51], v[68:71]
	s_waitcnt lgkmcnt(10)
	v_mfma_f32_16x16x32_bf16 v[128:131], v[16:19], v[60:63], v[68:71]
	v_mfma_f32_16x16x32_bf16 v[68:71], v[52:55], v[48:51], v[72:75]
	v_mfma_f32_16x16x32_bf16 v[124:127], v[56:59], v[60:63], v[68:71]
	s_waitcnt lgkmcnt(9)
	v_mfma_f32_16x16x32_bf16 v[68:71], v[12:15], v[64:67], v[76:79]
	s_waitcnt lgkmcnt(8)
	v_mfma_f32_16x16x32_bf16 v[112:115], v[16:19], v[214:217], v[68:71]
	v_mfma_f32_16x16x32_bf16 v[68:71], v[52:55], v[64:67], v[80:83]
	v_mfma_f32_16x16x32_bf16 v[108:111], v[56:59], v[214:217], v[68:71]
	s_waitcnt lgkmcnt(7)
	v_mfma_f32_16x16x32_bf16 v[68:71], v[12:15], v[218:221], v[84:87]
	s_waitcnt lgkmcnt(6)
	v_mfma_f32_16x16x32_bf16 v[96:99], v[16:19], v[222:225], v[68:71]
	v_mfma_f32_16x16x32_bf16 v[68:71], v[52:55], v[218:221], v[88:91]
	v_mfma_f32_16x16x32_bf16 v[92:95], v[56:59], v[222:225], v[68:71]
	s_waitcnt lgkmcnt(5)
	v_mfma_f32_16x16x32_bf16 v[68:71], v[12:15], v[226:229], v[100:103]
	s_waitcnt lgkmcnt(4)
	v_mfma_f32_16x16x32_bf16 v[80:83], v[16:19], v[230:233], v[68:71]
	v_mfma_f32_16x16x32_bf16 v[68:71], v[52:55], v[226:229], v[104:107]
	v_mfma_f32_16x16x32_bf16 v[76:79], v[56:59], v[230:233], v[68:71]
	s_add_u32 s16, s26, 0x100
	s_addc_u32 s17, s27, 0
	s_mov_b32 m0, s39
	s_nop 0
	global_load_lds_dwordx4 v138, s[16:17]
	s_mov_b32 m0, s42
	s_nop 0
	global_load_lds_dwordx4 v140, s[16:17]
	s_waitcnt lgkmcnt(1)
	v_mfma_f32_16x16x32_bf16 v[20:23], v[242:245], v[48:51], v[20:23]
	v_mfma_f32_16x16x32_bf16 v[68:71], v[234:237], v[48:51], v[116:119]
	s_waitcnt lgkmcnt(0)
	v_mfma_f32_16x16x32_bf16 v[116:119], v[246:249], v[60:63], v[20:23]
	v_mfma_f32_16x16x32_bf16 v[20:23], v[234:237], v[64:67], v[24:27]
	v_mfma_f32_16x16x32_bf16 v[104:107], v[238:241], v[214:217], v[20:23]
	v_mfma_f32_16x16x32_bf16 v[20:23], v[242:245], v[64:67], v[28:31]
	v_mfma_f32_16x16x32_bf16 v[100:103], v[246:249], v[214:217], v[20:23]
	v_mfma_f32_16x16x32_bf16 v[20:23], v[234:237], v[218:221], v[32:35]
	v_mfma_f32_16x16x32_bf16 v[88:91], v[238:241], v[222:225], v[20:23]
	v_mfma_f32_16x16x32_bf16 v[20:23], v[242:245], v[218:221], v[36:39]
	v_mfma_f32_16x16x32_bf16 v[84:87], v[246:249], v[222:225], v[20:23]
	v_mfma_f32_16x16x32_bf16 v[20:23], v[234:237], v[226:229], v[40:43]
	v_mfma_f32_16x16x32_bf16 v[72:75], v[238:241], v[230:233], v[20:23]
	v_mfma_f32_16x16x32_bf16 v[20:23], v[242:245], v[226:229], v[44:47]
	v_mfma_f32_16x16x32_bf16 v[120:123], v[238:241], v[60:63], v[68:71]
	v_mfma_f32_16x16x32_bf16 v[68:71], v[246:249], v[230:233], v[20:23]
	s_waitcnt vmcnt(4) lgkmcnt(0)
	s_barrier
	s_nop 4
	ds_read_b128 v[20:23], v154 offset:49152
	ds_read_b128 v[24:27], v154 offset:50176
	ds_read_b128 v[36:39], v154 offset:51200
	ds_read_b128 v[214:217], v154 offset:52224
	ds_read_b128 v[218:221], v154 offset:53248
	ds_read_b128 v[222:225], v154 offset:54272
	ds_read_b128 v[226:229], v154 offset:55296
	ds_read_b128 v[230:233], v154 offset:56320
	s_add_u32 s16, s24, 0x80100
	s_addc_u32 s17, s25, 0
	s_mov_b32 m0, s43
	s_nop 0
	global_load_lds_dwordx4 v139, s[16:17]
	s_mov_b32 m0, s44
	s_nop 0
	global_load_lds_dwordx4 v152, s[16:17]
	s_waitcnt lgkmcnt(7)
	v_mfma_f32_16x16x32_bf16 v[28:31], v[12:15], v[20:23], v[146:149]
	s_waitcnt lgkmcnt(6)
	v_mfma_f32_16x16x32_bf16 v[64:67], v[16:19], v[24:27], v[28:31]
	v_mfma_f32_16x16x32_bf16 v[28:31], v[52:55], v[20:23], v[156:159]
	v_mfma_f32_16x16x32_bf16 v[60:63], v[56:59], v[24:27], v[28:31]
	s_waitcnt lgkmcnt(5)
	v_mfma_f32_16x16x32_bf16 v[28:31], v[12:15], v[36:39], v[160:163]
	s_waitcnt lgkmcnt(4)
	v_mfma_f32_16x16x32_bf16 v[48:51], v[16:19], v[214:217], v[28:31]
	v_mfma_f32_16x16x32_bf16 v[28:31], v[52:55], v[36:39], v[170:173]
	v_mfma_f32_16x16x32_bf16 v[44:47], v[56:59], v[214:217], v[28:31]
	s_waitcnt lgkmcnt(3)
	v_mfma_f32_16x16x32_bf16 v[28:31], v[12:15], v[218:221], v[174:177]
	s_waitcnt lgkmcnt(1)
	v_mfma_f32_16x16x32_bf16 v[4:7], v[12:15], v[226:229], v[4:7]
	v_mfma_f32_16x16x32_bf16 v[32:35], v[16:19], v[222:225], v[28:31]
	v_mfma_f32_16x16x32_bf16 v[28:31], v[52:55], v[218:221], v[178:181]
	s_waitcnt lgkmcnt(0)
	v_mfma_f32_16x16x32_bf16 v[16:19], v[16:19], v[230:233], v[4:7]
	v_mfma_f32_16x16x32_bf16 v[4:7], v[52:55], v[226:229], v[8:11]
	v_mfma_f32_16x16x32_bf16 v[28:31], v[56:59], v[222:225], v[28:31]
	v_mfma_f32_16x16x32_bf16 v[12:15], v[56:59], v[230:233], v[4:7]
	s_add_u32 s16, s26, 0x80100
	s_addc_u32 s17, s27, 0
	s_mov_b32 m0, s45
	s_nop 0
	global_load_lds_dwordx4 v138, s[16:17]
	s_mov_b32 m0, s46
	s_nop 0
	global_load_lds_dwordx4 v140, s[16:17]
	v_mfma_f32_16x16x32_bf16 v[4:7], v[234:237], v[20:23], v[182:185]
	s_mov_b32 s58, 2
	v_mfma_f32_16x16x32_bf16 v[56:59], v[238:241], v[24:27], v[4:7]
	v_mfma_f32_16x16x32_bf16 v[4:7], v[242:245], v[20:23], v[186:189]
	v_mfma_f32_16x16x32_bf16 v[52:55], v[246:249], v[24:27], v[4:7]
	v_mfma_f32_16x16x32_bf16 v[4:7], v[234:237], v[36:39], v[190:193]
	v_mfma_f32_16x16x32_bf16 v[40:43], v[238:241], v[214:217], v[4:7]
	v_mfma_f32_16x16x32_bf16 v[4:7], v[242:245], v[36:39], v[194:197]
	v_mfma_f32_16x16x32_bf16 v[36:39], v[246:249], v[214:217], v[4:7]
	v_mfma_f32_16x16x32_bf16 v[4:7], v[234:237], v[218:221], v[198:201]
	v_mfma_f32_16x16x32_bf16 v[24:27], v[238:241], v[222:225], v[4:7]
	v_mfma_f32_16x16x32_bf16 v[4:7], v[242:245], v[218:221], v[202:205]
	v_mfma_f32_16x16x32_bf16 v[20:23], v[246:249], v[222:225], v[4:7]
	v_mfma_f32_16x16x32_bf16 v[4:7], v[234:237], v[226:229], v[206:209]
	v_mfma_f32_16x16x32_bf16 v[8:11], v[238:241], v[230:233], v[4:7]
	v_mfma_f32_16x16x32_bf16 v[4:7], v[242:245], v[226:229], v[210:213]
	v_mfma_f32_16x16x32_bf16 v[4:7], v[246:249], v[230:233], v[4:7]

; template <class Epi, class Sched>
; __device__ __forceinline__ void gemm_simple(PG8_LAS unsigned char* lds, const Gemm g, const Sched& S, const Epi& E, int wave_s) {
;     ...
;         for (; t < nt; t += 2) {
;             const bool last = (t == nt - 2);
;             PG8_TILE(0, cA + (size_t)(t + 1) * kstep, cB + (size_t)(t + 1) * kstep, true);
.LBB0_119:
	s_waitcnt vmcnt(2) lgkmcnt(0)
	s_barrier
	ds_read_b128 v[146:149], v132
	ds_read_b128 v[174:177], v154
	ds_read_b128 v[160:163], v132 offset:2048
	ds_read_b128 v[182:185], v154 offset:2048
	ds_read_b128 v[190:193], v154 offset:4096
	ds_read_b128 v[198:201], v154 offset:6144
	ds_read_b128 v[156:159], v132 offset:1024
	ds_read_b128 v[178:181], v154 offset:1024
	ds_read_b128 v[170:173], v132 offset:3072
	ds_read_b128 v[186:189], v154 offset:3072
	ds_read_b128 v[194:197], v154 offset:5120
	ds_read_b128 v[202:205], v154 offset:7168
	ds_read_b128 v[206:209], v133
	ds_read_b128 v[214:217], v133 offset:2048
	ds_read_b128 v[210:213], v133 offset:1024
	ds_read_b128 v[218:221], v133 offset:3072
	s_add_u32 s26, s69, s58
	s_addc_u32 s27, s70, 0
	s_mov_b32 m0, s47
	s_nop 0
	global_load_lds_dwordx4 v139, s[26:27]
	s_mov_b32 m0, s51
	s_nop 0
	global_load_lds_dwordx4 v152, s[26:27]
	s_waitcnt lgkmcnt(14)
	v_mfma_f32_16x16x32_bf16 v[128:131], v[146:149], v[174:177], v[128:131]
	s_waitcnt lgkmcnt(13)
	v_mfma_f32_16x16x32_bf16 v[124:127], v[160:163], v[174:177], v[124:127]
	s_waitcnt lgkmcnt(12)
	v_mfma_f32_16x16x32_bf16 v[112:115], v[146:149], v[182:185], v[112:115]
	v_mfma_f32_16x16x32_bf16 v[108:111], v[160:163], v[182:185], v[108:111]
	s_waitcnt lgkmcnt(11)
	v_mfma_f32_16x16x32_bf16 v[96:99], v[146:149], v[190:193], v[96:99]
	v_mfma_f32_16x16x32_bf16 v[92:95], v[160:163], v[190:193], v[92:95]
	s_waitcnt lgkmcnt(10)
	v_mfma_f32_16x16x32_bf16 v[80:83], v[146:149], v[198:201], v[80:83]
	v_mfma_f32_16x16x32_bf16 v[76:79], v[160:163], v[198:201], v[76:79]
	s_waitcnt lgkmcnt(8)
	v_mfma_f32_16x16x32_bf16 v[128:131], v[156:159], v[178:181], v[128:131]
	s_waitcnt lgkmcnt(7)
	v_mfma_f32_16x16x32_bf16 v[124:127], v[170:173], v[178:181], v[124:127]
	s_waitcnt lgkmcnt(6)
	v_mfma_f32_16x16x32_bf16 v[112:115], v[156:159], v[186:189], v[112:115]
	v_mfma_f32_16x16x32_bf16 v[108:111], v[170:173], v[186:189], v[108:111]
	s_waitcnt lgkmcnt(5)
	v_mfma_f32_16x16x32_bf16 v[96:99], v[156:159], v[194:197], v[96:99]
	v_mfma_f32_16x16x32_bf16 v[92:95], v[170:173], v[194:197], v[92:95]
	s_waitcnt lgkmcnt(4)
	v_mfma_f32_16x16x32_bf16 v[80:83], v[156:159], v[202:205], v[80:83]
	v_mfma_f32_16x16x32_bf16 v[76:79], v[170:173], v[202:205], v[76:79]
	s_add_u32 s26, s67, s58
	s_addc_u32 s27, s68, 0
	s_mov_b32 m0, s48
	s_nop 0
	global_load_lds_dwordx4 v138, s[26:27]
	s_mov_b32 m0, s52
	s_nop 0
	global_load_lds_dwordx4 v140, s[26:27]
	s_waitcnt lgkmcnt(3)
	v_mfma_f32_16x16x32_bf16 v[120:123], v[206:209], v[174:177], v[120:123]
	s_waitcnt lgkmcnt(2)
	v_mfma_f32_16x16x32_bf16 v[116:119], v[214:217], v[174:177], v[116:119]
	v_mfma_f32_16x16x32_bf16 v[104:107], v[206:209], v[182:185], v[104:107]
	v_mfma_f32_16x16x32_bf16 v[100:103], v[214:217], v[182:185], v[100:103]
	v_mfma_f32_16x16x32_bf16 v[88:91], v[206:209], v[190:193], v[88:91]
	v_mfma_f32_16x16x32_bf16 v[84:87], v[214:217], v[190:193], v[84:87]
	v_mfma_f32_16x16x32_bf16 v[72:75], v[206:209], v[198:201], v[72:75]
	v_mfma_f32_16x16x32_bf16 v[68:71], v[214:217], v[198:201], v[68:71]
	s_waitcnt lgkmcnt(1)
	v_mfma_f32_16x16x32_bf16 v[120:123], v[210:213], v[178:181], v[120:123]
	s_waitcnt lgkmcnt(0)
	v_mfma_f32_16x16x32_bf16 v[116:119], v[218:221], v[178:181], v[116:119]
	v_mfma_f32_16x16x32_bf16 v[104:107], v[210:213], v[186:189], v[104:107]
	v_mfma_f32_16x16x32_bf16 v[100:103], v[218:221], v[186:189], v[100:103]
	v_mfma_f32_16x16x32_bf16 v[88:91], v[210:213], v[194:197], v[88:91]
	v_mfma_f32_16x16x32_bf16 v[84:87], v[218:221], v[194:197], v[84:87]
	v_mfma_f32_16x16x32_bf16 v[72:75], v[210:213], v[202:205], v[72:75]
	v_mfma_f32_16x16x32_bf16 v[68:71], v[218:221], v[202:205], v[68:71]
	s_waitcnt vmcnt(4) lgkmcnt(0)
	s_barrier
	ds_read_b128 v[174:177], v154 offset:16384
	ds_read_b128 v[182:185], v154 offset:18432
	ds_read_b128 v[190:193], v154 offset:20480
	ds_read_b128 v[198:201], v154 offset:22528
	ds_read_b128 v[178:181], v154 offset:17408
	ds_read_b128 v[186:189], v154 offset:19456
	ds_read_b128 v[194:197], v154 offset:21504
	ds_read_b128 v[202:205], v154 offset:23552
	s_add_u32 s26, s65, s58
	s_addc_u32 s27, s66, 0
	s_mov_b32 m0, s49
	s_nop 0
	global_load_lds_dwordx4 v139, s[26:27]
	s_mov_b32 m0, s53
	s_nop 0
	global_load_lds_dwordx4 v152, s[26:27]
	s_waitcnt lgkmcnt(7)
	v_mfma_f32_16x16x32_bf16 v[64:67], v[146:149], v[174:177], v[64:67]
	v_mfma_f32_16x16x32_bf16 v[60:63], v[160:163], v[174:177], v[60:63]
	s_waitcnt lgkmcnt(6)
	v_mfma_f32_16x16x32_bf16 v[48:51], v[146:149], v[182:185], v[48:51]
	v_mfma_f32_16x16x32_bf16 v[44:47], v[160:163], v[182:185], v[44:47]
	s_waitcnt lgkmcnt(5)
	v_mfma_f32_16x16x32_bf16 v[32:35], v[146:149], v[190:193], v[32:35]
	v_mfma_f32_16x16x32_bf16 v[28:31], v[160:163], v[190:193], v[28:31]
	s_waitcnt lgkmcnt(4)
	v_mfma_f32_16x16x32_bf16 v[16:19], v[146:149], v[198:201], v[16:19]
	v_mfma_f32_16x16x32_bf16 v[12:15], v[160:163], v[198:201], v[12:15]
	s_waitcnt lgkmcnt(3)
	v_mfma_f32_16x16x32_bf16 v[64:67], v[156:159], v[178:181], v[64:67]
	v_mfma_f32_16x16x32_bf16 v[60:63], v[170:173], v[178:181], v[60:63]
	s_waitcnt lgkmcnt(2)
	v_mfma_f32_16x16x32_bf16 v[48:51], v[156:159], v[186:189], v[48:51]
	v_mfma_f32_16x16x32_bf16 v[44:47], v[170:173], v[186:189], v[44:47]
	s_waitcnt lgkmcnt(1)
	v_mfma_f32_16x16x32_bf16 v[32:35], v[156:159], v[194:197], v[32:35]
	v_mfma_f32_16x16x32_bf16 v[28:31], v[170:173], v[194:197], v[28:31]
	s_waitcnt lgkmcnt(0)
	v_mfma_f32_16x16x32_bf16 v[16:19], v[156:159], v[202:205], v[16:19]
	v_mfma_f32_16x16x32_bf16 v[12:15], v[170:173], v[202:205], v[12:15]
	s_add_u32 s26, s63, s58
	s_addc_u32 s27, s64, 0
	s_mov_b32 m0, s50
	s_nop 0
	global_load_lds_dwordx4 v138, s[26:27]
	s_mov_b32 m0, s54
	s_nop 0
	global_load_lds_dwordx4 v140, s[26:27]
	v_mfma_f32_16x16x32_bf16 v[56:59], v[206:209], v[174:177], v[56:59]
	s_add_u32 s26, s61, s58
	s_addc_u32 s27, s62, 0
	s_add_u32 s71, s59, s58
	v_mfma_f32_16x16x32_bf16 v[52:55], v[214:217], v[174:177], v[52:55]
	s_addc_u32 s72, s60, 0
	v_mfma_f32_16x16x32_bf16 v[40:43], v[206:209], v[182:185], v[40:43]
	v_mfma_f32_16x16x32_bf16 v[36:39], v[214:217], v[182:185], v[36:39]
	v_mfma_f32_16x16x32_bf16 v[24:27], v[206:209], v[190:193], v[24:27]
	v_mfma_f32_16x16x32_bf16 v[20:23], v[214:217], v[190:193], v[20:23]
	v_mfma_f32_16x16x32_bf16 v[8:11], v[206:209], v[198:201], v[8:11]
	v_mfma_f32_16x16x32_bf16 v[4:7], v[214:217], v[198:201], v[4:7]
	v_mfma_f32_16x16x32_bf16 v[56:59], v[210:213], v[178:181], v[56:59]
	v_mfma_f32_16x16x32_bf16 v[52:55], v[218:221], v[178:181], v[52:55]
	v_mfma_f32_16x16x32_bf16 v[40:43], v[210:213], v[186:189], v[40:43]
	v_mfma_f32_16x16x32_bf16 v[36:39], v[218:221], v[186:189], v[36:39]
	v_mfma_f32_16x16x32_bf16 v[24:27], v[210:213], v[194:197], v[24:27]
	v_mfma_f32_16x16x32_bf16 v[20:23], v[218:221], v[194:197], v[20:23]
	v_mfma_f32_16x16x32_bf16 v[8:11], v[210:213], v[202:205], v[8:11]
	v_mfma_f32_16x16x32_bf16 v[4:7], v[218:221], v[202:205], v[4:7]
	s_waitcnt vmcnt(2) lgkmcnt(0)
	s_barrier
; template <class Epi, class Sched>
; __device__ __forceinline__ void gemm_simple(PG8_LAS unsigned char* lds, const Gemm g, const Sched& S, const Epi& E, int wave_s) {
;     ...
;             const bool last = (t == nt - 2);
;             PG8_TILE(0, cA + (size_t)(t + 1) * kstep, cB + (size_t)(t + 1) * kstep, true);
;             const char* a2 = last ? nA : cA + (size_t)(t + 2) * kstep; const char* b2 = last ? nB : cB + (size_t)(t + 2) * kstep;
;             PG8_TILE(1, a2, b2, (!last || has_next));
	ds_read_b128 v[146:149], v134
	ds_read_b128 v[174:177], v154 offset:32768
	ds_read_b128 v[160:163], v134 offset:2048
	ds_read_b128 v[182:185], v154 offset:34816
	ds_read_b128 v[190:193], v154 offset:36864
	ds_read_b128 v[198:201], v154 offset:38912
	ds_read_b128 v[156:159], v134 offset:1024
	ds_read_b128 v[178:181], v154 offset:33792
	ds_read_b128 v[170:173], v134 offset:3072
	ds_read_b128 v[186:189], v154 offset:35840
	ds_read_b128 v[194:197], v154 offset:37888
	ds_read_b128 v[202:205], v154 offset:39936
	ds_read_b128 v[206:209], v135
	ds_read_b128 v[214:217], v135 offset:2048
	ds_read_b128 v[210:213], v135 offset:1024
	ds_read_b128 v[218:221], v135 offset:3072
	s_cmp_eq_u32 s58, s24
	s_cselect_b32 s27, s11, s27
	s_cselect_b32 s26, s21, s26
	s_cselect_b32 s73, s5, s72
	s_cselect_b32 s72, s23, s71
	s_mov_b32 m0, s40
	s_nop 0
	global_load_lds_dwordx4 v139, s[72:73]
	s_mov_b32 m0, s41
	s_nop 0
	global_load_lds_dwordx4 v152, s[72:73]
	s_waitcnt lgkmcnt(14)
	v_mfma_f32_16x16x32_bf16 v[128:131], v[146:149], v[174:177], v[128:131]
	s_waitcnt lgkmcnt(13)
	v_mfma_f32_16x16x32_bf16 v[124:127], v[160:163], v[174:177], v[124:127]
	s_waitcnt lgkmcnt(12)
	v_mfma_f32_16x16x32_bf16 v[112:115], v[146:149], v[182:185], v[112:115]
	v_mfma_f32_16x16x32_bf16 v[108:111], v[160:163], v[182:185], v[108:111]
	s_waitcnt lgkmcnt(11)
	v_mfma_f32_16x16x32_bf16 v[96:99], v[146:149], v[190:193], v[96:99]
	v_mfma_f32_16x16x32_bf16 v[92:95], v[160:163], v[190:193], v[92:95]
	s_waitcnt lgkmcnt(10)
	v_mfma_f32_16x16x32_bf16 v[80:83], v[146:149], v[198:201], v[80:83]
	v_mfma_f32_16x16x32_bf16 v[76:79], v[160:163], v[198:201], v[76:79]
	s_waitcnt lgkmcnt(8)
	v_mfma_f32_16x16x32_bf16 v[128:131], v[156:159], v[178:181], v[128:131]
	s_waitcnt lgkmcnt(7)
	v_mfma_f32_16x16x32_bf16 v[124:127], v[170:173], v[178:181], v[124:127]
	s_waitcnt lgkmcnt(6)
	v_mfma_f32_16x16x32_bf16 v[112:115], v[156:159], v[186:189], v[112:115]
	v_mfma_f32_16x16x32_bf16 v[108:111], v[170:173], v[186:189], v[108:111]
	s_waitcnt lgkmcnt(5)
	v_mfma_f32_16x16x32_bf16 v[96:99], v[156:159], v[194:197], v[96:99]
	v_mfma_f32_16x16x32_bf16 v[92:95], v[170:173], v[194:197], v[92:95]
	s_waitcnt lgkmcnt(4)
	v_mfma_f32_16x16x32_bf16 v[80:83], v[156:159], v[202:205], v[80:83]
	v_mfma_f32_16x16x32_bf16 v[76:79], v[170:173], v[202:205], v[76:79]
	s_mov_b32 m0, s39
	s_nop 0
	global_load_lds_dwordx4 v138, s[26:27]
	s_mov_b32 m0, s42
	s_nop 0
	global_load_lds_dwordx4 v140, s[26:27]
	s_waitcnt lgkmcnt(3)
	v_mfma_f32_16x16x32_bf16 v[120:123], v[206:209], v[174:177], v[120:123]
	s_waitcnt lgkmcnt(2)
	v_mfma_f32_16x16x32_bf16 v[116:119], v[214:217], v[174:177], v[116:119]
	v_mfma_f32_16x16x32_bf16 v[104:107], v[206:209], v[182:185], v[104:107]
	v_mfma_f32_16x16x32_bf16 v[100:103], v[214:217], v[182:185], v[100:103]
	v_mfma_f32_16x16x32_bf16 v[88:91], v[206:209], v[190:193], v[88:91]
	v_mfma_f32_16x16x32_bf16 v[84:87], v[214:217], v[190:193], v[84:87]
	v_mfma_f32_16x16x32_bf16 v[72:75], v[206:209], v[198:201], v[72:75]
	v_mfma_f32_16x16x32_bf16 v[68:71], v[214:217], v[198:201], v[68:71]
	s_waitcnt lgkmcnt(1)
	v_mfma_f32_16x16x32_bf16 v[120:123], v[210:213], v[178:181], v[120:123]
	s_waitcnt lgkmcnt(0)
	v_mfma_f32_16x16x32_bf16 v[116:119], v[218:221], v[178:181], v[116:119]
	v_mfma_f32_16x16x32_bf16 v[104:107], v[210:213], v[186:189], v[104:107]
	v_mfma_f32_16x16x32_bf16 v[100:103], v[218:221], v[186:189], v[100:103]
	v_mfma_f32_16x16x32_bf16 v[88:91], v[210:213], v[194:197], v[88:91]
	v_mfma_f32_16x16x32_bf16 v[84:87], v[218:221], v[194:197], v[84:87]
	v_mfma_f32_16x16x32_bf16 v[72:75], v[210:213], v[202:205], v[72:75]
	v_mfma_f32_16x16x32_bf16 v[68:71], v[218:221], v[202:205], v[68:71]
	s_waitcnt vmcnt(4) lgkmcnt(0)
	s_barrier
	ds_read_b128 v[174:177], v154 offset:49152
	ds_read_b128 v[182:185], v154 offset:51200
	ds_read_b128 v[190:193], v154 offset:53248
	ds_read_b128 v[198:201], v154 offset:55296
	ds_read_b128 v[178:181], v154 offset:50176
	ds_read_b128 v[186:189], v154 offset:52224
	ds_read_b128 v[194:197], v154 offset:54272
	ds_read_b128 v[202:205], v154 offset:56320
	s_add_u32 s72, s72, 0x80000
	s_addc_u32 s73, s73, 0
	s_mov_b32 m0, s43
	s_nop 0
	global_load_lds_dwordx4 v139, s[72:73]
	s_mov_b32 m0, s44
	s_nop 0
	global_load_lds_dwordx4 v152, s[72:73]
	s_waitcnt lgkmcnt(7)
	v_mfma_f32_16x16x32_bf16 v[64:67], v[146:149], v[174:177], v[64:67]
	v_mfma_f32_16x16x32_bf16 v[60:63], v[160:163], v[174:177], v[60:63]
	s_waitcnt lgkmcnt(6)
	v_mfma_f32_16x16x32_bf16 v[48:51], v[146:149], v[182:185], v[48:51]
	v_mfma_f32_16x16x32_bf16 v[44:47], v[160:163], v[182:185], v[44:47]
	s_waitcnt lgkmcnt(5)
	v_mfma_f32_16x16x32_bf16 v[32:35], v[146:149], v[190:193], v[32:35]
	v_mfma_f32_16x16x32_bf16 v[28:31], v[160:163], v[190:193], v[28:31]
	s_waitcnt lgkmcnt(4)
	v_mfma_f32_16x16x32_bf16 v[16:19], v[146:149], v[198:201], v[16:19]
	v_mfma_f32_16x16x32_bf16 v[12:15], v[160:163], v[198:201], v[12:15]
	s_waitcnt lgkmcnt(3)
	v_mfma_f32_16x16x32_bf16 v[64:67], v[156:159], v[178:181], v[64:67]
	v_mfma_f32_16x16x32_bf16 v[60:63], v[170:173], v[178:181], v[60:63]
	s_waitcnt lgkmcnt(2)
	v_mfma_f32_16x16x32_bf16 v[48:51], v[156:159], v[186:189], v[48:51]
	v_mfma_f32_16x16x32_bf16 v[44:47], v[170:173], v[186:189], v[44:47]
	s_waitcnt lgkmcnt(1)
	v_mfma_f32_16x16x32_bf16 v[32:35], v[156:159], v[194:197], v[32:35]
	v_mfma_f32_16x16x32_bf16 v[28:31], v[170:173], v[194:197], v[28:31]
	s_waitcnt lgkmcnt(0)
; __device__ __forceinline__ unsigned cvt_pk_bf16(float lo, float hi) { unsigned r; asm volatile("v_cvt_pk_bf16_f32 %0, %1, %2" : "=v"(r) : "v"(lo), "v"(hi)); return r; }
; #define LAS __attribute__((address_space(3)))
; __device__ __forceinline__ float bflo(unsigned w) { return __uint_as_float(w << 16); }
; __device__ __forceinline__ float bfhi(unsigned w) { return __uint_as_float(w & 0xffff0000u); }
;     __device__ __forceinline__ void operator()(const f32x4 (&acc)[2][2][4][2], const Unit& u, int wr, int wc, int fr, int fq, const LAS float* rt) const {
;         const int row0 = u.pm * 256 + wr * 64 + fr, col0 = u.pn * 256 + wc * 32 + 8 * fq, lane = fq * 16 + fr;
; #pragma unroll
;         for (int ai = 0; ai < 2; ++ai)
; #pragma unroll
;             for (int m = 0; m < 4; ++m) { const size_t row = (size_t)(row0 + ai * 128 + m * 16); const float rs = (MODE == 1) ? rt[ai * 128 + wr * 64 + m * 16 + fr] : 1.0f; float ss = 0.f;
; #pragma unroll
;                 for (int bj = 0; bj < 2; ++bj) { const size_t o = row * DM + col0 + bj * 128; const u32x4 xv = *(const u32x4*)(xin + o);
;                     f32x4 v0 = acc[ai][bj][m][0], v1 = acc[ai][bj][m][1];
;                     if (MODE == 1) { const u32x4 p = *(const u32x4*)(pe + o);
;                         v0[0] = sigmoidf_(v0[0] * rs) * bflo(p.x); v0[1] = sigmoidf_(v0[1] * rs) * bfhi(p.x); v0[2] = sigmoidf_(v0[2] * rs) * bflo(p.y); v0[3] = sigmoidf_(v0[3] * rs) * bfhi(p.y);
;                         v1[0] = sigmoidf_(v1[0] * rs) * bflo(p.z); v1[1] = sigmoidf_(v1[1] * rs) * bfhi(p.z); v1[2] = sigmoidf_(v1[2] * rs) * bflo(p.w); v1[3] = sigmoidf_(v1[3] * rs) * bfhi(p.w); }
;                     v0[0] += bflo(xv.x); v0[1] += bfhi(xv.x); v0[2] += bflo(xv.y); v0[3] += bfhi(xv.y); v1[0] += bflo(xv.z); v1[1] += bfhi(xv.z); v1[2] += bflo(xv.w); v1[3] += bfhi(xv.w);
;                     ss += (v0[0] * v0[0] + v0[1] * v0[1]) + (v0[2] * v0[2] + v0[3] * v0[3]) + (v1[0] * v1[0] + v1[1] * v1[1]) + (v1[2] * v1[2] + v1[3] * v1[3]);
;                     u32x4 w; w.x = cvt_pk_bf16(v0[0], v0[1]); w.y = cvt_pk_bf16(v0[2], v0[3]); w.z = cvt_pk_bf16(v1[0], v1[1]); w.w = cvt_pk_bf16(v1[2], v1[3]);
;                     __builtin_nontemporal_store(w, (u32x4*)(xout + o)); }
;                 ss += shx(ss, 16, lane); ss += shx(ss, 32, lane);
;                 if (fq == 0) ssq_out[row * 32 + u.pn * 4 + wc] = ss; }
	v_mfma_f32_16x16x32_bf16 v[16:19], v[156:159], v[202:205], v[16:19]
	v_mfma_f32_16x16x32_bf16 v[12:15], v[170:173], v[202:205], v[12:15]
	s_add_u32 s26, s26, 0x80000
	s_addc_u32 s27, s27, 0
	s_mov_b32 m0, s45
	s_nop 0
	global_load_lds_dwordx4 v138, s[26:27]
	s_mov_b32 m0, s46
	s_nop 0
	global_load_lds_dwordx4 v140, s[26:27]
	s_add_i32 s35, s35, 2
	s_add_u32 s24, s24, 0xffffff00
	s_addc_u32 s25, s25, -1
	s_add_u32 s59, s59, 0x100
	s_addc_u32 s60, s60, 0
	s_add_u32 s61, s61, 0x100
	s_addc_u32 s62, s62, 0
	s_add_u32 s63, s63, 0x100
	v_mfma_f32_16x16x32_bf16 v[56:59], v[206:209], v[174:177], v[56:59]
	s_addc_u32 s64, s64, 0
	s_add_u32 s65, s65, 0x100
	s_addc_u32 s66, s66, 0
	v_mfma_f32_16x16x32_bf16 v[52:55], v[214:217], v[174:177], v[52:55]
	s_add_u32 s67, s67, 0x100
	s_addc_u32 s68, s68, 0
	s_add_u32 s69, s69, 0x100
	v_mfma_f32_16x16x32_bf16 v[40:43], v[206:209], v[182:185], v[40:43]
	s_addc_u32 s70, s70, 0
	s_cmp_lt_u32 s35, 30
	v_mfma_f32_16x16x32_bf16 v[36:39], v[214:217], v[182:185], v[36:39]
	v_mfma_f32_16x16x32_bf16 v[24:27], v[206:209], v[190:193], v[24:27]
	v_mfma_f32_16x16x32_bf16 v[20:23], v[214:217], v[190:193], v[20:23]
	v_mfma_f32_16x16x32_bf16 v[8:11], v[206:209], v[198:201], v[8:11]
	v_mfma_f32_16x16x32_bf16 v[4:7], v[214:217], v[198:201], v[4:7]
	v_mfma_f32_16x16x32_bf16 v[56:59], v[210:213], v[178:181], v[56:59]
	v_mfma_f32_16x16x32_bf16 v[52:55], v[218:221], v[178:181], v[52:55]
	v_mfma_f32_16x16x32_bf16 v[40:43], v[210:213], v[186:189], v[40:43]
	v_mfma_f32_16x16x32_bf16 v[36:39], v[218:221], v[186:189], v[36:39]
	v_mfma_f32_16x16x32_bf16 v[24:27], v[210:213], v[194:197], v[24:27]
	v_mfma_f32_16x16x32_bf16 v[20:23], v[218:221], v[194:197], v[20:23]
	v_mfma_f32_16x16x32_bf16 v[8:11], v[210:213], v[202:205], v[8:11]
	v_mfma_f32_16x16x32_bf16 v[4:7], v[218:221], v[202:205], v[4:7]
	s_cbranch_scc1 .LBB0_119
	v_mov_b32_e32 v132, v141
	s_lshl_b32 s5, s22, 8
	v_mbcnt_lo_u32_b32 v132, -1, v132
	v_mbcnt_hi_u32_b32 v135, -1, v132
	v_and_b32_e32 v136, 15, v135
	s_add_i32 s5, s5, s37
	v_or_b32_e32 v134, s5, v136
	s_lshl_b32 s5, s20, 8
	v_ashrrev_i32_e32 v137, 4, v135
	s_or_b32 s5, s5, s38
	v_lshl_add_u32 v132, v137, 3, s5
	v_lshlrev_b32_e32 v137, 6, v137
	v_lshlrev_b32_e32 v136, 2, v136
	s_movk_i32 s5, 0x80
	v_cmp_gt_u32_e32 vcc, 16, v135
	v_ashrrev_i32_e32 v135, 31, v134
	v_bitop3_b32 v156, v137, 64, v136 bitop3:0x36
	v_bitop3_b32 v155, v137, s5, v136 bitop3:0x36
	v_lshlrev_b64 v[136:137], 12, v[134:135]
	v_ashrrev_i32_e32 v133, 31, v132
	v_lshl_add_u64 v[136:137], s[94:95], 0, v[136:137]
	v_lshl_add_u64 v[136:137], v[132:133], 1, v[136:137]
	v_lshlrev_b32_e32 v236, 12, v134
	v_lshl_add_u32 v236, v132, 1, v236
	global_load_dwordx4 v[172:175], v236, s[94:95]
	global_load_dwordx4 v[176:179], v236, s[94:95] offset:256
	v_add_u32_e32 v237, 0x10000, v236
	global_load_dwordx4 v[180:183], v237, s[94:95]
	global_load_dwordx4 v[184:187], v237, s[94:95] offset:256
	v_add_u32_e32 v237, 0x20000, v236
	global_load_dwordx4 v[188:191], v237, s[94:95]
	global_load_dwordx4 v[192:195], v237, s[94:95] offset:256
	v_add_u32_e32 v237, 0x30000, v236
	global_load_dwordx4 v[196:199], v237, s[94:95]
	global_load_dwordx4 v[200:203], v237, s[94:95] offset:256
	v_add_u32_e32 v237, 0x80000, v236
	global_load_dwordx4 v[204:207], v237, s[94:95]
	global_load_dwordx4 v[208:211], v237, s[94:95] offset:256
	v_add_u32_e32 v237, 0x90000, v236
	global_load_dwordx4 v[212:215], v237, s[94:95]
	global_load_dwordx4 v[216:219], v237, s[94:95] offset:256
	v_add_u32_e32 v237, 0xa0000, v236
	global_load_dwordx4 v[220:223], v237, s[94:95]
	global_load_dwordx4 v[224:227], v237, s[94:95] offset:256
	v_add_u32_e32 v237, 0xb0000, v236
	global_load_dwordx4 v[228:231], v237, s[94:95]
	global_load_dwordx4 v[232:235], v237, s[94:95] offset:256
	s_lshl_b32 s20, s20, 2
	s_ashr_i32 s21, s20, 31
	s_waitcnt vmcnt(15)
	s_nop 1
	v_mov_b64_e32 v[146:147], v[172:173]
	v_mov_b64_e32 v[148:149], v[174:175]
	v_lshlrev_b32_e32 v142, 16, v146
	v_add_f32_e32 v128, v128, v142
	v_and_b32_e32 v142, 0xffff0000, v146
	v_add_f32_e32 v129, v129, v142
	v_lshlrev_b32_e32 v142, 16, v147
	v_add_f32_e32 v130, v130, v142
	v_and_b32_e32 v142, 0xffff0000, v147
	v_add_f32_e32 v131, v131, v142
	v_lshlrev_b32_e32 v142, 16, v148
	v_add_f32_e32 v142, v124, v142
	v_and_b32_e32 v124, 0xffff0000, v148
	v_add_f32_e32 v143, v125, v124
	v_lshlrev_b32_e32 v124, 16, v149
	v_add_f32_e32 v144, v126, v124
	v_and_b32_e32 v124, 0xffff0000, v149
	v_add_f32_e32 v127, v127, v124
	v_mul_f32_e32 v124, v129, v129
	v_mul_f32_e32 v125, v131, v131
	v_fmac_f32_e32 v124, v128, v128
	v_fmac_f32_e32 v125, v130, v130
	v_add_f32_e32 v124, v124, v125
	v_mul_f32_e32 v125, v143, v143
	v_fmac_f32_e32 v125, v142, v142
	v_add_f32_e32 v124, v125, v124
	v_mul_f32_e32 v125, v127, v127
	v_fmac_f32_e32 v125, v144, v144
	v_add_f32_e32 v145, v125, v124
	v_cvt_pk_bf16_f32 v124, v128, v129
	v_cvt_pk_bf16_f32 v125, v130, v131
	v_cvt_pk_bf16_f32 v126, v142, v143
	v_cvt_pk_bf16_f32 v127, v144, v127
	global_store_dwordx4 v[136:137], v[124:127], off nt
	s_waitcnt vmcnt(15)
	s_nop 1
	v_mov_b64_e32 v[124:125], v[176:177]
	v_mov_b64_e32 v[126:127], v[178:179]
	v_lshlrev_b32_e32 v128, 16, v124
	v_and_b32_e32 v124, 0xffff0000, v124
	v_add_f32_e32 v121, v121, v124
	v_lshlrev_b32_e32 v124, 16, v125
	v_add_f32_e32 v122, v122, v124
	v_and_b32_e32 v124, 0xffff0000, v125
	v_add_f32_e32 v123, v123, v124
	v_lshlrev_b32_e32 v124, 16, v126
	v_add_f32_e32 v124, v116, v124
	v_and_b32_e32 v116, 0xffff0000, v126
	v_add_f32_e32 v125, v117, v116
	v_lshlrev_b32_e32 v116, 16, v127
	v_add_f32_e32 v126, v118, v116
	v_and_b32_e32 v116, 0xffff0000, v127
	v_add_f32_e32 v120, v120, v128
	v_add_f32_e32 v119, v119, v116
	v_mul_f32_e32 v116, v121, v121
	v_mul_f32_e32 v117, v123, v123
	v_fmac_f32_e32 v116, v120, v120
	v_fmac_f32_e32 v117, v122, v122
	v_add_f32_e32 v116, v116, v117
	v_mul_f32_e32 v117, v125, v125
	v_fmac_f32_e32 v117, v124, v124
	v_add_f32_e32 v116, v117, v116
	v_mul_f32_e32 v117, v119, v119
	v_fmac_f32_e32 v117, v126, v126
	v_add_f32_e32 v116, v117, v116
	v_add_f32_e32 v127, v145, v116
	v_cvt_pk_bf16_f32 v116, v120, v121
	v_cvt_pk_bf16_f32 v117, v122, v123
	v_cvt_pk_bf16_f32 v118, v124, v125
	v_cvt_pk_bf16_f32 v119, v126, v119
	global_store_dwordx4 v[136:137], v[116:119], off offset:256 nt
	ds_bpermute_b32 v116, v156, v127
	s_waitcnt lgkmcnt(0)
	v_add_f32_e32 v116, v127, v116
	ds_bpermute_b32 v117, v155, v116
	s_and_saveexec_b64 s[22:23], vcc
	s_cbranch_execz .LBB0_122
	v_lshlrev_b64 v[118:119], 7, v[134:135]
	v_lshl_add_u64 v[118:119], s[0:1], 0, v[118:119]
	v_lshl_add_u64 v[118:119], s[20:21], 2, v[118:119]
	s_lshl_b32 s84, s36, 2
	v_lshl_add_u64 v[118:119], v[118:119], 0, s[84:85]
	s_waitcnt lgkmcnt(0)
	v_add_f32_e32 v116, v116, v117
	global_store_dword v[118:119], v116, off

; #define PG8_STAGE4(b, pa, pb) do { PG8_STAGE(PG8_SB(b, 0), (pb), voffB); PG8_STAGE(PG8_SA(b, 0), (pa), voffA); PG8_STAGE(PG8_SB(b, 1), (pb) + hstep, voffB); PG8_STAGE(PG8_SA(b, 1), (pa) + hstep, voffA); } while (0)
; #define PG8_SYNC() do { asm volatile("s_waitcnt vmcnt(0) lgkmcnt(0)" ::: "memory"); __builtin_amdgcn_s_barrier(); asm volatile("" ::: "memory"); } while (0)
; template <class Epi, class Sched>
; __device__ __forceinline__ void gemm_simple(PG8_LAS unsigned char* lds, const Gemm g, const Sched& S, const Epi& E, int wave_s) {
;     ...
;     for (int i = 0; i < 2; ++i) { int R, C; stage_rc(tid * 16 + i * 8192, R, C); const int Rb = Epi::PERM ? ((R & ~31) + perm32(R & 31)) : R;
;         voffA[i] = (unsigned)(R * K + C) * 2u; voffB[i] = (unsigned)(Rb * K + C) * 2u; }
;     const size_t kstep = (size_t)(BK * 2), hstep = (size_t)HALF * K * 2, tstep = 2 * hstep;
;     const unsigned ldsw = (unsigned)wid * 1024u; const unsigned lds_u = (unsigned)(__UINTPTR_TYPE__)lds;
;     const int aoff = lds_byte(wr * 64 + fr, fq * 8), boff = lds_byte(wc * 32 + fr, fq * 8);
;     ...
;     const char* cA = (const char*)g.A + (size_t)cur.pm * tstep; const char* cB = (const char*)g.Bt + (size_t)cur.pn * tstep;
;     PG8_SYNC();
;     PG8_STAGE4(0, cA, cB);
.LBB0_142:
	v_ashrrev_i32_e32 v4, 31, v2
	v_lshrrev_b32_e32 v4, 26, v4
	v_lshlrev_b32_e32 v3, 4, v2
	v_add_u32_e32 v4, v2, v4
	v_bfe_i32 v2, v2, 27, 1
	v_lshrrev_b32_e32 v2, 22, v2
	v_add_u32_e32 v2, v3, v2
	v_and_b32_e32 v2, 0xfffffc00, v2
	v_sub_u32_e32 v2, v3, v2
	s_waitcnt lgkmcnt(0)
	v_lshrrev_b32_e32 v5, 4, v2
	v_readlane_b32 s4, v255, 0
	v_bitop3_b32 v2, v5, v2, 32 bitop3:0x6c
	v_readlane_b32 s5, v255, 1
	v_ashrrev_i32_e32 v6, 31, v2
	s_ashr_i32 s8, s8, 3
	s_lshl_b64 s[4:5], s[4:5], 24
	v_ashrrev_i32_e32 v4, 6, v4
	v_lshrrev_b32_e32 v6, 26, v6
	s_add_u32 s4, s90, s4
	v_lshlrev_b32_e32 v5, 3, v4
	v_add_u32_e32 v6, v2, v6
	s_addc_u32 s5, s91, s5
	v_and_b32_e32 v5, -16, v5
	v_ashrrev_i32_e32 v7, 6, v6
	v_and_b32_e32 v6, 0xc0, v6
	s_add_u32 s36, s4, 0x3c780000
	v_add_u32_e32 v5, v7, v5
	v_sub_u32_e32 v2, v2, v6
	s_addc_u32 s37, s5, 0
	v_lshlrev_b32_e32 v4, 5, v4
	v_ashrrev_i16_sdwa v2, v166, sext(v2) dst_sel:DWORD dst_unused:UNUSED_PAD src0_sel:DWORD src1_sel:BYTE_0
	v_lshlrev_b32_e32 v6, 1, v5
	v_lshrrev_b32_e32 v8, 2, v5
	v_and_b32_e32 v7, 3, v7
	s_mov_b32 s5, 0x7fffe0
	v_and_b32_e32 v4, 32, v4
	v_bfe_i32 v2, v2, 0, 16
	v_and_b32_e32 v6, 24, v6
	v_and_b32_e32 v8, 4, v8
	v_and_or_b32 v7, v5, s5, v7
	v_or3_b32 v6, v7, v8, v6
	v_add_lshl_u32 v2, v4, v2, 1
	v_lshl_add_u32 v134, v5, 9, v2
	v_lshl_add_u32 v135, v6, 9, v2
	v_add_u32_e32 v2, 0x2000, v3
	v_ashrrev_i32_e32 v3, 31, v2
	v_lshrrev_b32_e32 v3, 22, v3
	v_add_u32_e32 v3, v2, v3
	v_ashrrev_i32_e32 v3, 10, v3
	v_mul_i32_i24_e32 v4, 0x400, v3
	v_sub_u32_e32 v2, v2, v4
	v_lshrrev_b32_e32 v4, 4, v2
	v_bitop3_b32 v2, v4, v2, 32 bitop3:0x6c
	v_ashrrev_i32_e32 v5, 31, v2
	v_lshrrev_b32_e32 v5, 26, v5
	v_lshlrev_b32_e32 v4, 3, v3
	v_add_u32_e32 v5, v2, v5
	v_and_b32_e32 v4, -16, v4
	v_ashrrev_i32_e32 v6, 6, v5
	v_and_b32_e32 v5, 0xc0, v5
	v_readlane_b32 s4, v254, 57
	v_add_u32_e32 v4, v6, v4
	v_sub_u32_e32 v2, v2, v5
	s_add_u32 s38, s4, 0x8200000
	v_readlane_b32 s4, v254, 58
	v_lshlrev_b32_e32 v3, 5, v3
	v_ashrrev_i16_sdwa v2, v166, sext(v2) dst_sel:DWORD dst_unused:UNUSED_PAD src0_sel:DWORD src1_sel:BYTE_0
	v_lshlrev_b32_e32 v5, 1, v4
	v_lshrrev_b32_e32 v7, 2, v4
	v_and_b32_e32 v6, 3, v6
	s_addc_u32 s39, s4, 0
	s_ashr_i32 s4, s6, 6
	v_and_b32_e32 v3, 32, v3
	v_bfe_i32 v2, v2, 0, 16
	v_and_b32_e32 v5, 24, v5
	v_and_b32_e32 v7, 4, v7
	v_and_or_b32 v6, v4, s5, v6
	v_or3_b32 v5, v6, v7, v5
	v_add_lshl_u32 v2, v3, v2, 1
	s_lshl_b32 s9, s4, 10
	s_lshl_b32 s4, s4, 5
	v_lshl_add_u32 v136, v4, 9, v2
	v_lshl_add_u32 v137, v5, 9, v2
	s_ashr_i32 s40, s6, 2
	v_and_b32_e32 v2, 48, v1
	v_lshlrev_b32_e32 v3, 6, v1
	s_movk_i32 s6, 0x3c0
	v_lshlrev_b32_e32 v1, 2, v1
	s_and_b32 s41, s4, 0x60
	s_andn2_b32 s40, s40, 63
	v_and_or_b32 v2, v3, s6, v2
	v_and_b32_e32 v1, 32, v1
	s_lshl_b32 s4, s41, 7
	s_lshl_b32 s5, s40, 7
	v_bitop3_b32 v5, s4, v2, v1 bitop3:0xf6
	s_add_i32 s4, s7, s8
	v_bitop3_b32 v4, v2, s5, v1 bitop3:0xde
	s_ashr_i32 s5, s4, 31
	s_lshr_b32 s5, s5, 27
	s_add_i32 s5, s4, s5
	s_ashr_i32 s6, s5, 5
	s_and_b32 s5, s5, 0xffe0
	s_sub_i32 s5, s4, s5
	s_bfe_i32 s4, s5, 0x80000
	s_bfe_u32 s4, s4, 0x2000d
	s_add_i32 s7, s5, s4
	s_bfe_i32 s4, s7, 0x80000
	s_and_b32 s7, s7, 0xfc
	s_sub_i32 s5, s5, s7
	s_lshl_b32 s6, s6, 2
	s_sext_i32_i16 s8, s4
	s_sext_i32_i8 s5, s5
	s_lshr_b32 s4, s8, 2
	s_add_i32 s10, s6, s5
	s_ashr_i32 s11, s10, 31
	s_bfe_i64 s[4:5], s[4:5], 0x100000
	s_ashr_i32 s59, s8, 2
	s_lshl_b64 s[6:7], s[10:11], 17
	s_lshl_b64 s[4:5], s[4:5], 17
	s_add_u32 s16, s38, s4
	s_addc_u32 s17, s39, s5
	s_waitcnt vmcnt(0) lgkmcnt(0)
	s_barrier
	s_add_i32 s11, s9, 0
	s_add_i32 s42, s11, 0x10000
	s_mov_b32 m0, s42
	s_nop 0
	global_load_lds_dwordx4 v135, s[16:17]
	s_add_i32 s43, s11, 0x12000
	s_mov_b32 m0, s43
	s_nop 0
	global_load_lds_dwordx4 v137, s[16:17]
	s_add_u32 s18, s36, s6
	s_addc_u32 s19, s37, s7
	s_mov_b32 m0, s11
	s_nop 0
	global_load_lds_dwordx4 v134, s[18:19]
	s_add_i32 s44, s11, 0x2000
	s_mov_b32 m0, s44
	s_nop 0
	global_load_lds_dwordx4 v136, s[18:19]
	s_add_u32 s4, s16, 0x10000
	s_addc_u32 s5, s17, 0
	s_add_i32 s45, s11, 0x14000
	s_mov_b32 m0, s45
	s_nop 0
	global_load_lds_dwordx4 v135, s[4:5]
	s_add_i32 s46, s11, 0x16000
	s_mov_b32 m0, s46
	s_nop 0
	global_load_lds_dwordx4 v137, s[4:5]
	s_add_u32 s4, s18, 0x10000
	s_addc_u32 s5, s19, 0
	s_add_i32 s47, s11, 0x4000
	s_mov_b32 m0, s47
	s_nop 0
	global_load_lds_dwordx4 v134, s[4:5]
	s_add_i32 s48, s11, 0x6000
	s_mov_b32 m0, s48
	s_nop 0
	global_load_lds_dwordx4 v136, s[4:5]
	v_mov_b32_e32 v1, v0
	v_mov_b32_e32 v2, v0
	v_mov_b32_e32 v3, v0
	s_add_i32 s49, s11, 0x18000
	s_add_i32 s50, s11, 0x8000
	s_add_i32 s51, s11, 0x1c000
	s_add_i32 s52, s11, 0xc000
	s_add_i32 s53, s11, 0x1a000
	s_add_i32 s54, s11, 0xa000
	s_add_i32 s55, s11, 0x1e000
	s_add_i32 s56, s11, 0xe000
	s_ashr_i32 s57, s34, 31
	s_mov_b32 s9, 0
	v_add_u32_e32 v138, 0, v5
	v_add_u32_e32 v139, 0, v4

; template <class Epi, class Sched>
; __device__ __forceinline__ void gemm_simple(PG8_LAS unsigned char* lds, const Gemm g, const Sched& S, const Epi& E, int wave_s) {
;     ...
;             if constexpr (Epi::NST >= 16) PG8_TILE_W(0, cA + kstep, cB + kstep, "18", "20"); else PG8_TILE_W(0, cA + kstep, cB + kstep, "10", "12");
;             PG8_TILE_W(1, cA + 2 * kstep, cB + 2 * kstep, "2", "4");
.LBB0_149:
	s_cmp_lg_u32 s9, 0
	v_cmp_lt_i64_e32 vcc, s[20:21], v[168:169]
	s_cselect_b64 s[24:25], -1, 0
	s_cmp_eq_u32 s9, 0
	v_add_u32_e32 v132, 0x10000, v138
	v_add_u32_e32 v133, 0x14000, v138
	v_add_u32_e32 v140, 0x18000, v138
	v_add_u32_e32 v152, 0x1c000, v138
	s_cbranch_scc1 .LBB0_151
	s_waitcnt vmcnt(18) lgkmcnt(0)
	s_barrier
	ds_read_b128 v[4:7], v132
	ds_read_b128 v[8:11], v132 offset:1024
	ds_read_b128 v[12:15], v132 offset:2048
	ds_read_b128 v[16:19], v132 offset:3072
	ds_read_b128 v[20:23], v139
	ds_read_b128 v[24:27], v139 offset:1024
	ds_read_b128 v[28:31], v139 offset:2048
	ds_read_b128 v[32:35], v139 offset:3072
	ds_read_b128 v[36:39], v139 offset:4096
	ds_read_b128 v[40:43], v139 offset:5120
	ds_read_b128 v[44:47], v139 offset:6144
	ds_read_b128 v[48:51], v139 offset:7168
	ds_read_b128 v[52:55], v133
	ds_read_b128 v[56:59], v133 offset:1024
	ds_read_b128 v[60:63], v133 offset:2048
	ds_read_b128 v[64:67], v133 offset:3072
	s_add_u32 s20, s16, 0x80
	s_addc_u32 s21, s17, 0
	s_mov_b32 m0, s49
	s_nop 0
	global_load_lds_dwordx4 v135, s[20:21]
	s_mov_b32 m0, s53
	s_nop 0
	global_load_lds_dwordx4 v137, s[20:21]
	s_waitcnt lgkmcnt(11)
	v_mfma_f32_16x16x32_bf16 v[68:71], v[4:7], v[20:23], v[0:3]
	v_mfma_f32_16x16x32_bf16 v[72:75], v[12:15], v[20:23], v[0:3]
	s_waitcnt lgkmcnt(9)
	v_mfma_f32_16x16x32_bf16 v[76:79], v[4:7], v[28:31], v[0:3]
	v_mfma_f32_16x16x32_bf16 v[80:83], v[12:15], v[28:31], v[0:3]
	s_waitcnt lgkmcnt(7)
	v_mfma_f32_16x16x32_bf16 v[84:87], v[4:7], v[36:39], v[0:3]
	v_mfma_f32_16x16x32_bf16 v[88:91], v[12:15], v[36:39], v[0:3]
	s_waitcnt lgkmcnt(5)
	v_mfma_f32_16x16x32_bf16 v[92:95], v[4:7], v[44:47], v[0:3]
	v_mfma_f32_16x16x32_bf16 v[96:99], v[12:15], v[44:47], v[0:3]
	v_mfma_f32_16x16x32_bf16 v[68:71], v[8:11], v[24:27], v[68:71]
	v_mfma_f32_16x16x32_bf16 v[72:75], v[16:19], v[24:27], v[72:75]
	v_mfma_f32_16x16x32_bf16 v[76:79], v[8:11], v[32:35], v[76:79]
	v_mfma_f32_16x16x32_bf16 v[80:83], v[16:19], v[32:35], v[80:83]
	v_mfma_f32_16x16x32_bf16 v[84:87], v[8:11], v[40:43], v[84:87]
	v_mfma_f32_16x16x32_bf16 v[88:91], v[16:19], v[40:43], v[88:91]
	s_waitcnt lgkmcnt(4)
	v_mfma_f32_16x16x32_bf16 v[92:95], v[8:11], v[48:51], v[92:95]
	v_mfma_f32_16x16x32_bf16 v[100:103], v[16:19], v[48:51], v[96:99]
	s_add_u32 s20, s18, 0x80
	s_addc_u32 s21, s19, 0
	s_mov_b32 m0, s50
	s_nop 0
	global_load_lds_dwordx4 v134, s[20:21]
	s_mov_b32 m0, s54
	s_nop 0
	global_load_lds_dwordx4 v136, s[20:21]
	s_waitcnt lgkmcnt(3)
	v_mfma_f32_16x16x32_bf16 v[96:99], v[52:55], v[20:23], v[0:3]
	s_waitcnt lgkmcnt(1)
	v_mfma_f32_16x16x32_bf16 v[20:23], v[60:63], v[20:23], v[0:3]
	v_mfma_f32_16x16x32_bf16 v[108:111], v[56:59], v[24:27], v[96:99]
	s_waitcnt lgkmcnt(0)
	v_mfma_f32_16x16x32_bf16 v[20:23], v[64:67], v[24:27], v[20:23]
	v_mfma_f32_16x16x32_bf16 v[24:27], v[52:55], v[28:31], v[0:3]
	v_mfma_f32_16x16x32_bf16 v[28:31], v[60:63], v[28:31], v[0:3]
	v_mfma_f32_16x16x32_bf16 v[24:27], v[56:59], v[32:35], v[24:27]
	v_mfma_f32_16x16x32_bf16 v[28:31], v[64:67], v[32:35], v[28:31]
	v_mfma_f32_16x16x32_bf16 v[32:35], v[52:55], v[36:39], v[0:3]
	v_mfma_f32_16x16x32_bf16 v[36:39], v[60:63], v[36:39], v[0:3]
	v_mfma_f32_16x16x32_bf16 v[32:35], v[56:59], v[40:43], v[32:35]
	v_mfma_f32_16x16x32_bf16 v[36:39], v[64:67], v[40:43], v[36:39]
	v_mfma_f32_16x16x32_bf16 v[40:43], v[52:55], v[44:47], v[0:3]
	v_mfma_f32_16x16x32_bf16 v[44:47], v[60:63], v[44:47], v[0:3]
	v_mfma_f32_16x16x32_bf16 v[40:43], v[56:59], v[48:51], v[40:43]
	v_mfma_f32_16x16x32_bf16 v[44:47], v[64:67], v[48:51], v[44:47]
	s_waitcnt vmcnt(20) lgkmcnt(0)
	s_barrier
	ds_read_b128 v[48:51], v139 offset:16384
	ds_read_b128 v[96:99], v139 offset:17408
	ds_read_b128 v[104:107], v139 offset:18432
	ds_read_b128 v[112:115], v139 offset:19456
	ds_read_b128 v[116:119], v139 offset:20480
	ds_read_b128 v[120:123], v139 offset:21504
	ds_read_b128 v[124:127], v139 offset:22528
	ds_read_b128 v[128:131], v139 offset:23552
	s_add_u32 s20, s16, 0x10080
	s_addc_u32 s21, s17, 0
	s_mov_b32 m0, s51
	s_nop 0
	global_load_lds_dwordx4 v135, s[20:21]
	s_mov_b32 m0, s55
	s_nop 0
	global_load_lds_dwordx4 v137, s[20:21]
	s_waitcnt lgkmcnt(7)
	v_mfma_f32_16x16x32_bf16 v[146:149], v[4:7], v[48:51], v[0:3]
	s_waitcnt lgkmcnt(5)
	v_mfma_f32_16x16x32_bf16 v[158:161], v[4:7], v[104:107], v[0:3]
	s_waitcnt lgkmcnt(3)
	v_mfma_f32_16x16x32_bf16 v[174:177], v[4:7], v[116:119], v[0:3]
	s_waitcnt lgkmcnt(1)
	v_mfma_f32_16x16x32_bf16 v[4:7], v[4:7], v[124:127], v[0:3]
	v_mfma_f32_16x16x32_bf16 v[146:149], v[8:11], v[96:99], v[146:149]
	v_mfma_f32_16x16x32_bf16 v[158:161], v[8:11], v[112:115], v[158:161]
	v_mfma_f32_16x16x32_bf16 v[174:177], v[8:11], v[120:123], v[174:177]
	s_waitcnt lgkmcnt(0)
	v_mfma_f32_16x16x32_bf16 v[4:7], v[8:11], v[128:131], v[4:7]
	v_mfma_f32_16x16x32_bf16 v[8:11], v[12:15], v[124:127], v[0:3]
	v_mfma_f32_16x16x32_bf16 v[154:157], v[12:15], v[48:51], v[0:3]
	v_mfma_f32_16x16x32_bf16 v[170:173], v[12:15], v[104:107], v[0:3]
	v_mfma_f32_16x16x32_bf16 v[178:181], v[12:15], v[116:119], v[0:3]
	v_mfma_f32_16x16x32_bf16 v[12:15], v[16:19], v[128:131], v[8:11]
	v_mfma_f32_16x16x32_bf16 v[154:157], v[16:19], v[96:99], v[154:157]
	v_mfma_f32_16x16x32_bf16 v[170:173], v[16:19], v[112:115], v[170:173]
	v_mfma_f32_16x16x32_bf16 v[178:181], v[16:19], v[120:123], v[178:181]
	s_add_u32 s20, s18, 0x10080
	s_addc_u32 s21, s19, 0
	s_mov_b32 m0, s52
	s_nop 0
	global_load_lds_dwordx4 v134, s[20:21]
	s_mov_b32 m0, s56
	s_nop 0
	global_load_lds_dwordx4 v136, s[20:21]
	v_mfma_f32_16x16x32_bf16 v[8:11], v[52:55], v[48:51], v[0:3]
	v_mfma_f32_16x16x32_bf16 v[16:19], v[56:59], v[96:99], v[8:11]
	v_mfma_f32_16x16x32_bf16 v[8:11], v[60:63], v[48:51], v[0:3]
	v_mfma_f32_16x16x32_bf16 v[48:51], v[64:67], v[96:99], v[8:11]
	v_mfma_f32_16x16x32_bf16 v[8:11], v[52:55], v[104:107], v[0:3]
	v_mfma_f32_16x16x32_bf16 v[182:185], v[56:59], v[112:115], v[8:11]
	v_mfma_f32_16x16x32_bf16 v[8:11], v[60:63], v[104:107], v[0:3]
	v_mfma_f32_16x16x32_bf16 v[186:189], v[64:67], v[112:115], v[8:11]
	v_mfma_f32_16x16x32_bf16 v[8:11], v[52:55], v[116:119], v[0:3]
	v_mfma_f32_16x16x32_bf16 v[190:193], v[56:59], v[120:123], v[8:11]
	v_mfma_f32_16x16x32_bf16 v[8:11], v[60:63], v[116:119], v[0:3]
	v_mfma_f32_16x16x32_bf16 v[194:197], v[64:67], v[120:123], v[8:11]
	v_mfma_f32_16x16x32_bf16 v[8:11], v[52:55], v[124:127], v[0:3]
	v_mfma_f32_16x16x32_bf16 v[198:201], v[56:59], v[128:131], v[8:11]
	v_mfma_f32_16x16x32_bf16 v[8:11], v[60:63], v[124:127], v[0:3]
	v_mfma_f32_16x16x32_bf16 v[202:205], v[64:67], v[128:131], v[8:11]
	s_waitcnt vmcnt(2) lgkmcnt(0)
	s_barrier
; template <class Epi, class Sched>
; __device__ __forceinline__ void gemm_simple(PG8_LAS unsigned char* lds, const Gemm g, const Sched& S, const Epi& E, int wave_s) {
;     ...
;             PG8_TILE_W(1, cA + 2 * kstep, cB + 2 * kstep, "2", "4");
	s_nop 5
	ds_read_b128 v[8:11], v140
	ds_read_b128 v[206:209], v140 offset:1024
	ds_read_b128 v[210:213], v140 offset:2048
	ds_read_b128 v[214:217], v140 offset:3072
	ds_read_b128 v[52:55], v139 offset:32768
	ds_read_b128 v[60:63], v139 offset:33792
	ds_read_b128 v[218:221], v139 offset:34816
	ds_read_b128 v[222:225], v139 offset:35840
	ds_read_b128 v[226:229], v139 offset:36864
	ds_read_b128 v[230:233], v139 offset:37888
	ds_read_b128 v[234:237], v139 offset:38912
	ds_read_b128 v[238:241], v139 offset:39936
	ds_read_b128 v[242:245], v152
	ds_read_b128 v[246:249], v152 offset:1024
	ds_read_b128 v[250:253], v152 offset:2048
	ds_read_b128 v[142:145], v152 offset:3072
	s_add_u32 s20, s16, 0x100
	s_addc_u32 s21, s17, 0
	s_mov_b32 m0, s42
	s_nop 0
	global_load_lds_dwordx4 v135, s[20:21]
	s_mov_b64 s[26:27], 0x100
	s_mov_b32 m0, s43
	s_nop 0
	global_load_lds_dwordx4 v137, s[20:21]
	s_waitcnt lgkmcnt(11)
	v_mfma_f32_16x16x32_bf16 v[56:59], v[8:11], v[52:55], v[68:71]
	s_waitcnt lgkmcnt(10)
	v_mfma_f32_16x16x32_bf16 v[128:131], v[206:209], v[60:63], v[56:59]
	v_mfma_f32_16x16x32_bf16 v[56:59], v[210:213], v[52:55], v[72:75]
	v_mfma_f32_16x16x32_bf16 v[120:123], v[214:217], v[60:63], v[56:59]
	s_waitcnt lgkmcnt(9)
	v_mfma_f32_16x16x32_bf16 v[56:59], v[8:11], v[218:221], v[76:79]
	s_waitcnt lgkmcnt(8)
	v_mfma_f32_16x16x32_bf16 v[112:115], v[206:209], v[222:225], v[56:59]
	v_mfma_f32_16x16x32_bf16 v[56:59], v[210:213], v[218:221], v[80:83]
	v_mfma_f32_16x16x32_bf16 v[104:107], v[214:217], v[222:225], v[56:59]
	s_waitcnt lgkmcnt(7)
	v_mfma_f32_16x16x32_bf16 v[56:59], v[8:11], v[226:229], v[84:87]
	s_waitcnt lgkmcnt(6)
	v_mfma_f32_16x16x32_bf16 v[96:99], v[206:209], v[230:233], v[56:59]
	v_mfma_f32_16x16x32_bf16 v[56:59], v[210:213], v[226:229], v[88:91]
	v_mfma_f32_16x16x32_bf16 v[88:91], v[214:217], v[230:233], v[56:59]
	s_waitcnt lgkmcnt(5)
	v_mfma_f32_16x16x32_bf16 v[56:59], v[8:11], v[234:237], v[92:95]
	s_waitcnt lgkmcnt(4)
	v_mfma_f32_16x16x32_bf16 v[64:67], v[206:209], v[238:241], v[56:59]
	v_mfma_f32_16x16x32_bf16 v[56:59], v[210:213], v[234:237], v[100:103]
	v_mfma_f32_16x16x32_bf16 v[56:59], v[214:217], v[238:241], v[56:59]
	s_add_u32 s20, s18, 0x100
	s_addc_u32 s21, s19, 0
	s_mov_b32 m0, s11
	s_nop 0
	global_load_lds_dwordx4 v134, s[20:21]
	s_mov_b32 m0, s44
	s_nop 0
	global_load_lds_dwordx4 v136, s[20:21]
	s_waitcnt lgkmcnt(1)
	v_mfma_f32_16x16x32_bf16 v[20:23], v[250:253], v[52:55], v[20:23]
	s_waitcnt lgkmcnt(0)
	v_mfma_f32_16x16x32_bf16 v[116:119], v[142:145], v[60:63], v[20:23]
	v_mfma_f32_16x16x32_bf16 v[20:23], v[242:245], v[218:221], v[24:27]
	v_mfma_f32_16x16x32_bf16 v[68:71], v[242:245], v[52:55], v[108:111]
	v_mfma_f32_16x16x32_bf16 v[108:111], v[246:249], v[222:225], v[20:23]
	v_mfma_f32_16x16x32_bf16 v[20:23], v[250:253], v[218:221], v[28:31]
	v_mfma_f32_16x16x32_bf16 v[100:103], v[142:145], v[222:225], v[20:23]
	v_mfma_f32_16x16x32_bf16 v[20:23], v[242:245], v[226:229], v[32:35]
	v_mfma_f32_16x16x32_bf16 v[92:95], v[246:249], v[230:233], v[20:23]
	v_mfma_f32_16x16x32_bf16 v[20:23], v[250:253], v[226:229], v[36:39]
	v_mfma_f32_16x16x32_bf16 v[84:87], v[142:145], v[230:233], v[20:23]
	v_mfma_f32_16x16x32_bf16 v[20:23], v[242:245], v[234:237], v[40:43]
	v_mfma_f32_16x16x32_bf16 v[124:127], v[246:249], v[60:63], v[68:71]
	v_mfma_f32_16x16x32_bf16 v[60:63], v[246:249], v[238:241], v[20:23]
	v_mfma_f32_16x16x32_bf16 v[20:23], v[250:253], v[234:237], v[44:47]
	v_mfma_f32_16x16x32_bf16 v[52:55], v[142:145], v[238:241], v[20:23]
	s_waitcnt vmcnt(4) lgkmcnt(0)
	s_barrier
	ds_read_b128 v[28:31], v139 offset:49152
	ds_read_b128 v[32:35], v139 offset:50176
	ds_read_b128 v[44:47], v139 offset:51200
	ds_read_b128 v[218:221], v139 offset:52224
	ds_read_b128 v[222:225], v139 offset:53248
	ds_read_b128 v[226:229], v139 offset:54272
	ds_read_b128 v[230:233], v139 offset:55296
	ds_read_b128 v[234:237], v139 offset:56320
	s_add_u32 s20, s16, 0x10100
	s_addc_u32 s21, s17, 0
	s_mov_b32 m0, s45
	s_nop 0
	global_load_lds_dwordx4 v135, s[20:21]
	s_mov_b32 m0, s46
	s_nop 0
	global_load_lds_dwordx4 v137, s[20:21]
	s_waitcnt lgkmcnt(7)
	v_mfma_f32_16x16x32_bf16 v[20:23], v[8:11], v[28:31], v[146:149]
	s_waitcnt lgkmcnt(6)
	v_mfma_f32_16x16x32_bf16 v[72:75], v[206:209], v[32:35], v[20:23]
	v_mfma_f32_16x16x32_bf16 v[20:23], v[210:213], v[28:31], v[154:157]
	v_mfma_f32_16x16x32_bf16 v[68:71], v[214:217], v[32:35], v[20:23]
	s_waitcnt lgkmcnt(5)
	v_mfma_f32_16x16x32_bf16 v[20:23], v[8:11], v[44:47], v[158:161]
	s_waitcnt lgkmcnt(4)
	v_mfma_f32_16x16x32_bf16 v[40:43], v[206:209], v[218:221], v[20:23]
	v_mfma_f32_16x16x32_bf16 v[20:23], v[210:213], v[44:47], v[170:173]
	v_mfma_f32_16x16x32_bf16 v[36:39], v[214:217], v[218:221], v[20:23]
	s_waitcnt lgkmcnt(3)
	v_mfma_f32_16x16x32_bf16 v[20:23], v[8:11], v[222:225], v[174:177]
	s_waitcnt lgkmcnt(1)
	v_mfma_f32_16x16x32_bf16 v[4:7], v[8:11], v[230:233], v[4:7]
	v_mfma_f32_16x16x32_bf16 v[24:27], v[206:209], v[226:229], v[20:23]
	v_mfma_f32_16x16x32_bf16 v[20:23], v[210:213], v[222:225], v[178:181]
	s_waitcnt lgkmcnt(0)
	v_mfma_f32_16x16x32_bf16 v[8:11], v[206:209], v[234:237], v[4:7]
	v_mfma_f32_16x16x32_bf16 v[4:7], v[210:213], v[230:233], v[12:15]
	v_mfma_f32_16x16x32_bf16 v[20:23], v[214:217], v[226:229], v[20:23]
	v_mfma_f32_16x16x32_bf16 v[4:7], v[214:217], v[234:237], v[4:7]
	s_add_u32 s20, s18, 0x10100
	s_addc_u32 s21, s19, 0
	s_mov_b32 m0, s47
	s_nop 0
	global_load_lds_dwordx4 v134, s[20:21]
	s_mov_b32 m0, s48
	s_nop 0
	global_load_lds_dwordx4 v136, s[20:21]
	v_mfma_f32_16x16x32_bf16 v[12:15], v[242:245], v[28:31], v[16:19]
	v_mfma_f32_16x16x32_bf16 v[80:83], v[246:249], v[32:35], v[12:15]
	v_mfma_f32_16x16x32_bf16 v[12:15], v[250:253], v[28:31], v[48:51]
	v_mfma_f32_16x16x32_bf16 v[76:79], v[142:145], v[32:35], v[12:15]
	v_mfma_f32_16x16x32_bf16 v[12:15], v[242:245], v[44:47], v[182:185]
	v_mfma_f32_16x16x32_bf16 v[48:51], v[246:249], v[218:221], v[12:15]
	v_mfma_f32_16x16x32_bf16 v[12:15], v[250:253], v[44:47], v[186:189]
	v_mfma_f32_16x16x32_bf16 v[44:47], v[142:145], v[218:221], v[12:15]
	v_mfma_f32_16x16x32_bf16 v[12:15], v[242:245], v[222:225], v[190:193]
	v_mfma_f32_16x16x32_bf16 v[32:35], v[246:249], v[226:229], v[12:15]
	v_mfma_f32_16x16x32_bf16 v[12:15], v[250:253], v[222:225], v[194:197]
	v_mfma_f32_16x16x32_bf16 v[28:31], v[142:145], v[226:229], v[12:15]
	v_mfma_f32_16x16x32_bf16 v[12:15], v[242:245], v[230:233], v[198:201]
	v_mfma_f32_16x16x32_bf16 v[16:19], v[246:249], v[234:237], v[12:15]
	v_mfma_f32_16x16x32_bf16 v[12:15], v[250:253], v[230:233], v[202:205]
	v_mfma_f32_16x16x32_bf16 v[12:15], v[142:145], v[234:237], v[12:15]
	s_branch .LBB0_152

; template <class Epi, class Sched>
; __device__ __forceinline__ void gemm_simple(PG8_LAS unsigned char* lds, const Gemm g, const Sched& S, const Epi& E, int wave_s) {
;     ...
;         for (; t < nt; t += 2) {
;             const bool last = (t == nt - 2);
;             PG8_TILE(0, cA + (size_t)(t + 1) * kstep, cB + (size_t)(t + 1) * kstep, true);
.LBB0_153:
	s_waitcnt vmcnt(2) lgkmcnt(0)
	s_barrier
	ds_read_b128 v[142:145], v132
	ds_read_b128 v[146:149], v132 offset:1024
	ds_read_b128 v[154:157], v132 offset:2048
	ds_read_b128 v[158:161], v132 offset:3072
	ds_read_b128 v[170:173], v139
	ds_read_b128 v[174:177], v139 offset:1024
	ds_read_b128 v[178:181], v139 offset:2048
	ds_read_b128 v[182:185], v139 offset:3072
	ds_read_b128 v[186:189], v139 offset:4096
	ds_read_b128 v[190:193], v139 offset:5120
	ds_read_b128 v[194:197], v139 offset:6144
	ds_read_b128 v[198:201], v139 offset:7168
	ds_read_b128 v[202:205], v133
	ds_read_b128 v[206:209], v133 offset:1024
	ds_read_b128 v[210:213], v133 offset:2048
	ds_read_b128 v[214:217], v133 offset:3072
	s_add_u32 s64, s16, s26
	s_addc_u32 s65, s17, s27
	s_add_u32 s62, s64, 0x80
	s_addc_u32 s63, s65, 0
	s_mov_b32 m0, s49
	s_nop 0
	global_load_lds_dwordx4 v135, s[62:63]
	s_mov_b32 m0, s53
	s_nop 0
	global_load_lds_dwordx4 v137, s[62:63]
	s_waitcnt lgkmcnt(11)
	v_mfma_f32_16x16x32_bf16 v[128:131], v[142:145], v[170:173], v[128:131]
	v_mfma_f32_16x16x32_bf16 v[120:123], v[154:157], v[170:173], v[120:123]
	s_waitcnt lgkmcnt(9)
	v_mfma_f32_16x16x32_bf16 v[112:115], v[142:145], v[178:181], v[112:115]
	v_mfma_f32_16x16x32_bf16 v[104:107], v[154:157], v[178:181], v[104:107]
	s_waitcnt lgkmcnt(7)
	v_mfma_f32_16x16x32_bf16 v[96:99], v[142:145], v[186:189], v[96:99]
	v_mfma_f32_16x16x32_bf16 v[88:91], v[154:157], v[186:189], v[88:91]
	s_waitcnt lgkmcnt(5)
	v_mfma_f32_16x16x32_bf16 v[64:67], v[142:145], v[194:197], v[64:67]
	v_mfma_f32_16x16x32_bf16 v[56:59], v[154:157], v[194:197], v[56:59]
	v_mfma_f32_16x16x32_bf16 v[128:131], v[146:149], v[174:177], v[128:131]
	v_mfma_f32_16x16x32_bf16 v[120:123], v[158:161], v[174:177], v[120:123]
	v_mfma_f32_16x16x32_bf16 v[112:115], v[146:149], v[182:185], v[112:115]
	v_mfma_f32_16x16x32_bf16 v[104:107], v[158:161], v[182:185], v[104:107]
	v_mfma_f32_16x16x32_bf16 v[96:99], v[146:149], v[190:193], v[96:99]
	v_mfma_f32_16x16x32_bf16 v[88:91], v[158:161], v[190:193], v[88:91]
	s_waitcnt lgkmcnt(4)
	v_mfma_f32_16x16x32_bf16 v[64:67], v[146:149], v[198:201], v[64:67]
	v_mfma_f32_16x16x32_bf16 v[56:59], v[158:161], v[198:201], v[56:59]
	s_add_u32 s62, s18, s26
	s_addc_u32 s63, s19, s27
	s_add_u32 s26, s62, 0x80
	s_addc_u32 s27, s63, 0
	s_mov_b32 m0, s50
	s_nop 0
	global_load_lds_dwordx4 v134, s[26:27]
	s_mov_b32 m0, s54
	s_nop 0
	global_load_lds_dwordx4 v136, s[26:27]
	s_waitcnt lgkmcnt(3)
	v_mfma_f32_16x16x32_bf16 v[124:127], v[202:205], v[170:173], v[124:127]
	s_waitcnt lgkmcnt(1)
	v_mfma_f32_16x16x32_bf16 v[116:119], v[210:213], v[170:173], v[116:119]
	v_mfma_f32_16x16x32_bf16 v[108:111], v[202:205], v[178:181], v[108:111]
	v_mfma_f32_16x16x32_bf16 v[100:103], v[210:213], v[178:181], v[100:103]
	v_mfma_f32_16x16x32_bf16 v[92:95], v[202:205], v[186:189], v[92:95]
	v_mfma_f32_16x16x32_bf16 v[84:87], v[210:213], v[186:189], v[84:87]
	v_mfma_f32_16x16x32_bf16 v[60:63], v[202:205], v[194:197], v[60:63]
	v_mfma_f32_16x16x32_bf16 v[52:55], v[210:213], v[194:197], v[52:55]
	v_mfma_f32_16x16x32_bf16 v[124:127], v[206:209], v[174:177], v[124:127]
	s_waitcnt lgkmcnt(0)
	v_mfma_f32_16x16x32_bf16 v[116:119], v[214:217], v[174:177], v[116:119]
	v_mfma_f32_16x16x32_bf16 v[108:111], v[206:209], v[182:185], v[108:111]
	v_mfma_f32_16x16x32_bf16 v[100:103], v[214:217], v[182:185], v[100:103]
	v_mfma_f32_16x16x32_bf16 v[92:95], v[206:209], v[190:193], v[92:95]
	v_mfma_f32_16x16x32_bf16 v[84:87], v[214:217], v[190:193], v[84:87]
	v_mfma_f32_16x16x32_bf16 v[60:63], v[206:209], v[198:201], v[60:63]
	v_mfma_f32_16x16x32_bf16 v[52:55], v[214:217], v[198:201], v[52:55]
	s_waitcnt vmcnt(4) lgkmcnt(0)
	s_barrier
	ds_read_b128 v[170:173], v139 offset:16384
	ds_read_b128 v[174:177], v139 offset:17408
	ds_read_b128 v[178:181], v139 offset:18432
	ds_read_b128 v[182:185], v139 offset:19456
	ds_read_b128 v[186:189], v139 offset:20480
	ds_read_b128 v[190:193], v139 offset:21504
	ds_read_b128 v[194:197], v139 offset:22528
	ds_read_b128 v[198:201], v139 offset:23552
	s_add_u32 s26, s64, 0x10080
	s_addc_u32 s27, s65, 0
	s_mov_b32 m0, s51
	s_nop 0
	global_load_lds_dwordx4 v135, s[26:27]
	s_mov_b32 m0, s55
	s_nop 0
	global_load_lds_dwordx4 v137, s[26:27]
	s_waitcnt lgkmcnt(7)
	v_mfma_f32_16x16x32_bf16 v[72:75], v[142:145], v[170:173], v[72:75]
	v_mfma_f32_16x16x32_bf16 v[68:71], v[154:157], v[170:173], v[68:71]
	s_waitcnt lgkmcnt(5)
	v_mfma_f32_16x16x32_bf16 v[40:43], v[142:145], v[178:181], v[40:43]
	v_mfma_f32_16x16x32_bf16 v[36:39], v[154:157], v[178:181], v[36:39]
	s_waitcnt lgkmcnt(3)
	v_mfma_f32_16x16x32_bf16 v[24:27], v[142:145], v[186:189], v[24:27]
	v_mfma_f32_16x16x32_bf16 v[20:23], v[154:157], v[186:189], v[20:23]
	s_waitcnt lgkmcnt(1)
	v_mfma_f32_16x16x32_bf16 v[8:11], v[142:145], v[194:197], v[8:11]
	v_mfma_f32_16x16x32_bf16 v[4:7], v[154:157], v[194:197], v[4:7]
	v_mfma_f32_16x16x32_bf16 v[72:75], v[146:149], v[174:177], v[72:75]
	v_mfma_f32_16x16x32_bf16 v[68:71], v[158:161], v[174:177], v[68:71]
	v_mfma_f32_16x16x32_bf16 v[40:43], v[146:149], v[182:185], v[40:43]
	v_mfma_f32_16x16x32_bf16 v[36:39], v[158:161], v[182:185], v[36:39]
	v_mfma_f32_16x16x32_bf16 v[24:27], v[146:149], v[190:193], v[24:27]
	v_mfma_f32_16x16x32_bf16 v[20:23], v[158:161], v[190:193], v[20:23]
	s_waitcnt lgkmcnt(0)
	v_mfma_f32_16x16x32_bf16 v[8:11], v[146:149], v[198:201], v[8:11]
	v_mfma_f32_16x16x32_bf16 v[4:7], v[158:161], v[198:201], v[4:7]
	s_add_u32 s26, s62, 0x10080
	s_addc_u32 s27, s63, 0
	s_mov_b32 m0, s52
	s_nop 0
	global_load_lds_dwordx4 v134, s[26:27]
	s_mov_b32 m0, s56
	s_nop 0
	global_load_lds_dwordx4 v136, s[26:27]
	v_mfma_f32_16x16x32_bf16 v[80:83], v[202:205], v[170:173], v[80:83]
	s_add_u32 s62, s62, 0x100
	s_addc_u32 s63, s63, 0
	s_mov_b64 s[26:27], 0x100
	v_mfma_f32_16x16x32_bf16 v[76:79], v[210:213], v[170:173], v[76:79]
	s_add_u32 s64, s64, 0x100
	s_addc_u32 s65, s65, 0
	v_mfma_f32_16x16x32_bf16 v[48:51], v[202:205], v[178:181], v[48:51]
	v_mfma_f32_16x16x32_bf16 v[44:47], v[210:213], v[178:181], v[44:47]
	v_mfma_f32_16x16x32_bf16 v[32:35], v[202:205], v[186:189], v[32:35]
	v_mfma_f32_16x16x32_bf16 v[28:31], v[210:213], v[186:189], v[28:31]
	v_mfma_f32_16x16x32_bf16 v[16:19], v[202:205], v[194:197], v[16:19]
	v_mfma_f32_16x16x32_bf16 v[12:15], v[210:213], v[194:197], v[12:15]
	v_mfma_f32_16x16x32_bf16 v[80:83], v[206:209], v[174:177], v[80:83]
	v_mfma_f32_16x16x32_bf16 v[76:79], v[214:217], v[174:177], v[76:79]
	v_mfma_f32_16x16x32_bf16 v[48:51], v[206:209], v[182:185], v[48:51]
	v_mfma_f32_16x16x32_bf16 v[44:47], v[214:217], v[182:185], v[44:47]
	v_mfma_f32_16x16x32_bf16 v[32:35], v[206:209], v[190:193], v[32:35]
	v_mfma_f32_16x16x32_bf16 v[28:31], v[214:217], v[190:193], v[28:31]
	v_mfma_f32_16x16x32_bf16 v[16:19], v[206:209], v[198:201], v[16:19]
	v_mfma_f32_16x16x32_bf16 v[12:15], v[214:217], v[198:201], v[12:15]
	s_waitcnt vmcnt(2) lgkmcnt(0)
	s_barrier
; template <class Epi, class Sched>
; __device__ __forceinline__ void gemm_simple(PG8_LAS unsigned char* lds, const Gemm g, const Sched& S, const Epi& E, int wave_s) {
;     ...
;             const char* a2 = last ? nA : cA + (size_t)(t + 2) * kstep; const char* b2 = last ? nB : cB + (size_t)(t + 2) * kstep;
;             PG8_TILE(1, a2, b2, (!last || has_next));
	ds_read_b128 v[142:145], v140
	ds_read_b128 v[146:149], v140 offset:1024
	ds_read_b128 v[154:157], v140 offset:2048
	ds_read_b128 v[158:161], v140 offset:3072
	ds_read_b128 v[170:173], v139 offset:32768
	ds_read_b128 v[174:177], v139 offset:33792
	ds_read_b128 v[178:181], v139 offset:34816
	ds_read_b128 v[182:185], v139 offset:35840
	ds_read_b128 v[186:189], v139 offset:36864
	ds_read_b128 v[190:193], v139 offset:37888
	ds_read_b128 v[194:197], v139 offset:38912
	ds_read_b128 v[198:201], v139 offset:39936
	ds_read_b128 v[202:205], v152
	ds_read_b128 v[206:209], v152 offset:1024
	ds_read_b128 v[210:213], v152 offset:2048
	ds_read_b128 v[214:217], v152 offset:3072
	s_and_b64 s[24:25], s[24:25], exec
	s_cselect_b32 s25, s9, s63
	s_cselect_b32 s24, s60, s62
	s_cselect_b32 s63, s5, s65
	s_cselect_b32 s62, s61, s64
	s_mov_b32 m0, s42
	s_nop 0
	global_load_lds_dwordx4 v135, s[62:63]
	s_mov_b32 m0, s43
	s_nop 0
	global_load_lds_dwordx4 v137, s[62:63]
	s_waitcnt lgkmcnt(11)
	v_mfma_f32_16x16x32_bf16 v[128:131], v[142:145], v[170:173], v[128:131]
	v_mfma_f32_16x16x32_bf16 v[120:123], v[154:157], v[170:173], v[120:123]
	s_waitcnt lgkmcnt(9)
	v_mfma_f32_16x16x32_bf16 v[112:115], v[142:145], v[178:181], v[112:115]
	v_mfma_f32_16x16x32_bf16 v[104:107], v[154:157], v[178:181], v[104:107]
	s_waitcnt lgkmcnt(7)
	v_mfma_f32_16x16x32_bf16 v[96:99], v[142:145], v[186:189], v[96:99]
	v_mfma_f32_16x16x32_bf16 v[88:91], v[154:157], v[186:189], v[88:91]
	s_waitcnt lgkmcnt(5)
	v_mfma_f32_16x16x32_bf16 v[64:67], v[142:145], v[194:197], v[64:67]
	v_mfma_f32_16x16x32_bf16 v[56:59], v[154:157], v[194:197], v[56:59]
	v_mfma_f32_16x16x32_bf16 v[128:131], v[146:149], v[174:177], v[128:131]
	v_mfma_f32_16x16x32_bf16 v[120:123], v[158:161], v[174:177], v[120:123]
	v_mfma_f32_16x16x32_bf16 v[112:115], v[146:149], v[182:185], v[112:115]
	v_mfma_f32_16x16x32_bf16 v[104:107], v[158:161], v[182:185], v[104:107]
	v_mfma_f32_16x16x32_bf16 v[96:99], v[146:149], v[190:193], v[96:99]
	v_mfma_f32_16x16x32_bf16 v[88:91], v[158:161], v[190:193], v[88:91]
	s_waitcnt lgkmcnt(4)
	v_mfma_f32_16x16x32_bf16 v[64:67], v[146:149], v[198:201], v[64:67]
	v_mfma_f32_16x16x32_bf16 v[56:59], v[158:161], v[198:201], v[56:59]
	s_mov_b32 m0, s11
	s_nop 0
	global_load_lds_dwordx4 v134, s[24:25]
	s_mov_b32 m0, s44
	s_nop 0
	global_load_lds_dwordx4 v136, s[24:25]
	s_waitcnt lgkmcnt(3)
	v_mfma_f32_16x16x32_bf16 v[124:127], v[202:205], v[170:173], v[124:127]
	s_waitcnt lgkmcnt(1)
	v_mfma_f32_16x16x32_bf16 v[116:119], v[210:213], v[170:173], v[116:119]
	v_mfma_f32_16x16x32_bf16 v[108:111], v[202:205], v[178:181], v[108:111]
	v_mfma_f32_16x16x32_bf16 v[100:103], v[210:213], v[178:181], v[100:103]
	v_mfma_f32_16x16x32_bf16 v[92:95], v[202:205], v[186:189], v[92:95]
	v_mfma_f32_16x16x32_bf16 v[84:87], v[210:213], v[186:189], v[84:87]
	v_mfma_f32_16x16x32_bf16 v[60:63], v[202:205], v[194:197], v[60:63]
	v_mfma_f32_16x16x32_bf16 v[52:55], v[210:213], v[194:197], v[52:55]
	v_mfma_f32_16x16x32_bf16 v[124:127], v[206:209], v[174:177], v[124:127]
	s_waitcnt lgkmcnt(0)
	v_mfma_f32_16x16x32_bf16 v[116:119], v[214:217], v[174:177], v[116:119]
	v_mfma_f32_16x16x32_bf16 v[108:111], v[206:209], v[182:185], v[108:111]
	v_mfma_f32_16x16x32_bf16 v[100:103], v[214:217], v[182:185], v[100:103]
	v_mfma_f32_16x16x32_bf16 v[92:95], v[206:209], v[190:193], v[92:95]
	v_mfma_f32_16x16x32_bf16 v[84:87], v[214:217], v[190:193], v[84:87]
	v_mfma_f32_16x16x32_bf16 v[60:63], v[206:209], v[198:201], v[60:63]
	v_mfma_f32_16x16x32_bf16 v[52:55], v[214:217], v[198:201], v[52:55]
	s_waitcnt vmcnt(4) lgkmcnt(0)
	s_barrier
	ds_read_b128 v[170:173], v139 offset:49152
	ds_read_b128 v[174:177], v139 offset:50176
	ds_read_b128 v[178:181], v139 offset:51200
	ds_read_b128 v[182:185], v139 offset:52224
	ds_read_b128 v[186:189], v139 offset:53248
	ds_read_b128 v[190:193], v139 offset:54272
	ds_read_b128 v[194:197], v139 offset:55296
	ds_read_b128 v[198:201], v139 offset:56320
	s_add_u32 s62, s62, 0x10000
	s_addc_u32 s63, s63, 0
	s_mov_b32 m0, s45
	s_nop 0
	global_load_lds_dwordx4 v135, s[62:63]
	s_mov_b32 m0, s46
	s_nop 0
	global_load_lds_dwordx4 v137, s[62:63]
	s_waitcnt lgkmcnt(7)
	v_mfma_f32_16x16x32_bf16 v[72:75], v[142:145], v[170:173], v[72:75]
	v_mfma_f32_16x16x32_bf16 v[68:71], v[154:157], v[170:173], v[68:71]
	s_waitcnt lgkmcnt(5)
	v_mfma_f32_16x16x32_bf16 v[40:43], v[142:145], v[178:181], v[40:43]
	v_mfma_f32_16x16x32_bf16 v[36:39], v[154:157], v[178:181], v[36:39]
	s_waitcnt lgkmcnt(3)
	v_mfma_f32_16x16x32_bf16 v[24:27], v[142:145], v[186:189], v[24:27]
	v_mfma_f32_16x16x32_bf16 v[20:23], v[154:157], v[186:189], v[20:23]
	s_waitcnt lgkmcnt(1)
	v_mfma_f32_16x16x32_bf16 v[8:11], v[142:145], v[194:197], v[8:11]
	v_mfma_f32_16x16x32_bf16 v[4:7], v[154:157], v[194:197], v[4:7]
	v_mfma_f32_16x16x32_bf16 v[72:75], v[146:149], v[174:177], v[72:75]
	v_mfma_f32_16x16x32_bf16 v[68:71], v[158:161], v[174:177], v[68:71]
	v_mfma_f32_16x16x32_bf16 v[40:43], v[146:149], v[182:185], v[40:43]
	v_mfma_f32_16x16x32_bf16 v[36:39], v[158:161], v[182:185], v[36:39]
	v_mfma_f32_16x16x32_bf16 v[24:27], v[146:149], v[190:193], v[24:27]
	v_mfma_f32_16x16x32_bf16 v[20:23], v[158:161], v[190:193], v[20:23]
	s_waitcnt lgkmcnt(0)
	v_mfma_f32_16x16x32_bf16 v[8:11], v[146:149], v[198:201], v[8:11]
	v_mfma_f32_16x16x32_bf16 v[4:7], v[158:161], v[198:201], v[4:7]
	s_add_u32 s24, s24, 0x10000
	s_addc_u32 s25, s25, 0
	s_mov_b32 m0, s47
	s_nop 0
	global_load_lds_dwordx4 v134, s[24:25]
	s_mov_b32 m0, s48
	s_nop 0
	global_load_lds_dwordx4 v136, s[24:25]
	v_mfma_f32_16x16x32_bf16 v[80:83], v[202:205], v[170:173], v[80:83]
	s_mov_b64 s[24:25], -1
	s_and_b64 vcc, exec, s[28:29]
	s_mov_b64 s[28:29], 0
	v_mfma_f32_16x16x32_bf16 v[76:79], v[210:213], v[170:173], v[76:79]
	v_mfma_f32_16x16x32_bf16 v[48:51], v[202:205], v[178:181], v[48:51]
	v_mfma_f32_16x16x32_bf16 v[44:47], v[210:213], v[178:181], v[44:47]
	v_mfma_f32_16x16x32_bf16 v[32:35], v[202:205], v[186:189], v[32:35]
	v_mfma_f32_16x16x32_bf16 v[28:31], v[210:213], v[186:189], v[28:31]
	v_mfma_f32_16x16x32_bf16 v[16:19], v[202:205], v[194:197], v[16:19]
	v_mfma_f32_16x16x32_bf16 v[12:15], v[210:213], v[194:197], v[12:15]
	v_mfma_f32_16x16x32_bf16 v[80:83], v[206:209], v[174:177], v[80:83]
	v_mfma_f32_16x16x32_bf16 v[76:79], v[214:217], v[174:177], v[76:79]
	v_mfma_f32_16x16x32_bf16 v[48:51], v[206:209], v[182:185], v[48:51]
	v_mfma_f32_16x16x32_bf16 v[44:47], v[214:217], v[182:185], v[44:47]
	v_mfma_f32_16x16x32_bf16 v[32:35], v[206:209], v[190:193], v[32:35]
	v_mfma_f32_16x16x32_bf16 v[28:31], v[214:217], v[190:193], v[28:31]
	v_mfma_f32_16x16x32_bf16 v[16:19], v[206:209], v[198:201], v[16:19]
	v_mfma_f32_16x16x32_bf16 v[12:15], v[214:217], v[198:201], v[12:15]
	s_cbranch_vccnz .LBB0_153
; __device__ __forceinline__ unsigned cvt_pk_bf16(float lo, float hi) { unsigned r; asm volatile("v_cvt_pk_bf16_f32 %0, %1, %2" : "=v"(r) : "v"(lo), "v"(hi)); return r; }
; __device__ __forceinline__ float sigmoidf_(float y) { return __builtin_amdgcn_rcpf(1.0f + __builtin_amdgcn_exp2f(-1.4426950408889634f * y)); }
; __device__ __forceinline__ float gelu_tanh(float x) { const float y = 1.5957691216057308f * (x + 0.044715f * x * x * x); return x * sigmoidf_(y); }
;     __device__ __forceinline__ void operator()(const f32x4 (&acc)[2][2][4][2], const Unit& u, int wr, int wc, int fr, int fq, const LAS float* rt) const {
;         const int row0 = u.pm * 256 + wr * 64 + fr, col0 = u.pn * 256 + wc * 32 + 8 * fq;
; #pragma unroll
;         for (int ai = 0; ai < 2; ++ai)
; #pragma unroll
;             for (int m = 0; m < 4; ++m) { bf16_t* rowp = O + (size_t)(row0 + ai * 128 + m * 16) * ldc + col0; const float rs = RS ? rt[ai * 128 + wr * 64 + m * 16 + fr] : 1.0f;
; #pragma unroll
;                 for (int bj = 0; bj < 2; ++bj) { f32x4 v0 = acc[ai][bj][m][0], v1 = acc[ai][bj][m][1];
;                     if (RS) { v0 = v0 * rs; v1 = v1 * rs; }
;                     if (ACT == 1) {
; #pragma unroll
;                         for (int j = 0; j < 4; ++j) { v0[j] = gelu_tanh(v0[j]); v1[j] = gelu_tanh(v1[j]); } }
;                     if (ACT == 2) {
; #pragma unroll
;                         for (int j = 0; j < 4; ++j) { v0[j] = sigmoidf_(v0[j]); v1[j] = sigmoidf_(v1[j]); } }
;                     u32x4 w; w.x = cvt_pk_bf16(v0[0], v0[1]); w.y = cvt_pk_bf16(v0[2], v0[3]); w.z = cvt_pk_bf16(v1[0], v1[1]); w.w = cvt_pk_bf16(v1[2], v1[3]);
;                     __builtin_nontemporal_store(w, (u32x4*)(rowp + bj * 128)); } }
	v_mov_b32_e32 v132, v141
	s_lshl_b32 s5, s10, 8
	v_mbcnt_lo_u32_b32 v132, -1, v132
	v_mbcnt_hi_u32_b32 v132, -1, v132
	s_add_i32 s5, s5, s40
	v_and_or_b32 v142, v132, 15, s5
	s_lshl_b32 s5, s59, 8
	v_ashrrev_i32_e32 v132, 1, v132
	s_or_b32 s5, s5, s41
	v_and_b32_e32 v132, -8, v132
	v_add_u32_e32 v132, s5, v132
	v_ashrrev_i32_e32 v143, 31, v142
	v_ashrrev_i32_e32 v133, 31, v132
	v_lshlrev_b64 v[144:145], 12, v[142:143]
	v_lshl_add_u64 v[144:145], s[88:89], 0, v[144:145]
	v_lshlrev_b64 v[146:147], 1, v[132:133]
	v_lshl_add_u64 v[132:133], v[144:145], 0, v[146:147]
	v_cvt_pk_bf16_f32 v128, v128, v129
	v_cvt_pk_bf16_f32 v129, v130, v131
	v_cvt_pk_bf16_f32 v130, v120, v121
	v_cvt_pk_bf16_f32 v131, v122, v123
	global_store_dwordx4 v[132:133], v[128:131], off nt
	v_cvt_pk_bf16_f32 v120, v124, v125
	v_cvt_pk_bf16_f32 v121, v126, v127
	v_cvt_pk_bf16_f32 v122, v116, v117
	v_or_b32_e32 v116, 16, v142
	v_ashrrev_i32_e32 v117, 31, v116
	v_lshlrev_b64 v[116:117], 12, v[116:117]
	v_lshl_add_u64 v[116:117], s[88:89], 0, v[116:117]
	v_lshl_add_u64 v[116:117], v[116:117], 0, v[146:147]
	v_cvt_pk_bf16_f32 v123, v118, v119
	global_store_dwordx4 v[132:133], v[120:123], off offset:256 nt
	v_cvt_pk_bf16_f32 v112, v112, v113
	v_cvt_pk_bf16_f32 v113, v114, v115
	v_cvt_pk_bf16_f32 v114, v104, v105
	v_cvt_pk_bf16_f32 v115, v106, v107
	global_store_dwordx4 v[116:117], v[112:115], off nt
	v_cvt_pk_bf16_f32 v104, v108, v109
	v_cvt_pk_bf16_f32 v105, v110, v111
	v_cvt_pk_bf16_f32 v106, v100, v101
	v_or_b32_e32 v100, 32, v142
	v_ashrrev_i32_e32 v101, 31, v100
	v_lshlrev_b64 v[100:101], 12, v[100:101]
	v_lshl_add_u64 v[100:101], s[88:89], 0, v[100:101]
	v_lshl_add_u64 v[100:101], v[100:101], 0, v[146:147]
	v_cvt_pk_bf16_f32 v107, v102, v103
	global_store_dwordx4 v[116:117], v[104:107], off offset:256 nt
	v_cvt_pk_bf16_f32 v96, v96, v97
	v_cvt_pk_bf16_f32 v97, v98, v99
	v_cvt_pk_bf16_f32 v98, v88, v89
	v_cvt_pk_bf16_f32 v99, v90, v91
	global_store_dwordx4 v[100:101], v[96:99], off nt
	v_cvt_pk_bf16_f32 v88, v92, v93
	v_cvt_pk_bf16_f32 v89, v94, v95
	v_cvt_pk_bf16_f32 v90, v84, v85
	v_or_b32_e32 v84, 48, v142
	v_ashrrev_i32_e32 v85, 31, v84
	v_lshlrev_b64 v[84:85], 12, v[84:85]
	v_lshl_add_u64 v[84:85], s[88:89], 0, v[84:85]
	v_lshl_add_u64 v[84:85], v[84:85], 0, v[146:147]
	v_cvt_pk_bf16_f32 v91, v86, v87
	global_store_dwordx4 v[100:101], v[88:91], off offset:256 nt
	v_cvt_pk_bf16_f32 v64, v64, v65
	v_cvt_pk_bf16_f32 v65, v66, v67
	v_cvt_pk_bf16_f32 v66, v56, v57
	v_cvt_pk_bf16_f32 v67, v58, v59
	global_store_dwordx4 v[84:85], v[64:67], off nt
	v_cvt_pk_bf16_f32 v56, v60, v61
	v_cvt_pk_bf16_f32 v57, v62, v63
	v_cvt_pk_bf16_f32 v58, v52, v53
	s_mov_b32 s5, 0x80000
	v_cvt_pk_bf16_f32 v59, v54, v55
	global_store_dwordx4 v[84:85], v[56:59], off offset:256 nt
	s_mov_b64 s[16:17], 0x80000
	v_cvt_pk_bf16_f32 v52, v72, v73
	v_cvt_pk_bf16_f32 v53, v74, v75
	v_cvt_pk_bf16_f32 v54, v68, v69
	v_cvt_pk_bf16_f32 v55, v70, v71
	s_nop 0
	v_add_co_u32_e32 v58, vcc, s5, v132
	v_lshl_add_u64 v[56:57], v[132:133], 0, s[16:17]
	s_nop 0
	v_addc_co_u32_e32 v59, vcc, 0, v133, vcc
	s_mov_b32 s5, 0x90000
	global_store_dwordx4 v[58:59], v[52:55], off nt
	s_mov_b64 s[16:17], 0x90000
	s_mov_b32 s59, s4
	v_cvt_pk_bf16_f32 v52, v80, v81
	v_cvt_pk_bf16_f32 v53, v82, v83
	v_cvt_pk_bf16_f32 v54, v76, v77
	v_cvt_pk_bf16_f32 v55, v78, v79
	global_store_dwordx4 v[56:57], v[52:55], off offset:256 nt
	v_cvt_pk_bf16_f32 v40, v40, v41
	v_cvt_pk_bf16_f32 v41, v42, v43
	v_cvt_pk_bf16_f32 v42, v36, v37
	v_add_co_u32_e32 v36, vcc, s5, v132
	s_nop 0
	v_lshl_add_u64 v[52:53], v[132:133], 0, s[16:17]
	v_addc_co_u32_e32 v37, vcc, 0, v133, vcc
	s_mov_b32 s5, 0xa0000
	v_cvt_pk_bf16_f32 v43, v38, v39
	global_store_dwordx4 v[36:37], v[40:43], off nt
	v_cvt_pk_bf16_f32 v36, v48, v49
	v_cvt_pk_bf16_f32 v37, v50, v51
	v_cvt_pk_bf16_f32 v38, v44, v45
	v_cvt_pk_bf16_f32 v39, v46, v47
	global_store_dwordx4 v[52:53], v[36:39], off offset:256 nt
	s_mov_b64 s[16:17], 0xa0000
	v_cvt_pk_bf16_f32 v24, v24, v25
	v_cvt_pk_bf16_f32 v25, v26, v27
	v_cvt_pk_bf16_f32 v26, v20, v21
	v_add_co_u32_e32 v20, vcc, s5, v132
	v_lshl_add_u64 v[36:37], v[132:133], 0, s[16:17]
	s_nop 0
	v_addc_co_u32_e32 v21, vcc, 0, v133, vcc
	s_mov_b32 s5, 0xb0000
	v_cvt_pk_bf16_f32 v27, v22, v23
	global_store_dwordx4 v[20:21], v[24:27], off nt
	v_cvt_pk_bf16_f32 v20, v32, v33
	v_cvt_pk_bf16_f32 v21, v34, v35
	v_cvt_pk_bf16_f32 v22, v28, v29
	v_cvt_pk_bf16_f32 v23, v30, v31
	global_store_dwordx4 v[36:37], v[20:23], off offset:256 nt
	v_cvt_pk_bf16_f32 v8, v8, v9
	v_cvt_pk_bf16_f32 v9, v10, v11
	v_cvt_pk_bf16_f32 v10, v4, v5
	v_add_co_u32_e32 v4, vcc, s5, v132
	s_mov_b64 s[16:17], 0xb0000
	s_nop 0
	v_addc_co_u32_e32 v5, vcc, 0, v133, vcc
	v_lshl_add_u64 v[20:21], v[132:133], 0, s[16:17]
	s_andn2_b64 vcc, exec, s[6:7]
	s_mov_b32 s10, s8
	s_mov_b64 s[16:17], s[22:23]
	s_mov_b64 s[18:19], s[20:21]
	s_mov_b32 s9, s58
	v_cvt_pk_bf16_f32 v11, v6, v7
	global_store_dwordx4 v[4:5], v[8:11], off nt
	v_cvt_pk_bf16_f32 v4, v16, v17
	v_cvt_pk_bf16_f32 v5, v18, v19
	v_cvt_pk_bf16_f32 v6, v12, v13
	v_cvt_pk_bf16_f32 v7, v14, v15
	global_store_dwordx4 v[20:21], v[4:7], off offset:256 nt
	s_cbranch_vccnz .LBB0_143
	s_waitcnt vmcnt(0) lgkmcnt(0)
	s_barrier

; #define PG8_STAGE4(b, pa, pb) do { PG8_STAGE(PG8_SB(b, 0), (pb), voffB); PG8_STAGE(PG8_SA(b, 0), (pa), voffA); PG8_STAGE(PG8_SB(b, 1), (pb) + hstep, voffB); PG8_STAGE(PG8_SA(b, 1), (pa) + hstep, voffA); } while (0)
; #define PG8_SYNC() do { asm volatile("s_waitcnt vmcnt(0) lgkmcnt(0)" ::: "memory"); __builtin_amdgcn_s_barrier(); asm volatile("" ::: "memory"); } while (0)
; template <class Epi, class Sched>
; __device__ __forceinline__ void gemm_simple(PG8_LAS unsigned char* lds, const Gemm g, const Sched& S, const Epi& E, int wave_s) {
;     ...
;     for (int i = 0; i < 2; ++i) { int R, C; stage_rc(tid * 16 + i * 8192, R, C); const int Rb = Epi::PERM ? ((R & ~31) + perm32(R & 31)) : R;
;         voffA[i] = (unsigned)(R * K + C) * 2u; voffB[i] = (unsigned)(Rb * K + C) * 2u; }
;     const size_t kstep = (size_t)(BK * 2), hstep = (size_t)HALF * K * 2, tstep = 2 * hstep;
;     const unsigned ldsw = (unsigned)wid * 1024u; const unsigned lds_u = (unsigned)(__UINTPTR_TYPE__)lds;
;     const int aoff = lds_byte(wr * 64 + fr, fq * 8), boff = lds_byte(wc * 32 + fr, fq * 8);
;     ...
;     const char* cA = (const char*)g.A + (size_t)cur.pm * tstep; const char* cB = (const char*)g.Bt + (size_t)cur.pn * tstep;
;     PG8_SYNC();
;     PG8_STAGE4(0, cA, cB);
.LBB0_163:
	v_ashrrev_i32_e32 v4, 31, v2
	v_lshrrev_b32_e32 v4, 26, v4
	v_lshlrev_b32_e32 v3, 4, v2
	v_add_u32_e32 v4, v2, v4
	v_bfe_i32 v2, v2, 27, 1
	v_lshrrev_b32_e32 v2, 22, v2
	v_add_u32_e32 v2, v3, v2
	v_and_b32_e32 v2, 0xfffffc00, v2
	v_sub_u32_e32 v2, v3, v2
	s_waitcnt lgkmcnt(0)
	v_lshrrev_b32_e32 v5, 4, v2
	v_bitop3_b32 v2, v5, v2, 32 bitop3:0x6c
	v_ashrrev_i32_e32 v6, 31, v2
	v_ashrrev_i32_e32 v4, 6, v4
	v_lshrrev_b32_e32 v6, 26, v6
	v_lshlrev_b32_e32 v5, 3, v4
	v_add_u32_e32 v6, v2, v6
	v_and_b32_e32 v5, -16, v5
	v_ashrrev_i32_e32 v7, 6, v6
	v_and_b32_e32 v6, 0xc0, v6
	v_add_u32_e32 v5, v7, v5
	v_sub_u32_e32 v2, v2, v6
	s_ashr_i32 s4, s8, 3
	v_lshlrev_b32_e32 v4, 5, v4
	v_ashrrev_i16_sdwa v2, v166, sext(v2) dst_sel:DWORD dst_unused:UNUSED_PAD src0_sel:DWORD src1_sel:BYTE_0
	v_lshlrev_b32_e32 v6, 1, v5
	v_lshrrev_b32_e32 v8, 2, v5
	v_and_b32_e32 v7, 3, v7
	s_mov_b32 s8, 0x1fffe0
	v_and_b32_e32 v4, 32, v4
	v_bfe_i32 v2, v2, 0, 16
	v_and_b32_e32 v6, 24, v6
	v_and_b32_e32 v8, 4, v8
	v_and_or_b32 v7, v5, s8, v7
	v_or3_b32 v6, v7, v8, v6
	v_add_lshl_u32 v2, v4, v2, 1
	v_lshl_add_u32 v136, v5, 11, v2
	v_lshl_add_u32 v137, v6, 11, v2
	v_add_u32_e32 v2, 0x2000, v3
	v_ashrrev_i32_e32 v3, 31, v2
	v_lshrrev_b32_e32 v3, 22, v3
	v_add_u32_e32 v3, v2, v3
	v_ashrrev_i32_e32 v3, 10, v3
	v_mul_i32_i24_e32 v4, 0x400, v3
	v_sub_u32_e32 v2, v2, v4
	v_lshrrev_b32_e32 v4, 4, v2
	v_bitop3_b32 v2, v4, v2, 32 bitop3:0x6c
	v_ashrrev_i32_e32 v5, 31, v2
	v_lshrrev_b32_e32 v5, 26, v5
	v_lshlrev_b32_e32 v4, 3, v3
	v_add_u32_e32 v5, v2, v5
	v_and_b32_e32 v4, -16, v4
	v_ashrrev_i32_e32 v6, 6, v5
	v_and_b32_e32 v5, 0xc0, v5
	v_readlane_b32 s5, v254, 57
	v_add_u32_e32 v4, v6, v4
	v_sub_u32_e32 v2, v2, v5
	s_add_u32 s29, s5, 0x2c00000
	v_readlane_b32 s5, v254, 58
	v_lshlrev_b32_e32 v3, 5, v3
	v_ashrrev_i16_sdwa v2, v166, sext(v2) dst_sel:DWORD dst_unused:UNUSED_PAD src0_sel:DWORD src1_sel:BYTE_0
	v_lshlrev_b32_e32 v5, 1, v4
	v_lshrrev_b32_e32 v7, 2, v4
	v_and_b32_e32 v6, 3, v6
	s_addc_u32 s36, s5, 0
	s_ashr_i32 s5, s7, 6
	v_and_b32_e32 v3, 32, v3
	v_bfe_i32 v2, v2, 0, 16
	v_and_b32_e32 v5, 24, v5
	v_and_b32_e32 v7, 4, v7
	v_and_or_b32 v6, v4, s8, v6
	v_or3_b32 v5, v6, v7, v5
	v_add_lshl_u32 v2, v3, v2, 1
	s_lshl_b32 s8, s5, 10
	s_lshl_b32 s5, s5, 5
	v_lshl_add_u32 v138, v4, 11, v2
	v_lshl_add_u32 v139, v5, 11, v2
	v_and_b32_e32 v2, 48, v1
	v_lshlrev_b32_e32 v3, 6, v1
	s_movk_i32 s9, 0x3c0
	v_lshlrev_b32_e32 v1, 2, v1
	s_and_b32 s38, s5, 0x60
	v_and_or_b32 v2, v3, s9, v2
	v_and_b32_e32 v1, 32, v1
	s_lshl_b32 s5, s38, 7
	s_add_i32 s4, s6, s4
	v_bitop3_b32 v5, s5, v2, v1 bitop3:0xf6
	s_ashr_i32 s5, s4, 31
	s_lshr_b32 s5, s5, 27
	s_add_i32 s5, s4, s5
	s_ashr_i32 s6, s5, 5
	s_and_b32 s5, s5, 0xffe0
	s_ashr_i32 s37, s7, 2
	s_sub_i32 s5, s4, s5
	s_andn2_b32 s37, s37, 63
	s_bfe_i32 s4, s5, 0x80000
	s_lshl_b32 s7, s37, 7
	s_bfe_u32 s4, s4, 0x2000d
	v_bitop3_b32 v4, v2, s7, v1 bitop3:0xde
	s_add_i32 s7, s5, s4
	s_bfe_i32 s4, s7, 0x80000
	s_and_b32 s7, s7, 0xfc
	s_sub_i32 s5, s5, s7
	s_lshl_b32 s6, s6, 2
	s_sext_i32_i16 s9, s4
	s_sext_i32_i8 s5, s5
	s_lshr_b32 s4, s9, 2
	s_add_i32 s18, s6, s5
	s_ashr_i32 s19, s18, 31
	s_bfe_i64 s[4:5], s[4:5], 0x100000
	s_ashr_i32 s35, s9, 2
	s_lshl_b64 s[6:7], s[18:19], 19
	s_lshl_b64 s[4:5], s[4:5], 19
	s_add_u32 s20, s29, s4
	s_addc_u32 s21, s36, s5
	s_waitcnt vmcnt(0) lgkmcnt(0)
	s_barrier
	s_add_i32 s19, s8, 0
	s_add_i32 s39, s19, 0x10000
	s_mov_b32 m0, s39
	s_nop 0
	global_load_lds_dwordx4 v137, s[20:21]
	s_add_i32 s40, s19, 0x12000
	s_mov_b32 m0, s40
	s_nop 0
	global_load_lds_dwordx4 v139, s[20:21]
	v_mov_b32_e32 v1, v0
	v_readlane_b32 s4, v255, 4
	v_readlane_b32 s5, v255, 5
	s_add_u32 s22, s4, s6
	s_addc_u32 s23, s5, s7
	s_mov_b32 m0, s19
	s_nop 0
	global_load_lds_dwordx4 v136, s[22:23]
	s_add_i32 s41, s19, 0x2000
	s_mov_b32 m0, s41
	s_nop 0
	global_load_lds_dwordx4 v138, s[22:23]
	s_add_u32 s4, s20, 0x40000
	s_addc_u32 s5, s21, 0
	s_add_i32 s42, s19, 0x14000
	s_mov_b32 m0, s42
	s_nop 0
	global_load_lds_dwordx4 v137, s[4:5]
	s_add_i32 s43, s19, 0x16000
	s_mov_b32 m0, s43
	s_nop 0
	global_load_lds_dwordx4 v139, s[4:5]
	s_add_u32 s4, s22, 0x40000
	s_addc_u32 s5, s23, 0
	s_add_i32 s44, s19, 0x4000
	s_mov_b32 m0, s44
	s_nop 0
	global_load_lds_dwordx4 v136, s[4:5]
	s_add_i32 s45, s19, 0x6000
	s_mov_b32 m0, s45
	s_nop 0
	global_load_lds_dwordx4 v138, s[4:5]
	v_mov_b32_e32 v2, v0
	v_mov_b32_e32 v3, v0
	s_add_i32 s46, s19, 0x18000
	s_add_i32 s47, s19, 0x8000
	s_add_i32 s48, s19, 0x1c000
	s_add_i32 s49, s19, 0xc000
	s_add_i32 s50, s19, 0x1a000
	s_add_i32 s51, s19, 0xa000
	s_add_i32 s52, s19, 0x1e000
	s_add_i32 s53, s19, 0xe000
	s_ashr_i32 s54, s34, 31
	s_mov_b32 s9, 0
	v_add_u32_e32 v140, 0, v5
	v_add_u32_e32 v152, 0, v4

; template <class Epi, class Sched>
; __device__ __forceinline__ void gemm_simple(PG8_LAS unsigned char* lds, const Gemm g, const Sched& S, const Epi& E, int wave_s) {
;     ...
; #pragma unroll
;         for (int a = 0; a < 2; ++a)
; #pragma unroll
;             for (int b = 0; b < 2; ++b)
; #pragma unroll
;                 for (int m = 0; m < 4; ++m)
; #pragma unroll
;                     for (int n = 0; n < 2; ++n) acc[a][b][m][n] = (f32x4){zero_o, zero_o, zero_o, zero_o};
.LBB0_170:
	v_mov_b64_e32 v[10:11], v[2:3]
	v_mov_b64_e32 v[6:7], v[2:3]
	v_mov_b64_e32 v[22:23], v[2:3]
	v_mov_b64_e32 v[26:27], v[2:3]
	v_mov_b64_e32 v[38:39], v[2:3]
	v_mov_b64_e32 v[42:43], v[2:3]
	v_mov_b64_e32 v[54:55], v[2:3]
	v_mov_b64_e32 v[58:59], v[2:3]
	v_mov_b64_e32 v[14:15], v[2:3]
	v_mov_b64_e32 v[18:19], v[2:3]
	v_mov_b64_e32 v[30:31], v[2:3]
	v_mov_b64_e32 v[34:35], v[2:3]
	v_mov_b64_e32 v[46:47], v[2:3]
	v_mov_b64_e32 v[50:51], v[2:3]
	v_mov_b64_e32 v[62:63], v[2:3]
	v_mov_b64_e32 v[66:67], v[2:3]
	v_mov_b64_e32 v[70:71], v[2:3]
	v_mov_b64_e32 v[74:75], v[2:3]
	v_mov_b64_e32 v[86:87], v[2:3]
	v_mov_b64_e32 v[90:91], v[2:3]
	v_mov_b64_e32 v[102:103], v[2:3]
	v_mov_b64_e32 v[106:107], v[2:3]
	v_mov_b64_e32 v[118:119], v[2:3]
	v_mov_b64_e32 v[122:123], v[2:3]
	v_mov_b64_e32 v[78:79], v[2:3]
	v_mov_b64_e32 v[82:83], v[2:3]
	v_mov_b64_e32 v[94:95], v[2:3]
	v_mov_b64_e32 v[98:99], v[2:3]
	v_mov_b64_e32 v[110:111], v[2:3]
	v_mov_b64_e32 v[114:115], v[2:3]
	v_mov_b64_e32 v[126:127], v[2:3]
	v_mov_b64_e32 v[130:131], v[2:3]
	v_cmp_lt_i64_e32 vcc, s[10:11], v[168:169]
	s_mov_b32 s24, 0
	s_cmp_eq_u32 s9, 0
	v_add_u32_e32 v132, 0x10000, v140
	v_add_u32_e32 v133, 0x14000, v140
	v_add_u32_e32 v134, 0x18000, v140
	v_add_u32_e32 v135, 0x1c000, v140
	v_mov_b64_e32 v[8:9], v[0:1]
	v_mov_b64_e32 v[4:5], v[0:1]
	v_mov_b64_e32 v[20:21], v[0:1]
	v_mov_b64_e32 v[24:25], v[0:1]
	v_mov_b64_e32 v[36:37], v[0:1]
	v_mov_b64_e32 v[40:41], v[0:1]
	v_mov_b64_e32 v[52:53], v[0:1]
	v_mov_b64_e32 v[56:57], v[0:1]
	v_mov_b64_e32 v[12:13], v[0:1]
	v_mov_b64_e32 v[16:17], v[0:1]
	v_mov_b64_e32 v[28:29], v[0:1]
	v_mov_b64_e32 v[32:33], v[0:1]
	v_mov_b64_e32 v[44:45], v[0:1]
	v_mov_b64_e32 v[48:49], v[0:1]
	v_mov_b64_e32 v[60:61], v[0:1]
	v_mov_b64_e32 v[64:65], v[0:1]
	v_mov_b64_e32 v[68:69], v[0:1]
	v_mov_b64_e32 v[72:73], v[0:1]
	v_mov_b64_e32 v[84:85], v[0:1]
	v_mov_b64_e32 v[88:89], v[0:1]
	v_mov_b64_e32 v[100:101], v[0:1]
	v_mov_b64_e32 v[104:105], v[0:1]
	v_mov_b64_e32 v[116:117], v[0:1]
	v_mov_b64_e32 v[120:121], v[0:1]
	v_mov_b64_e32 v[76:77], v[0:1]
	v_mov_b64_e32 v[80:81], v[0:1]
	v_mov_b64_e32 v[92:93], v[0:1]
	v_mov_b64_e32 v[96:97], v[0:1]
	v_mov_b64_e32 v[108:109], v[0:1]
	v_mov_b64_e32 v[112:113], v[0:1]
	v_mov_b64_e32 v[124:125], v[0:1]
	v_mov_b64_e32 v[128:129], v[0:1]
	s_cbranch_scc1 .LBB0_172
	s_waitcnt vmcnt(18) lgkmcnt(0)
	s_barrier
	ds_read_b128 v[4:7], v132
	ds_read_b128 v[8:11], v132 offset:1024
	ds_read_b128 v[12:15], v132 offset:2048
	ds_read_b128 v[16:19], v132 offset:3072
	ds_read_b128 v[20:23], v152
	ds_read_b128 v[24:27], v152 offset:1024
	ds_read_b128 v[28:31], v152 offset:2048
	ds_read_b128 v[32:35], v152 offset:3072
	ds_read_b128 v[36:39], v152 offset:4096
	ds_read_b128 v[40:43], v152 offset:5120
	ds_read_b128 v[44:47], v152 offset:6144
	ds_read_b128 v[48:51], v152 offset:7168
	ds_read_b128 v[52:55], v133
	ds_read_b128 v[56:59], v133 offset:1024
	ds_read_b128 v[60:63], v133 offset:2048
	ds_read_b128 v[64:67], v133 offset:3072
	s_add_u32 s10, s20, 0x80
	s_addc_u32 s11, s21, 0
	s_mov_b32 m0, s46
	s_nop 0
	global_load_lds_dwordx4 v137, s[10:11]
	s_mov_b32 m0, s50
	s_nop 0
	global_load_lds_dwordx4 v139, s[10:11]
	s_waitcnt lgkmcnt(5)
	v_mfma_f32_16x16x32_bf16 v[92:95], v[4:7], v[44:47], v[0:3]
	v_mfma_f32_16x16x32_bf16 v[68:71], v[4:7], v[20:23], v[0:3]
	v_mfma_f32_16x16x32_bf16 v[72:75], v[12:15], v[20:23], v[0:3]
	v_mfma_f32_16x16x32_bf16 v[76:79], v[4:7], v[28:31], v[0:3]
	v_mfma_f32_16x16x32_bf16 v[80:83], v[12:15], v[28:31], v[0:3]
	v_mfma_f32_16x16x32_bf16 v[84:87], v[4:7], v[36:39], v[0:3]
	v_mfma_f32_16x16x32_bf16 v[88:91], v[12:15], v[36:39], v[0:3]
	s_waitcnt lgkmcnt(4)
	v_mfma_f32_16x16x32_bf16 v[100:103], v[8:11], v[48:51], v[92:95]
	v_mfma_f32_16x16x32_bf16 v[92:95], v[12:15], v[44:47], v[0:3]
	v_mfma_f32_16x16x32_bf16 v[68:71], v[8:11], v[24:27], v[68:71]
	v_mfma_f32_16x16x32_bf16 v[72:75], v[16:19], v[24:27], v[72:75]
	v_mfma_f32_16x16x32_bf16 v[76:79], v[8:11], v[32:35], v[76:79]
	v_mfma_f32_16x16x32_bf16 v[80:83], v[16:19], v[32:35], v[80:83]
	v_mfma_f32_16x16x32_bf16 v[84:87], v[8:11], v[40:43], v[84:87]
	v_mfma_f32_16x16x32_bf16 v[88:91], v[16:19], v[40:43], v[88:91]
	v_mfma_f32_16x16x32_bf16 v[104:107], v[16:19], v[48:51], v[92:95]
	s_add_u32 s10, s22, 0x80
	s_addc_u32 s11, s23, 0
	s_mov_b32 m0, s47
	s_nop 0
	global_load_lds_dwordx4 v136, s[10:11]
	s_mov_b32 m0, s51
	s_nop 0
	global_load_lds_dwordx4 v138, s[10:11]
	s_waitcnt lgkmcnt(3)
	v_mfma_f32_16x16x32_bf16 v[92:95], v[52:55], v[20:23], v[0:3]
	s_waitcnt lgkmcnt(1)
	v_mfma_f32_16x16x32_bf16 v[20:23], v[60:63], v[20:23], v[0:3]
	v_mfma_f32_16x16x32_bf16 v[116:119], v[56:59], v[24:27], v[92:95]
	s_waitcnt lgkmcnt(0)
	v_mfma_f32_16x16x32_bf16 v[20:23], v[64:67], v[24:27], v[20:23]
	v_mfma_f32_16x16x32_bf16 v[24:27], v[52:55], v[28:31], v[0:3]
	v_mfma_f32_16x16x32_bf16 v[28:31], v[60:63], v[28:31], v[0:3]
	v_mfma_f32_16x16x32_bf16 v[24:27], v[56:59], v[32:35], v[24:27]
	v_mfma_f32_16x16x32_bf16 v[28:31], v[64:67], v[32:35], v[28:31]
	v_mfma_f32_16x16x32_bf16 v[32:35], v[52:55], v[36:39], v[0:3]
	v_mfma_f32_16x16x32_bf16 v[36:39], v[60:63], v[36:39], v[0:3]
	v_mfma_f32_16x16x32_bf16 v[32:35], v[56:59], v[40:43], v[32:35]
	v_mfma_f32_16x16x32_bf16 v[36:39], v[64:67], v[40:43], v[36:39]
	v_mfma_f32_16x16x32_bf16 v[40:43], v[52:55], v[44:47], v[0:3]
	v_mfma_f32_16x16x32_bf16 v[44:47], v[60:63], v[44:47], v[0:3]
	v_mfma_f32_16x16x32_bf16 v[40:43], v[56:59], v[48:51], v[40:43]
	v_mfma_f32_16x16x32_bf16 v[44:47], v[64:67], v[48:51], v[44:47]
	s_waitcnt vmcnt(20) lgkmcnt(0)
	s_barrier
; template <class Epi, class Sched>
; __device__ __forceinline__ void gemm_simple(PG8_LAS unsigned char* lds, const Gemm g, const Sched& S, const Epi& E, int wave_s) {
;     ...
;             if constexpr (Epi::NST >= 16) PG8_TILE_W(0, cA + kstep, cB + kstep, "18", "20"); else PG8_TILE_W(0, cA + kstep, cB + kstep, "10", "12");
;             PG8_TILE_W(1, cA + 2 * kstep, cB + 2 * kstep, "2", "4");
	ds_read_b128 v[48:51], v152 offset:16384
	ds_read_b128 v[92:95], v152 offset:17408
	ds_read_b128 v[96:99], v152 offset:18432
	ds_read_b128 v[108:111], v152 offset:19456
	ds_read_b128 v[112:115], v152 offset:20480
	ds_read_b128 v[120:123], v152 offset:21504
	ds_read_b128 v[124:127], v152 offset:22528
	ds_read_b128 v[128:131], v152 offset:23552
	s_add_u32 s10, s20, 0x40080
	s_addc_u32 s11, s21, 0
	s_mov_b32 m0, s48
	s_nop 0
	global_load_lds_dwordx4 v137, s[10:11]
	s_mov_b32 m0, s52
	s_nop 0
	global_load_lds_dwordx4 v139, s[10:11]
	s_waitcnt lgkmcnt(7)
	v_mfma_f32_16x16x32_bf16 v[146:149], v[4:7], v[48:51], v[0:3]
	s_waitcnt lgkmcnt(5)
	v_mfma_f32_16x16x32_bf16 v[158:161], v[4:7], v[96:99], v[0:3]
	s_waitcnt lgkmcnt(3)
	v_mfma_f32_16x16x32_bf16 v[174:177], v[4:7], v[112:115], v[0:3]
	s_waitcnt lgkmcnt(1)
	v_mfma_f32_16x16x32_bf16 v[4:7], v[4:7], v[124:127], v[0:3]
	v_mfma_f32_16x16x32_bf16 v[146:149], v[8:11], v[92:95], v[146:149]
	v_mfma_f32_16x16x32_bf16 v[158:161], v[8:11], v[108:111], v[158:161]
	v_mfma_f32_16x16x32_bf16 v[174:177], v[8:11], v[120:123], v[174:177]
	s_waitcnt lgkmcnt(0)
	v_mfma_f32_16x16x32_bf16 v[4:7], v[8:11], v[128:131], v[4:7]
	v_mfma_f32_16x16x32_bf16 v[8:11], v[12:15], v[124:127], v[0:3]
	v_mfma_f32_16x16x32_bf16 v[154:157], v[12:15], v[48:51], v[0:3]
	v_mfma_f32_16x16x32_bf16 v[170:173], v[12:15], v[96:99], v[0:3]
	v_mfma_f32_16x16x32_bf16 v[178:181], v[12:15], v[112:115], v[0:3]
	v_mfma_f32_16x16x32_bf16 v[8:11], v[16:19], v[128:131], v[8:11]
	v_mfma_f32_16x16x32_bf16 v[154:157], v[16:19], v[92:95], v[154:157]
	v_mfma_f32_16x16x32_bf16 v[170:173], v[16:19], v[108:111], v[170:173]
	v_mfma_f32_16x16x32_bf16 v[178:181], v[16:19], v[120:123], v[178:181]
	s_add_u32 s10, s22, 0x40080
	s_addc_u32 s11, s23, 0
	s_mov_b32 m0, s49
	s_nop 0
	global_load_lds_dwordx4 v136, s[10:11]
	s_mov_b32 m0, s53
	s_nop 0
	global_load_lds_dwordx4 v138, s[10:11]
	v_mfma_f32_16x16x32_bf16 v[12:15], v[52:55], v[48:51], v[0:3]
	v_mfma_f32_16x16x32_bf16 v[182:185], v[56:59], v[92:95], v[12:15]
	v_mfma_f32_16x16x32_bf16 v[12:15], v[60:63], v[48:51], v[0:3]
	v_mfma_f32_16x16x32_bf16 v[186:189], v[64:67], v[92:95], v[12:15]
	v_mfma_f32_16x16x32_bf16 v[12:15], v[52:55], v[96:99], v[0:3]
	v_mfma_f32_16x16x32_bf16 v[190:193], v[56:59], v[108:111], v[12:15]
	v_mfma_f32_16x16x32_bf16 v[12:15], v[60:63], v[96:99], v[0:3]
	v_mfma_f32_16x16x32_bf16 v[194:197], v[64:67], v[108:111], v[12:15]
	v_mfma_f32_16x16x32_bf16 v[12:15], v[52:55], v[112:115], v[0:3]
	v_mfma_f32_16x16x32_bf16 v[198:201], v[56:59], v[120:123], v[12:15]
	v_mfma_f32_16x16x32_bf16 v[12:15], v[60:63], v[112:115], v[0:3]
	v_mfma_f32_16x16x32_bf16 v[202:205], v[64:67], v[120:123], v[12:15]
	v_mfma_f32_16x16x32_bf16 v[12:15], v[52:55], v[124:127], v[0:3]
	v_mfma_f32_16x16x32_bf16 v[206:209], v[56:59], v[128:131], v[12:15]
	v_mfma_f32_16x16x32_bf16 v[12:15], v[60:63], v[124:127], v[0:3]
	v_mfma_f32_16x16x32_bf16 v[210:213], v[64:67], v[128:131], v[12:15]
	s_waitcnt vmcnt(2) lgkmcnt(0)
	s_barrier
	s_nop 5
	ds_read_b128 v[12:15], v134
	ds_read_b128 v[16:19], v134 offset:1024
	ds_read_b128 v[52:55], v134 offset:2048
	ds_read_b128 v[56:59], v134 offset:3072
	ds_read_b128 v[48:51], v152 offset:32768
	ds_read_b128 v[60:63], v152 offset:33792
	ds_read_b128 v[64:67], v152 offset:34816
	ds_read_b128 v[214:217], v152 offset:35840
	ds_read_b128 v[218:221], v152 offset:36864
	ds_read_b128 v[222:225], v152 offset:37888
	ds_read_b128 v[226:229], v152 offset:38912
	ds_read_b128 v[230:233], v152 offset:39936
	ds_read_b128 v[234:237], v135
	ds_read_b128 v[238:241], v135 offset:1024
	ds_read_b128 v[242:245], v135 offset:2048
	ds_read_b128 v[246:249], v135 offset:3072
	s_add_u32 s10, s20, 0x100
	s_addc_u32 s11, s21, 0
	s_mov_b32 m0, s39
	s_nop 0
	global_load_lds_dwordx4 v137, s[10:11]
	s_mov_b32 m0, s40
	s_nop 0
	global_load_lds_dwordx4 v139, s[10:11]
	s_waitcnt lgkmcnt(11)
	v_mfma_f32_16x16x32_bf16 v[68:71], v[12:15], v[48:51], v[68:71]
	s_waitcnt lgkmcnt(10)
	v_mfma_f32_16x16x32_bf16 v[128:131], v[16:19], v[60:63], v[68:71]
	v_mfma_f32_16x16x32_bf16 v[68:71], v[52:55], v[48:51], v[72:75]
	v_mfma_f32_16x16x32_bf16 v[124:127], v[56:59], v[60:63], v[68:71]
	s_waitcnt lgkmcnt(9)
	v_mfma_f32_16x16x32_bf16 v[68:71], v[12:15], v[64:67], v[76:79]
	s_waitcnt lgkmcnt(8)
	v_mfma_f32_16x16x32_bf16 v[112:115], v[16:19], v[214:217], v[68:71]
	v_mfma_f32_16x16x32_bf16 v[68:71], v[52:55], v[64:67], v[80:83]
	v_mfma_f32_16x16x32_bf16 v[108:111], v[56:59], v[214:217], v[68:71]
	s_waitcnt lgkmcnt(7)
	v_mfma_f32_16x16x32_bf16 v[68:71], v[12:15], v[218:221], v[84:87]
	s_waitcnt lgkmcnt(6)
	v_mfma_f32_16x16x32_bf16 v[96:99], v[16:19], v[222:225], v[68:71]
	v_mfma_f32_16x16x32_bf16 v[68:71], v[52:55], v[218:221], v[88:91]
	v_mfma_f32_16x16x32_bf16 v[92:95], v[56:59], v[222:225], v[68:71]
	s_waitcnt lgkmcnt(5)
	v_mfma_f32_16x16x32_bf16 v[68:71], v[12:15], v[226:229], v[100:103]
	s_waitcnt lgkmcnt(4)
	v_mfma_f32_16x16x32_bf16 v[80:83], v[16:19], v[230:233], v[68:71]
	v_mfma_f32_16x16x32_bf16 v[68:71], v[52:55], v[226:229], v[104:107]
	v_mfma_f32_16x16x32_bf16 v[76:79], v[56:59], v[230:233], v[68:71]
	s_add_u32 s10, s22, 0x100
	s_addc_u32 s11, s23, 0
	s_mov_b32 m0, s19
	s_nop 0
	global_load_lds_dwordx4 v136, s[10:11]
	s_mov_b32 m0, s41
	s_nop 0
	global_load_lds_dwordx4 v138, s[10:11]
	s_waitcnt lgkmcnt(1)
	v_mfma_f32_16x16x32_bf16 v[20:23], v[242:245], v[48:51], v[20:23]
	v_mfma_f32_16x16x32_bf16 v[68:71], v[234:237], v[48:51], v[116:119]
	s_waitcnt lgkmcnt(0)
	v_mfma_f32_16x16x32_bf16 v[116:119], v[246:249], v[60:63], v[20:23]
	v_mfma_f32_16x16x32_bf16 v[20:23], v[234:237], v[64:67], v[24:27]
	v_mfma_f32_16x16x32_bf16 v[104:107], v[238:241], v[214:217], v[20:23]
	v_mfma_f32_16x16x32_bf16 v[20:23], v[242:245], v[64:67], v[28:31]
	v_mfma_f32_16x16x32_bf16 v[100:103], v[246:249], v[214:217], v[20:23]
	v_mfma_f32_16x16x32_bf16 v[20:23], v[234:237], v[218:221], v[32:35]
	v_mfma_f32_16x16x32_bf16 v[88:91], v[238:241], v[222:225], v[20:23]
	v_mfma_f32_16x16x32_bf16 v[20:23], v[242:245], v[218:221], v[36:39]
	v_mfma_f32_16x16x32_bf16 v[84:87], v[246:249], v[222:225], v[20:23]
	v_mfma_f32_16x16x32_bf16 v[20:23], v[234:237], v[226:229], v[40:43]
	v_mfma_f32_16x16x32_bf16 v[72:75], v[238:241], v[230:233], v[20:23]
	v_mfma_f32_16x16x32_bf16 v[20:23], v[242:245], v[226:229], v[44:47]
	v_mfma_f32_16x16x32_bf16 v[120:123], v[238:241], v[60:63], v[68:71]
	v_mfma_f32_16x16x32_bf16 v[68:71], v[246:249], v[230:233], v[20:23]
	s_waitcnt vmcnt(4) lgkmcnt(0)
	s_barrier
; template <class Epi, class Sched>
; __device__ __forceinline__ void gemm_simple(PG8_LAS unsigned char* lds, const Gemm g, const Sched& S, const Epi& E, int wave_s) {
;     ...
;             PG8_TILE_W(1, cA + 2 * kstep, cB + 2 * kstep, "2", "4");
;             t = 2;
	s_nop 4
	ds_read_b128 v[20:23], v152 offset:49152
	ds_read_b128 v[24:27], v152 offset:50176
	ds_read_b128 v[36:39], v152 offset:51200
	ds_read_b128 v[214:217], v152 offset:52224
	ds_read_b128 v[218:221], v152 offset:53248
	ds_read_b128 v[222:225], v152 offset:54272
	ds_read_b128 v[226:229], v152 offset:55296
	ds_read_b128 v[230:233], v152 offset:56320
	s_add_u32 s10, s20, 0x40100
	s_addc_u32 s11, s21, 0
	s_mov_b32 m0, s42
	s_nop 0
	global_load_lds_dwordx4 v137, s[10:11]
	s_mov_b32 m0, s43
	s_nop 0
	global_load_lds_dwordx4 v139, s[10:11]
	s_waitcnt lgkmcnt(7)
	v_mfma_f32_16x16x32_bf16 v[28:31], v[12:15], v[20:23], v[146:149]
	s_waitcnt lgkmcnt(6)
	v_mfma_f32_16x16x32_bf16 v[64:67], v[16:19], v[24:27], v[28:31]
	v_mfma_f32_16x16x32_bf16 v[28:31], v[52:55], v[20:23], v[154:157]
	v_mfma_f32_16x16x32_bf16 v[60:63], v[56:59], v[24:27], v[28:31]
	s_waitcnt lgkmcnt(5)
	v_mfma_f32_16x16x32_bf16 v[28:31], v[12:15], v[36:39], v[158:161]
	s_waitcnt lgkmcnt(4)
	v_mfma_f32_16x16x32_bf16 v[48:51], v[16:19], v[214:217], v[28:31]
	v_mfma_f32_16x16x32_bf16 v[28:31], v[52:55], v[36:39], v[170:173]
	v_mfma_f32_16x16x32_bf16 v[44:47], v[56:59], v[214:217], v[28:31]
	s_waitcnt lgkmcnt(3)
	v_mfma_f32_16x16x32_bf16 v[28:31], v[12:15], v[218:221], v[174:177]
	s_waitcnt lgkmcnt(1)
	v_mfma_f32_16x16x32_bf16 v[4:7], v[12:15], v[226:229], v[4:7]
	v_mfma_f32_16x16x32_bf16 v[32:35], v[16:19], v[222:225], v[28:31]
	v_mfma_f32_16x16x32_bf16 v[28:31], v[52:55], v[218:221], v[178:181]
	s_waitcnt lgkmcnt(0)
	v_mfma_f32_16x16x32_bf16 v[16:19], v[16:19], v[230:233], v[4:7]
	v_mfma_f32_16x16x32_bf16 v[4:7], v[52:55], v[226:229], v[8:11]
	v_mfma_f32_16x16x32_bf16 v[28:31], v[56:59], v[222:225], v[28:31]
	v_mfma_f32_16x16x32_bf16 v[12:15], v[56:59], v[230:233], v[4:7]
	s_add_u32 s10, s22, 0x40100
	s_addc_u32 s11, s23, 0
	s_mov_b32 m0, s44
	s_nop 0
	global_load_lds_dwordx4 v136, s[10:11]
	s_mov_b32 m0, s45
	s_nop 0
	global_load_lds_dwordx4 v138, s[10:11]
	v_mfma_f32_16x16x32_bf16 v[4:7], v[234:237], v[20:23], v[182:185]
	s_mov_b32 s24, 2
	v_mfma_f32_16x16x32_bf16 v[56:59], v[238:241], v[24:27], v[4:7]
	v_mfma_f32_16x16x32_bf16 v[4:7], v[242:245], v[20:23], v[186:189]
	v_mfma_f32_16x16x32_bf16 v[52:55], v[246:249], v[24:27], v[4:7]
	v_mfma_f32_16x16x32_bf16 v[4:7], v[234:237], v[36:39], v[190:193]
	v_mfma_f32_16x16x32_bf16 v[40:43], v[238:241], v[214:217], v[4:7]
	v_mfma_f32_16x16x32_bf16 v[4:7], v[242:245], v[36:39], v[194:197]
	v_mfma_f32_16x16x32_bf16 v[36:39], v[246:249], v[214:217], v[4:7]
	v_mfma_f32_16x16x32_bf16 v[4:7], v[234:237], v[218:221], v[198:201]
	v_mfma_f32_16x16x32_bf16 v[24:27], v[238:241], v[222:225], v[4:7]
	v_mfma_f32_16x16x32_bf16 v[4:7], v[242:245], v[218:221], v[202:205]
	v_mfma_f32_16x16x32_bf16 v[20:23], v[246:249], v[222:225], v[4:7]
	v_mfma_f32_16x16x32_bf16 v[4:7], v[234:237], v[226:229], v[206:209]
	v_mfma_f32_16x16x32_bf16 v[8:11], v[242:245], v[226:229], v[210:213]
	v_mfma_f32_16x16x32_bf16 v[4:7], v[238:241], v[230:233], v[4:7]
	v_mfma_f32_16x16x32_bf16 v[8:11], v[246:249], v[230:233], v[8:11]

; template <class Epi, class Sched>
; __device__ __forceinline__ void gemm_simple(PG8_LAS unsigned char* lds, const Gemm g, const Sched& S, const Epi& E, int wave_s) {
;     ...
;         for (; t < nt; t += 2) {
;             const bool last = (t == nt - 2);
;             PG8_TILE(0, cA + (size_t)(t + 1) * kstep, cB + (size_t)(t + 1) * kstep, true);
.LBB0_173:
	s_waitcnt vmcnt(2) lgkmcnt(0)
	s_barrier
	ds_read_b128 v[146:149], v132
	ds_read_b128 v[174:177], v152
	ds_read_b128 v[158:161], v132 offset:2048
	ds_read_b128 v[182:185], v152 offset:2048
	ds_read_b128 v[190:193], v152 offset:4096
	ds_read_b128 v[198:201], v152 offset:6144
	ds_read_b128 v[154:157], v132 offset:1024
	ds_read_b128 v[178:181], v152 offset:1024
	ds_read_b128 v[170:173], v132 offset:3072
	ds_read_b128 v[186:189], v152 offset:3072
	ds_read_b128 v[194:197], v152 offset:5120
	ds_read_b128 v[202:205], v152 offset:7168
	ds_read_b128 v[206:209], v133
	ds_read_b128 v[214:217], v133 offset:2048
	ds_read_b128 v[210:213], v133 offset:1024
	ds_read_b128 v[218:221], v133 offset:3072
	s_add_u32 s60, s20, s59
	s_addc_u32 s61, s21, 0
	s_add_u32 s26, s60, 0x80
	s_addc_u32 s27, s61, 0
	s_mov_b32 m0, s46
	s_nop 0
	global_load_lds_dwordx4 v137, s[26:27]
	s_mov_b32 m0, s50
	s_nop 0
	global_load_lds_dwordx4 v139, s[26:27]
	s_waitcnt lgkmcnt(14)
	v_mfma_f32_16x16x32_bf16 v[128:131], v[146:149], v[174:177], v[128:131]
	s_waitcnt lgkmcnt(13)
	v_mfma_f32_16x16x32_bf16 v[124:127], v[158:161], v[174:177], v[124:127]
	s_waitcnt lgkmcnt(12)
	v_mfma_f32_16x16x32_bf16 v[112:115], v[146:149], v[182:185], v[112:115]
	v_mfma_f32_16x16x32_bf16 v[108:111], v[158:161], v[182:185], v[108:111]
	s_waitcnt lgkmcnt(11)
	v_mfma_f32_16x16x32_bf16 v[96:99], v[146:149], v[190:193], v[96:99]
	v_mfma_f32_16x16x32_bf16 v[92:95], v[158:161], v[190:193], v[92:95]
	s_waitcnt lgkmcnt(10)
	v_mfma_f32_16x16x32_bf16 v[80:83], v[146:149], v[198:201], v[80:83]
	v_mfma_f32_16x16x32_bf16 v[76:79], v[158:161], v[198:201], v[76:79]
	s_waitcnt lgkmcnt(8)
	v_mfma_f32_16x16x32_bf16 v[128:131], v[154:157], v[178:181], v[128:131]
	s_waitcnt lgkmcnt(7)
	v_mfma_f32_16x16x32_bf16 v[124:127], v[170:173], v[178:181], v[124:127]
	s_waitcnt lgkmcnt(6)
	v_mfma_f32_16x16x32_bf16 v[112:115], v[154:157], v[186:189], v[112:115]
	v_mfma_f32_16x16x32_bf16 v[108:111], v[170:173], v[186:189], v[108:111]
	s_waitcnt lgkmcnt(5)
	v_mfma_f32_16x16x32_bf16 v[96:99], v[154:157], v[194:197], v[96:99]
	v_mfma_f32_16x16x32_bf16 v[92:95], v[170:173], v[194:197], v[92:95]
	s_waitcnt lgkmcnt(4)
	v_mfma_f32_16x16x32_bf16 v[80:83], v[154:157], v[202:205], v[80:83]
	v_mfma_f32_16x16x32_bf16 v[76:79], v[170:173], v[202:205], v[76:79]
	s_add_u32 s62, s22, s59
	s_addc_u32 s63, s23, 0
	s_add_u32 s26, s62, 0x80
	s_addc_u32 s27, s63, 0
	s_mov_b32 m0, s47
	s_nop 0
	global_load_lds_dwordx4 v136, s[26:27]
	s_mov_b32 m0, s51
	s_nop 0
	global_load_lds_dwordx4 v138, s[26:27]
	s_waitcnt lgkmcnt(3)
	v_mfma_f32_16x16x32_bf16 v[120:123], v[206:209], v[174:177], v[120:123]
	s_waitcnt lgkmcnt(2)
	v_mfma_f32_16x16x32_bf16 v[116:119], v[214:217], v[174:177], v[116:119]
	v_mfma_f32_16x16x32_bf16 v[104:107], v[206:209], v[182:185], v[104:107]
	v_mfma_f32_16x16x32_bf16 v[100:103], v[214:217], v[182:185], v[100:103]
	v_mfma_f32_16x16x32_bf16 v[88:91], v[206:209], v[190:193], v[88:91]
	v_mfma_f32_16x16x32_bf16 v[84:87], v[214:217], v[190:193], v[84:87]
	v_mfma_f32_16x16x32_bf16 v[72:75], v[206:209], v[198:201], v[72:75]
	v_mfma_f32_16x16x32_bf16 v[68:71], v[214:217], v[198:201], v[68:71]
	s_waitcnt lgkmcnt(1)
	v_mfma_f32_16x16x32_bf16 v[120:123], v[210:213], v[178:181], v[120:123]
	s_waitcnt lgkmcnt(0)
	v_mfma_f32_16x16x32_bf16 v[116:119], v[218:221], v[178:181], v[116:119]
	v_mfma_f32_16x16x32_bf16 v[104:107], v[210:213], v[186:189], v[104:107]
	v_mfma_f32_16x16x32_bf16 v[100:103], v[218:221], v[186:189], v[100:103]
	v_mfma_f32_16x16x32_bf16 v[88:91], v[210:213], v[194:197], v[88:91]
	v_mfma_f32_16x16x32_bf16 v[84:87], v[218:221], v[194:197], v[84:87]
	v_mfma_f32_16x16x32_bf16 v[72:75], v[210:213], v[202:205], v[72:75]
	v_mfma_f32_16x16x32_bf16 v[68:71], v[218:221], v[202:205], v[68:71]
	s_waitcnt vmcnt(4) lgkmcnt(0)
	s_barrier
	ds_read_b128 v[174:177], v152 offset:16384
	ds_read_b128 v[182:185], v152 offset:18432
	ds_read_b128 v[190:193], v152 offset:20480
	ds_read_b128 v[198:201], v152 offset:22528
	ds_read_b128 v[178:181], v152 offset:17408
	ds_read_b128 v[186:189], v152 offset:19456
	ds_read_b128 v[194:197], v152 offset:21504
	ds_read_b128 v[202:205], v152 offset:23552
	s_add_u32 s26, s60, 0x40080
	s_addc_u32 s27, s61, 0
	s_mov_b32 m0, s48
	s_nop 0
	global_load_lds_dwordx4 v137, s[26:27]
	s_mov_b32 m0, s52
	s_nop 0
	global_load_lds_dwordx4 v139, s[26:27]
	s_waitcnt lgkmcnt(7)
	v_mfma_f32_16x16x32_bf16 v[64:67], v[146:149], v[174:177], v[64:67]
	v_mfma_f32_16x16x32_bf16 v[60:63], v[158:161], v[174:177], v[60:63]
	s_waitcnt lgkmcnt(6)
	v_mfma_f32_16x16x32_bf16 v[48:51], v[146:149], v[182:185], v[48:51]
	v_mfma_f32_16x16x32_bf16 v[44:47], v[158:161], v[182:185], v[44:47]
	s_waitcnt lgkmcnt(5)
	v_mfma_f32_16x16x32_bf16 v[32:35], v[146:149], v[190:193], v[32:35]
	v_mfma_f32_16x16x32_bf16 v[28:31], v[158:161], v[190:193], v[28:31]
	s_waitcnt lgkmcnt(4)
	v_mfma_f32_16x16x32_bf16 v[16:19], v[146:149], v[198:201], v[16:19]
	v_mfma_f32_16x16x32_bf16 v[12:15], v[158:161], v[198:201], v[12:15]
	s_waitcnt lgkmcnt(3)
	v_mfma_f32_16x16x32_bf16 v[64:67], v[154:157], v[178:181], v[64:67]
	v_mfma_f32_16x16x32_bf16 v[60:63], v[170:173], v[178:181], v[60:63]
	s_waitcnt lgkmcnt(2)
	v_mfma_f32_16x16x32_bf16 v[48:51], v[154:157], v[186:189], v[48:51]
	v_mfma_f32_16x16x32_bf16 v[44:47], v[170:173], v[186:189], v[44:47]
	s_waitcnt lgkmcnt(1)
	v_mfma_f32_16x16x32_bf16 v[32:35], v[154:157], v[194:197], v[32:35]
	v_mfma_f32_16x16x32_bf16 v[28:31], v[170:173], v[194:197], v[28:31]
	s_waitcnt lgkmcnt(0)
	v_mfma_f32_16x16x32_bf16 v[16:19], v[154:157], v[202:205], v[16:19]
	v_mfma_f32_16x16x32_bf16 v[12:15], v[170:173], v[202:205], v[12:15]
	s_add_u32 s26, s62, 0x40080
	s_addc_u32 s27, s63, 0
	s_mov_b32 m0, s49
	s_nop 0
	global_load_lds_dwordx4 v136, s[26:27]
	s_mov_b32 m0, s53
	s_nop 0
	global_load_lds_dwordx4 v138, s[26:27]
	v_mfma_f32_16x16x32_bf16 v[56:59], v[206:209], v[174:177], v[56:59]
	s_add_u32 s26, s62, 0x100
	s_addc_u32 s27, s63, 0
	s_add_u32 s60, s60, 0x100
	v_mfma_f32_16x16x32_bf16 v[52:55], v[214:217], v[174:177], v[52:55]
	s_addc_u32 s61, s61, 0
	v_mfma_f32_16x16x32_bf16 v[40:43], v[206:209], v[182:185], v[40:43]
	v_mfma_f32_16x16x32_bf16 v[36:39], v[214:217], v[182:185], v[36:39]
	v_mfma_f32_16x16x32_bf16 v[24:27], v[206:209], v[190:193], v[24:27]
	v_mfma_f32_16x16x32_bf16 v[20:23], v[214:217], v[190:193], v[20:23]
	v_mfma_f32_16x16x32_bf16 v[4:7], v[206:209], v[198:201], v[4:7]
	v_mfma_f32_16x16x32_bf16 v[8:11], v[214:217], v[198:201], v[8:11]
	v_mfma_f32_16x16x32_bf16 v[56:59], v[210:213], v[178:181], v[56:59]
	v_mfma_f32_16x16x32_bf16 v[52:55], v[218:221], v[178:181], v[52:55]
	v_mfma_f32_16x16x32_bf16 v[40:43], v[210:213], v[186:189], v[40:43]
	v_mfma_f32_16x16x32_bf16 v[36:39], v[218:221], v[186:189], v[36:39]
	v_mfma_f32_16x16x32_bf16 v[24:27], v[210:213], v[194:197], v[24:27]
	v_mfma_f32_16x16x32_bf16 v[20:23], v[218:221], v[194:197], v[20:23]
	v_mfma_f32_16x16x32_bf16 v[4:7], v[210:213], v[202:205], v[4:7]
	v_mfma_f32_16x16x32_bf16 v[8:11], v[218:221], v[202:205], v[8:11]
	s_waitcnt vmcnt(2) lgkmcnt(0)
	s_barrier
; template <class Epi, class Sched>
; __device__ __forceinline__ void gemm_simple(PG8_LAS unsigned char* lds, const Gemm g, const Sched& S, const Epi& E, int wave_s) {
;     ...
;             const char* a2 = last ? nA : cA + (size_t)(t + 2) * kstep; const char* b2 = last ? nB : cB + (size_t)(t + 2) * kstep;
;             PG8_TILE(1, a2, b2, (!last || has_next));
	ds_read_b128 v[146:149], v134
	ds_read_b128 v[174:177], v152 offset:32768
	ds_read_b128 v[158:161], v134 offset:2048
	ds_read_b128 v[182:185], v152 offset:34816
	ds_read_b128 v[190:193], v152 offset:36864
	ds_read_b128 v[198:201], v152 offset:38912
	ds_read_b128 v[154:157], v134 offset:1024
	ds_read_b128 v[178:181], v152 offset:33792
	ds_read_b128 v[170:173], v134 offset:3072
	ds_read_b128 v[186:189], v152 offset:35840
	ds_read_b128 v[194:197], v152 offset:37888
	ds_read_b128 v[202:205], v152 offset:39936
	ds_read_b128 v[206:209], v135
	ds_read_b128 v[214:217], v135 offset:2048
	ds_read_b128 v[210:213], v135 offset:1024
	ds_read_b128 v[218:221], v135 offset:3072
	s_cmp_eq_u32 s59, s24
	s_cselect_b32 s27, s9, s27
	s_cselect_b32 s26, s56, s26
	s_cselect_b32 s61, s5, s61
	s_cselect_b32 s60, s57, s60
	s_mov_b32 m0, s39
	s_nop 0
	global_load_lds_dwordx4 v137, s[60:61]
	s_mov_b32 m0, s40
	s_nop 0
	global_load_lds_dwordx4 v139, s[60:61]
	s_waitcnt lgkmcnt(14)
	v_mfma_f32_16x16x32_bf16 v[128:131], v[146:149], v[174:177], v[128:131]
	s_waitcnt lgkmcnt(13)
	v_mfma_f32_16x16x32_bf16 v[124:127], v[158:161], v[174:177], v[124:127]
	s_waitcnt lgkmcnt(12)
	v_mfma_f32_16x16x32_bf16 v[112:115], v[146:149], v[182:185], v[112:115]
	v_mfma_f32_16x16x32_bf16 v[108:111], v[158:161], v[182:185], v[108:111]
	s_waitcnt lgkmcnt(11)
	v_mfma_f32_16x16x32_bf16 v[96:99], v[146:149], v[190:193], v[96:99]
	v_mfma_f32_16x16x32_bf16 v[92:95], v[158:161], v[190:193], v[92:95]
	s_waitcnt lgkmcnt(10)
	v_mfma_f32_16x16x32_bf16 v[80:83], v[146:149], v[198:201], v[80:83]
	v_mfma_f32_16x16x32_bf16 v[76:79], v[158:161], v[198:201], v[76:79]
	s_waitcnt lgkmcnt(8)
	v_mfma_f32_16x16x32_bf16 v[128:131], v[154:157], v[178:181], v[128:131]
	s_waitcnt lgkmcnt(7)
	v_mfma_f32_16x16x32_bf16 v[124:127], v[170:173], v[178:181], v[124:127]
	s_waitcnt lgkmcnt(6)
	v_mfma_f32_16x16x32_bf16 v[112:115], v[154:157], v[186:189], v[112:115]
	v_mfma_f32_16x16x32_bf16 v[108:111], v[170:173], v[186:189], v[108:111]
	s_waitcnt lgkmcnt(5)
	v_mfma_f32_16x16x32_bf16 v[96:99], v[154:157], v[194:197], v[96:99]
	v_mfma_f32_16x16x32_bf16 v[92:95], v[170:173], v[194:197], v[92:95]
	s_waitcnt lgkmcnt(4)
	v_mfma_f32_16x16x32_bf16 v[80:83], v[154:157], v[202:205], v[80:83]
	v_mfma_f32_16x16x32_bf16 v[76:79], v[170:173], v[202:205], v[76:79]
	s_mov_b32 m0, s19
	s_nop 0
	global_load_lds_dwordx4 v136, s[26:27]
	s_mov_b32 m0, s41
	s_nop 0
	global_load_lds_dwordx4 v138, s[26:27]
	s_waitcnt lgkmcnt(3)
	v_mfma_f32_16x16x32_bf16 v[120:123], v[206:209], v[174:177], v[120:123]
	s_waitcnt lgkmcnt(2)
	v_mfma_f32_16x16x32_bf16 v[116:119], v[214:217], v[174:177], v[116:119]
	v_mfma_f32_16x16x32_bf16 v[104:107], v[206:209], v[182:185], v[104:107]
	v_mfma_f32_16x16x32_bf16 v[100:103], v[214:217], v[182:185], v[100:103]
	v_mfma_f32_16x16x32_bf16 v[88:91], v[206:209], v[190:193], v[88:91]
	v_mfma_f32_16x16x32_bf16 v[84:87], v[214:217], v[190:193], v[84:87]
	v_mfma_f32_16x16x32_bf16 v[72:75], v[206:209], v[198:201], v[72:75]
	v_mfma_f32_16x16x32_bf16 v[68:71], v[214:217], v[198:201], v[68:71]
	s_waitcnt lgkmcnt(1)
	v_mfma_f32_16x16x32_bf16 v[120:123], v[210:213], v[178:181], v[120:123]
	s_waitcnt lgkmcnt(0)
	v_mfma_f32_16x16x32_bf16 v[116:119], v[218:221], v[178:181], v[116:119]
	v_mfma_f32_16x16x32_bf16 v[104:107], v[210:213], v[186:189], v[104:107]
	v_mfma_f32_16x16x32_bf16 v[100:103], v[218:221], v[186:189], v[100:103]
	v_mfma_f32_16x16x32_bf16 v[88:91], v[210:213], v[194:197], v[88:91]
	v_mfma_f32_16x16x32_bf16 v[84:87], v[218:221], v[194:197], v[84:87]
	v_mfma_f32_16x16x32_bf16 v[72:75], v[210:213], v[202:205], v[72:75]
	v_mfma_f32_16x16x32_bf16 v[68:71], v[218:221], v[202:205], v[68:71]
	s_waitcnt vmcnt(4) lgkmcnt(0)
	s_barrier
	ds_read_b128 v[174:177], v152 offset:49152
	ds_read_b128 v[182:185], v152 offset:51200
	ds_read_b128 v[190:193], v152 offset:53248
	ds_read_b128 v[198:201], v152 offset:55296
	ds_read_b128 v[178:181], v152 offset:50176
	ds_read_b128 v[186:189], v152 offset:52224
	ds_read_b128 v[194:197], v152 offset:54272
	ds_read_b128 v[202:205], v152 offset:56320
	s_add_u32 s60, s60, 0x40000
	s_addc_u32 s61, s61, 0
	s_mov_b32 m0, s42
	s_nop 0
	global_load_lds_dwordx4 v137, s[60:61]
	s_mov_b32 m0, s43
	s_nop 0
	global_load_lds_dwordx4 v139, s[60:61]
	s_waitcnt lgkmcnt(7)
	v_mfma_f32_16x16x32_bf16 v[64:67], v[146:149], v[174:177], v[64:67]
	v_mfma_f32_16x16x32_bf16 v[60:63], v[158:161], v[174:177], v[60:63]
	s_waitcnt lgkmcnt(6)
	v_mfma_f32_16x16x32_bf16 v[48:51], v[146:149], v[182:185], v[48:51]
	v_mfma_f32_16x16x32_bf16 v[44:47], v[158:161], v[182:185], v[44:47]
	s_waitcnt lgkmcnt(5)
	v_mfma_f32_16x16x32_bf16 v[32:35], v[146:149], v[190:193], v[32:35]
	v_mfma_f32_16x16x32_bf16 v[28:31], v[158:161], v[190:193], v[28:31]
	s_waitcnt lgkmcnt(4)
	v_mfma_f32_16x16x32_bf16 v[16:19], v[146:149], v[198:201], v[16:19]
	v_mfma_f32_16x16x32_bf16 v[12:15], v[158:161], v[198:201], v[12:15]
	s_waitcnt lgkmcnt(3)
	v_mfma_f32_16x16x32_bf16 v[64:67], v[154:157], v[178:181], v[64:67]
	v_mfma_f32_16x16x32_bf16 v[60:63], v[170:173], v[178:181], v[60:63]
	s_waitcnt lgkmcnt(2)
	v_mfma_f32_16x16x32_bf16 v[48:51], v[154:157], v[186:189], v[48:51]
	v_mfma_f32_16x16x32_bf16 v[44:47], v[170:173], v[186:189], v[44:47]
	s_waitcnt lgkmcnt(1)
	v_mfma_f32_16x16x32_bf16 v[32:35], v[154:157], v[194:197], v[32:35]
	v_mfma_f32_16x16x32_bf16 v[28:31], v[170:173], v[194:197], v[28:31]
	s_waitcnt lgkmcnt(0)
	v_mfma_f32_16x16x32_bf16 v[16:19], v[154:157], v[202:205], v[16:19]
	v_mfma_f32_16x16x32_bf16 v[12:15], v[170:173], v[202:205], v[12:15]
	s_add_u32 s26, s26, 0x40000
	s_addc_u32 s27, s27, 0
	s_mov_b32 m0, s44
	s_nop 0
	global_load_lds_dwordx4 v136, s[26:27]
	s_mov_b32 m0, s45
	s_nop 0
	global_load_lds_dwordx4 v138, s[26:27]
	v_mfma_f32_16x16x32_bf16 v[56:59], v[206:209], v[174:177], v[56:59]
	s_add_i32 s58, s58, 2
	s_add_u32 s24, s24, 0xffffff00
	s_addc_u32 s25, s25, -1
	v_mfma_f32_16x16x32_bf16 v[52:55], v[214:217], v[174:177], v[52:55]
	s_add_u32 s20, s20, 0x100
	s_addc_u32 s21, s21, 0
	s_add_u32 s22, s22, 0x100
	v_mfma_f32_16x16x32_bf16 v[40:43], v[206:209], v[182:185], v[40:43]
	s_addc_u32 s23, s23, 0
	s_cmp_lt_u32 s58, 14
	v_mfma_f32_16x16x32_bf16 v[36:39], v[214:217], v[182:185], v[36:39]
	v_mfma_f32_16x16x32_bf16 v[24:27], v[206:209], v[190:193], v[24:27]
	v_mfma_f32_16x16x32_bf16 v[20:23], v[214:217], v[190:193], v[20:23]
	v_mfma_f32_16x16x32_bf16 v[4:7], v[206:209], v[198:201], v[4:7]
	v_mfma_f32_16x16x32_bf16 v[8:11], v[214:217], v[198:201], v[8:11]
	v_mfma_f32_16x16x32_bf16 v[56:59], v[210:213], v[178:181], v[56:59]
	v_mfma_f32_16x16x32_bf16 v[52:55], v[218:221], v[178:181], v[52:55]
	v_mfma_f32_16x16x32_bf16 v[40:43], v[210:213], v[186:189], v[40:43]
	v_mfma_f32_16x16x32_bf16 v[36:39], v[218:221], v[186:189], v[36:39]
	v_mfma_f32_16x16x32_bf16 v[24:27], v[210:213], v[194:197], v[24:27]
	v_mfma_f32_16x16x32_bf16 v[20:23], v[218:221], v[194:197], v[20:23]
	v_mfma_f32_16x16x32_bf16 v[4:7], v[210:213], v[202:205], v[4:7]
	v_mfma_f32_16x16x32_bf16 v[8:11], v[218:221], v[202:205], v[8:11]
	s_cbranch_scc1 .LBB0_173
; __device__ __forceinline__ unsigned cvt_pk_bf16(float lo, float hi) { unsigned r; asm volatile("v_cvt_pk_bf16_f32 %0, %1, %2" : "=v"(r) : "v"(lo), "v"(hi)); return r; }
; #define LAS __attribute__((address_space(3)))
; __device__ __forceinline__ float bflo(unsigned w) { return __uint_as_float(w << 16); }
; __device__ __forceinline__ float bfhi(unsigned w) { return __uint_as_float(w & 0xffff0000u); }
;     __device__ __forceinline__ void operator()(const f32x4 (&acc)[2][2][4][2], const Unit& u, int wr, int wc, int fr, int fq, const LAS float*) const {
;         const int row0 = u.pm * 256 + wr * 64 + fr, col0 = u.pn * 256 + wc * 32 + 8 * fq;
; #pragma unroll
;         for (int ai = 0; ai < 2; ++ai)
; #pragma unroll
;             for (int m = 0; m < 4; ++m) { const size_t row = (size_t)(row0 + ai * 128 + m * 16);
; #pragma unroll
;                 for (int bj = 0; bj < 2; ++bj) { const int col = col0 + bj * 128;
;                     const u32x4 g = *(const u32x4*)(G + row * NGATE + MODE * DM + col);
;                     f32x4 v0 = acc[ai][bj][m][0], v1 = acc[ai][bj][m][1];
;                     v0[0] *= bflo(g.x); v0[1] *= bfhi(g.x); v0[2] *= bflo(g.y); v0[3] *= bfhi(g.y); v1[0] *= bflo(g.z); v1[1] *= bfhi(g.z); v1[2] *= bflo(g.w); v1[3] *= bfhi(g.w);
;                     bf16_t* tp = T + row * DM + col;
;                     if (MODE == 1) { const u32x4 t = *(const u32x4*)tp;
;                         v0[0] += bflo(t.x); v0[1] += bfhi(t.x); v0[2] += bflo(t.y); v0[3] += bfhi(t.y); v1[0] += bflo(t.z); v1[1] += bfhi(t.z); v1[2] += bflo(t.w); v1[3] += bfhi(t.w); }
;                     u32x4 w; w.x = cvt_pk_bf16(v0[0], v0[1]); w.y = cvt_pk_bf16(v0[2], v0[3]); w.z = cvt_pk_bf16(v1[0], v1[1]); w.w = cvt_pk_bf16(v1[2], v1[3]);
;                     *(u32x4*)tp = w; } }
	v_mov_b32_e32 v132, v141
	s_lshl_b32 s5, s18, 8
	v_mbcnt_lo_u32_b32 v132, -1, v132
	v_mbcnt_hi_u32_b32 v132, -1, v132
	s_add_i32 s5, s5, s37
	v_and_or_b32 v134, v132, 15, s5
	s_lshl_b32 s5, s35, 8
	v_ashrrev_i32_e32 v132, 1, v132
	s_or_b32 s5, s5, s38
	v_and_b32_e32 v132, -8, v132
	v_add_u32_e32 v132, s5, v132
	v_ashrrev_i32_e32 v135, 31, v134
	v_lshlrev_b64 v[142:143], 13, v[134:135]
	v_ashrrev_i32_e32 v133, 31, v132
	v_lshl_add_u64 v[142:143], s[2:3], 0, v[142:143]
	v_lshlrev_b64 v[132:133], 1, v[132:133]
	v_lshl_add_u64 v[142:143], v[142:143], 0, v[132:133]
	s_mov_b64 s[20:21], 0x1000
	v_lshl_add_u64 v[154:155], v[142:143], 0, s[20:21]
	v_add_co_u32_e32 v142, vcc, s76, v142
	v_lshlrev_b64 v[144:145], 12, v[134:135]
	s_nop 0
	v_addc_co_u32_e32 v143, vcc, 0, v143, vcc
	v_lshlrev_b32_e32 v236, 13, v134
	v_add_u32_e32 v236, v236, v132
	v_add_u32_e32 v236, 0x1000, v236
	v_lshlrev_b32_e32 v238, 12, v134
	v_add_u32_e32 v238, v238, v132
	global_load_dwordx4 v[172:175], v236, s[2:3]
	global_load_dwordx4 v[176:179], v238, s[12:13]
	global_load_dwordx4 v[180:183], v236, s[2:3] offset:256
	global_load_dwordx4 v[184:187], v238, s[12:13] offset:256
	v_add_u32_e32 v237, 0x20000, v236
	v_add_u32_e32 v239, 0x10000, v238
	global_load_dwordx4 v[188:191], v237, s[2:3]
	global_load_dwordx4 v[192:195], v239, s[12:13]
	global_load_dwordx4 v[196:199], v237, s[2:3] offset:256
	global_load_dwordx4 v[200:203], v239, s[12:13] offset:256
	v_add_u32_e32 v237, 0x40000, v236
	v_add_u32_e32 v239, 0x20000, v238
	global_load_dwordx4 v[204:207], v237, s[2:3]
	global_load_dwordx4 v[208:211], v239, s[12:13]
	global_load_dwordx4 v[212:215], v237, s[2:3] offset:256
	global_load_dwordx4 v[216:219], v239, s[12:13] offset:256
	v_add_u32_e32 v237, 0x60000, v236
	v_add_u32_e32 v239, 0x30000, v238
	global_load_dwordx4 v[220:223], v237, s[2:3]
	global_load_dwordx4 v[224:227], v239, s[12:13]
	global_load_dwordx4 v[228:231], v237, s[2:3] offset:256
	global_load_dwordx4 v[232:235], v239, s[12:13] offset:256
	v_lshl_add_u64 v[142:143], s[12:13], 0, v[144:145]
	v_lshl_add_u64 v[142:143], v[142:143], 0, v[132:133]
	s_mov_b32 s35, s4
	s_mov_b32 s18, s8
	s_mov_b64 s[22:23], s[10:11]
	s_mov_b32 s9, s55
	s_waitcnt vmcnt(15)
	s_nop 1
	v_mov_b64_e32 v[146:147], v[172:173]
	v_mov_b64_e32 v[148:149], v[174:175]
	v_lshlrev_b32_e32 v135, 16, v146
	v_and_b32_e32 v153, 0xffff0000, v146
	v_lshlrev_b32_e32 v156, 16, v147
	v_and_b32_e32 v157, 0xffff0000, v147
	v_lshlrev_b32_e32 v158, 16, v148
	v_and_b32_e32 v159, 0xffff0000, v148
	v_lshlrev_b32_e32 v160, 16, v149
	v_and_b32_e32 v161, 0xffff0000, v149
	s_waitcnt vmcnt(14)
	s_nop 1
	v_mov_b64_e32 v[146:147], v[176:177]
	v_mov_b64_e32 v[148:149], v[178:179]
	v_lshlrev_b32_e32 v144, 16, v146
	v_fmac_f32_e32 v144, v128, v135
	v_and_b32_e32 v128, 0xffff0000, v146
	v_fmac_f32_e32 v128, v129, v153
	v_lshlrev_b32_e32 v129, 16, v147
	v_fmac_f32_e32 v129, v130, v156
	v_and_b32_e32 v130, 0xffff0000, v147
	v_fmac_f32_e32 v130, v131, v157
	v_lshlrev_b32_e32 v131, 16, v148
	v_and_b32_e32 v135, 0xffff0000, v148
	v_lshlrev_b32_e32 v145, 16, v149
	v_and_b32_e32 v146, 0xffff0000, v149
	v_fmac_f32_e32 v131, v124, v158
	v_fmac_f32_e32 v135, v125, v159
	v_fmac_f32_e32 v145, v126, v160
	v_fmac_f32_e32 v146, v127, v161
	v_cvt_pk_bf16_f32 v124, v144, v128
	v_cvt_pk_bf16_f32 v125, v129, v130
	v_cvt_pk_bf16_f32 v126, v131, v135
	v_cvt_pk_bf16_f32 v127, v145, v146
	global_store_dwordx4 v[142:143], v[124:127], off
	s_waitcnt vmcnt(14)
	s_nop 1
	v_mov_b64_e32 v[124:125], v[180:181]
	v_mov_b64_e32 v[126:127], v[182:183]
	v_lshlrev_b32_e32 v128, 16, v124
	v_and_b32_e32 v129, 0xffff0000, v124
	v_lshlrev_b32_e32 v130, 16, v125
	v_and_b32_e32 v131, 0xffff0000, v125
	v_lshlrev_b32_e32 v135, 16, v126
	v_and_b32_e32 v144, 0xffff0000, v126
	v_lshlrev_b32_e32 v145, 16, v127
	v_and_b32_e32 v146, 0xffff0000, v127
	s_waitcnt vmcnt(13)
	s_nop 1
	v_mov_b64_e32 v[124:125], v[184:185]
	v_mov_b64_e32 v[126:127], v[186:187]
	v_lshlrev_b32_e32 v147, 16, v124
	v_fmac_f32_e32 v147, v120, v128
	v_and_b32_e32 v120, 0xffff0000, v124
	v_fmac_f32_e32 v120, v121, v129
	v_lshlrev_b32_e32 v121, 16, v125
	v_fmac_f32_e32 v121, v122, v130
	v_and_b32_e32 v122, 0xffff0000, v125
	v_fmac_f32_e32 v122, v123, v131
	v_lshlrev_b32_e32 v123, 16, v126
	v_fmac_f32_e32 v123, v116, v135
	v_and_b32_e32 v124, 0xffff0000, v126
	v_lshlrev_b32_e32 v125, 16, v127
	v_and_b32_e32 v126, 0xffff0000, v127
	v_cvt_pk_bf16_f32 v116, v147, v120
	v_fmac_f32_e32 v124, v117, v144
	v_fmac_f32_e32 v125, v118, v145
	v_fmac_f32_e32 v126, v119, v146
	v_cvt_pk_bf16_f32 v117, v121, v122
	v_cvt_pk_bf16_f32 v118, v123, v124
	v_cvt_pk_bf16_f32 v119, v125, v126
	global_store_dwordx4 v[142:143], v[116:119], off offset:256
	v_add_u32_e32 v237, 0x100000, v236
	v_add_u32_e32 v239, 0x80000, v238
	global_load_dwordx4 v[172:175], v237, s[2:3]
	global_load_dwordx4 v[176:179], v239, s[12:13]
	global_load_dwordx4 v[180:183], v237, s[2:3] offset:256
	global_load_dwordx4 v[184:187], v239, s[12:13] offset:256
	s_nop 1
	v_or_b32_e32 v116, 16, v134
	v_ashrrev_i32_e32 v117, 31, v116
	v_lshlrev_b64 v[118:119], 13, v[116:117]
	v_lshlrev_b64 v[122:123], 12, v[116:117]
	v_lshl_add_u64 v[116:117], s[2:3], 0, v[118:119]
	v_lshl_add_u64 v[118:119], v[116:117], 0, v[132:133]
	v_lshl_add_u64 v[116:117], v[118:119], 0, s[20:21]
	v_add_co_u32_e32 v118, vcc, s76, v118
	s_nop 1
	v_addc_co_u32_e32 v119, vcc, 0, v119, vcc
	s_waitcnt vmcnt(17)
; __device__ __forceinline__ unsigned cvt_pk_bf16(float lo, float hi) { unsigned r; asm volatile("v_cvt_pk_bf16_f32 %0, %1, %2" : "=v"(r) : "v"(lo), "v"(hi)); return r; }
; #define LAS __attribute__((address_space(3)))
; __device__ __forceinline__ float bflo(unsigned w) { return __uint_as_float(w << 16); }
; __device__ __forceinline__ float bfhi(unsigned w) { return __uint_as_float(w & 0xffff0000u); }
;     __device__ __forceinline__ void operator()(const f32x4 (&acc)[2][2][4][2], const Unit& u, int wr, int wc, int fr, int fq, const LAS float*) const {
;         const int row0 = u.pm * 256 + wr * 64 + fr, col0 = u.pn * 256 + wc * 32 + 8 * fq;
; #pragma unroll
;         for (int ai = 0; ai < 2; ++ai)
; #pragma unroll
;             for (int m = 0; m < 4; ++m) { const size_t row = (size_t)(row0 + ai * 128 + m * 16);
; #pragma unroll
;                 for (int bj = 0; bj < 2; ++bj) { const int col = col0 + bj * 128;
;                     const u32x4 g = *(const u32x4*)(G + row * NGATE + MODE * DM + col);
;                     f32x4 v0 = acc[ai][bj][m][0], v1 = acc[ai][bj][m][1];
;                     v0[0] *= bflo(g.x); v0[1] *= bfhi(g.x); v0[2] *= bflo(g.y); v0[3] *= bfhi(g.y); v1[0] *= bflo(g.z); v1[1] *= bfhi(g.z); v1[2] *= bflo(g.w); v1[3] *= bfhi(g.w);
;                     bf16_t* tp = T + row * DM + col;
;                     if (MODE == 1) { const u32x4 t = *(const u32x4*)tp;
;                         v0[0] += bflo(t.x); v0[1] += bfhi(t.x); v0[2] += bflo(t.y); v0[3] += bfhi(t.y); v1[0] += bflo(t.z); v1[1] += bfhi(t.z); v1[2] += bflo(t.w); v1[3] += bfhi(t.w); }
;                     u32x4 w; w.x = cvt_pk_bf16(v0[0], v0[1]); w.y = cvt_pk_bf16(v0[2], v0[3]); w.z = cvt_pk_bf16(v1[0], v1[1]); w.w = cvt_pk_bf16(v1[2], v1[3]);
;                     *(u32x4*)tp = w; } }
	s_nop 1
	v_mov_b64_e32 v[118:119], v[188:189]
	v_mov_b64_e32 v[120:121], v[190:191]
	v_lshlrev_b32_e32 v124, 16, v118
	v_and_b32_e32 v125, 0xffff0000, v118
	v_lshlrev_b32_e32 v126, 16, v119
	v_and_b32_e32 v127, 0xffff0000, v119
	v_lshl_add_u64 v[118:119], s[12:13], 0, v[122:123]
	v_lshl_add_u64 v[122:123], v[118:119], 0, v[132:133]
	v_lshlrev_b32_e32 v128, 16, v120
	v_and_b32_e32 v129, 0xffff0000, v120
	v_lshlrev_b32_e32 v130, 16, v121
	v_and_b32_e32 v131, 0xffff0000, v121
	s_waitcnt vmcnt(16)
	s_nop 1
	v_mov_b64_e32 v[118:119], v[192:193]
	v_mov_b64_e32 v[120:121], v[194:195]
	v_lshlrev_b32_e32 v135, 16, v118
	v_fmac_f32_e32 v135, v112, v124
	v_and_b32_e32 v112, 0xffff0000, v118
	v_fmac_f32_e32 v112, v113, v125
	v_lshlrev_b32_e32 v113, 16, v119
	v_fmac_f32_e32 v113, v114, v126
	v_and_b32_e32 v114, 0xffff0000, v119
	v_fmac_f32_e32 v114, v115, v127
	v_lshlrev_b32_e32 v115, 16, v120
	v_and_b32_e32 v118, 0xffff0000, v120
	v_lshlrev_b32_e32 v119, 16, v121
	v_and_b32_e32 v120, 0xffff0000, v121
	v_fmac_f32_e32 v115, v108, v128
	v_fmac_f32_e32 v118, v109, v129
	v_fmac_f32_e32 v119, v110, v130
	v_fmac_f32_e32 v120, v111, v131
	v_cvt_pk_bf16_f32 v108, v135, v112
	v_cvt_pk_bf16_f32 v109, v113, v114
	v_cvt_pk_bf16_f32 v110, v115, v118
	v_cvt_pk_bf16_f32 v111, v119, v120
	global_store_dwordx4 v[122:123], v[108:111], off
	s_waitcnt vmcnt(16)
	s_nop 1
	v_mov_b64_e32 v[108:109], v[196:197]
	v_mov_b64_e32 v[110:111], v[198:199]
	v_lshlrev_b32_e32 v112, 16, v108
	v_and_b32_e32 v113, 0xffff0000, v108
	v_lshlrev_b32_e32 v114, 16, v109
	v_and_b32_e32 v115, 0xffff0000, v109
	v_lshlrev_b32_e32 v116, 16, v110
	v_and_b32_e32 v117, 0xffff0000, v110
	v_lshlrev_b32_e32 v118, 16, v111
	v_and_b32_e32 v119, 0xffff0000, v111
	s_waitcnt vmcnt(15)
	s_nop 1
	v_mov_b64_e32 v[108:109], v[200:201]
	v_mov_b64_e32 v[110:111], v[202:203]
	v_lshlrev_b32_e32 v120, 16, v108
	v_fmac_f32_e32 v120, v104, v112
	v_and_b32_e32 v104, 0xffff0000, v108
	v_fmac_f32_e32 v104, v105, v113
	v_lshlrev_b32_e32 v105, 16, v109
	v_fmac_f32_e32 v105, v106, v114
	v_and_b32_e32 v106, 0xffff0000, v109
	v_fmac_f32_e32 v106, v107, v115
	v_lshlrev_b32_e32 v107, 16, v110
	v_fmac_f32_e32 v107, v100, v116
	v_and_b32_e32 v108, 0xffff0000, v110
	v_lshlrev_b32_e32 v109, 16, v111
	v_and_b32_e32 v110, 0xffff0000, v111
	v_cvt_pk_bf16_f32 v100, v120, v104
	v_fmac_f32_e32 v108, v101, v117
	v_fmac_f32_e32 v109, v102, v118
	v_fmac_f32_e32 v110, v103, v119
	v_cvt_pk_bf16_f32 v101, v105, v106
	v_cvt_pk_bf16_f32 v102, v107, v108
	v_cvt_pk_bf16_f32 v103, v109, v110
	global_store_dwordx4 v[122:123], v[100:103], off offset:256
	v_add_u32_e32 v237, 0x120000, v236
	v_add_u32_e32 v239, 0x90000, v238
	global_load_dwordx4 v[188:191], v237, s[2:3]
	global_load_dwordx4 v[192:195], v239, s[12:13]
	global_load_dwordx4 v[196:199], v237, s[2:3] offset:256
	global_load_dwordx4 v[200:203], v239, s[12:13] offset:256
	s_nop 1
	v_or_b32_e32 v100, 32, v134
	v_ashrrev_i32_e32 v101, 31, v100
	v_lshlrev_b64 v[102:103], 13, v[100:101]
	v_lshlrev_b64 v[106:107], 12, v[100:101]
	v_lshl_add_u64 v[100:101], s[2:3], 0, v[102:103]
	v_lshl_add_u64 v[102:103], v[100:101], 0, v[132:133]
	v_lshl_add_u64 v[100:101], v[102:103], 0, s[20:21]
	v_add_co_u32_e32 v102, vcc, s76, v102
	s_nop 1
	v_addc_co_u32_e32 v103, vcc, 0, v103, vcc
	s_waitcnt vmcnt(19)
	s_nop 1
	v_mov_b64_e32 v[102:103], v[204:205]
	v_mov_b64_e32 v[104:105], v[206:207]
	v_lshlrev_b32_e32 v108, 16, v102
	v_and_b32_e32 v109, 0xffff0000, v102
	v_lshlrev_b32_e32 v110, 16, v103
	v_and_b32_e32 v111, 0xffff0000, v103
	v_lshl_add_u64 v[102:103], s[12:13], 0, v[106:107]
	v_lshl_add_u64 v[106:107], v[102:103], 0, v[132:133]
	v_lshlrev_b32_e32 v112, 16, v104
	v_and_b32_e32 v113, 0xffff0000, v104
	v_lshlrev_b32_e32 v114, 16, v105
	v_and_b32_e32 v115, 0xffff0000, v105
	s_waitcnt vmcnt(18)
	s_nop 1
	v_mov_b64_e32 v[102:103], v[208:209]
	v_mov_b64_e32 v[104:105], v[210:211]
	v_lshlrev_b32_e32 v116, 16, v102
	v_fmac_f32_e32 v116, v96, v108
	v_and_b32_e32 v96, 0xffff0000, v102
	v_fmac_f32_e32 v96, v97, v109
	v_lshlrev_b32_e32 v97, 16, v103
	v_fmac_f32_e32 v97, v98, v110
	v_and_b32_e32 v98, 0xffff0000, v103
	v_fmac_f32_e32 v98, v99, v111
	v_lshlrev_b32_e32 v99, 16, v104
	v_and_b32_e32 v102, 0xffff0000, v104
	v_lshlrev_b32_e32 v103, 16, v105
	v_and_b32_e32 v104, 0xffff0000, v105
	v_fmac_f32_e32 v99, v92, v112
	v_fmac_f32_e32 v102, v93, v113
	v_fmac_f32_e32 v103, v94, v114
	v_fmac_f32_e32 v104, v95, v115
	v_cvt_pk_bf16_f32 v92, v116, v96
	v_cvt_pk_bf16_f32 v93, v97, v98
	v_cvt_pk_bf16_f32 v94, v99, v102
	v_cvt_pk_bf16_f32 v95, v103, v104
	global_store_dwordx4 v[106:107], v[92:95], off
	s_waitcnt vmcnt(18)
	s_nop 1
	v_mov_b64_e32 v[92:93], v[212:213]
	v_mov_b64_e32 v[94:95], v[214:215]
	v_lshlrev_b32_e32 v96, 16, v92
	v_and_b32_e32 v97, 0xffff0000, v92
	v_lshlrev_b32_e32 v98, 16, v93
	v_and_b32_e32 v99, 0xffff0000, v93
	v_lshlrev_b32_e32 v100, 16, v94
	v_and_b32_e32 v101, 0xffff0000, v94
	v_lshlrev_b32_e32 v102, 16, v95
	v_and_b32_e32 v103, 0xffff0000, v95
	s_waitcnt vmcnt(17)
; __device__ __forceinline__ unsigned cvt_pk_bf16(float lo, float hi) { unsigned r; asm volatile("v_cvt_pk_bf16_f32 %0, %1, %2" : "=v"(r) : "v"(lo), "v"(hi)); return r; }
; #define LAS __attribute__((address_space(3)))
; __device__ __forceinline__ float bflo(unsigned w) { return __uint_as_float(w << 16); }
; __device__ __forceinline__ float bfhi(unsigned w) { return __uint_as_float(w & 0xffff0000u); }
;     __device__ __forceinline__ void operator()(const f32x4 (&acc)[2][2][4][2], const Unit& u, int wr, int wc, int fr, int fq, const LAS float*) const {
;         const int row0 = u.pm * 256 + wr * 64 + fr, col0 = u.pn * 256 + wc * 32 + 8 * fq;
; #pragma unroll
;         for (int ai = 0; ai < 2; ++ai)
; #pragma unroll
;             for (int m = 0; m < 4; ++m) { const size_t row = (size_t)(row0 + ai * 128 + m * 16);
; #pragma unroll
;                 for (int bj = 0; bj < 2; ++bj) { const int col = col0 + bj * 128;
;                     const u32x4 g = *(const u32x4*)(G + row * NGATE + MODE * DM + col);
;                     f32x4 v0 = acc[ai][bj][m][0], v1 = acc[ai][bj][m][1];
;                     v0[0] *= bflo(g.x); v0[1] *= bfhi(g.x); v0[2] *= bflo(g.y); v0[3] *= bfhi(g.y); v1[0] *= bflo(g.z); v1[1] *= bfhi(g.z); v1[2] *= bflo(g.w); v1[3] *= bfhi(g.w);
;                     bf16_t* tp = T + row * DM + col;
;                     if (MODE == 1) { const u32x4 t = *(const u32x4*)tp;
;                         v0[0] += bflo(t.x); v0[1] += bfhi(t.x); v0[2] += bflo(t.y); v0[3] += bfhi(t.y); v1[0] += bflo(t.z); v1[1] += bfhi(t.z); v1[2] += bflo(t.w); v1[3] += bfhi(t.w); }
;                     u32x4 w; w.x = cvt_pk_bf16(v0[0], v0[1]); w.y = cvt_pk_bf16(v0[2], v0[3]); w.z = cvt_pk_bf16(v1[0], v1[1]); w.w = cvt_pk_bf16(v1[2], v1[3]);
;                     *(u32x4*)tp = w; } }
	s_nop 1
	v_mov_b64_e32 v[92:93], v[216:217]
	v_mov_b64_e32 v[94:95], v[218:219]
	v_lshlrev_b32_e32 v104, 16, v92
	v_fmac_f32_e32 v104, v88, v96
	v_and_b32_e32 v88, 0xffff0000, v92
	v_fmac_f32_e32 v88, v89, v97
	v_lshlrev_b32_e32 v89, 16, v93
	v_fmac_f32_e32 v89, v90, v98
	v_and_b32_e32 v90, 0xffff0000, v93
	v_fmac_f32_e32 v90, v91, v99
	v_lshlrev_b32_e32 v91, 16, v94
	v_fmac_f32_e32 v91, v84, v100
	v_and_b32_e32 v92, 0xffff0000, v94
	v_lshlrev_b32_e32 v93, 16, v95
	v_and_b32_e32 v94, 0xffff0000, v95
	v_cvt_pk_bf16_f32 v84, v104, v88
	v_fmac_f32_e32 v92, v85, v101
	v_fmac_f32_e32 v93, v86, v102
	v_fmac_f32_e32 v94, v87, v103
	v_cvt_pk_bf16_f32 v85, v89, v90
	v_cvt_pk_bf16_f32 v86, v91, v92
	v_cvt_pk_bf16_f32 v87, v93, v94
	global_store_dwordx4 v[106:107], v[84:87], off offset:256
	v_add_u32_e32 v237, 0x140000, v236
	v_add_u32_e32 v239, 0xa0000, v238
	global_load_dwordx4 v[204:207], v237, s[2:3]
	global_load_dwordx4 v[208:211], v239, s[12:13]
	global_load_dwordx4 v[212:215], v237, s[2:3] offset:256
	global_load_dwordx4 v[216:219], v239, s[12:13] offset:256
	s_nop 1
	v_or_b32_e32 v84, 48, v134
	v_ashrrev_i32_e32 v85, 31, v84
	v_lshlrev_b64 v[86:87], 13, v[84:85]
	v_lshlrev_b64 v[90:91], 12, v[84:85]
	v_lshl_add_u64 v[84:85], s[2:3], 0, v[86:87]
	v_lshl_add_u64 v[86:87], v[84:85], 0, v[132:133]
	v_lshl_add_u64 v[84:85], v[86:87], 0, s[20:21]
	v_add_co_u32_e32 v86, vcc, s76, v86
	s_nop 1
	v_addc_co_u32_e32 v87, vcc, 0, v87, vcc
	s_waitcnt vmcnt(21)
	s_nop 1
	v_mov_b64_e32 v[86:87], v[220:221]
	v_mov_b64_e32 v[88:89], v[222:223]
	v_lshlrev_b32_e32 v92, 16, v86
	v_and_b32_e32 v93, 0xffff0000, v86
	v_lshlrev_b32_e32 v94, 16, v87
	v_and_b32_e32 v95, 0xffff0000, v87
	v_lshl_add_u64 v[86:87], s[12:13], 0, v[90:91]
	v_lshl_add_u64 v[90:91], v[86:87], 0, v[132:133]
	v_lshlrev_b32_e32 v96, 16, v88
	v_and_b32_e32 v97, 0xffff0000, v88
	v_lshlrev_b32_e32 v98, 16, v89
	v_and_b32_e32 v99, 0xffff0000, v89
	s_waitcnt vmcnt(20)
	s_nop 1
	v_mov_b64_e32 v[86:87], v[224:225]
	v_mov_b64_e32 v[88:89], v[226:227]
	v_lshlrev_b32_e32 v100, 16, v86
	v_fmac_f32_e32 v100, v80, v92
	v_and_b32_e32 v80, 0xffff0000, v86
	v_fmac_f32_e32 v80, v81, v93
	v_lshlrev_b32_e32 v81, 16, v87
	v_fmac_f32_e32 v81, v82, v94
	v_and_b32_e32 v82, 0xffff0000, v87
	v_fmac_f32_e32 v82, v83, v95
	v_lshlrev_b32_e32 v83, 16, v88
	v_and_b32_e32 v86, 0xffff0000, v88
	v_lshlrev_b32_e32 v87, 16, v89
	v_and_b32_e32 v88, 0xffff0000, v89
	v_fmac_f32_e32 v83, v76, v96
	v_fmac_f32_e32 v86, v77, v97
	v_fmac_f32_e32 v87, v78, v98
	v_fmac_f32_e32 v88, v79, v99
	v_cvt_pk_bf16_f32 v76, v100, v80
	v_cvt_pk_bf16_f32 v77, v81, v82
	v_cvt_pk_bf16_f32 v78, v83, v86
	v_cvt_pk_bf16_f32 v79, v87, v88
	global_store_dwordx4 v[90:91], v[76:79], off
	s_waitcnt vmcnt(20)
	s_nop 1
	v_mov_b64_e32 v[76:77], v[228:229]
	v_mov_b64_e32 v[78:79], v[230:231]
	v_lshlrev_b32_e32 v80, 16, v76
	v_and_b32_e32 v81, 0xffff0000, v76
	v_lshlrev_b32_e32 v82, 16, v77
	v_and_b32_e32 v83, 0xffff0000, v77
	v_lshlrev_b32_e32 v84, 16, v78
	v_and_b32_e32 v85, 0xffff0000, v78
	v_lshlrev_b32_e32 v86, 16, v79
	v_and_b32_e32 v87, 0xffff0000, v79
	s_waitcnt vmcnt(19)
	s_nop 1
	v_mov_b64_e32 v[76:77], v[232:233]
	v_mov_b64_e32 v[78:79], v[234:235]
	v_lshlrev_b32_e32 v88, 16, v76
	v_fmac_f32_e32 v88, v72, v80
	v_and_b32_e32 v72, 0xffff0000, v76
	v_fmac_f32_e32 v72, v73, v81
	v_lshlrev_b32_e32 v73, 16, v77
	v_fmac_f32_e32 v73, v74, v82
	v_and_b32_e32 v74, 0xffff0000, v77
	v_fmac_f32_e32 v74, v75, v83
	v_lshlrev_b32_e32 v75, 16, v78
	v_fmac_f32_e32 v75, v68, v84
	v_and_b32_e32 v76, 0xffff0000, v78
	v_lshlrev_b32_e32 v77, 16, v79
	v_and_b32_e32 v78, 0xffff0000, v79
	v_cvt_pk_bf16_f32 v68, v88, v72
	v_fmac_f32_e32 v76, v69, v85
	v_fmac_f32_e32 v77, v70, v86
	v_fmac_f32_e32 v78, v71, v87
	v_cvt_pk_bf16_f32 v69, v73, v74
	v_cvt_pk_bf16_f32 v70, v75, v76
	v_cvt_pk_bf16_f32 v71, v77, v78
	global_store_dwordx4 v[90:91], v[68:71], off offset:256
	v_add_u32_e32 v237, 0x160000, v236
	v_add_u32_e32 v239, 0xb0000, v238
	global_load_dwordx4 v[220:223], v237, s[2:3]
	global_load_dwordx4 v[224:227], v239, s[12:13]
	global_load_dwordx4 v[228:231], v237, s[2:3] offset:256
	global_load_dwordx4 v[232:235], v239, s[12:13] offset:256
	s_nop 1
	v_add_u32_e32 v68, 0x80, v134
	v_ashrrev_i32_e32 v69, 31, v68
	v_lshlrev_b64 v[70:71], 13, v[68:69]
	v_lshlrev_b64 v[74:75], 12, v[68:69]
	v_lshl_add_u64 v[68:69], s[2:3], 0, v[70:71]
	v_lshl_add_u64 v[70:71], v[68:69], 0, v[132:133]
	v_lshl_add_u64 v[68:69], v[70:71], 0, s[20:21]
	v_add_co_u32_e32 v70, vcc, s76, v70
	s_nop 1
	v_addc_co_u32_e32 v71, vcc, 0, v71, vcc
	s_waitcnt vmcnt(21)
	s_nop 1
	v_mov_b64_e32 v[70:71], v[172:173]
	v_mov_b64_e32 v[72:73], v[174:175]
	v_lshlrev_b32_e32 v76, 16, v70
	v_and_b32_e32 v77, 0xffff0000, v70
	v_lshlrev_b32_e32 v78, 16, v71
	v_and_b32_e32 v79, 0xffff0000, v71
	v_lshl_add_u64 v[70:71], s[12:13], 0, v[74:75]
	v_lshl_add_u64 v[74:75], v[70:71], 0, v[132:133]
	v_lshlrev_b32_e32 v80, 16, v72
	v_and_b32_e32 v81, 0xffff0000, v72
	v_lshlrev_b32_e32 v82, 16, v73
	v_and_b32_e32 v83, 0xffff0000, v73
	s_waitcnt vmcnt(20)
	s_nop 1
	v_mov_b64_e32 v[70:71], v[176:177]
	v_mov_b64_e32 v[72:73], v[178:179]
	v_lshlrev_b32_e32 v84, 16, v70
	v_fmac_f32_e32 v84, v64, v76
	v_and_b32_e32 v64, 0xffff0000, v70
	v_fmac_f32_e32 v64, v65, v77
	v_lshlrev_b32_e32 v65, 16, v71
	v_fmac_f32_e32 v65, v66, v78
	v_and_b32_e32 v66, 0xffff0000, v71
	v_fmac_f32_e32 v66, v67, v79
	v_lshlrev_b32_e32 v67, 16, v72
	v_and_b32_e32 v70, 0xffff0000, v72
	v_lshlrev_b32_e32 v71, 16, v73
	v_and_b32_e32 v72, 0xffff0000, v73
	v_fmac_f32_e32 v67, v60, v80
	v_fmac_f32_e32 v70, v61, v81
	v_fmac_f32_e32 v71, v62, v82
	v_fmac_f32_e32 v72, v63, v83
	v_cvt_pk_bf16_f32 v60, v84, v64
	v_cvt_pk_bf16_f32 v61, v65, v66
	v_cvt_pk_bf16_f32 v62, v67, v70
	v_cvt_pk_bf16_f32 v63, v71, v72
	global_store_dwordx4 v[74:75], v[60:63], off
	s_waitcnt vmcnt(20)
; __device__ __forceinline__ unsigned cvt_pk_bf16(float lo, float hi) { unsigned r; asm volatile("v_cvt_pk_bf16_f32 %0, %1, %2" : "=v"(r) : "v"(lo), "v"(hi)); return r; }
; #define LAS __attribute__((address_space(3)))
; __device__ __forceinline__ float bflo(unsigned w) { return __uint_as_float(w << 16); }
; __device__ __forceinline__ float bfhi(unsigned w) { return __uint_as_float(w & 0xffff0000u); }
;     __device__ __forceinline__ void operator()(const f32x4 (&acc)[2][2][4][2], const Unit& u, int wr, int wc, int fr, int fq, const LAS float*) const {
;         const int row0 = u.pm * 256 + wr * 64 + fr, col0 = u.pn * 256 + wc * 32 + 8 * fq;
; #pragma unroll
;         for (int ai = 0; ai < 2; ++ai)
; #pragma unroll
;             for (int m = 0; m < 4; ++m) { const size_t row = (size_t)(row0 + ai * 128 + m * 16);
; #pragma unroll
;                 for (int bj = 0; bj < 2; ++bj) { const int col = col0 + bj * 128;
;                     const u32x4 g = *(const u32x4*)(G + row * NGATE + MODE * DM + col);
;                     f32x4 v0 = acc[ai][bj][m][0], v1 = acc[ai][bj][m][1];
;                     v0[0] *= bflo(g.x); v0[1] *= bfhi(g.x); v0[2] *= bflo(g.y); v0[3] *= bfhi(g.y); v1[0] *= bflo(g.z); v1[1] *= bfhi(g.z); v1[2] *= bflo(g.w); v1[3] *= bfhi(g.w);
;                     bf16_t* tp = T + row * DM + col;
;                     if (MODE == 1) { const u32x4 t = *(const u32x4*)tp;
;                         v0[0] += bflo(t.x); v0[1] += bfhi(t.x); v0[2] += bflo(t.y); v0[3] += bfhi(t.y); v1[0] += bflo(t.z); v1[1] += bfhi(t.z); v1[2] += bflo(t.w); v1[3] += bfhi(t.w); }
;                     u32x4 w; w.x = cvt_pk_bf16(v0[0], v0[1]); w.y = cvt_pk_bf16(v0[2], v0[3]); w.z = cvt_pk_bf16(v1[0], v1[1]); w.w = cvt_pk_bf16(v1[2], v1[3]);
;                     *(u32x4*)tp = w; } }
	s_nop 1
	v_mov_b64_e32 v[60:61], v[180:181]
	v_mov_b64_e32 v[62:63], v[182:183]
	v_lshlrev_b32_e32 v64, 16, v60
	v_and_b32_e32 v65, 0xffff0000, v60
	v_lshlrev_b32_e32 v66, 16, v61
	v_and_b32_e32 v67, 0xffff0000, v61
	v_lshlrev_b32_e32 v68, 16, v62
	v_and_b32_e32 v69, 0xffff0000, v62
	v_lshlrev_b32_e32 v70, 16, v63
	v_and_b32_e32 v71, 0xffff0000, v63
	s_waitcnt vmcnt(19)
	s_nop 1
	v_mov_b64_e32 v[60:61], v[184:185]
	v_mov_b64_e32 v[62:63], v[186:187]
	v_lshlrev_b32_e32 v72, 16, v60
	v_fmac_f32_e32 v72, v56, v64
	v_and_b32_e32 v56, 0xffff0000, v60
	v_fmac_f32_e32 v56, v57, v65
	v_lshlrev_b32_e32 v57, 16, v61
	v_fmac_f32_e32 v57, v58, v66
	v_and_b32_e32 v58, 0xffff0000, v61
	v_fmac_f32_e32 v58, v59, v67
	v_lshlrev_b32_e32 v59, 16, v62
	v_fmac_f32_e32 v59, v52, v68
	v_and_b32_e32 v60, 0xffff0000, v62
	v_lshlrev_b32_e32 v61, 16, v63
	v_and_b32_e32 v62, 0xffff0000, v63
	v_cvt_pk_bf16_f32 v52, v72, v56
	v_fmac_f32_e32 v60, v53, v69
	v_fmac_f32_e32 v61, v54, v70
	v_fmac_f32_e32 v62, v55, v71
	v_cvt_pk_bf16_f32 v53, v57, v58
	v_cvt_pk_bf16_f32 v54, v59, v60
	v_cvt_pk_bf16_f32 v55, v61, v62
	global_store_dwordx4 v[74:75], v[52:55], off offset:256
	s_nop 1
	v_add_u32_e32 v52, 0x90, v134
	v_ashrrev_i32_e32 v53, 31, v52
	v_lshlrev_b64 v[54:55], 13, v[52:53]
	v_lshlrev_b64 v[58:59], 12, v[52:53]
	v_lshl_add_u64 v[52:53], s[2:3], 0, v[54:55]
	v_lshl_add_u64 v[54:55], v[52:53], 0, v[132:133]
	v_lshl_add_u64 v[52:53], v[54:55], 0, s[20:21]
	v_add_co_u32_e32 v54, vcc, s76, v54
	s_nop 1
	v_addc_co_u32_e32 v55, vcc, 0, v55, vcc
	s_waitcnt vmcnt(17)
	s_nop 1
	v_mov_b64_e32 v[54:55], v[188:189]
	v_mov_b64_e32 v[56:57], v[190:191]
	v_lshlrev_b32_e32 v60, 16, v54
	v_and_b32_e32 v61, 0xffff0000, v54
	v_lshlrev_b32_e32 v62, 16, v55
	v_and_b32_e32 v63, 0xffff0000, v55
	v_lshl_add_u64 v[54:55], s[12:13], 0, v[58:59]
	v_lshl_add_u64 v[58:59], v[54:55], 0, v[132:133]
	v_lshlrev_b32_e32 v64, 16, v56
	v_and_b32_e32 v65, 0xffff0000, v56
	v_lshlrev_b32_e32 v66, 16, v57
	v_and_b32_e32 v67, 0xffff0000, v57
	s_waitcnt vmcnt(16)
	s_nop 1
	v_mov_b64_e32 v[54:55], v[192:193]
	v_mov_b64_e32 v[56:57], v[194:195]
	v_lshlrev_b32_e32 v68, 16, v54
	v_fmac_f32_e32 v68, v48, v60
	v_and_b32_e32 v48, 0xffff0000, v54
	v_fmac_f32_e32 v48, v49, v61
	v_lshlrev_b32_e32 v49, 16, v55
	v_fmac_f32_e32 v49, v50, v62
	v_and_b32_e32 v50, 0xffff0000, v55
	v_fmac_f32_e32 v50, v51, v63
	v_lshlrev_b32_e32 v51, 16, v56
	v_and_b32_e32 v54, 0xffff0000, v56
	v_lshlrev_b32_e32 v55, 16, v57
	v_and_b32_e32 v56, 0xffff0000, v57
	v_fmac_f32_e32 v51, v44, v64
	v_fmac_f32_e32 v54, v45, v65
	v_fmac_f32_e32 v55, v46, v66
	v_fmac_f32_e32 v56, v47, v67
	v_cvt_pk_bf16_f32 v44, v68, v48
	v_cvt_pk_bf16_f32 v45, v49, v50
	v_cvt_pk_bf16_f32 v46, v51, v54
	v_cvt_pk_bf16_f32 v47, v55, v56
	global_store_dwordx4 v[58:59], v[44:47], off
	s_waitcnt vmcnt(16)
	s_nop 1
	v_mov_b64_e32 v[44:45], v[196:197]
	v_mov_b64_e32 v[46:47], v[198:199]
	v_lshlrev_b32_e32 v48, 16, v44
	v_and_b32_e32 v49, 0xffff0000, v44
	v_lshlrev_b32_e32 v50, 16, v45
	v_and_b32_e32 v51, 0xffff0000, v45
	v_lshlrev_b32_e32 v52, 16, v46
	v_and_b32_e32 v53, 0xffff0000, v46
	v_lshlrev_b32_e32 v54, 16, v47
	v_and_b32_e32 v55, 0xffff0000, v47
	s_waitcnt vmcnt(15)
	s_nop 1
	v_mov_b64_e32 v[44:45], v[200:201]
	v_mov_b64_e32 v[46:47], v[202:203]
	v_lshlrev_b32_e32 v56, 16, v44
	v_fmac_f32_e32 v56, v40, v48
	v_and_b32_e32 v40, 0xffff0000, v44
	v_fmac_f32_e32 v40, v41, v49
	v_lshlrev_b32_e32 v41, 16, v45
	v_fmac_f32_e32 v41, v42, v50
	v_and_b32_e32 v42, 0xffff0000, v45
	v_fmac_f32_e32 v42, v43, v51
	v_lshlrev_b32_e32 v43, 16, v46
	v_fmac_f32_e32 v43, v36, v52
	v_and_b32_e32 v44, 0xffff0000, v46
	v_lshlrev_b32_e32 v45, 16, v47
	v_and_b32_e32 v46, 0xffff0000, v47
	v_cvt_pk_bf16_f32 v36, v56, v40
	v_fmac_f32_e32 v44, v37, v53
	v_fmac_f32_e32 v45, v38, v54
	v_fmac_f32_e32 v46, v39, v55
	v_cvt_pk_bf16_f32 v37, v41, v42
	v_cvt_pk_bf16_f32 v38, v43, v44
	v_cvt_pk_bf16_f32 v39, v45, v46
	global_store_dwordx4 v[58:59], v[36:39], off offset:256
	s_nop 1
	v_add_u32_e32 v36, 0xa0, v134
	v_ashrrev_i32_e32 v37, 31, v36
	v_lshlrev_b64 v[38:39], 13, v[36:37]
	v_lshlrev_b64 v[42:43], 12, v[36:37]
	v_lshl_add_u64 v[36:37], s[2:3], 0, v[38:39]
	v_lshl_add_u64 v[38:39], v[36:37], 0, v[132:133]
	v_lshl_add_u64 v[36:37], v[38:39], 0, s[20:21]
	v_add_co_u32_e32 v38, vcc, s76, v38
	s_nop 1
	v_addc_co_u32_e32 v39, vcc, 0, v39, vcc
	s_waitcnt vmcnt(13)
	s_nop 1
	v_mov_b64_e32 v[38:39], v[204:205]
	v_mov_b64_e32 v[40:41], v[206:207]
	v_lshlrev_b32_e32 v44, 16, v38
	v_and_b32_e32 v45, 0xffff0000, v38
	v_lshlrev_b32_e32 v46, 16, v39
	v_and_b32_e32 v47, 0xffff0000, v39
	v_lshl_add_u64 v[38:39], s[12:13], 0, v[42:43]
	v_lshl_add_u64 v[42:43], v[38:39], 0, v[132:133]
	v_lshlrev_b32_e32 v48, 16, v40
	v_and_b32_e32 v49, 0xffff0000, v40
	v_lshlrev_b32_e32 v50, 16, v41
	v_and_b32_e32 v51, 0xffff0000, v41
	s_waitcnt vmcnt(12)
; __device__ __forceinline__ unsigned cvt_pk_bf16(float lo, float hi) { unsigned r; asm volatile("v_cvt_pk_bf16_f32 %0, %1, %2" : "=v"(r) : "v"(lo), "v"(hi)); return r; }
; #define LAS __attribute__((address_space(3)))
; __device__ __forceinline__ float bflo(unsigned w) { return __uint_as_float(w << 16); }
; __device__ __forceinline__ float bfhi(unsigned w) { return __uint_as_float(w & 0xffff0000u); }
;     __device__ __forceinline__ void operator()(const f32x4 (&acc)[2][2][4][2], const Unit& u, int wr, int wc, int fr, int fq, const LAS float*) const {
;         const int row0 = u.pm * 256 + wr * 64 + fr, col0 = u.pn * 256 + wc * 32 + 8 * fq;
; #pragma unroll
;         for (int ai = 0; ai < 2; ++ai)
; #pragma unroll
;             for (int m = 0; m < 4; ++m) { const size_t row = (size_t)(row0 + ai * 128 + m * 16);
; #pragma unroll
;                 for (int bj = 0; bj < 2; ++bj) { const int col = col0 + bj * 128;
;                     const u32x4 g = *(const u32x4*)(G + row * NGATE + MODE * DM + col);
;                     f32x4 v0 = acc[ai][bj][m][0], v1 = acc[ai][bj][m][1];
;                     v0[0] *= bflo(g.x); v0[1] *= bfhi(g.x); v0[2] *= bflo(g.y); v0[3] *= bfhi(g.y); v1[0] *= bflo(g.z); v1[1] *= bfhi(g.z); v1[2] *= bflo(g.w); v1[3] *= bfhi(g.w);
;                     bf16_t* tp = T + row * DM + col;
;                     if (MODE == 1) { const u32x4 t = *(const u32x4*)tp;
;                         v0[0] += bflo(t.x); v0[1] += bfhi(t.x); v0[2] += bflo(t.y); v0[3] += bfhi(t.y); v1[0] += bflo(t.z); v1[1] += bfhi(t.z); v1[2] += bflo(t.w); v1[3] += bfhi(t.w); }
;                     u32x4 w; w.x = cvt_pk_bf16(v0[0], v0[1]); w.y = cvt_pk_bf16(v0[2], v0[3]); w.z = cvt_pk_bf16(v1[0], v1[1]); w.w = cvt_pk_bf16(v1[2], v1[3]);
;                     *(u32x4*)tp = w; } }
	s_nop 1
	v_mov_b64_e32 v[38:39], v[208:209]
	v_mov_b64_e32 v[40:41], v[210:211]
	v_lshlrev_b32_e32 v52, 16, v38
	v_fmac_f32_e32 v52, v32, v44
	v_and_b32_e32 v32, 0xffff0000, v38
	v_fmac_f32_e32 v32, v33, v45
	v_lshlrev_b32_e32 v33, 16, v39
	v_fmac_f32_e32 v33, v34, v46
	v_and_b32_e32 v34, 0xffff0000, v39
	v_fmac_f32_e32 v34, v35, v47
	v_lshlrev_b32_e32 v35, 16, v40
	v_and_b32_e32 v38, 0xffff0000, v40
	v_lshlrev_b32_e32 v39, 16, v41
	v_and_b32_e32 v40, 0xffff0000, v41
	v_fmac_f32_e32 v35, v28, v48
	v_fmac_f32_e32 v38, v29, v49
	v_fmac_f32_e32 v39, v30, v50
	v_fmac_f32_e32 v40, v31, v51
	v_cvt_pk_bf16_f32 v28, v52, v32
	v_cvt_pk_bf16_f32 v29, v33, v34
	v_cvt_pk_bf16_f32 v30, v35, v38
	v_cvt_pk_bf16_f32 v31, v39, v40
	global_store_dwordx4 v[42:43], v[28:31], off
	s_waitcnt vmcnt(12)
	s_nop 1
	v_mov_b64_e32 v[28:29], v[212:213]
	v_mov_b64_e32 v[30:31], v[214:215]
	v_lshlrev_b32_e32 v32, 16, v28
	v_and_b32_e32 v33, 0xffff0000, v28
	v_lshlrev_b32_e32 v34, 16, v29
	v_and_b32_e32 v35, 0xffff0000, v29
	v_lshlrev_b32_e32 v36, 16, v30
	v_and_b32_e32 v37, 0xffff0000, v30
	v_lshlrev_b32_e32 v38, 16, v31
	v_and_b32_e32 v39, 0xffff0000, v31
	s_waitcnt vmcnt(11)
	s_nop 1
	v_mov_b64_e32 v[28:29], v[216:217]
	v_mov_b64_e32 v[30:31], v[218:219]
	v_lshlrev_b32_e32 v40, 16, v28
	v_fmac_f32_e32 v40, v24, v32
	v_and_b32_e32 v24, 0xffff0000, v28
	v_fmac_f32_e32 v24, v25, v33
	v_lshlrev_b32_e32 v25, 16, v29
	v_fmac_f32_e32 v25, v26, v34
	v_and_b32_e32 v26, 0xffff0000, v29
	v_fmac_f32_e32 v26, v27, v35
	v_lshlrev_b32_e32 v27, 16, v30
	v_fmac_f32_e32 v27, v20, v36
	v_and_b32_e32 v28, 0xffff0000, v30
	v_lshlrev_b32_e32 v29, 16, v31
	v_and_b32_e32 v30, 0xffff0000, v31
	v_cvt_pk_bf16_f32 v20, v40, v24
	v_fmac_f32_e32 v28, v21, v37
	v_fmac_f32_e32 v29, v22, v38
	v_fmac_f32_e32 v30, v23, v39
	v_cvt_pk_bf16_f32 v21, v25, v26
	v_cvt_pk_bf16_f32 v22, v27, v28
	v_cvt_pk_bf16_f32 v23, v29, v30
	global_store_dwordx4 v[42:43], v[20:23], off offset:256
	s_nop 1
	v_add_u32_e32 v20, 0xb0, v134
	v_ashrrev_i32_e32 v21, 31, v20
	v_lshlrev_b64 v[22:23], 13, v[20:21]
	v_lshlrev_b64 v[26:27], 12, v[20:21]
	v_lshl_add_u64 v[20:21], s[2:3], 0, v[22:23]
	v_lshl_add_u64 v[22:23], v[20:21], 0, v[132:133]
	v_lshl_add_u64 v[20:21], v[22:23], 0, s[20:21]
	v_add_co_u32_e32 v22, vcc, s76, v22
	s_mov_b64 s[20:21], s[16:17]
	s_nop 0
	v_addc_co_u32_e32 v23, vcc, 0, v23, vcc
	s_andn2_b64 vcc, exec, s[6:7]
	s_waitcnt vmcnt(9)
	s_nop 1
	v_mov_b64_e32 v[22:23], v[220:221]
	v_mov_b64_e32 v[24:25], v[222:223]
	v_lshlrev_b32_e32 v28, 16, v22
	v_and_b32_e32 v29, 0xffff0000, v22
	v_lshlrev_b32_e32 v30, 16, v23
	v_and_b32_e32 v31, 0xffff0000, v23
	v_lshl_add_u64 v[22:23], s[12:13], 0, v[26:27]
	v_lshl_add_u64 v[26:27], v[22:23], 0, v[132:133]
	v_lshlrev_b32_e32 v32, 16, v24
	v_and_b32_e32 v33, 0xffff0000, v24
	v_lshlrev_b32_e32 v34, 16, v25
	v_and_b32_e32 v35, 0xffff0000, v25
	s_waitcnt vmcnt(8)
	s_nop 1
	v_mov_b64_e32 v[22:23], v[224:225]
	v_mov_b64_e32 v[24:25], v[226:227]
	v_lshlrev_b32_e32 v36, 16, v22
	v_fmac_f32_e32 v36, v16, v28
	v_and_b32_e32 v16, 0xffff0000, v22
	v_fmac_f32_e32 v16, v17, v29
	v_lshlrev_b32_e32 v17, 16, v23
	v_fmac_f32_e32 v17, v18, v30
	v_and_b32_e32 v18, 0xffff0000, v23
	v_fmac_f32_e32 v18, v19, v31
	v_lshlrev_b32_e32 v19, 16, v24
	v_and_b32_e32 v22, 0xffff0000, v24
	v_lshlrev_b32_e32 v23, 16, v25
	v_and_b32_e32 v24, 0xffff0000, v25
	v_fmac_f32_e32 v19, v12, v32
	v_fmac_f32_e32 v22, v13, v33
	v_fmac_f32_e32 v23, v14, v34
	v_fmac_f32_e32 v24, v15, v35
	v_cvt_pk_bf16_f32 v12, v36, v16
	v_cvt_pk_bf16_f32 v13, v17, v18
	v_cvt_pk_bf16_f32 v14, v19, v22
	v_cvt_pk_bf16_f32 v15, v23, v24
	global_store_dwordx4 v[26:27], v[12:15], off
	s_waitcnt vmcnt(8)
	s_nop 1
	v_mov_b64_e32 v[12:13], v[228:229]
	v_mov_b64_e32 v[14:15], v[230:231]
	v_lshlrev_b32_e32 v16, 16, v12
	v_and_b32_e32 v17, 0xffff0000, v12
	v_lshlrev_b32_e32 v18, 16, v13
	v_and_b32_e32 v19, 0xffff0000, v13
	v_lshlrev_b32_e32 v20, 16, v14
	v_and_b32_e32 v21, 0xffff0000, v14
	v_lshlrev_b32_e32 v22, 16, v15
	v_and_b32_e32 v23, 0xffff0000, v15
	s_waitcnt vmcnt(7)
	s_nop 1
	v_mov_b64_e32 v[12:13], v[232:233]
	v_mov_b64_e32 v[14:15], v[234:235]
	v_lshlrev_b32_e32 v24, 16, v12
	v_fmac_f32_e32 v24, v4, v16
	v_and_b32_e32 v4, 0xffff0000, v12
	v_fmac_f32_e32 v4, v5, v17
	v_lshlrev_b32_e32 v5, 16, v13
	v_fmac_f32_e32 v5, v6, v18
	v_and_b32_e32 v6, 0xffff0000, v13
	v_fmac_f32_e32 v6, v7, v19
	v_lshlrev_b32_e32 v7, 16, v14
	v_fmac_f32_e32 v7, v8, v20
	v_and_b32_e32 v8, 0xffff0000, v14
	v_fmac_f32_e32 v8, v9, v21
	v_lshlrev_b32_e32 v9, 16, v15
	v_fmac_f32_e32 v9, v10, v22
	v_and_b32_e32 v10, 0xffff0000, v15
	v_fmac_f32_e32 v10, v11, v23
	v_cvt_pk_bf16_f32 v4, v24, v4
	v_cvt_pk_bf16_f32 v5, v5, v6
	v_cvt_pk_bf16_f32 v6, v7, v8
	v_cvt_pk_bf16_f32 v7, v9, v10
	global_store_dwordx4 v[26:27], v[4:7], off offset:256
	s_cbranch_vccnz .LBB0_164
	s_waitcnt vmcnt(0) lgkmcnt(0)
	s_barrier

; #define PG8_STAGE4(b, pa, pb) do { PG8_STAGE(PG8_SB(b, 0), (pb), voffB); PG8_STAGE(PG8_SA(b, 0), (pa), voffA); PG8_STAGE(PG8_SB(b, 1), (pb) + hstep, voffB); PG8_STAGE(PG8_SA(b, 1), (pa) + hstep, voffA); } while (0)
; #define PG8_SYNC() do { asm volatile("s_waitcnt vmcnt(0) lgkmcnt(0)" ::: "memory"); __builtin_amdgcn_s_barrier(); asm volatile("" ::: "memory"); } while (0)
; template <class Epi, class Sched>
; __device__ __forceinline__ void gemm_simple(PG8_LAS unsigned char* lds, const Gemm g, const Sched& S, const Epi& E, int wave_s) {
;     ...
;     for (int i = 0; i < 2; ++i) { int R, C; stage_rc(tid * 16 + i * 8192, R, C); const int Rb = Epi::PERM ? ((R & ~31) + perm32(R & 31)) : R;
;         voffA[i] = (unsigned)(R * K + C) * 2u; voffB[i] = (unsigned)(Rb * K + C) * 2u; }
;     const size_t kstep = (size_t)(BK * 2), hstep = (size_t)HALF * K * 2, tstep = 2 * hstep;
;     const unsigned ldsw = (unsigned)wid * 1024u; const unsigned lds_u = (unsigned)(__UINTPTR_TYPE__)lds;
;     const int aoff = lds_byte(wr * 64 + fr, fq * 8), boff = lds_byte(wc * 32 + fr, fq * 8);
;     ...
;     const char* cA = (const char*)g.A + (size_t)cur.pm * tstep; const char* cB = (const char*)g.Bt + (size_t)cur.pn * tstep;
;     PG8_SYNC();
;     PG8_STAGE4(0, cA, cB);
.LBB0_185:
	v_ashrrev_i32_e32 v4, 31, v2
	v_lshrrev_b32_e32 v4, 26, v4
	v_lshlrev_b32_e32 v3, 4, v2
	v_add_u32_e32 v4, v2, v4
	v_bfe_i32 v2, v2, 27, 1
	v_lshrrev_b32_e32 v2, 22, v2
	v_add_u32_e32 v2, v3, v2
	v_and_b32_e32 v2, 0xfffffc00, v2
	v_sub_u32_e32 v2, v3, v2
	s_waitcnt lgkmcnt(0)
	v_lshrrev_b32_e32 v5, 4, v2
	v_bitop3_b32 v2, v5, v2, 32 bitop3:0x6c
	v_ashrrev_i32_e32 v6, 31, v2
	v_ashrrev_i32_e32 v4, 6, v4
	v_lshrrev_b32_e32 v6, 26, v6
	v_lshlrev_b32_e32 v5, 3, v4
	v_add_u32_e32 v6, v2, v6
	v_and_b32_e32 v5, -16, v5
	v_ashrrev_i32_e32 v7, 6, v6
	v_and_b32_e32 v6, 0xc0, v6
	v_add_u32_e32 v5, v7, v5
	v_sub_u32_e32 v2, v2, v6
	s_ashr_i32 s4, s8, 3
	v_lshlrev_b32_e32 v4, 5, v4
	v_ashrrev_i16_sdwa v2, v166, sext(v2) dst_sel:DWORD dst_unused:UNUSED_PAD src0_sel:DWORD src1_sel:BYTE_0
	v_lshlrev_b32_e32 v6, 1, v5
	v_lshrrev_b32_e32 v8, 2, v5
	v_and_b32_e32 v7, 3, v7
	s_mov_b32 s8, 0x3fffe0
	v_and_b32_e32 v4, 32, v4
	v_bfe_i32 v2, v2, 0, 16
	v_and_b32_e32 v6, 24, v6
	v_and_b32_e32 v8, 4, v8
	v_and_or_b32 v7, v5, s8, v7
	v_or3_b32 v6, v7, v8, v6
	v_add_lshl_u32 v2, v4, v2, 1
	v_lshl_add_u32 v136, v5, 10, v2
	v_lshl_add_u32 v137, v6, 10, v2
	v_add_u32_e32 v2, 0x2000, v3
	v_ashrrev_i32_e32 v3, 31, v2
	v_lshrrev_b32_e32 v3, 22, v3
	v_add_u32_e32 v3, v2, v3
	v_ashrrev_i32_e32 v3, 10, v3
	v_mul_i32_i24_e32 v4, 0x400, v3
	v_sub_u32_e32 v2, v2, v4
	v_lshrrev_b32_e32 v4, 4, v2
	v_bitop3_b32 v2, v4, v2, 32 bitop3:0x6c
	v_ashrrev_i32_e32 v5, 31, v2
	v_lshrrev_b32_e32 v5, 26, v5
	v_lshlrev_b32_e32 v4, 3, v3
	v_add_u32_e32 v5, v2, v5
	v_and_b32_e32 v4, -16, v4
	v_ashrrev_i32_e32 v6, 6, v5
	v_and_b32_e32 v5, 0xc0, v5
	v_readlane_b32 s5, v254, 57
	v_add_u32_e32 v4, v6, v4
	v_sub_u32_e32 v2, v2, v5
	s_add_u32 s27, s5, 0x2a00000
	v_readlane_b32 s5, v254, 58
	v_lshlrev_b32_e32 v3, 5, v3
	v_ashrrev_i16_sdwa v2, v166, sext(v2) dst_sel:DWORD dst_unused:UNUSED_PAD src0_sel:DWORD src1_sel:BYTE_0
	v_lshlrev_b32_e32 v5, 1, v4
	v_lshrrev_b32_e32 v7, 2, v4
	v_and_b32_e32 v6, 3, v6
	s_addc_u32 s28, s5, 0
	s_ashr_i32 s5, s6, 6
	v_and_b32_e32 v3, 32, v3
	v_bfe_i32 v2, v2, 0, 16
	v_and_b32_e32 v5, 24, v5
	v_and_b32_e32 v7, 4, v7
	v_and_or_b32 v6, v4, s8, v6
	v_or3_b32 v5, v6, v7, v5
	v_add_lshl_u32 v2, v3, v2, 1
	s_lshl_b32 s8, s5, 10
	s_lshl_b32 s5, s5, 5
	v_lshl_add_u32 v138, v4, 10, v2
	v_lshl_add_u32 v139, v5, 10, v2
	v_and_b32_e32 v2, 48, v1
	v_lshlrev_b32_e32 v3, 6, v1
	s_movk_i32 s9, 0x3c0
	v_lshlrev_b32_e32 v1, 2, v1
	s_and_b32 s35, s5, 0x60
	v_and_or_b32 v2, v3, s9, v2
	v_and_b32_e32 v1, 32, v1
	s_lshl_b32 s5, s35, 7
	s_add_i32 s4, s7, s4
	s_ashr_i32 s29, s6, 2
	v_bitop3_b32 v5, s5, v2, v1 bitop3:0xf6
	s_ashr_i32 s5, s4, 31
	s_andn2_b32 s29, s29, 63
	s_lshr_b32 s5, s5, 27
	s_lshl_b32 s6, s29, 7
	s_add_i32 s5, s4, s5
	v_bitop3_b32 v4, v2, s6, v1 bitop3:0xde
	s_ashr_i32 s6, s5, 5
	s_and_b32 s5, s5, 0xffe0
	s_sub_i32 s5, s4, s5
	s_bfe_i32 s4, s5, 0x80000
	s_bfe_u32 s4, s4, 0x2000d
	s_add_i32 s7, s5, s4
	s_bfe_i32 s4, s7, 0x80000
	s_and_b32 s7, s7, 0xfc
	s_sub_i32 s5, s5, s7
	s_lshl_b32 s6, s6, 2
	s_sext_i32_i16 s9, s4
	s_sext_i32_i8 s5, s5
	s_lshr_b32 s4, s9, 2
	s_add_i32 s16, s6, s5
	s_ashr_i32 s17, s16, 31
	s_bfe_i64 s[4:5], s[4:5], 0x100000
	s_ashr_i32 s53, s9, 2
	s_lshl_b64 s[6:7], s[16:17], 18
	s_lshl_b64 s[4:5], s[4:5], 18
	s_add_u32 s18, s27, s4
	s_addc_u32 s19, s28, s5
	s_waitcnt vmcnt(0) lgkmcnt(0)
	s_barrier
	s_add_i32 s17, s8, 0
	s_add_i32 s36, s17, 0x10000
	s_mov_b32 m0, s36
	s_nop 0
	global_load_lds_dwordx4 v137, s[18:19]
	s_add_i32 s37, s17, 0x12000
	s_mov_b32 m0, s37
	s_nop 0
	global_load_lds_dwordx4 v139, s[18:19]
	s_add_u32 s20, s96, s6
	s_addc_u32 s21, s97, s7
	s_mov_b32 m0, s17
	s_nop 0
	global_load_lds_dwordx4 v136, s[20:21]
	s_add_i32 s38, s17, 0x2000
	s_mov_b32 m0, s38
	s_nop 0
	global_load_lds_dwordx4 v138, s[20:21]
	s_add_u32 s4, s18, 0x20000
	s_addc_u32 s5, s19, 0
	s_add_i32 s39, s17, 0x14000
	s_mov_b32 m0, s39
	s_nop 0
	global_load_lds_dwordx4 v137, s[4:5]
	s_add_i32 s40, s17, 0x16000
	s_mov_b32 m0, s40
	s_nop 0
	global_load_lds_dwordx4 v139, s[4:5]
	s_add_u32 s4, s20, 0x20000
	s_addc_u32 s5, s21, 0
	s_add_i32 s41, s17, 0x4000
	s_mov_b32 m0, s41
	s_nop 0
	global_load_lds_dwordx4 v136, s[4:5]
	s_add_i32 s42, s17, 0x6000
	s_mov_b32 m0, s42
	s_nop 0
	global_load_lds_dwordx4 v138, s[4:5]
	v_mov_b32_e32 v1, v0
	v_mov_b32_e32 v2, v0
	v_mov_b32_e32 v3, v0
	s_add_i32 s43, s17, 0x18000
	s_add_i32 s44, s17, 0x8000
	s_add_i32 s45, s17, 0x1c000
	s_add_i32 s46, s17, 0xc000
	s_add_i32 s47, s17, 0x1a000
	s_add_i32 s48, s17, 0xa000
	s_add_i32 s49, s17, 0x1e000
	s_add_i32 s50, s17, 0xe000
	s_ashr_i32 s51, s34, 31
	s_mov_b32 s9, 0
	v_add_u32_e32 v140, 0, v5
	v_add_u32_e32 v152, 0, v4

; template <class Epi, class Sched>
; __device__ __forceinline__ void gemm_simple(PG8_LAS unsigned char* lds, const Gemm g, const Sched& S, const Epi& E, int wave_s) {
;     ...
; #pragma unroll
;         for (int a = 0; a < 2; ++a)
; #pragma unroll
;             for (int b = 0; b < 2; ++b)
; #pragma unroll
;                 for (int m = 0; m < 4; ++m)
; #pragma unroll
;                     for (int n = 0; n < 2; ++n) acc[a][b][m][n] = (f32x4){zero_o, zero_o, zero_o, zero_o};
.LBB0_192:
	v_mov_b64_e32 v[10:11], v[2:3]
	v_mov_b64_e32 v[6:7], v[2:3]
	v_mov_b64_e32 v[22:23], v[2:3]
	v_mov_b64_e32 v[26:27], v[2:3]
	v_mov_b64_e32 v[38:39], v[2:3]
	v_mov_b64_e32 v[42:43], v[2:3]
	v_mov_b64_e32 v[54:55], v[2:3]
	v_mov_b64_e32 v[58:59], v[2:3]
	v_mov_b64_e32 v[14:15], v[2:3]
	v_mov_b64_e32 v[18:19], v[2:3]
	v_mov_b64_e32 v[30:31], v[2:3]
	v_mov_b64_e32 v[34:35], v[2:3]
	v_mov_b64_e32 v[46:47], v[2:3]
	v_mov_b64_e32 v[50:51], v[2:3]
	v_mov_b64_e32 v[62:63], v[2:3]
	v_mov_b64_e32 v[66:67], v[2:3]
	v_mov_b64_e32 v[70:71], v[2:3]
	v_mov_b64_e32 v[74:75], v[2:3]
	v_mov_b64_e32 v[86:87], v[2:3]
	v_mov_b64_e32 v[90:91], v[2:3]
	v_mov_b64_e32 v[102:103], v[2:3]
	v_mov_b64_e32 v[106:107], v[2:3]
	v_mov_b64_e32 v[118:119], v[2:3]
	v_mov_b64_e32 v[122:123], v[2:3]
	v_mov_b64_e32 v[78:79], v[2:3]
	v_mov_b64_e32 v[82:83], v[2:3]
	v_mov_b64_e32 v[94:95], v[2:3]
	v_mov_b64_e32 v[98:99], v[2:3]
	v_mov_b64_e32 v[110:111], v[2:3]
	v_mov_b64_e32 v[114:115], v[2:3]
	v_mov_b64_e32 v[126:127], v[2:3]
	v_mov_b64_e32 v[130:131], v[2:3]
	v_cmp_lt_i64_e32 vcc, s[10:11], v[168:169]
	s_mov_b32 s22, 0
	s_cmp_eq_u32 s9, 0
	v_add_u32_e32 v132, 0x10000, v140
	v_add_u32_e32 v133, 0x14000, v140
	v_add_u32_e32 v134, 0x18000, v140
	v_add_u32_e32 v135, 0x1c000, v140
	v_mov_b64_e32 v[8:9], v[0:1]
	v_mov_b64_e32 v[4:5], v[0:1]
	v_mov_b64_e32 v[20:21], v[0:1]
	v_mov_b64_e32 v[24:25], v[0:1]
	v_mov_b64_e32 v[36:37], v[0:1]
	v_mov_b64_e32 v[40:41], v[0:1]
	v_mov_b64_e32 v[52:53], v[0:1]
	v_mov_b64_e32 v[56:57], v[0:1]
	v_mov_b64_e32 v[12:13], v[0:1]
	v_mov_b64_e32 v[16:17], v[0:1]
	v_mov_b64_e32 v[28:29], v[0:1]
	v_mov_b64_e32 v[32:33], v[0:1]
	v_mov_b64_e32 v[44:45], v[0:1]
	v_mov_b64_e32 v[48:49], v[0:1]
	v_mov_b64_e32 v[60:61], v[0:1]
	v_mov_b64_e32 v[64:65], v[0:1]
	v_mov_b64_e32 v[68:69], v[0:1]
	v_mov_b64_e32 v[72:73], v[0:1]
	v_mov_b64_e32 v[84:85], v[0:1]
	v_mov_b64_e32 v[88:89], v[0:1]
	v_mov_b64_e32 v[100:101], v[0:1]
	v_mov_b64_e32 v[104:105], v[0:1]
	v_mov_b64_e32 v[116:117], v[0:1]
	v_mov_b64_e32 v[120:121], v[0:1]
	v_mov_b64_e32 v[76:77], v[0:1]
	v_mov_b64_e32 v[80:81], v[0:1]
	v_mov_b64_e32 v[92:93], v[0:1]
	v_mov_b64_e32 v[96:97], v[0:1]
	v_mov_b64_e32 v[108:109], v[0:1]
	v_mov_b64_e32 v[112:113], v[0:1]
	v_mov_b64_e32 v[124:125], v[0:1]
	v_mov_b64_e32 v[128:129], v[0:1]
	s_cbranch_scc1 .LBB0_194
	s_waitcnt vmcnt(18) lgkmcnt(0)
	s_barrier
	ds_read_b128 v[4:7], v132
	ds_read_b128 v[8:11], v132 offset:1024
	ds_read_b128 v[12:15], v132 offset:2048
	ds_read_b128 v[16:19], v132 offset:3072
	ds_read_b128 v[20:23], v152
	ds_read_b128 v[24:27], v152 offset:1024
	ds_read_b128 v[28:31], v152 offset:2048
	ds_read_b128 v[32:35], v152 offset:3072
	ds_read_b128 v[36:39], v152 offset:4096
	ds_read_b128 v[40:43], v152 offset:5120
	ds_read_b128 v[44:47], v152 offset:6144
	ds_read_b128 v[48:51], v152 offset:7168
	ds_read_b128 v[52:55], v133
	ds_read_b128 v[56:59], v133 offset:1024
	ds_read_b128 v[60:63], v133 offset:2048
	ds_read_b128 v[64:67], v133 offset:3072
	s_add_u32 s10, s18, 0x80
	s_addc_u32 s11, s19, 0
	s_mov_b32 m0, s43
	s_nop 0
	global_load_lds_dwordx4 v137, s[10:11]
	s_mov_b32 m0, s47
	s_nop 0
	global_load_lds_dwordx4 v139, s[10:11]
	s_waitcnt lgkmcnt(5)
	v_mfma_f32_16x16x32_bf16 v[92:95], v[4:7], v[44:47], v[0:3]
	v_mfma_f32_16x16x32_bf16 v[68:71], v[4:7], v[20:23], v[0:3]
	v_mfma_f32_16x16x32_bf16 v[72:75], v[12:15], v[20:23], v[0:3]
	v_mfma_f32_16x16x32_bf16 v[76:79], v[4:7], v[28:31], v[0:3]
	v_mfma_f32_16x16x32_bf16 v[80:83], v[12:15], v[28:31], v[0:3]
	v_mfma_f32_16x16x32_bf16 v[84:87], v[4:7], v[36:39], v[0:3]
	v_mfma_f32_16x16x32_bf16 v[88:91], v[12:15], v[36:39], v[0:3]
	s_waitcnt lgkmcnt(4)
	v_mfma_f32_16x16x32_bf16 v[100:103], v[8:11], v[48:51], v[92:95]
	v_mfma_f32_16x16x32_bf16 v[92:95], v[12:15], v[44:47], v[0:3]
	v_mfma_f32_16x16x32_bf16 v[68:71], v[8:11], v[24:27], v[68:71]
	v_mfma_f32_16x16x32_bf16 v[72:75], v[16:19], v[24:27], v[72:75]
	v_mfma_f32_16x16x32_bf16 v[76:79], v[8:11], v[32:35], v[76:79]
	v_mfma_f32_16x16x32_bf16 v[80:83], v[16:19], v[32:35], v[80:83]
	v_mfma_f32_16x16x32_bf16 v[84:87], v[8:11], v[40:43], v[84:87]
	v_mfma_f32_16x16x32_bf16 v[88:91], v[16:19], v[40:43], v[88:91]
	v_mfma_f32_16x16x32_bf16 v[104:107], v[16:19], v[48:51], v[92:95]
	s_add_u32 s10, s20, 0x80
	s_addc_u32 s11, s21, 0
	s_mov_b32 m0, s44
	s_nop 0
	global_load_lds_dwordx4 v136, s[10:11]
	s_mov_b32 m0, s48
	s_nop 0
	global_load_lds_dwordx4 v138, s[10:11]
	s_waitcnt lgkmcnt(3)
	v_mfma_f32_16x16x32_bf16 v[92:95], v[52:55], v[20:23], v[0:3]
	s_waitcnt lgkmcnt(1)
	v_mfma_f32_16x16x32_bf16 v[20:23], v[60:63], v[20:23], v[0:3]
	v_mfma_f32_16x16x32_bf16 v[116:119], v[56:59], v[24:27], v[92:95]
	s_waitcnt lgkmcnt(0)
	v_mfma_f32_16x16x32_bf16 v[20:23], v[64:67], v[24:27], v[20:23]
	v_mfma_f32_16x16x32_bf16 v[24:27], v[52:55], v[28:31], v[0:3]
	v_mfma_f32_16x16x32_bf16 v[28:31], v[60:63], v[28:31], v[0:3]
	v_mfma_f32_16x16x32_bf16 v[24:27], v[56:59], v[32:35], v[24:27]
	v_mfma_f32_16x16x32_bf16 v[28:31], v[64:67], v[32:35], v[28:31]
	v_mfma_f32_16x16x32_bf16 v[32:35], v[52:55], v[36:39], v[0:3]
	v_mfma_f32_16x16x32_bf16 v[36:39], v[60:63], v[36:39], v[0:3]
	v_mfma_f32_16x16x32_bf16 v[32:35], v[56:59], v[40:43], v[32:35]
	v_mfma_f32_16x16x32_bf16 v[36:39], v[64:67], v[40:43], v[36:39]
	v_mfma_f32_16x16x32_bf16 v[40:43], v[52:55], v[44:47], v[0:3]
	v_mfma_f32_16x16x32_bf16 v[44:47], v[60:63], v[44:47], v[0:3]
	v_mfma_f32_16x16x32_bf16 v[40:43], v[56:59], v[48:51], v[40:43]
	v_mfma_f32_16x16x32_bf16 v[44:47], v[64:67], v[48:51], v[44:47]
	s_waitcnt vmcnt(20) lgkmcnt(0)
	s_barrier
	ds_read_b128 v[48:51], v152 offset:16384
	ds_read_b128 v[92:95], v152 offset:17408
	ds_read_b128 v[96:99], v152 offset:18432
	ds_read_b128 v[108:111], v152 offset:19456
	ds_read_b128 v[112:115], v152 offset:20480
	ds_read_b128 v[120:123], v152 offset:21504
	ds_read_b128 v[124:127], v152 offset:22528
	ds_read_b128 v[128:131], v152 offset:23552
	s_add_u32 s10, s18, 0x20080
	s_addc_u32 s11, s19, 0
	s_mov_b32 m0, s45
	s_nop 0
	global_load_lds_dwordx4 v137, s[10:11]
	s_mov_b32 m0, s49
	s_nop 0
	global_load_lds_dwordx4 v139, s[10:11]
	s_waitcnt lgkmcnt(7)
	v_mfma_f32_16x16x32_bf16 v[146:149], v[4:7], v[48:51], v[0:3]
	s_waitcnt lgkmcnt(5)
	v_mfma_f32_16x16x32_bf16 v[158:161], v[4:7], v[96:99], v[0:3]
	s_waitcnt lgkmcnt(3)
	v_mfma_f32_16x16x32_bf16 v[174:177], v[4:7], v[112:115], v[0:3]
	s_waitcnt lgkmcnt(1)
	v_mfma_f32_16x16x32_bf16 v[4:7], v[4:7], v[124:127], v[0:3]
	v_mfma_f32_16x16x32_bf16 v[146:149], v[8:11], v[92:95], v[146:149]
	v_mfma_f32_16x16x32_bf16 v[158:161], v[8:11], v[108:111], v[158:161]
	v_mfma_f32_16x16x32_bf16 v[174:177], v[8:11], v[120:123], v[174:177]
	s_waitcnt lgkmcnt(0)
	v_mfma_f32_16x16x32_bf16 v[4:7], v[8:11], v[128:131], v[4:7]
	v_mfma_f32_16x16x32_bf16 v[8:11], v[12:15], v[124:127], v[0:3]
	v_mfma_f32_16x16x32_bf16 v[154:157], v[12:15], v[48:51], v[0:3]
	v_mfma_f32_16x16x32_bf16 v[170:173], v[12:15], v[96:99], v[0:3]
	v_mfma_f32_16x16x32_bf16 v[178:181], v[12:15], v[112:115], v[0:3]
	v_mfma_f32_16x16x32_bf16 v[8:11], v[16:19], v[128:131], v[8:11]
	v_mfma_f32_16x16x32_bf16 v[154:157], v[16:19], v[92:95], v[154:157]
	v_mfma_f32_16x16x32_bf16 v[170:173], v[16:19], v[108:111], v[170:173]
	v_mfma_f32_16x16x32_bf16 v[178:181], v[16:19], v[120:123], v[178:181]
	s_add_u32 s10, s20, 0x20080
	s_addc_u32 s11, s21, 0
	s_mov_b32 m0, s46
	s_nop 0
	global_load_lds_dwordx4 v136, s[10:11]
	s_mov_b32 m0, s50
	s_nop 0
	global_load_lds_dwordx4 v138, s[10:11]
	v_mfma_f32_16x16x32_bf16 v[12:15], v[52:55], v[48:51], v[0:3]
	v_mfma_f32_16x16x32_bf16 v[182:185], v[56:59], v[92:95], v[12:15]
	v_mfma_f32_16x16x32_bf16 v[12:15], v[60:63], v[48:51], v[0:3]
	v_mfma_f32_16x16x32_bf16 v[186:189], v[64:67], v[92:95], v[12:15]
	v_mfma_f32_16x16x32_bf16 v[12:15], v[52:55], v[96:99], v[0:3]
	v_mfma_f32_16x16x32_bf16 v[190:193], v[56:59], v[108:111], v[12:15]
	v_mfma_f32_16x16x32_bf16 v[12:15], v[60:63], v[96:99], v[0:3]
	v_mfma_f32_16x16x32_bf16 v[194:197], v[64:67], v[108:111], v[12:15]
	v_mfma_f32_16x16x32_bf16 v[12:15], v[52:55], v[112:115], v[0:3]
	v_mfma_f32_16x16x32_bf16 v[198:201], v[56:59], v[120:123], v[12:15]
	v_mfma_f32_16x16x32_bf16 v[12:15], v[60:63], v[112:115], v[0:3]
	v_mfma_f32_16x16x32_bf16 v[202:205], v[64:67], v[120:123], v[12:15]
	v_mfma_f32_16x16x32_bf16 v[12:15], v[52:55], v[124:127], v[0:3]
	v_mfma_f32_16x16x32_bf16 v[206:209], v[56:59], v[128:131], v[12:15]
	v_mfma_f32_16x16x32_bf16 v[12:15], v[60:63], v[124:127], v[0:3]
	v_mfma_f32_16x16x32_bf16 v[210:213], v[64:67], v[128:131], v[12:15]
	s_waitcnt vmcnt(2) lgkmcnt(0)
	s_barrier
	s_nop 5
	ds_read_b128 v[12:15], v134
	ds_read_b128 v[16:19], v134 offset:1024
	ds_read_b128 v[52:55], v134 offset:2048
	ds_read_b128 v[56:59], v134 offset:3072
	ds_read_b128 v[48:51], v152 offset:32768
	ds_read_b128 v[60:63], v152 offset:33792
	ds_read_b128 v[64:67], v152 offset:34816
	ds_read_b128 v[214:217], v152 offset:35840
	ds_read_b128 v[218:221], v152 offset:36864
	ds_read_b128 v[222:225], v152 offset:37888
	ds_read_b128 v[226:229], v152 offset:38912
	ds_read_b128 v[230:233], v152 offset:39936
	ds_read_b128 v[234:237], v135
	ds_read_b128 v[238:241], v135 offset:1024
	ds_read_b128 v[242:245], v135 offset:2048
	ds_read_b128 v[246:249], v135 offset:3072
	s_add_u32 s10, s18, 0x100
	s_addc_u32 s11, s19, 0
	s_mov_b32 m0, s36
	s_nop 0
	global_load_lds_dwordx4 v137, s[10:11]
	s_mov_b32 m0, s37
	s_nop 0
	global_load_lds_dwordx4 v139, s[10:11]
	s_waitcnt lgkmcnt(11)
	v_mfma_f32_16x16x32_bf16 v[68:71], v[12:15], v[48:51], v[68:71]
	s_waitcnt lgkmcnt(10)
	v_mfma_f32_16x16x32_bf16 v[128:131], v[16:19], v[60:63], v[68:71]
	v_mfma_f32_16x16x32_bf16 v[68:71], v[52:55], v[48:51], v[72:75]
	v_mfma_f32_16x16x32_bf16 v[124:127], v[56:59], v[60:63], v[68:71]
	s_waitcnt lgkmcnt(9)
	v_mfma_f32_16x16x32_bf16 v[68:71], v[12:15], v[64:67], v[76:79]
	s_waitcnt lgkmcnt(8)
	v_mfma_f32_16x16x32_bf16 v[112:115], v[16:19], v[214:217], v[68:71]
	v_mfma_f32_16x16x32_bf16 v[68:71], v[52:55], v[64:67], v[80:83]
	v_mfma_f32_16x16x32_bf16 v[108:111], v[56:59], v[214:217], v[68:71]
	s_waitcnt lgkmcnt(7)
	v_mfma_f32_16x16x32_bf16 v[68:71], v[12:15], v[218:221], v[84:87]
	s_waitcnt lgkmcnt(6)
	v_mfma_f32_16x16x32_bf16 v[96:99], v[16:19], v[222:225], v[68:71]
	v_mfma_f32_16x16x32_bf16 v[68:71], v[52:55], v[218:221], v[88:91]
	v_mfma_f32_16x16x32_bf16 v[92:95], v[56:59], v[222:225], v[68:71]
	s_waitcnt lgkmcnt(5)
	v_mfma_f32_16x16x32_bf16 v[68:71], v[12:15], v[226:229], v[100:103]
	s_waitcnt lgkmcnt(4)
	v_mfma_f32_16x16x32_bf16 v[80:83], v[16:19], v[230:233], v[68:71]
	v_mfma_f32_16x16x32_bf16 v[68:71], v[52:55], v[226:229], v[104:107]
	v_mfma_f32_16x16x32_bf16 v[76:79], v[56:59], v[230:233], v[68:71]
	s_add_u32 s10, s20, 0x100
	s_addc_u32 s11, s21, 0
	s_mov_b32 m0, s17
	s_nop 0
	global_load_lds_dwordx4 v136, s[10:11]
	s_mov_b32 m0, s38
	s_nop 0
	global_load_lds_dwordx4 v138, s[10:11]
	s_waitcnt lgkmcnt(1)
	v_mfma_f32_16x16x32_bf16 v[20:23], v[242:245], v[48:51], v[20:23]
	v_mfma_f32_16x16x32_bf16 v[68:71], v[234:237], v[48:51], v[116:119]
	s_waitcnt lgkmcnt(0)
	v_mfma_f32_16x16x32_bf16 v[116:119], v[246:249], v[60:63], v[20:23]
	v_mfma_f32_16x16x32_bf16 v[20:23], v[234:237], v[64:67], v[24:27]
	v_mfma_f32_16x16x32_bf16 v[104:107], v[238:241], v[214:217], v[20:23]
	v_mfma_f32_16x16x32_bf16 v[20:23], v[242:245], v[64:67], v[28:31]
	v_mfma_f32_16x16x32_bf16 v[100:103], v[246:249], v[214:217], v[20:23]
	v_mfma_f32_16x16x32_bf16 v[20:23], v[234:237], v[218:221], v[32:35]
	v_mfma_f32_16x16x32_bf16 v[88:91], v[238:241], v[222:225], v[20:23]
	v_mfma_f32_16x16x32_bf16 v[20:23], v[242:245], v[218:221], v[36:39]
	v_mfma_f32_16x16x32_bf16 v[84:87], v[246:249], v[222:225], v[20:23]
	v_mfma_f32_16x16x32_bf16 v[20:23], v[234:237], v[226:229], v[40:43]
	v_mfma_f32_16x16x32_bf16 v[72:75], v[238:241], v[230:233], v[20:23]
	v_mfma_f32_16x16x32_bf16 v[20:23], v[242:245], v[226:229], v[44:47]
	v_mfma_f32_16x16x32_bf16 v[120:123], v[238:241], v[60:63], v[68:71]
	v_mfma_f32_16x16x32_bf16 v[68:71], v[246:249], v[230:233], v[20:23]
	s_waitcnt vmcnt(4) lgkmcnt(0)
	s_barrier
	s_nop 4
	ds_read_b128 v[20:23], v152 offset:49152
	ds_read_b128 v[24:27], v152 offset:50176
	ds_read_b128 v[36:39], v152 offset:51200
	ds_read_b128 v[214:217], v152 offset:52224
	ds_read_b128 v[218:221], v152 offset:53248
	ds_read_b128 v[222:225], v152 offset:54272
	ds_read_b128 v[226:229], v152 offset:55296
	ds_read_b128 v[230:233], v152 offset:56320
	s_add_u32 s10, s18, 0x20100
	s_addc_u32 s11, s19, 0
	s_mov_b32 m0, s39
	s_nop 0
	global_load_lds_dwordx4 v137, s[10:11]
	s_mov_b32 m0, s40
	s_nop 0
	global_load_lds_dwordx4 v139, s[10:11]
	s_waitcnt lgkmcnt(7)
	v_mfma_f32_16x16x32_bf16 v[28:31], v[12:15], v[20:23], v[146:149]
	s_waitcnt lgkmcnt(6)
	v_mfma_f32_16x16x32_bf16 v[64:67], v[16:19], v[24:27], v[28:31]
	v_mfma_f32_16x16x32_bf16 v[28:31], v[52:55], v[20:23], v[154:157]
	v_mfma_f32_16x16x32_bf16 v[60:63], v[56:59], v[24:27], v[28:31]
	s_waitcnt lgkmcnt(5)
	v_mfma_f32_16x16x32_bf16 v[28:31], v[12:15], v[36:39], v[158:161]
	s_waitcnt lgkmcnt(4)
	v_mfma_f32_16x16x32_bf16 v[48:51], v[16:19], v[214:217], v[28:31]
	v_mfma_f32_16x16x32_bf16 v[28:31], v[52:55], v[36:39], v[170:173]
	v_mfma_f32_16x16x32_bf16 v[44:47], v[56:59], v[214:217], v[28:31]
	s_waitcnt lgkmcnt(3)
	v_mfma_f32_16x16x32_bf16 v[28:31], v[12:15], v[218:221], v[174:177]
	s_waitcnt lgkmcnt(1)
	v_mfma_f32_16x16x32_bf16 v[4:7], v[12:15], v[226:229], v[4:7]
	v_mfma_f32_16x16x32_bf16 v[32:35], v[16:19], v[222:225], v[28:31]
	v_mfma_f32_16x16x32_bf16 v[28:31], v[52:55], v[218:221], v[178:181]
	s_waitcnt lgkmcnt(0)
	v_mfma_f32_16x16x32_bf16 v[16:19], v[16:19], v[230:233], v[4:7]
	v_mfma_f32_16x16x32_bf16 v[4:7], v[52:55], v[226:229], v[8:11]
	v_mfma_f32_16x16x32_bf16 v[28:31], v[56:59], v[222:225], v[28:31]
	v_mfma_f32_16x16x32_bf16 v[12:15], v[56:59], v[230:233], v[4:7]
	s_add_u32 s10, s20, 0x20100
	s_addc_u32 s11, s21, 0
	s_mov_b32 m0, s41
	s_nop 0
	global_load_lds_dwordx4 v136, s[10:11]
	s_mov_b32 m0, s42
	s_nop 0
	global_load_lds_dwordx4 v138, s[10:11]
	v_mfma_f32_16x16x32_bf16 v[4:7], v[234:237], v[20:23], v[182:185]
	s_mov_b32 s22, 2
	v_mfma_f32_16x16x32_bf16 v[56:59], v[238:241], v[24:27], v[4:7]
	v_mfma_f32_16x16x32_bf16 v[4:7], v[242:245], v[20:23], v[186:189]
	v_mfma_f32_16x16x32_bf16 v[52:55], v[246:249], v[24:27], v[4:7]
	v_mfma_f32_16x16x32_bf16 v[4:7], v[234:237], v[36:39], v[190:193]
	v_mfma_f32_16x16x32_bf16 v[40:43], v[238:241], v[214:217], v[4:7]
	v_mfma_f32_16x16x32_bf16 v[4:7], v[242:245], v[36:39], v[194:197]
	v_mfma_f32_16x16x32_bf16 v[36:39], v[246:249], v[214:217], v[4:7]
	v_mfma_f32_16x16x32_bf16 v[4:7], v[234:237], v[218:221], v[198:201]
	v_mfma_f32_16x16x32_bf16 v[24:27], v[238:241], v[222:225], v[4:7]
	v_mfma_f32_16x16x32_bf16 v[4:7], v[242:245], v[218:221], v[202:205]
	v_mfma_f32_16x16x32_bf16 v[20:23], v[246:249], v[222:225], v[4:7]
	v_mfma_f32_16x16x32_bf16 v[4:7], v[234:237], v[226:229], v[206:209]
	v_mfma_f32_16x16x32_bf16 v[8:11], v[242:245], v[226:229], v[210:213]
	v_mfma_f32_16x16x32_bf16 v[4:7], v[238:241], v[230:233], v[4:7]
	v_mfma_f32_16x16x32_bf16 v[8:11], v[246:249], v[230:233], v[8:11]

.LBB0_195:
	s_waitcnt vmcnt(2) lgkmcnt(0)
	s_barrier
	ds_read_b128 v[146:149], v132
	ds_read_b128 v[174:177], v152
	ds_read_b128 v[158:161], v132 offset:2048
	ds_read_b128 v[182:185], v152 offset:2048
	ds_read_b128 v[190:193], v152 offset:4096
	ds_read_b128 v[198:201], v152 offset:6144
	ds_read_b128 v[154:157], v132 offset:1024
	ds_read_b128 v[178:181], v152 offset:1024
	ds_read_b128 v[170:173], v132 offset:3072
	ds_read_b128 v[186:189], v152 offset:3072
	ds_read_b128 v[194:197], v152 offset:5120
	ds_read_b128 v[202:205], v152 offset:7168
	ds_read_b128 v[206:209], v133
	ds_read_b128 v[214:217], v133 offset:2048
	ds_read_b128 v[210:213], v133 offset:1024
	ds_read_b128 v[218:221], v133 offset:3072
	s_add_u32 s58, s18, s57
	s_addc_u32 s59, s19, 0
	s_add_u32 s24, s58, 0x80
	s_addc_u32 s25, s59, 0
	s_mov_b32 m0, s43
	s_nop 0
	global_load_lds_dwordx4 v137, s[24:25]
	s_mov_b32 m0, s47
	s_nop 0
	global_load_lds_dwordx4 v139, s[24:25]
	s_waitcnt lgkmcnt(14)
	v_mfma_f32_16x16x32_bf16 v[128:131], v[146:149], v[174:177], v[128:131]
	s_waitcnt lgkmcnt(13)
	v_mfma_f32_16x16x32_bf16 v[124:127], v[158:161], v[174:177], v[124:127]
	s_waitcnt lgkmcnt(12)
	v_mfma_f32_16x16x32_bf16 v[112:115], v[146:149], v[182:185], v[112:115]
	v_mfma_f32_16x16x32_bf16 v[108:111], v[158:161], v[182:185], v[108:111]
	s_waitcnt lgkmcnt(11)
	v_mfma_f32_16x16x32_bf16 v[96:99], v[146:149], v[190:193], v[96:99]
	v_mfma_f32_16x16x32_bf16 v[92:95], v[158:161], v[190:193], v[92:95]
	s_waitcnt lgkmcnt(10)
	v_mfma_f32_16x16x32_bf16 v[80:83], v[146:149], v[198:201], v[80:83]
	v_mfma_f32_16x16x32_bf16 v[76:79], v[158:161], v[198:201], v[76:79]
	s_waitcnt lgkmcnt(8)
	v_mfma_f32_16x16x32_bf16 v[128:131], v[154:157], v[178:181], v[128:131]
	s_waitcnt lgkmcnt(7)
	v_mfma_f32_16x16x32_bf16 v[124:127], v[170:173], v[178:181], v[124:127]
	s_waitcnt lgkmcnt(6)
	v_mfma_f32_16x16x32_bf16 v[112:115], v[154:157], v[186:189], v[112:115]
	v_mfma_f32_16x16x32_bf16 v[108:111], v[170:173], v[186:189], v[108:111]
	s_waitcnt lgkmcnt(5)
	v_mfma_f32_16x16x32_bf16 v[96:99], v[154:157], v[194:197], v[96:99]
	v_mfma_f32_16x16x32_bf16 v[92:95], v[170:173], v[194:197], v[92:95]
	s_waitcnt lgkmcnt(4)
	v_mfma_f32_16x16x32_bf16 v[80:83], v[154:157], v[202:205], v[80:83]
	v_mfma_f32_16x16x32_bf16 v[76:79], v[170:173], v[202:205], v[76:79]
	s_add_u32 s60, s20, s57
	s_addc_u32 s61, s21, 0
	s_add_u32 s24, s60, 0x80
	s_addc_u32 s25, s61, 0
	s_mov_b32 m0, s44
	s_nop 0
	global_load_lds_dwordx4 v136, s[24:25]
	s_mov_b32 m0, s48
	s_nop 0
	global_load_lds_dwordx4 v138, s[24:25]
	s_waitcnt lgkmcnt(3)
	v_mfma_f32_16x16x32_bf16 v[120:123], v[206:209], v[174:177], v[120:123]
	s_waitcnt lgkmcnt(2)
	v_mfma_f32_16x16x32_bf16 v[116:119], v[214:217], v[174:177], v[116:119]
	v_mfma_f32_16x16x32_bf16 v[104:107], v[206:209], v[182:185], v[104:107]
	v_mfma_f32_16x16x32_bf16 v[100:103], v[214:217], v[182:185], v[100:103]
	v_mfma_f32_16x16x32_bf16 v[88:91], v[206:209], v[190:193], v[88:91]
	v_mfma_f32_16x16x32_bf16 v[84:87], v[214:217], v[190:193], v[84:87]
	v_mfma_f32_16x16x32_bf16 v[72:75], v[206:209], v[198:201], v[72:75]
	v_mfma_f32_16x16x32_bf16 v[68:71], v[214:217], v[198:201], v[68:71]
	s_waitcnt lgkmcnt(1)
	v_mfma_f32_16x16x32_bf16 v[120:123], v[210:213], v[178:181], v[120:123]
	s_waitcnt lgkmcnt(0)
	v_mfma_f32_16x16x32_bf16 v[116:119], v[218:221], v[178:181], v[116:119]
	v_mfma_f32_16x16x32_bf16 v[104:107], v[210:213], v[186:189], v[104:107]
	v_mfma_f32_16x16x32_bf16 v[100:103], v[218:221], v[186:189], v[100:103]
	v_mfma_f32_16x16x32_bf16 v[88:91], v[210:213], v[194:197], v[88:91]
	v_mfma_f32_16x16x32_bf16 v[84:87], v[218:221], v[194:197], v[84:87]
	v_mfma_f32_16x16x32_bf16 v[72:75], v[210:213], v[202:205], v[72:75]
	v_mfma_f32_16x16x32_bf16 v[68:71], v[218:221], v[202:205], v[68:71]
	s_waitcnt vmcnt(4) lgkmcnt(0)
	s_barrier
	ds_read_b128 v[174:177], v152 offset:16384
	ds_read_b128 v[182:185], v152 offset:18432
	ds_read_b128 v[190:193], v152 offset:20480
	ds_read_b128 v[198:201], v152 offset:22528
	ds_read_b128 v[178:181], v152 offset:17408
	ds_read_b128 v[186:189], v152 offset:19456
	ds_read_b128 v[194:197], v152 offset:21504
	ds_read_b128 v[202:205], v152 offset:23552
	s_add_u32 s24, s58, 0x20080
	s_addc_u32 s25, s59, 0
	s_mov_b32 m0, s45
	s_nop 0
	global_load_lds_dwordx4 v137, s[24:25]
	s_mov_b32 m0, s49
	s_nop 0
	global_load_lds_dwordx4 v139, s[24:25]
	s_waitcnt lgkmcnt(7)
	v_mfma_f32_16x16x32_bf16 v[64:67], v[146:149], v[174:177], v[64:67]
	v_mfma_f32_16x16x32_bf16 v[60:63], v[158:161], v[174:177], v[60:63]
	s_waitcnt lgkmcnt(6)
	v_mfma_f32_16x16x32_bf16 v[48:51], v[146:149], v[182:185], v[48:51]
	v_mfma_f32_16x16x32_bf16 v[44:47], v[158:161], v[182:185], v[44:47]
	s_waitcnt lgkmcnt(5)
	v_mfma_f32_16x16x32_bf16 v[32:35], v[146:149], v[190:193], v[32:35]
	v_mfma_f32_16x16x32_bf16 v[28:31], v[158:161], v[190:193], v[28:31]
	s_waitcnt lgkmcnt(4)
	v_mfma_f32_16x16x32_bf16 v[16:19], v[146:149], v[198:201], v[16:19]
	v_mfma_f32_16x16x32_bf16 v[12:15], v[158:161], v[198:201], v[12:15]
	s_waitcnt lgkmcnt(3)
	v_mfma_f32_16x16x32_bf16 v[64:67], v[154:157], v[178:181], v[64:67]
	v_mfma_f32_16x16x32_bf16 v[60:63], v[170:173], v[178:181], v[60:63]
	s_waitcnt lgkmcnt(2)
	v_mfma_f32_16x16x32_bf16 v[48:51], v[154:157], v[186:189], v[48:51]
	v_mfma_f32_16x16x32_bf16 v[44:47], v[170:173], v[186:189], v[44:47]
	s_waitcnt lgkmcnt(1)
	v_mfma_f32_16x16x32_bf16 v[32:35], v[154:157], v[194:197], v[32:35]
	v_mfma_f32_16x16x32_bf16 v[28:31], v[170:173], v[194:197], v[28:31]
	s_waitcnt lgkmcnt(0)
	v_mfma_f32_16x16x32_bf16 v[16:19], v[154:157], v[202:205], v[16:19]
	v_mfma_f32_16x16x32_bf16 v[12:15], v[170:173], v[202:205], v[12:15]
	s_add_u32 s24, s60, 0x20080
	s_addc_u32 s25, s61, 0
	s_mov_b32 m0, s46
	s_nop 0
	global_load_lds_dwordx4 v136, s[24:25]
	s_mov_b32 m0, s50
	s_nop 0
	global_load_lds_dwordx4 v138, s[24:25]
	v_mfma_f32_16x16x32_bf16 v[56:59], v[206:209], v[174:177], v[56:59]
	s_add_u32 s24, s60, 0x100
	s_addc_u32 s25, s61, 0
	s_add_u32 s58, s58, 0x100
	v_mfma_f32_16x16x32_bf16 v[52:55], v[214:217], v[174:177], v[52:55]
	s_addc_u32 s59, s59, 0
	v_mfma_f32_16x16x32_bf16 v[40:43], v[206:209], v[182:185], v[40:43]
	v_mfma_f32_16x16x32_bf16 v[36:39], v[214:217], v[182:185], v[36:39]
	v_mfma_f32_16x16x32_bf16 v[24:27], v[206:209], v[190:193], v[24:27]
	v_mfma_f32_16x16x32_bf16 v[20:23], v[214:217], v[190:193], v[20:23]
	v_mfma_f32_16x16x32_bf16 v[4:7], v[206:209], v[198:201], v[4:7]
	v_mfma_f32_16x16x32_bf16 v[8:11], v[214:217], v[198:201], v[8:11]
	v_mfma_f32_16x16x32_bf16 v[56:59], v[210:213], v[178:181], v[56:59]
	v_mfma_f32_16x16x32_bf16 v[52:55], v[218:221], v[178:181], v[52:55]
	v_mfma_f32_16x16x32_bf16 v[40:43], v[210:213], v[186:189], v[40:43]
	v_mfma_f32_16x16x32_bf16 v[36:39], v[218:221], v[186:189], v[36:39]
	v_mfma_f32_16x16x32_bf16 v[24:27], v[210:213], v[194:197], v[24:27]
	v_mfma_f32_16x16x32_bf16 v[20:23], v[218:221], v[194:197], v[20:23]
	v_mfma_f32_16x16x32_bf16 v[4:7], v[210:213], v[202:205], v[4:7]
	v_mfma_f32_16x16x32_bf16 v[8:11], v[218:221], v[202:205], v[8:11]
	s_waitcnt vmcnt(2) lgkmcnt(0)
	s_barrier
; template <class Epi, class Sched>
; __device__ __forceinline__ void gemm_simple(PG8_LAS unsigned char* lds, const Gemm g, const Sched& S, const Epi& E, int wave_s) {
;     ...
;         for (; t < nt; t += 2) {
;             const bool last = (t == nt - 2);
;             PG8_TILE(0, cA + (size_t)(t + 1) * kstep, cB + (size_t)(t + 1) * kstep, true);
;             const char* a2 = last ? nA : cA + (size_t)(t + 2) * kstep; const char* b2 = last ? nB : cB + (size_t)(t + 2) * kstep;
;             PG8_TILE(1, a2, b2, (!last || has_next));
	ds_read_b128 v[146:149], v134
	ds_read_b128 v[174:177], v152 offset:32768
	ds_read_b128 v[158:161], v134 offset:2048
	ds_read_b128 v[182:185], v152 offset:34816
	ds_read_b128 v[190:193], v152 offset:36864
	ds_read_b128 v[198:201], v152 offset:38912
	ds_read_b128 v[154:157], v134 offset:1024
	ds_read_b128 v[178:181], v152 offset:33792
	ds_read_b128 v[170:173], v134 offset:3072
	ds_read_b128 v[186:189], v152 offset:35840
	ds_read_b128 v[194:197], v152 offset:37888
	ds_read_b128 v[202:205], v152 offset:39936
	ds_read_b128 v[206:209], v135
	ds_read_b128 v[214:217], v135 offset:2048
	ds_read_b128 v[210:213], v135 offset:1024
	ds_read_b128 v[218:221], v135 offset:3072
	s_cmp_eq_u32 s57, s22
	s_cselect_b32 s25, s9, s25
	s_cselect_b32 s24, s54, s24
	s_cselect_b32 s59, s5, s59
	s_cselect_b32 s58, s55, s58
	s_mov_b32 m0, s36
	s_nop 0
	global_load_lds_dwordx4 v137, s[58:59]
	s_mov_b32 m0, s37
	s_nop 0
	global_load_lds_dwordx4 v139, s[58:59]
	s_waitcnt lgkmcnt(14)
	v_mfma_f32_16x16x32_bf16 v[128:131], v[146:149], v[174:177], v[128:131]
	s_waitcnt lgkmcnt(13)
	v_mfma_f32_16x16x32_bf16 v[124:127], v[158:161], v[174:177], v[124:127]
	s_waitcnt lgkmcnt(12)
	v_mfma_f32_16x16x32_bf16 v[112:115], v[146:149], v[182:185], v[112:115]
	v_mfma_f32_16x16x32_bf16 v[108:111], v[158:161], v[182:185], v[108:111]
	s_waitcnt lgkmcnt(11)
	v_mfma_f32_16x16x32_bf16 v[96:99], v[146:149], v[190:193], v[96:99]
	v_mfma_f32_16x16x32_bf16 v[92:95], v[158:161], v[190:193], v[92:95]
	s_waitcnt lgkmcnt(10)
	v_mfma_f32_16x16x32_bf16 v[80:83], v[146:149], v[198:201], v[80:83]
	v_mfma_f32_16x16x32_bf16 v[76:79], v[158:161], v[198:201], v[76:79]
	s_waitcnt lgkmcnt(8)
	v_mfma_f32_16x16x32_bf16 v[128:131], v[154:157], v[178:181], v[128:131]
	s_waitcnt lgkmcnt(7)
	v_mfma_f32_16x16x32_bf16 v[124:127], v[170:173], v[178:181], v[124:127]
	s_waitcnt lgkmcnt(6)
	v_mfma_f32_16x16x32_bf16 v[112:115], v[154:157], v[186:189], v[112:115]
	v_mfma_f32_16x16x32_bf16 v[108:111], v[170:173], v[186:189], v[108:111]
	s_waitcnt lgkmcnt(5)
	v_mfma_f32_16x16x32_bf16 v[96:99], v[154:157], v[194:197], v[96:99]
	v_mfma_f32_16x16x32_bf16 v[92:95], v[170:173], v[194:197], v[92:95]
	s_waitcnt lgkmcnt(4)
	v_mfma_f32_16x16x32_bf16 v[80:83], v[154:157], v[202:205], v[80:83]
	v_mfma_f32_16x16x32_bf16 v[76:79], v[170:173], v[202:205], v[76:79]
	s_mov_b32 m0, s17
	s_nop 0
	global_load_lds_dwordx4 v136, s[24:25]
	s_mov_b32 m0, s38
	s_nop 0
	global_load_lds_dwordx4 v138, s[24:25]
	s_waitcnt lgkmcnt(3)
	v_mfma_f32_16x16x32_bf16 v[120:123], v[206:209], v[174:177], v[120:123]
	s_waitcnt lgkmcnt(2)
	v_mfma_f32_16x16x32_bf16 v[116:119], v[214:217], v[174:177], v[116:119]
	v_mfma_f32_16x16x32_bf16 v[104:107], v[206:209], v[182:185], v[104:107]
	v_mfma_f32_16x16x32_bf16 v[100:103], v[214:217], v[182:185], v[100:103]
	v_mfma_f32_16x16x32_bf16 v[88:91], v[206:209], v[190:193], v[88:91]
	v_mfma_f32_16x16x32_bf16 v[84:87], v[214:217], v[190:193], v[84:87]
	v_mfma_f32_16x16x32_bf16 v[72:75], v[206:209], v[198:201], v[72:75]
	v_mfma_f32_16x16x32_bf16 v[68:71], v[214:217], v[198:201], v[68:71]
	s_waitcnt lgkmcnt(1)
	v_mfma_f32_16x16x32_bf16 v[120:123], v[210:213], v[178:181], v[120:123]
	s_waitcnt lgkmcnt(0)
	v_mfma_f32_16x16x32_bf16 v[116:119], v[218:221], v[178:181], v[116:119]
	v_mfma_f32_16x16x32_bf16 v[104:107], v[210:213], v[186:189], v[104:107]
	v_mfma_f32_16x16x32_bf16 v[100:103], v[218:221], v[186:189], v[100:103]
	v_mfma_f32_16x16x32_bf16 v[88:91], v[210:213], v[194:197], v[88:91]
	v_mfma_f32_16x16x32_bf16 v[84:87], v[218:221], v[194:197], v[84:87]
	v_mfma_f32_16x16x32_bf16 v[72:75], v[210:213], v[202:205], v[72:75]
	v_mfma_f32_16x16x32_bf16 v[68:71], v[218:221], v[202:205], v[68:71]
	s_waitcnt vmcnt(4) lgkmcnt(0)
	s_barrier
	ds_read_b128 v[174:177], v152 offset:49152
	ds_read_b128 v[182:185], v152 offset:51200
	ds_read_b128 v[190:193], v152 offset:53248
	ds_read_b128 v[198:201], v152 offset:55296
	ds_read_b128 v[178:181], v152 offset:50176
	ds_read_b128 v[186:189], v152 offset:52224
	ds_read_b128 v[194:197], v152 offset:54272
	ds_read_b128 v[202:205], v152 offset:56320
	s_add_u32 s58, s58, 0x20000
	s_addc_u32 s59, s59, 0
	s_mov_b32 m0, s39
	s_nop 0
	global_load_lds_dwordx4 v137, s[58:59]
	s_mov_b32 m0, s40
	s_nop 0
	global_load_lds_dwordx4 v139, s[58:59]
	s_waitcnt lgkmcnt(7)
	v_mfma_f32_16x16x32_bf16 v[64:67], v[146:149], v[174:177], v[64:67]
	v_mfma_f32_16x16x32_bf16 v[60:63], v[158:161], v[174:177], v[60:63]
	s_waitcnt lgkmcnt(6)
	v_mfma_f32_16x16x32_bf16 v[48:51], v[146:149], v[182:185], v[48:51]
	v_mfma_f32_16x16x32_bf16 v[44:47], v[158:161], v[182:185], v[44:47]
	s_waitcnt lgkmcnt(5)
	v_mfma_f32_16x16x32_bf16 v[32:35], v[146:149], v[190:193], v[32:35]
	v_mfma_f32_16x16x32_bf16 v[28:31], v[158:161], v[190:193], v[28:31]
	s_waitcnt lgkmcnt(4)
	v_mfma_f32_16x16x32_bf16 v[16:19], v[146:149], v[198:201], v[16:19]
	v_mfma_f32_16x16x32_bf16 v[12:15], v[158:161], v[198:201], v[12:15]
	s_waitcnt lgkmcnt(3)
	v_mfma_f32_16x16x32_bf16 v[64:67], v[154:157], v[178:181], v[64:67]
	v_mfma_f32_16x16x32_bf16 v[60:63], v[170:173], v[178:181], v[60:63]
	s_waitcnt lgkmcnt(2)
	v_mfma_f32_16x16x32_bf16 v[48:51], v[154:157], v[186:189], v[48:51]
	v_mfma_f32_16x16x32_bf16 v[44:47], v[170:173], v[186:189], v[44:47]
	s_waitcnt lgkmcnt(1)
	v_mfma_f32_16x16x32_bf16 v[32:35], v[154:157], v[194:197], v[32:35]
	v_mfma_f32_16x16x32_bf16 v[28:31], v[170:173], v[194:197], v[28:31]
	s_waitcnt lgkmcnt(0)
	v_mfma_f32_16x16x32_bf16 v[16:19], v[154:157], v[202:205], v[16:19]
	v_mfma_f32_16x16x32_bf16 v[12:15], v[170:173], v[202:205], v[12:15]
	s_add_u32 s24, s24, 0x20000
	s_addc_u32 s25, s25, 0
	s_mov_b32 m0, s41
	s_nop 0
	global_load_lds_dwordx4 v136, s[24:25]
	s_mov_b32 m0, s42
	s_nop 0
	global_load_lds_dwordx4 v138, s[24:25]
	v_mfma_f32_16x16x32_bf16 v[56:59], v[206:209], v[174:177], v[56:59]
	s_add_i32 s56, s56, 2
	s_add_u32 s22, s22, 0xffffff00
	s_addc_u32 s23, s23, -1
	v_mfma_f32_16x16x32_bf16 v[52:55], v[214:217], v[174:177], v[52:55]
	s_add_u32 s18, s18, 0x100
	s_addc_u32 s19, s19, 0
	s_add_u32 s20, s20, 0x100
	v_mfma_f32_16x16x32_bf16 v[40:43], v[206:209], v[182:185], v[40:43]
	s_addc_u32 s21, s21, 0
	s_cmp_lt_u32 s56, 6
	v_mfma_f32_16x16x32_bf16 v[36:39], v[214:217], v[182:185], v[36:39]
	v_mfma_f32_16x16x32_bf16 v[24:27], v[206:209], v[190:193], v[24:27]
	v_mfma_f32_16x16x32_bf16 v[20:23], v[214:217], v[190:193], v[20:23]
	v_mfma_f32_16x16x32_bf16 v[4:7], v[206:209], v[198:201], v[4:7]
	v_mfma_f32_16x16x32_bf16 v[8:11], v[214:217], v[198:201], v[8:11]
	v_mfma_f32_16x16x32_bf16 v[56:59], v[210:213], v[178:181], v[56:59]
	v_mfma_f32_16x16x32_bf16 v[52:55], v[218:221], v[178:181], v[52:55]
	v_mfma_f32_16x16x32_bf16 v[40:43], v[210:213], v[186:189], v[40:43]
	v_mfma_f32_16x16x32_bf16 v[36:39], v[218:221], v[186:189], v[36:39]
	v_mfma_f32_16x16x32_bf16 v[24:27], v[210:213], v[194:197], v[24:27]
	v_mfma_f32_16x16x32_bf16 v[20:23], v[218:221], v[194:197], v[20:23]
	v_mfma_f32_16x16x32_bf16 v[4:7], v[210:213], v[202:205], v[4:7]
	v_mfma_f32_16x16x32_bf16 v[8:11], v[218:221], v[202:205], v[8:11]
	s_cbranch_scc1 .LBB0_195
; __device__ __forceinline__ unsigned cvt_pk_bf16(float lo, float hi) { unsigned r; asm volatile("v_cvt_pk_bf16_f32 %0, %1, %2" : "=v"(r) : "v"(lo), "v"(hi)); return r; }
; #define LAS __attribute__((address_space(3)))
; __device__ __forceinline__ float bflo(unsigned w) { return __uint_as_float(w << 16); }
; __device__ __forceinline__ float bfhi(unsigned w) { return __uint_as_float(w & 0xffff0000u); }
;     __device__ __forceinline__ void operator()(const f32x4 (&acc)[2][2][4][2], const Unit& u, int wr, int wc, int fr, int fq, const LAS float*) const {
;         const int row0 = u.pm * 256 + wr * 64 + fr, col0 = u.pn * 256 + wc * 32 + 8 * fq;
; #pragma unroll
;         for (int ai = 0; ai < 2; ++ai)
; #pragma unroll
;             for (int m = 0; m < 4; ++m) { const size_t row = (size_t)(row0 + ai * 128 + m * 16);
; #pragma unroll
;                 for (int bj = 0; bj < 2; ++bj) { const int col = col0 + bj * 128;
;                     const u32x4 g = *(const u32x4*)(G + row * NGATE + MODE * DM + col);
;                     f32x4 v0 = acc[ai][bj][m][0], v1 = acc[ai][bj][m][1];
;                     v0[0] *= bflo(g.x); v0[1] *= bfhi(g.x); v0[2] *= bflo(g.y); v0[3] *= bfhi(g.y); v1[0] *= bflo(g.z); v1[1] *= bfhi(g.z); v1[2] *= bflo(g.w); v1[3] *= bfhi(g.w);
;                     bf16_t* tp = T + row * DM + col;
;                     if (MODE == 1) { const u32x4 t = *(const u32x4*)tp;
;                         v0[0] += bflo(t.x); v0[1] += bfhi(t.x); v0[2] += bflo(t.y); v0[3] += bfhi(t.y); v1[0] += bflo(t.z); v1[1] += bfhi(t.z); v1[2] += bflo(t.w); v1[3] += bfhi(t.w); }
;                     u32x4 w; w.x = cvt_pk_bf16(v0[0], v0[1]); w.y = cvt_pk_bf16(v0[2], v0[3]); w.z = cvt_pk_bf16(v1[0], v1[1]); w.w = cvt_pk_bf16(v1[2], v1[3]);
;                     *(u32x4*)tp = w; } }
	v_mov_b32_e32 v132, v141
	s_lshl_b32 s5, s16, 8
	v_mbcnt_lo_u32_b32 v132, -1, v132
	v_mbcnt_hi_u32_b32 v132, -1, v132
	s_add_i32 s5, s5, s29
	v_and_or_b32 v134, v132, 15, s5
	s_lshl_b32 s5, s53, 8
	v_ashrrev_i32_e32 v132, 1, v132
	s_or_b32 s5, s5, s35
	v_and_b32_e32 v132, -8, v132
	v_add_u32_e32 v132, s5, v132
	v_ashrrev_i32_e32 v135, 31, v134
	v_lshlrev_b64 v[142:143], 13, v[134:135]
	v_ashrrev_i32_e32 v133, 31, v132
	v_lshl_add_u64 v[142:143], s[2:3], 0, v[142:143]
	v_lshlrev_b64 v[132:133], 1, v[132:133]
	v_lshl_add_u64 v[142:143], v[142:143], 0, v[132:133]
	v_lshlrev_b32_e32 v236, 13, v134
	v_add_u32_e32 v236, v236, v132
	global_load_dwordx4 v[172:175], v236, s[2:3]
	global_load_dwordx4 v[176:179], v236, s[2:3] offset:256
	v_add_u32_e32 v237, 0x20000, v236
	global_load_dwordx4 v[180:183], v237, s[2:3]
	global_load_dwordx4 v[184:187], v237, s[2:3] offset:256
	v_add_u32_e32 v237, 0x40000, v236
	global_load_dwordx4 v[188:191], v237, s[2:3]
	global_load_dwordx4 v[192:195], v237, s[2:3] offset:256
	v_add_u32_e32 v237, 0x60000, v236
	global_load_dwordx4 v[196:199], v237, s[2:3]
	global_load_dwordx4 v[200:203], v237, s[2:3] offset:256
	v_add_u32_e32 v237, 0x100000, v236
	global_load_dwordx4 v[204:207], v237, s[2:3]
	global_load_dwordx4 v[208:211], v237, s[2:3] offset:256
	v_add_u32_e32 v237, 0x120000, v236
	global_load_dwordx4 v[212:215], v237, s[2:3]
	global_load_dwordx4 v[216:219], v237, s[2:3] offset:256
	v_add_u32_e32 v237, 0x140000, v236
	global_load_dwordx4 v[220:223], v237, s[2:3]
	global_load_dwordx4 v[224:227], v237, s[2:3] offset:256
	v_add_u32_e32 v237, 0x160000, v236
	global_load_dwordx4 v[228:231], v237, s[2:3]
	global_load_dwordx4 v[232:235], v237, s[2:3] offset:256
	v_lshlrev_b64 v[144:145], 12, v[134:135]
	s_andn2_b64 vcc, exec, s[6:7]
	s_mov_b32 s53, s4
	s_mov_b32 s16, s8
	s_mov_b64 s[18:19], s[14:15]
	s_mov_b64 s[20:21], s[10:11]
	s_mov_b32 s9, s52
	s_waitcnt vmcnt(15)
	s_nop 1
	v_mov_b64_e32 v[146:147], v[172:173]
	v_mov_b64_e32 v[148:149], v[174:175]
	v_lshlrev_b32_e32 v135, 16, v146
	v_mul_f32_e32 v135, v128, v135
	v_and_b32_e32 v128, 0xffff0000, v146
	v_mul_f32_e32 v146, v129, v128
	v_lshlrev_b32_e32 v128, 16, v147
	v_mul_f32_e32 v130, v130, v128
	v_and_b32_e32 v128, 0xffff0000, v147
	v_mul_f32_e32 v131, v131, v128
	v_lshlrev_b32_e32 v128, 16, v148
	v_mul_f32_e32 v147, v124, v128
	v_and_b32_e32 v124, 0xffff0000, v148
	v_mul_f32_e32 v148, v125, v124
	v_lshlrev_b32_e32 v124, 16, v149
	v_mul_f32_e32 v153, v126, v124
	v_and_b32_e32 v124, 0xffff0000, v149
	v_mul_f32_e32 v127, v127, v124
	v_lshl_add_u64 v[124:125], s[12:13], 0, v[144:145]
	v_lshl_add_u64 v[128:129], v[124:125], 0, v[132:133]
	v_cvt_pk_bf16_f32 v124, v135, v146
	v_cvt_pk_bf16_f32 v125, v130, v131
	v_cvt_pk_bf16_f32 v126, v147, v148
	v_cvt_pk_bf16_f32 v127, v153, v127
	global_store_dwordx4 v[128:129], v[124:127], off
	s_waitcnt vmcnt(15)
	s_nop 1
	v_mov_b64_e32 v[124:125], v[176:177]
	v_mov_b64_e32 v[126:127], v[178:179]
	v_lshlrev_b32_e32 v130, 16, v124
	v_and_b32_e32 v124, 0xffff0000, v124
	v_mul_f32_e32 v121, v121, v124
	v_lshlrev_b32_e32 v124, 16, v125
	v_mul_f32_e32 v122, v122, v124
	v_and_b32_e32 v124, 0xffff0000, v125
	v_mul_f32_e32 v123, v123, v124
	v_lshlrev_b32_e32 v124, 16, v126
	v_mul_f32_e32 v124, v116, v124
	v_and_b32_e32 v116, 0xffff0000, v126
	v_mul_f32_e32 v125, v117, v116
	v_lshlrev_b32_e32 v116, 16, v127
	v_mul_f32_e32 v126, v118, v116
	v_and_b32_e32 v116, 0xffff0000, v127
	v_mul_f32_e32 v120, v120, v130
	v_mul_f32_e32 v119, v119, v116
	v_cvt_pk_bf16_f32 v116, v120, v121
	v_cvt_pk_bf16_f32 v117, v122, v123
	v_cvt_pk_bf16_f32 v118, v124, v125
	v_cvt_pk_bf16_f32 v119, v126, v119
	global_store_dwordx4 v[128:129], v[116:119], off offset:256
	s_nop 1
	v_or_b32_e32 v116, 16, v134
	v_ashrrev_i32_e32 v117, 31, v116
	v_lshlrev_b64 v[118:119], 13, v[116:117]
	v_lshlrev_b64 v[120:121], 12, v[116:117]
	v_lshl_add_u64 v[116:117], s[2:3], 0, v[118:119]
	v_lshl_add_u64 v[122:123], v[116:117], 0, v[132:133]
	s_waitcnt vmcnt(15)
	s_nop 1
	v_mov_b64_e32 v[116:117], v[180:181]
	v_mov_b64_e32 v[118:119], v[182:183]
	v_lshlrev_b32_e32 v124, 16, v116
	v_mul_f32_e32 v124, v112, v124
	v_and_b32_e32 v112, 0xffff0000, v116
	v_mul_f32_e32 v116, v113, v112
	v_lshlrev_b32_e32 v112, 16, v117
	v_mul_f32_e32 v114, v114, v112
	v_and_b32_e32 v112, 0xffff0000, v117
	v_mul_f32_e32 v115, v115, v112
	v_lshlrev_b32_e32 v112, 16, v118
	v_mul_f32_e32 v117, v108, v112
	v_and_b32_e32 v108, 0xffff0000, v118
	v_mul_f32_e32 v118, v109, v108
	v_lshlrev_b32_e32 v108, 16, v119
	v_mul_f32_e32 v125, v110, v108
	v_and_b32_e32 v108, 0xffff0000, v119
	v_mul_f32_e32 v111, v111, v108
	v_lshl_add_u64 v[108:109], s[12:13], 0, v[120:121]
	v_lshl_add_u64 v[112:113], v[108:109], 0, v[132:133]
	v_cvt_pk_bf16_f32 v108, v124, v116
	v_cvt_pk_bf16_f32 v109, v114, v115
	v_cvt_pk_bf16_f32 v110, v117, v118
	v_cvt_pk_bf16_f32 v111, v125, v111
	global_store_dwordx4 v[112:113], v[108:111], off
	s_waitcnt vmcnt(15)
	s_nop 1
	v_mov_b64_e32 v[108:109], v[184:185]
	v_mov_b64_e32 v[110:111], v[186:187]
	v_lshlrev_b32_e32 v114, 16, v108
	v_and_b32_e32 v108, 0xffff0000, v108
	v_mul_f32_e32 v105, v105, v108
	v_lshlrev_b32_e32 v108, 16, v109
	v_mul_f32_e32 v106, v106, v108
	v_and_b32_e32 v108, 0xffff0000, v109
	v_mul_f32_e32 v107, v107, v108
	v_lshlrev_b32_e32 v108, 16, v110
	v_mul_f32_e32 v108, v100, v108
	v_and_b32_e32 v100, 0xffff0000, v110
	v_mul_f32_e32 v109, v101, v100
	v_lshlrev_b32_e32 v100, 16, v111
	v_mul_f32_e32 v110, v102, v100
	v_and_b32_e32 v100, 0xffff0000, v111
	v_mul_f32_e32 v104, v104, v114
	v_mul_f32_e32 v103, v103, v100
	v_cvt_pk_bf16_f32 v100, v104, v105
	v_cvt_pk_bf16_f32 v101, v106, v107
	v_cvt_pk_bf16_f32 v102, v108, v109
	v_cvt_pk_bf16_f32 v103, v110, v103
	global_store_dwordx4 v[112:113], v[100:103], off offset:256
	s_nop 1
	v_or_b32_e32 v100, 32, v134
	v_ashrrev_i32_e32 v101, 31, v100
	v_lshlrev_b64 v[102:103], 13, v[100:101]
	v_lshlrev_b64 v[104:105], 12, v[100:101]
	v_lshl_add_u64 v[100:101], s[2:3], 0, v[102:103]
	v_lshl_add_u64 v[106:107], v[100:101], 0, v[132:133]
	s_waitcnt vmcnt(15)
; __device__ __forceinline__ unsigned cvt_pk_bf16(float lo, float hi) { unsigned r; asm volatile("v_cvt_pk_bf16_f32 %0, %1, %2" : "=v"(r) : "v"(lo), "v"(hi)); return r; }
; __device__ __forceinline__ float bflo(unsigned w) { return __uint_as_float(w << 16); }
; __device__ __forceinline__ float bfhi(unsigned w) { return __uint_as_float(w & 0xffff0000u); }
;     __device__ __forceinline__ void operator()(const f32x4 (&acc)[2][2][4][2], const Unit& u, int wr, int wc, int fr, int fq, const LAS float*) const {
;     ...
;             for (int m = 0; m < 4; ++m) { const size_t row = (size_t)(row0 + ai * 128 + m * 16);
; #pragma unroll
;                 for (int bj = 0; bj < 2; ++bj) { const int col = col0 + bj * 128;
;                     const u32x4 g = *(const u32x4*)(G + row * NGATE + MODE * DM + col);
;                     f32x4 v0 = acc[ai][bj][m][0], v1 = acc[ai][bj][m][1];
;                     v0[0] *= bflo(g.x); v0[1] *= bfhi(g.x); v0[2] *= bflo(g.y); v0[3] *= bfhi(g.y); v1[0] *= bflo(g.z); v1[1] *= bfhi(g.z); v1[2] *= bflo(g.w); v1[3] *= bfhi(g.w);
;                     bf16_t* tp = T + row * DM + col;
;                     if (MODE == 1) { const u32x4 t = *(const u32x4*)tp;
;                         v0[0] += bflo(t.x); v0[1] += bfhi(t.x); v0[2] += bflo(t.y); v0[3] += bfhi(t.y); v1[0] += bflo(t.z); v1[1] += bfhi(t.z); v1[2] += bflo(t.w); v1[3] += bfhi(t.w); }
;                     u32x4 w; w.x = cvt_pk_bf16(v0[0], v0[1]); w.y = cvt_pk_bf16(v0[2], v0[3]); w.z = cvt_pk_bf16(v1[0], v1[1]); w.w = cvt_pk_bf16(v1[2], v1[3]);
;                     *(u32x4*)tp = w; } }
	s_nop 1
	v_mov_b64_e32 v[100:101], v[188:189]
	v_mov_b64_e32 v[102:103], v[190:191]
	v_lshlrev_b32_e32 v108, 16, v100
	v_mul_f32_e32 v108, v96, v108
	v_and_b32_e32 v96, 0xffff0000, v100
	v_mul_f32_e32 v100, v97, v96
	v_lshlrev_b32_e32 v96, 16, v101
	v_mul_f32_e32 v98, v98, v96
	v_and_b32_e32 v96, 0xffff0000, v101
	v_mul_f32_e32 v99, v99, v96
	v_lshlrev_b32_e32 v96, 16, v102
	v_mul_f32_e32 v101, v92, v96
	v_and_b32_e32 v92, 0xffff0000, v102
	v_mul_f32_e32 v102, v93, v92
	v_lshlrev_b32_e32 v92, 16, v103
	v_mul_f32_e32 v109, v94, v92
	v_and_b32_e32 v92, 0xffff0000, v103
	v_mul_f32_e32 v95, v95, v92
	v_lshl_add_u64 v[92:93], s[12:13], 0, v[104:105]
	v_lshl_add_u64 v[96:97], v[92:93], 0, v[132:133]
	v_cvt_pk_bf16_f32 v92, v108, v100
	v_cvt_pk_bf16_f32 v93, v98, v99
	v_cvt_pk_bf16_f32 v94, v101, v102
	v_cvt_pk_bf16_f32 v95, v109, v95
	global_store_dwordx4 v[96:97], v[92:95], off
	s_waitcnt vmcnt(15)
	s_nop 1
	v_mov_b64_e32 v[92:93], v[192:193]
	v_mov_b64_e32 v[94:95], v[194:195]
	v_lshlrev_b32_e32 v98, 16, v92
	v_and_b32_e32 v92, 0xffff0000, v92
	v_mul_f32_e32 v89, v89, v92
	v_lshlrev_b32_e32 v92, 16, v93
	v_mul_f32_e32 v90, v90, v92
	v_and_b32_e32 v92, 0xffff0000, v93
	v_mul_f32_e32 v91, v91, v92
	v_lshlrev_b32_e32 v92, 16, v94
	v_mul_f32_e32 v92, v84, v92
	v_and_b32_e32 v84, 0xffff0000, v94
	v_mul_f32_e32 v93, v85, v84
	v_lshlrev_b32_e32 v84, 16, v95
	v_mul_f32_e32 v94, v86, v84
	v_and_b32_e32 v84, 0xffff0000, v95
	v_mul_f32_e32 v88, v88, v98
	v_mul_f32_e32 v87, v87, v84
	v_cvt_pk_bf16_f32 v84, v88, v89
	v_cvt_pk_bf16_f32 v85, v90, v91
	v_cvt_pk_bf16_f32 v86, v92, v93
	v_cvt_pk_bf16_f32 v87, v94, v87
	global_store_dwordx4 v[96:97], v[84:87], off offset:256
	s_nop 1
	v_or_b32_e32 v84, 48, v134
	v_ashrrev_i32_e32 v85, 31, v84
	v_lshlrev_b64 v[86:87], 13, v[84:85]
	v_lshlrev_b64 v[88:89], 12, v[84:85]
	v_lshl_add_u64 v[84:85], s[2:3], 0, v[86:87]
	v_lshl_add_u64 v[90:91], v[84:85], 0, v[132:133]
	s_waitcnt vmcnt(15)
	s_nop 1
	v_mov_b64_e32 v[84:85], v[196:197]
	v_mov_b64_e32 v[86:87], v[198:199]
	v_lshlrev_b32_e32 v92, 16, v84
	v_mul_f32_e32 v92, v80, v92
	v_and_b32_e32 v80, 0xffff0000, v84
	v_mul_f32_e32 v84, v81, v80
	v_lshlrev_b32_e32 v80, 16, v85
	v_mul_f32_e32 v82, v82, v80
	v_and_b32_e32 v80, 0xffff0000, v85
	v_mul_f32_e32 v83, v83, v80
	v_lshlrev_b32_e32 v80, 16, v86
	v_mul_f32_e32 v85, v76, v80
	v_and_b32_e32 v76, 0xffff0000, v86
	v_mul_f32_e32 v86, v77, v76
	v_lshlrev_b32_e32 v76, 16, v87
	v_mul_f32_e32 v93, v78, v76
	v_and_b32_e32 v76, 0xffff0000, v87
	v_mul_f32_e32 v79, v79, v76
	v_lshl_add_u64 v[76:77], s[12:13], 0, v[88:89]
	v_lshl_add_u64 v[80:81], v[76:77], 0, v[132:133]
	v_cvt_pk_bf16_f32 v76, v92, v84
	v_cvt_pk_bf16_f32 v77, v82, v83
	v_cvt_pk_bf16_f32 v78, v85, v86
	v_cvt_pk_bf16_f32 v79, v93, v79
	global_store_dwordx4 v[80:81], v[76:79], off
	s_waitcnt vmcnt(15)
	s_nop 1
	v_mov_b64_e32 v[76:77], v[200:201]
	v_mov_b64_e32 v[78:79], v[202:203]
	v_lshlrev_b32_e32 v82, 16, v76
	v_and_b32_e32 v76, 0xffff0000, v76
	v_mul_f32_e32 v73, v73, v76
	v_lshlrev_b32_e32 v76, 16, v77
	v_mul_f32_e32 v74, v74, v76
	v_and_b32_e32 v76, 0xffff0000, v77
	v_mul_f32_e32 v75, v75, v76
	v_lshlrev_b32_e32 v76, 16, v78
	v_mul_f32_e32 v76, v68, v76
	v_and_b32_e32 v68, 0xffff0000, v78
	v_mul_f32_e32 v77, v69, v68
	v_lshlrev_b32_e32 v68, 16, v79
	v_mul_f32_e32 v78, v70, v68
	v_and_b32_e32 v68, 0xffff0000, v79
	v_mul_f32_e32 v72, v72, v82
	v_mul_f32_e32 v71, v71, v68
	v_cvt_pk_bf16_f32 v68, v72, v73
	v_cvt_pk_bf16_f32 v69, v74, v75
	v_cvt_pk_bf16_f32 v70, v76, v77
	v_cvt_pk_bf16_f32 v71, v78, v71
	global_store_dwordx4 v[80:81], v[68:71], off offset:256
	s_nop 1
	v_add_u32_e32 v68, 0x80, v134
	v_ashrrev_i32_e32 v69, 31, v68
	v_lshlrev_b64 v[70:71], 13, v[68:69]
	v_lshlrev_b64 v[72:73], 12, v[68:69]
	v_lshl_add_u64 v[68:69], s[2:3], 0, v[70:71]
	v_lshl_add_u64 v[74:75], v[68:69], 0, v[132:133]
	s_waitcnt vmcnt(15)
	s_nop 1
	v_mov_b64_e32 v[68:69], v[204:205]
	v_mov_b64_e32 v[70:71], v[206:207]
	v_lshlrev_b32_e32 v76, 16, v68
	v_mul_f32_e32 v76, v64, v76
	v_and_b32_e32 v64, 0xffff0000, v68
	v_mul_f32_e32 v68, v65, v64
	v_lshlrev_b32_e32 v64, 16, v69
	v_mul_f32_e32 v66, v66, v64
	v_and_b32_e32 v64, 0xffff0000, v69
	v_mul_f32_e32 v67, v67, v64
	v_lshlrev_b32_e32 v64, 16, v70
	v_mul_f32_e32 v69, v60, v64
	v_and_b32_e32 v60, 0xffff0000, v70
	v_mul_f32_e32 v70, v61, v60
	v_lshlrev_b32_e32 v60, 16, v71
	v_mul_f32_e32 v77, v62, v60
	v_and_b32_e32 v60, 0xffff0000, v71
	v_mul_f32_e32 v63, v63, v60
	v_lshl_add_u64 v[60:61], s[12:13], 0, v[72:73]
	v_lshl_add_u64 v[64:65], v[60:61], 0, v[132:133]
	v_cvt_pk_bf16_f32 v60, v76, v68
	v_cvt_pk_bf16_f32 v61, v66, v67
	v_cvt_pk_bf16_f32 v62, v69, v70
	v_cvt_pk_bf16_f32 v63, v77, v63
	global_store_dwordx4 v[64:65], v[60:63], off
	s_waitcnt vmcnt(15)
	s_nop 1
	v_mov_b64_e32 v[60:61], v[208:209]
	v_mov_b64_e32 v[62:63], v[210:211]
	v_lshlrev_b32_e32 v66, 16, v60
	v_and_b32_e32 v60, 0xffff0000, v60
	v_mul_f32_e32 v57, v57, v60
	v_lshlrev_b32_e32 v60, 16, v61
	v_mul_f32_e32 v58, v58, v60
	v_and_b32_e32 v60, 0xffff0000, v61
	v_mul_f32_e32 v59, v59, v60
	v_lshlrev_b32_e32 v60, 16, v62
	v_mul_f32_e32 v60, v52, v60
	v_and_b32_e32 v52, 0xffff0000, v62
	v_mul_f32_e32 v61, v53, v52
	v_lshlrev_b32_e32 v52, 16, v63
	v_mul_f32_e32 v62, v54, v52
	v_and_b32_e32 v52, 0xffff0000, v63
	v_mul_f32_e32 v56, v56, v66
	v_mul_f32_e32 v55, v55, v52
	v_cvt_pk_bf16_f32 v52, v56, v57
	v_cvt_pk_bf16_f32 v53, v58, v59
	v_cvt_pk_bf16_f32 v54, v60, v61
	v_cvt_pk_bf16_f32 v55, v62, v55
	global_store_dwordx4 v[64:65], v[52:55], off offset:256
	s_nop 1
	v_add_u32_e32 v52, 0x90, v134
	v_ashrrev_i32_e32 v53, 31, v52
	v_lshlrev_b64 v[54:55], 13, v[52:53]
	v_lshlrev_b64 v[56:57], 12, v[52:53]
	v_lshl_add_u64 v[52:53], s[2:3], 0, v[54:55]
	v_lshl_add_u64 v[58:59], v[52:53], 0, v[132:133]
	s_waitcnt vmcnt(15)
; __device__ __forceinline__ unsigned cvt_pk_bf16(float lo, float hi) { unsigned r; asm volatile("v_cvt_pk_bf16_f32 %0, %1, %2" : "=v"(r) : "v"(lo), "v"(hi)); return r; }
; __device__ __forceinline__ float bflo(unsigned w) { return __uint_as_float(w << 16); }
; __device__ __forceinline__ float bfhi(unsigned w) { return __uint_as_float(w & 0xffff0000u); }
;     __device__ __forceinline__ void operator()(const f32x4 (&acc)[2][2][4][2], const Unit& u, int wr, int wc, int fr, int fq, const LAS float*) const {
;     ...
;             for (int m = 0; m < 4; ++m) { const size_t row = (size_t)(row0 + ai * 128 + m * 16);
; #pragma unroll
;                 for (int bj = 0; bj < 2; ++bj) { const int col = col0 + bj * 128;
;                     const u32x4 g = *(const u32x4*)(G + row * NGATE + MODE * DM + col);
;                     f32x4 v0 = acc[ai][bj][m][0], v1 = acc[ai][bj][m][1];
;                     v0[0] *= bflo(g.x); v0[1] *= bfhi(g.x); v0[2] *= bflo(g.y); v0[3] *= bfhi(g.y); v1[0] *= bflo(g.z); v1[1] *= bfhi(g.z); v1[2] *= bflo(g.w); v1[3] *= bfhi(g.w);
;                     bf16_t* tp = T + row * DM + col;
;                     if (MODE == 1) { const u32x4 t = *(const u32x4*)tp;
;                         v0[0] += bflo(t.x); v0[1] += bfhi(t.x); v0[2] += bflo(t.y); v0[3] += bfhi(t.y); v1[0] += bflo(t.z); v1[1] += bfhi(t.z); v1[2] += bflo(t.w); v1[3] += bfhi(t.w); }
;                     u32x4 w; w.x = cvt_pk_bf16(v0[0], v0[1]); w.y = cvt_pk_bf16(v0[2], v0[3]); w.z = cvt_pk_bf16(v1[0], v1[1]); w.w = cvt_pk_bf16(v1[2], v1[3]);
;                     *(u32x4*)tp = w; } }
	s_nop 1
	v_mov_b64_e32 v[52:53], v[212:213]
	v_mov_b64_e32 v[54:55], v[214:215]
	v_lshlrev_b32_e32 v60, 16, v52
	v_mul_f32_e32 v60, v48, v60
	v_and_b32_e32 v48, 0xffff0000, v52
	v_mul_f32_e32 v52, v49, v48
	v_lshlrev_b32_e32 v48, 16, v53
	v_mul_f32_e32 v50, v50, v48
	v_and_b32_e32 v48, 0xffff0000, v53
	v_mul_f32_e32 v51, v51, v48
	v_lshlrev_b32_e32 v48, 16, v54
	v_mul_f32_e32 v53, v44, v48
	v_and_b32_e32 v44, 0xffff0000, v54
	v_mul_f32_e32 v54, v45, v44
	v_lshlrev_b32_e32 v44, 16, v55
	v_mul_f32_e32 v61, v46, v44
	v_and_b32_e32 v44, 0xffff0000, v55
	v_mul_f32_e32 v47, v47, v44
	v_lshl_add_u64 v[44:45], s[12:13], 0, v[56:57]
	v_lshl_add_u64 v[48:49], v[44:45], 0, v[132:133]
	v_cvt_pk_bf16_f32 v44, v60, v52
	v_cvt_pk_bf16_f32 v45, v50, v51
	v_cvt_pk_bf16_f32 v46, v53, v54
	v_cvt_pk_bf16_f32 v47, v61, v47
	global_store_dwordx4 v[48:49], v[44:47], off
	s_waitcnt vmcnt(15)
	s_nop 1
	v_mov_b64_e32 v[44:45], v[216:217]
	v_mov_b64_e32 v[46:47], v[218:219]
	v_lshlrev_b32_e32 v50, 16, v44
	v_and_b32_e32 v44, 0xffff0000, v44
	v_mul_f32_e32 v41, v41, v44
	v_lshlrev_b32_e32 v44, 16, v45
	v_mul_f32_e32 v42, v42, v44
	v_and_b32_e32 v44, 0xffff0000, v45
	v_mul_f32_e32 v43, v43, v44
	v_lshlrev_b32_e32 v44, 16, v46
	v_mul_f32_e32 v44, v36, v44
	v_and_b32_e32 v36, 0xffff0000, v46
	v_mul_f32_e32 v45, v37, v36
	v_lshlrev_b32_e32 v36, 16, v47
	v_mul_f32_e32 v46, v38, v36
	v_and_b32_e32 v36, 0xffff0000, v47
	v_mul_f32_e32 v40, v40, v50
	v_mul_f32_e32 v39, v39, v36
	v_cvt_pk_bf16_f32 v36, v40, v41
	v_cvt_pk_bf16_f32 v37, v42, v43
	v_cvt_pk_bf16_f32 v38, v44, v45
	v_cvt_pk_bf16_f32 v39, v46, v39
	global_store_dwordx4 v[48:49], v[36:39], off offset:256
	s_nop 1
	v_add_u32_e32 v36, 0xa0, v134
	v_ashrrev_i32_e32 v37, 31, v36
	v_lshlrev_b64 v[38:39], 13, v[36:37]
	v_lshlrev_b64 v[40:41], 12, v[36:37]
	v_lshl_add_u64 v[36:37], s[2:3], 0, v[38:39]
	v_lshl_add_u64 v[42:43], v[36:37], 0, v[132:133]
	s_waitcnt vmcnt(15)
	s_nop 1
	v_mov_b64_e32 v[36:37], v[220:221]
	v_mov_b64_e32 v[38:39], v[222:223]
	v_lshlrev_b32_e32 v44, 16, v36
	v_mul_f32_e32 v44, v32, v44
	v_and_b32_e32 v32, 0xffff0000, v36
	v_mul_f32_e32 v36, v33, v32
	v_lshlrev_b32_e32 v32, 16, v37
	v_mul_f32_e32 v34, v34, v32
	v_and_b32_e32 v32, 0xffff0000, v37
	v_mul_f32_e32 v35, v35, v32
	v_lshlrev_b32_e32 v32, 16, v38
	v_mul_f32_e32 v37, v28, v32
	v_and_b32_e32 v28, 0xffff0000, v38
	v_mul_f32_e32 v38, v29, v28
	v_lshlrev_b32_e32 v28, 16, v39
	v_mul_f32_e32 v45, v30, v28
	v_and_b32_e32 v28, 0xffff0000, v39
	v_mul_f32_e32 v31, v31, v28
	v_lshl_add_u64 v[28:29], s[12:13], 0, v[40:41]
	v_lshl_add_u64 v[32:33], v[28:29], 0, v[132:133]
	v_cvt_pk_bf16_f32 v28, v44, v36
	v_cvt_pk_bf16_f32 v29, v34, v35
	v_cvt_pk_bf16_f32 v30, v37, v38
	v_cvt_pk_bf16_f32 v31, v45, v31
	global_store_dwordx4 v[32:33], v[28:31], off
	s_waitcnt vmcnt(15)
	s_nop 1
	v_mov_b64_e32 v[28:29], v[224:225]
	v_mov_b64_e32 v[30:31], v[226:227]
	v_lshlrev_b32_e32 v34, 16, v28
	v_and_b32_e32 v28, 0xffff0000, v28
	v_mul_f32_e32 v25, v25, v28
	v_lshlrev_b32_e32 v28, 16, v29
	v_mul_f32_e32 v26, v26, v28
	v_and_b32_e32 v28, 0xffff0000, v29
	v_mul_f32_e32 v27, v27, v28
	v_lshlrev_b32_e32 v28, 16, v30
	v_mul_f32_e32 v28, v20, v28
	v_and_b32_e32 v20, 0xffff0000, v30
	v_mul_f32_e32 v29, v21, v20
	v_lshlrev_b32_e32 v20, 16, v31
	v_mul_f32_e32 v30, v22, v20
	v_and_b32_e32 v20, 0xffff0000, v31
	v_mul_f32_e32 v24, v24, v34
	v_mul_f32_e32 v23, v23, v20
	v_cvt_pk_bf16_f32 v20, v24, v25
	v_cvt_pk_bf16_f32 v21, v26, v27
	v_cvt_pk_bf16_f32 v22, v28, v29
	v_cvt_pk_bf16_f32 v23, v30, v23
	global_store_dwordx4 v[32:33], v[20:23], off offset:256
	s_nop 1
	v_add_u32_e32 v20, 0xb0, v134
	v_ashrrev_i32_e32 v21, 31, v20
	v_lshlrev_b64 v[22:23], 13, v[20:21]
	v_lshlrev_b64 v[24:25], 12, v[20:21]
	v_lshl_add_u64 v[20:21], s[2:3], 0, v[22:23]
	v_lshl_add_u64 v[26:27], v[20:21], 0, v[132:133]
	s_waitcnt vmcnt(15)
	s_nop 1
	v_mov_b64_e32 v[20:21], v[228:229]
	v_mov_b64_e32 v[22:23], v[230:231]
	v_lshlrev_b32_e32 v28, 16, v20
	v_mul_f32_e32 v28, v16, v28
	v_and_b32_e32 v16, 0xffff0000, v20
	v_mul_f32_e32 v20, v17, v16
	v_lshlrev_b32_e32 v16, 16, v21
	v_mul_f32_e32 v18, v18, v16
	v_and_b32_e32 v16, 0xffff0000, v21
	v_mul_f32_e32 v19, v19, v16
	v_lshlrev_b32_e32 v16, 16, v22
	v_mul_f32_e32 v21, v12, v16
	v_and_b32_e32 v12, 0xffff0000, v22
	v_mul_f32_e32 v22, v13, v12
	v_lshlrev_b32_e32 v12, 16, v23
	v_mul_f32_e32 v29, v14, v12
	v_and_b32_e32 v12, 0xffff0000, v23
	v_mul_f32_e32 v15, v15, v12
	v_lshl_add_u64 v[12:13], s[12:13], 0, v[24:25]
	v_lshl_add_u64 v[16:17], v[12:13], 0, v[132:133]
	v_cvt_pk_bf16_f32 v12, v28, v20
	v_cvt_pk_bf16_f32 v13, v18, v19
	v_cvt_pk_bf16_f32 v14, v21, v22
	v_cvt_pk_bf16_f32 v15, v29, v15
	global_store_dwordx4 v[16:17], v[12:15], off
	s_waitcnt vmcnt(15)
	s_nop 1
	v_mov_b64_e32 v[12:13], v[232:233]
	v_mov_b64_e32 v[14:15], v[234:235]
	v_lshlrev_b32_e32 v18, 16, v12
	v_and_b32_e32 v12, 0xffff0000, v12
	v_mul_f32_e32 v5, v5, v12
	v_lshlrev_b32_e32 v12, 16, v13
	v_mul_f32_e32 v6, v6, v12
	v_and_b32_e32 v12, 0xffff0000, v13
	v_mul_f32_e32 v7, v7, v12
	v_lshlrev_b32_e32 v12, 16, v14
	v_mul_f32_e32 v8, v8, v12
	v_and_b32_e32 v12, 0xffff0000, v14
	v_mul_f32_e32 v9, v9, v12
	v_lshlrev_b32_e32 v12, 16, v15
	v_mul_f32_e32 v4, v4, v18
	v_mul_f32_e32 v10, v10, v12
	v_and_b32_e32 v12, 0xffff0000, v15
	v_mul_f32_e32 v11, v11, v12
	v_cvt_pk_bf16_f32 v4, v4, v5
	v_cvt_pk_bf16_f32 v5, v6, v7
	v_cvt_pk_bf16_f32 v6, v8, v9
	v_cvt_pk_bf16_f32 v7, v10, v11
	global_store_dwordx4 v[16:17], v[4:7], off offset:256
	s_cbranch_vccnz .LBB0_186
	s_waitcnt vmcnt(0) lgkmcnt(0)
	s_barrier

; #define LAS __attribute__((address_space(3)))
; template <class Epi, class Sched>
; __device__ __forceinline__ void gemm_simple(PG8_LAS unsigned char* lds, const Gemm g, const Sched& S, const Epi& E, int wave_s) {
;     ...
;     for (int i = 0; i < 2; ++i) { int R, C; stage_rc(tid * 16 + i * 8192, R, C); const int Rb = Epi::PERM ? ((R & ~31) + perm32(R & 31)) : R;
;         voffA[i] = (unsigned)(R * K + C) * 2u; voffB[i] = (unsigned)(Rb * K + C) * 2u; }
;     const size_t kstep = (size_t)(BK * 2), hstep = (size_t)HALF * K * 2, tstep = 2 * hstep;
;     const unsigned ldsw = (unsigned)wid * 1024u; const unsigned lds_u = (unsigned)(__UINTPTR_TYPE__)lds;
;     const int aoff = lds_byte(wr * 64 + fr, fq * 8), boff = lds_byte(wc * 32 + fr, fq * 8);
; __device__ __forceinline__ void rstd_table(const float* ssq, LAS unsigned char* lds, const Unit& u, int tid, int par) {
;     if (tid < 256) { const f32x4* p = (const f32x4*)(ssq + (size_t)(u.pm * 256 + tid) * 32); f32x4 a = p[0];
; #pragma unroll
;         for (int i = 1; i < 8; ++i) a += p[i];
;         ((LAS float*)(lds + 131072 + par * 1024))[tid] = 1.0f / sqrtf(((a[0] + a[1]) + (a[2] + a[3])) * (1.0f / DM) + 1e-6f); }
.LBB0_208:
	v_bfe_i32 v3, v138, 27, 1
	v_lshlrev_b32_e32 v1, 4, v138
	v_lshrrev_b32_e32 v3, 22, v3
	v_add_u32_e32 v3, v1, v3
	v_and_b32_e32 v3, 0xfffffc00, v3
	v_sub_u32_e32 v3, v1, v3
	v_ashrrev_i32_e32 v2, 31, v138
	s_waitcnt lgkmcnt(0)
	v_lshrrev_b32_e32 v5, 4, v3
	v_lshrrev_b32_e32 v2, 26, v2
	v_bitop3_b32 v3, v5, v3, 32 bitop3:0x6c
	v_add_u32_e32 v2, v138, v2
	v_ashrrev_i32_e32 v6, 31, v3
	v_ashrrev_i32_e32 v2, 6, v2
	v_lshrrev_b32_e32 v6, 26, v6
	v_lshlrev_b32_e32 v5, 3, v2
	v_add_u32_e32 v6, v3, v6
	v_and_b32_e32 v5, -16, v5
	v_ashrrev_i32_e32 v7, 6, v6
	v_and_b32_e32 v6, 0xc0, v6
	v_add_u32_e32 v5, v7, v5
	v_sub_u32_e32 v3, v3, v6
	s_ashr_i32 s4, s7, 3
	v_lshlrev_b32_e32 v2, 5, v2
	v_ashrrev_i16_sdwa v3, v166, sext(v3) dst_sel:DWORD dst_unused:UNUSED_PAD src0_sel:DWORD src1_sel:BYTE_0
	v_lshlrev_b32_e32 v6, 1, v5
	v_lshrrev_b32_e32 v8, 2, v5
	v_and_b32_e32 v7, 3, v7
	s_mov_b32 s7, 0xfffe0
	v_and_b32_e32 v2, 32, v2
	v_bfe_i32 v3, v3, 0, 16
	v_and_b32_e32 v6, 24, v6
	v_and_b32_e32 v8, 4, v8
	v_and_or_b32 v7, v5, s7, v7
	v_or3_b32 v6, v7, v8, v6
	v_add_lshl_u32 v2, v2, v3, 1
	v_add_u32_e32 v1, 0x2000, v1
	v_lshl_add_u32 v139, v5, 12, v2
	v_lshl_add_u32 v140, v6, 12, v2
	v_ashrrev_i32_e32 v2, 31, v1
	v_lshrrev_b32_e32 v2, 22, v2
	v_add_u32_e32 v2, v1, v2
	v_ashrrev_i32_e32 v2, 10, v2
	v_mul_i32_i24_e32 v3, 0x400, v2
	v_sub_u32_e32 v1, v1, v3
	v_lshrrev_b32_e32 v3, 4, v1
	v_readlane_b32 s5, v254, 57
	v_bitop3_b32 v1, v3, v1, 32 bitop3:0x6c
	s_add_u32 s27, s5, 0x1a00000
	v_readlane_b32 s5, v254, 58
	v_ashrrev_i32_e32 v5, 31, v1
	s_addc_u32 s28, s5, 0
	v_lshrrev_b32_e32 v5, 26, v5
	s_add_i32 s4, s6, s4
	v_lshlrev_b32_e32 v3, 3, v2
	v_add_u32_e32 v5, v1, v5
	s_ashr_i32 s6, s4, 31
	v_and_b32_e32 v3, -16, v3
	v_ashrrev_i32_e32 v6, 6, v5
	s_lshr_b32 s6, s6, 26
	v_add_u32_e32 v3, v6, v3
	v_and_b32_e32 v6, 3, v6
	s_add_i32 s6, s4, s6
	v_and_or_b32 v6, v3, s7, v6
	s_ashr_i32 s7, s6, 6
	s_and_b32 s6, s6, 0xffc0
	s_sub_i32 s6, s4, s6
	s_bfe_i32 s4, s6, 0x80000
	s_bfe_u32 s4, s4, 0x2000d
	s_add_i32 s8, s6, s4
	s_bfe_i32 s4, s8, 0x80000
	s_and_b32 s8, s8, 0xfc
	s_sub_i32 s6, s6, s8
	s_lshl_b32 s7, s7, 2
	s_sext_i32_i16 s4, s4
	s_sext_i32_i8 s6, s6
	s_ashr_i32 s5, s14, 6
	s_lshr_b32 s4, s4, 2
	s_add_i32 s18, s7, s6
	v_and_b32_e32 v5, 0xc0, v5
	s_ashr_i32 s19, s18, 31
	s_bfe_i64 s[8:9], s[4:5], 0x100000
	v_sub_u32_e32 v1, v1, v5
	s_lshl_b32 s12, s5, 10
	s_lshl_b64 s[6:7], s[18:19], 20
	s_lshl_b64 s[8:9], s[8:9], 20
	v_lshlrev_b32_e32 v2, 5, v2
	v_ashrrev_i16_sdwa v1, v166, sext(v1) dst_sel:DWORD dst_unused:UNUSED_PAD src0_sel:DWORD src1_sel:BYTE_0
	v_lshlrev_b32_e32 v5, 1, v3
	v_lshrrev_b32_e32 v7, 2, v3
	s_add_u32 s10, s27, s8
	v_and_b32_e32 v2, 32, v2
	v_bfe_i32 v1, v1, 0, 16
	v_and_b32_e32 v5, 24, v5
	v_and_b32_e32 v7, 4, v7
	s_addc_u32 s11, s28, s9
	s_waitcnt vmcnt(0) lgkmcnt(0)
	s_barrier
	s_add_i32 s19, s12, 0
	v_or3_b32 v5, v6, v7, v5
	v_add_lshl_u32 v1, v2, v1, 1
	s_add_i32 s29, s19, 0x10000
	s_mov_b32 m0, s29
	s_nop 0
	global_load_lds_dwordx4 v140, s[10:11]
	s_add_i32 s35, s19, 0x12000
	v_lshl_add_u32 v153, v5, 12, v1
	s_mov_b32 m0, s35
	s_nop 0
	global_load_lds_dwordx4 v153, s[10:11]
	s_add_u32 s20, s94, s6
	s_addc_u32 s21, s95, s7
	s_mov_b32 m0, s19
	s_nop 0
	global_load_lds_dwordx4 v139, s[20:21]
	v_lshl_add_u32 v152, v3, 12, v1
	s_add_i32 s36, s19, 0x2000
	s_mov_b32 m0, s36
	s_nop 0
	global_load_lds_dwordx4 v152, s[20:21]
	s_add_u32 s6, s10, 0x80000
	s_addc_u32 s7, s11, 0
	s_add_i32 s37, s19, 0x14000
	s_mov_b32 m0, s37
	s_nop 0
	global_load_lds_dwordx4 v140, s[6:7]
	s_add_i32 s38, s19, 0x16000
	s_mov_b32 m0, s38
	s_nop 0
	global_load_lds_dwordx4 v153, s[6:7]
	s_add_u32 s6, s20, 0x80000
	s_addc_u32 s7, s21, 0
	s_add_i32 s39, s19, 0x4000
	s_mov_b32 m0, s39
	s_nop 0
	global_load_lds_dwordx4 v139, s[6:7]
	s_add_i32 s40, s19, 0x6000
	s_mov_b32 m0, s40
	s_nop 0
	global_load_lds_dwordx4 v152, s[6:7]
	s_movk_i32 s6, 0xff
	s_movk_i32 s8, 0x100
	v_cmp_lt_i32_e64 s[6:7], s6, v138
	v_cmp_gt_i32_e32 vcc, s8, v138
	s_and_saveexec_b64 s[12:13], vcc
	s_cbranch_execz .LBB0_210
	v_lshl_add_u32 v2, s18, 8, v138
	v_ashrrev_i32_e32 v3, 31, v2
	v_readlane_b32 s8, v255, 2
	v_lshlrev_b64 v[2:3], 7, v[2:3]
	v_readlane_b32 s9, v255, 3
	s_nop 1
	v_lshl_add_u64 v[2:3], s[8:9], 0, v[2:3]
	global_load_dwordx4 v[6:9], v[2:3], off offset:48
	global_load_dwordx4 v[10:13], v[2:3], off offset:32
	global_load_dwordx4 v[14:17], v[2:3], off
	global_load_dwordx4 v[18:21], v[2:3], off offset:16
	s_waitcnt vmcnt(0)
	v_pk_add_f32 v[16:17], v[16:17], v[20:21]
	v_pk_add_f32 v[14:15], v[14:15], v[18:19]
	v_pk_add_f32 v[12:13], v[16:17], v[12:13]
	v_pk_add_f32 v[10:11], v[14:15], v[10:11]
	v_pk_add_f32 v[22:23], v[12:13], v[8:9]
	v_pk_add_f32 v[24:25], v[10:11], v[6:7]
	global_load_dwordx4 v[6:9], v[2:3], off offset:112
	global_load_dwordx4 v[10:13], v[2:3], off offset:96
	global_load_dwordx4 v[14:17], v[2:3], off offset:80
	global_load_dwordx4 v[18:21], v[2:3], off offset:64
	s_waitcnt vmcnt(0)
	v_pk_add_f32 v[2:3], v[22:23], v[20:21]
	v_pk_add_f32 v[18:19], v[24:25], v[18:19]
	v_pk_add_f32 v[2:3], v[2:3], v[16:17]
	v_pk_add_f32 v[14:15], v[18:19], v[14:15]
	v_pk_add_f32 v[2:3], v[2:3], v[12:13]
	v_pk_add_f32 v[10:11], v[14:15], v[10:11]
	v_pk_add_f32 v[2:3], v[2:3], v[8:9]
	v_pk_add_f32 v[6:7], v[10:11], v[6:7]
	s_nop 0
	v_pk_mov_b32 v[8:9], v[6:7], v[2:3] op_sel:[1,0]
	v_mov_b32_e32 v7, v3
	v_pk_add_f32 v[2:3], v[8:9], v[6:7]
	s_nop 0
	v_add_f32_e32 v1, v2, v3
	v_fmamk_f32 v1, v1, 0x3a000000, v164
	v_cmp_gt_f32_e32 vcc, s69, v1
	v_mul_f32_e32 v2, 0x4f800000, v1
	s_nop 0
	v_cndmask_b32_e32 v1, v1, v2, vcc
	v_sqrt_f32_e32 v2, v1
	s_nop 0
	v_add_u32_e32 v3, -1, v2
	v_fma_f32 v5, -v3, v2, v1
	v_cmp_ge_f32_e64 s[8:9], 0, v5
	v_add_u32_e32 v5, 1, v2
	s_nop 0
	v_cndmask_b32_e64 v3, v2, v3, s[8:9]
	v_fma_f32 v2, -v5, v2, v1
	v_cmp_lt_f32_e64 s[8:9], 0, v2
	s_nop 1
	v_cndmask_b32_e64 v2, v3, v5, s[8:9]
	v_mul_f32_e32 v3, 0x37800000, v2
	v_cndmask_b32_e32 v2, v2, v3, vcc
	v_cmp_class_f32_e32 vcc, v1, v165
	s_nop 1
	v_cndmask_b32_e32 v1, v2, v1, vcc
	v_div_scale_f32 v2, s[8:9], v1, v1, 1.0
	v_rcp_f32_e32 v3, v2
	s_nop 0
	v_fma_f32 v5, -v2, v3, 1.0
	v_fmac_f32_e32 v3, v5, v3
	v_div_scale_f32 v5, vcc, 1.0, v1, 1.0
	v_mul_f32_e32 v6, v5, v3
	v_fma_f32 v7, -v2, v6, v5
	v_fmac_f32_e32 v6, v7, v3
	v_fma_f32 v2, -v2, v6, v5
	v_div_fmas_f32 v2, v2, v3, v6
	v_div_fixup_f32 v1, v2, v1, 1.0
	v_lshl_add_u32 v2, v138, 2, 0
	v_add_u32_e32 v2, 0x20000, v2
	ds_write_b32 v2, v1

; template <class Epi, class Sched>
; __device__ __forceinline__ void gemm_simple(PG8_LAS unsigned char* lds, const Gemm g, const Sched& S, const Epi& E, int wave_s) {
;     ...
; #pragma unroll
;         for (int a = 0; a < 2; ++a)
; #pragma unroll
;             for (int b = 0; b < 2; ++b)
; #pragma unroll
;                 for (int m = 0; m < 4; ++m)
; #pragma unroll
;                     for (int n = 0; n < 2; ++n) acc[a][b][m][n] = (f32x4){zero_o, zero_o, zero_o, zero_o};
.LBB0_218:
	v_mov_b64_e32 v[10:11], v[2:3]
	v_mov_b64_e32 v[6:7], v[2:3]
	v_mov_b64_e32 v[22:23], v[2:3]
	v_mov_b64_e32 v[26:27], v[2:3]
	v_mov_b64_e32 v[38:39], v[2:3]
	v_mov_b64_e32 v[42:43], v[2:3]
	v_mov_b64_e32 v[54:55], v[2:3]
	v_mov_b64_e32 v[58:59], v[2:3]
	v_mov_b64_e32 v[14:15], v[2:3]
	v_mov_b64_e32 v[18:19], v[2:3]
	v_mov_b64_e32 v[30:31], v[2:3]
	v_mov_b64_e32 v[34:35], v[2:3]
	v_mov_b64_e32 v[46:47], v[2:3]
	v_mov_b64_e32 v[50:51], v[2:3]
	v_mov_b64_e32 v[62:63], v[2:3]
	v_mov_b64_e32 v[66:67], v[2:3]
	v_mov_b64_e32 v[70:71], v[2:3]
	v_mov_b64_e32 v[74:75], v[2:3]
	v_mov_b64_e32 v[86:87], v[2:3]
	v_mov_b64_e32 v[90:91], v[2:3]
	v_mov_b64_e32 v[102:103], v[2:3]
	v_mov_b64_e32 v[106:107], v[2:3]
	v_mov_b64_e32 v[118:119], v[2:3]
	v_mov_b64_e32 v[122:123], v[2:3]
	v_mov_b64_e32 v[78:79], v[2:3]
	v_mov_b64_e32 v[82:83], v[2:3]
	v_mov_b64_e32 v[94:95], v[2:3]
	v_mov_b64_e32 v[98:99], v[2:3]
	v_mov_b64_e32 v[110:111], v[2:3]
	v_mov_b64_e32 v[114:115], v[2:3]
	v_mov_b64_e32 v[126:127], v[2:3]
	v_mov_b64_e32 v[130:131], v[2:3]
	s_mov_b32 s22, 0
	s_cmp_eq_u32 s55, 0
	v_add_u32_e32 v132, 0x10000, v155
	v_add_u32_e32 v133, 0x14000, v155
	v_add_u32_e32 v134, 0x18000, v155
	v_add_u32_e32 v135, 0x1c000, v155
	v_mov_b64_e32 v[8:9], v[0:1]
	v_mov_b64_e32 v[4:5], v[0:1]
	v_mov_b64_e32 v[20:21], v[0:1]
	v_mov_b64_e32 v[24:25], v[0:1]
	v_mov_b64_e32 v[36:37], v[0:1]
	v_mov_b64_e32 v[40:41], v[0:1]
	v_mov_b64_e32 v[52:53], v[0:1]
	v_mov_b64_e32 v[56:57], v[0:1]
	v_mov_b64_e32 v[12:13], v[0:1]
	v_mov_b64_e32 v[16:17], v[0:1]
	v_mov_b64_e32 v[28:29], v[0:1]
	v_mov_b64_e32 v[32:33], v[0:1]
	v_mov_b64_e32 v[44:45], v[0:1]
	v_mov_b64_e32 v[48:49], v[0:1]
	v_mov_b64_e32 v[60:61], v[0:1]
	v_mov_b64_e32 v[64:65], v[0:1]
	v_mov_b64_e32 v[68:69], v[0:1]
	v_mov_b64_e32 v[72:73], v[0:1]
	v_mov_b64_e32 v[84:85], v[0:1]
	v_mov_b64_e32 v[88:89], v[0:1]
	v_mov_b64_e32 v[100:101], v[0:1]
	v_mov_b64_e32 v[104:105], v[0:1]
	v_mov_b64_e32 v[116:117], v[0:1]
	v_mov_b64_e32 v[120:121], v[0:1]
	v_mov_b64_e32 v[76:77], v[0:1]
	v_mov_b64_e32 v[80:81], v[0:1]
	v_mov_b64_e32 v[92:93], v[0:1]
	v_mov_b64_e32 v[96:97], v[0:1]
	v_mov_b64_e32 v[108:109], v[0:1]
	v_mov_b64_e32 v[112:113], v[0:1]
	v_mov_b64_e32 v[124:125], v[0:1]
	v_mov_b64_e32 v[128:129], v[0:1]
	s_cbranch_scc1 .LBB0_220
	s_waitcnt vmcnt(18) lgkmcnt(0)
	s_barrier
	ds_read_b128 v[4:7], v132
	ds_read_b128 v[8:11], v132 offset:1024
	ds_read_b128 v[12:15], v132 offset:2048
	ds_read_b128 v[16:19], v132 offset:3072
	ds_read_b128 v[20:23], v156
	ds_read_b128 v[24:27], v156 offset:1024
	ds_read_b128 v[28:31], v156 offset:2048
	ds_read_b128 v[32:35], v156 offset:3072
	ds_read_b128 v[36:39], v156 offset:4096
	ds_read_b128 v[40:43], v156 offset:5120
	ds_read_b128 v[44:47], v156 offset:6144
	ds_read_b128 v[48:51], v156 offset:7168
	ds_read_b128 v[52:55], v133
	ds_read_b128 v[56:59], v133 offset:1024
	ds_read_b128 v[60:63], v133 offset:2048
	ds_read_b128 v[64:67], v133 offset:3072
	s_add_u32 s14, s10, 0x80
	s_addc_u32 s15, s11, 0
	s_mov_b32 m0, s44
	s_nop 0
	global_load_lds_dwordx4 v140, s[14:15]
	s_mov_b32 m0, s48
	s_nop 0
	global_load_lds_dwordx4 v153, s[14:15]
	s_waitcnt lgkmcnt(5)
	v_mfma_f32_16x16x32_bf16 v[92:95], v[4:7], v[44:47], v[0:3]
	v_mfma_f32_16x16x32_bf16 v[68:71], v[4:7], v[20:23], v[0:3]
	v_mfma_f32_16x16x32_bf16 v[72:75], v[12:15], v[20:23], v[0:3]
	v_mfma_f32_16x16x32_bf16 v[76:79], v[4:7], v[28:31], v[0:3]
	v_mfma_f32_16x16x32_bf16 v[80:83], v[12:15], v[28:31], v[0:3]
	v_mfma_f32_16x16x32_bf16 v[84:87], v[4:7], v[36:39], v[0:3]
	v_mfma_f32_16x16x32_bf16 v[88:91], v[12:15], v[36:39], v[0:3]
	s_waitcnt lgkmcnt(4)
	v_mfma_f32_16x16x32_bf16 v[100:103], v[8:11], v[48:51], v[92:95]
	v_mfma_f32_16x16x32_bf16 v[92:95], v[12:15], v[44:47], v[0:3]
	v_mfma_f32_16x16x32_bf16 v[68:71], v[8:11], v[24:27], v[68:71]
	v_mfma_f32_16x16x32_bf16 v[72:75], v[16:19], v[24:27], v[72:75]
	v_mfma_f32_16x16x32_bf16 v[76:79], v[8:11], v[32:35], v[76:79]
	v_mfma_f32_16x16x32_bf16 v[80:83], v[16:19], v[32:35], v[80:83]
	v_mfma_f32_16x16x32_bf16 v[84:87], v[8:11], v[40:43], v[84:87]
	v_mfma_f32_16x16x32_bf16 v[88:91], v[16:19], v[40:43], v[88:91]
	v_mfma_f32_16x16x32_bf16 v[104:107], v[16:19], v[48:51], v[92:95]
	s_add_u32 s14, s20, 0x80
	s_addc_u32 s15, s21, 0
	s_mov_b32 m0, s45
	s_nop 0
	global_load_lds_dwordx4 v139, s[14:15]
	s_mov_b32 m0, s49
	s_nop 0
	global_load_lds_dwordx4 v152, s[14:15]
	s_waitcnt lgkmcnt(3)
	v_mfma_f32_16x16x32_bf16 v[92:95], v[52:55], v[20:23], v[0:3]
	s_waitcnt lgkmcnt(1)
	v_mfma_f32_16x16x32_bf16 v[20:23], v[60:63], v[20:23], v[0:3]
	v_mfma_f32_16x16x32_bf16 v[116:119], v[56:59], v[24:27], v[92:95]
	s_waitcnt lgkmcnt(0)
	v_mfma_f32_16x16x32_bf16 v[20:23], v[64:67], v[24:27], v[20:23]
	v_mfma_f32_16x16x32_bf16 v[24:27], v[52:55], v[28:31], v[0:3]
	v_mfma_f32_16x16x32_bf16 v[28:31], v[60:63], v[28:31], v[0:3]
	v_mfma_f32_16x16x32_bf16 v[24:27], v[56:59], v[32:35], v[24:27]
	v_mfma_f32_16x16x32_bf16 v[28:31], v[64:67], v[32:35], v[28:31]
	v_mfma_f32_16x16x32_bf16 v[32:35], v[52:55], v[36:39], v[0:3]
	v_mfma_f32_16x16x32_bf16 v[36:39], v[60:63], v[36:39], v[0:3]
	v_mfma_f32_16x16x32_bf16 v[32:35], v[56:59], v[40:43], v[32:35]
	v_mfma_f32_16x16x32_bf16 v[36:39], v[64:67], v[40:43], v[36:39]
	v_mfma_f32_16x16x32_bf16 v[40:43], v[52:55], v[44:47], v[0:3]
	v_mfma_f32_16x16x32_bf16 v[44:47], v[60:63], v[44:47], v[0:3]
	v_mfma_f32_16x16x32_bf16 v[40:43], v[56:59], v[48:51], v[40:43]
	v_mfma_f32_16x16x32_bf16 v[44:47], v[64:67], v[48:51], v[44:47]
	s_waitcnt vmcnt(20) lgkmcnt(0)
	s_barrier
	ds_read_b128 v[48:51], v156 offset:16384
	ds_read_b128 v[92:95], v156 offset:17408
	ds_read_b128 v[96:99], v156 offset:18432
	ds_read_b128 v[108:111], v156 offset:19456
	ds_read_b128 v[112:115], v156 offset:20480
	ds_read_b128 v[120:123], v156 offset:21504
	ds_read_b128 v[124:127], v156 offset:22528
	ds_read_b128 v[128:131], v156 offset:23552
	s_add_u32 s14, s10, 0x80080
	s_addc_u32 s15, s11, 0
	s_mov_b32 m0, s46
	s_nop 0
	global_load_lds_dwordx4 v140, s[14:15]
	s_mov_b32 m0, s50
	s_nop 0
	global_load_lds_dwordx4 v153, s[14:15]
	s_waitcnt lgkmcnt(7)
	v_mfma_f32_16x16x32_bf16 v[158:161], v[4:7], v[48:51], v[0:3]
	s_waitcnt lgkmcnt(5)
	v_mfma_f32_16x16x32_bf16 v[174:177], v[4:7], v[96:99], v[0:3]
	s_waitcnt lgkmcnt(3)
	v_mfma_f32_16x16x32_bf16 v[182:185], v[4:7], v[112:115], v[0:3]
	s_waitcnt lgkmcnt(1)
	v_mfma_f32_16x16x32_bf16 v[4:7], v[4:7], v[124:127], v[0:3]
	v_mfma_f32_16x16x32_bf16 v[158:161], v[8:11], v[92:95], v[158:161]
	v_mfma_f32_16x16x32_bf16 v[174:177], v[8:11], v[108:111], v[174:177]
	v_mfma_f32_16x16x32_bf16 v[182:185], v[8:11], v[120:123], v[182:185]
	s_waitcnt lgkmcnt(0)
	v_mfma_f32_16x16x32_bf16 v[4:7], v[8:11], v[128:131], v[4:7]
	v_mfma_f32_16x16x32_bf16 v[8:11], v[12:15], v[124:127], v[0:3]
	v_mfma_f32_16x16x32_bf16 v[170:173], v[12:15], v[48:51], v[0:3]
	v_mfma_f32_16x16x32_bf16 v[178:181], v[12:15], v[96:99], v[0:3]
	v_mfma_f32_16x16x32_bf16 v[186:189], v[12:15], v[112:115], v[0:3]
	v_mfma_f32_16x16x32_bf16 v[8:11], v[16:19], v[128:131], v[8:11]
	v_mfma_f32_16x16x32_bf16 v[170:173], v[16:19], v[92:95], v[170:173]
	v_mfma_f32_16x16x32_bf16 v[178:181], v[16:19], v[108:111], v[178:181]
	v_mfma_f32_16x16x32_bf16 v[186:189], v[16:19], v[120:123], v[186:189]
	s_add_u32 s14, s20, 0x80080
	s_addc_u32 s15, s21, 0
	s_mov_b32 m0, s47
	s_nop 0
	global_load_lds_dwordx4 v139, s[14:15]
	s_mov_b32 m0, s51
	s_nop 0
	global_load_lds_dwordx4 v152, s[14:15]
	v_mfma_f32_16x16x32_bf16 v[12:15], v[52:55], v[48:51], v[0:3]
	v_mfma_f32_16x16x32_bf16 v[190:193], v[56:59], v[92:95], v[12:15]
	v_mfma_f32_16x16x32_bf16 v[12:15], v[60:63], v[48:51], v[0:3]
	v_mfma_f32_16x16x32_bf16 v[194:197], v[64:67], v[92:95], v[12:15]
	v_mfma_f32_16x16x32_bf16 v[12:15], v[52:55], v[96:99], v[0:3]
	v_mfma_f32_16x16x32_bf16 v[198:201], v[56:59], v[108:111], v[12:15]
	v_mfma_f32_16x16x32_bf16 v[12:15], v[60:63], v[96:99], v[0:3]
	v_mfma_f32_16x16x32_bf16 v[202:205], v[64:67], v[108:111], v[12:15]
	v_mfma_f32_16x16x32_bf16 v[12:15], v[52:55], v[112:115], v[0:3]
	v_mfma_f32_16x16x32_bf16 v[206:209], v[56:59], v[120:123], v[12:15]
	v_mfma_f32_16x16x32_bf16 v[12:15], v[60:63], v[112:115], v[0:3]
	v_mfma_f32_16x16x32_bf16 v[210:213], v[64:67], v[120:123], v[12:15]
	v_mfma_f32_16x16x32_bf16 v[12:15], v[52:55], v[124:127], v[0:3]
	v_mfma_f32_16x16x32_bf16 v[214:217], v[56:59], v[128:131], v[12:15]
	v_mfma_f32_16x16x32_bf16 v[12:15], v[60:63], v[124:127], v[0:3]
	v_mfma_f32_16x16x32_bf16 v[218:221], v[64:67], v[128:131], v[12:15]
	s_waitcnt vmcnt(2) lgkmcnt(0)
	s_barrier
	s_nop 5
	ds_read_b128 v[12:15], v134
	ds_read_b128 v[16:19], v134 offset:1024
	ds_read_b128 v[52:55], v134 offset:2048
	ds_read_b128 v[56:59], v134 offset:3072
	ds_read_b128 v[48:51], v156 offset:32768
	ds_read_b128 v[60:63], v156 offset:33792
	ds_read_b128 v[64:67], v156 offset:34816
	ds_read_b128 v[222:225], v156 offset:35840
	ds_read_b128 v[226:229], v156 offset:36864
	ds_read_b128 v[230:233], v156 offset:37888
	ds_read_b128 v[234:237], v156 offset:38912
	ds_read_b128 v[238:241], v156 offset:39936
	ds_read_b128 v[242:245], v135
	ds_read_b128 v[246:249], v135 offset:1024
	ds_read_b128 v[250:253], v135 offset:2048
	ds_read_b128 v[146:149], v135 offset:3072
	s_add_u32 s14, s10, 0x100
	s_addc_u32 s15, s11, 0
	s_mov_b32 m0, s29
	s_nop 0
	global_load_lds_dwordx4 v140, s[14:15]
	s_mov_b32 m0, s35
	s_nop 0
	global_load_lds_dwordx4 v153, s[14:15]
	s_waitcnt lgkmcnt(11)
	v_mfma_f32_16x16x32_bf16 v[68:71], v[12:15], v[48:51], v[68:71]
	s_waitcnt lgkmcnt(10)
	v_mfma_f32_16x16x32_bf16 v[128:131], v[16:19], v[60:63], v[68:71]
	v_mfma_f32_16x16x32_bf16 v[68:71], v[52:55], v[48:51], v[72:75]
	v_mfma_f32_16x16x32_bf16 v[124:127], v[56:59], v[60:63], v[68:71]
	s_waitcnt lgkmcnt(9)
	v_mfma_f32_16x16x32_bf16 v[68:71], v[12:15], v[64:67], v[76:79]
	s_waitcnt lgkmcnt(8)
	v_mfma_f32_16x16x32_bf16 v[112:115], v[16:19], v[222:225], v[68:71]
	v_mfma_f32_16x16x32_bf16 v[68:71], v[52:55], v[64:67], v[80:83]
	v_mfma_f32_16x16x32_bf16 v[108:111], v[56:59], v[222:225], v[68:71]
	s_waitcnt lgkmcnt(7)
	v_mfma_f32_16x16x32_bf16 v[68:71], v[12:15], v[226:229], v[84:87]
	s_waitcnt lgkmcnt(6)
	v_mfma_f32_16x16x32_bf16 v[96:99], v[16:19], v[230:233], v[68:71]
	v_mfma_f32_16x16x32_bf16 v[68:71], v[52:55], v[226:229], v[88:91]
	v_mfma_f32_16x16x32_bf16 v[92:95], v[56:59], v[230:233], v[68:71]
	s_waitcnt lgkmcnt(5)
	v_mfma_f32_16x16x32_bf16 v[68:71], v[12:15], v[234:237], v[100:103]
	s_waitcnt lgkmcnt(4)
	v_mfma_f32_16x16x32_bf16 v[80:83], v[16:19], v[238:241], v[68:71]
	v_mfma_f32_16x16x32_bf16 v[68:71], v[52:55], v[234:237], v[104:107]
	v_mfma_f32_16x16x32_bf16 v[76:79], v[56:59], v[238:241], v[68:71]
	s_add_u32 s14, s20, 0x100
	s_addc_u32 s15, s21, 0
	s_mov_b32 m0, s19
	s_nop 0
	global_load_lds_dwordx4 v139, s[14:15]
	s_mov_b32 m0, s36
	s_nop 0
	global_load_lds_dwordx4 v152, s[14:15]
	s_waitcnt lgkmcnt(1)
	v_mfma_f32_16x16x32_bf16 v[20:23], v[250:253], v[48:51], v[20:23]
	v_mfma_f32_16x16x32_bf16 v[68:71], v[242:245], v[48:51], v[116:119]
	s_waitcnt lgkmcnt(0)
	v_mfma_f32_16x16x32_bf16 v[116:119], v[146:149], v[60:63], v[20:23]
	v_mfma_f32_16x16x32_bf16 v[20:23], v[242:245], v[64:67], v[24:27]
	v_mfma_f32_16x16x32_bf16 v[104:107], v[246:249], v[222:225], v[20:23]
	v_mfma_f32_16x16x32_bf16 v[20:23], v[250:253], v[64:67], v[28:31]
	v_mfma_f32_16x16x32_bf16 v[100:103], v[146:149], v[222:225], v[20:23]
	v_mfma_f32_16x16x32_bf16 v[20:23], v[242:245], v[226:229], v[32:35]
	v_mfma_f32_16x16x32_bf16 v[88:91], v[246:249], v[230:233], v[20:23]
	v_mfma_f32_16x16x32_bf16 v[20:23], v[250:253], v[226:229], v[36:39]
	v_mfma_f32_16x16x32_bf16 v[84:87], v[146:149], v[230:233], v[20:23]
	v_mfma_f32_16x16x32_bf16 v[20:23], v[242:245], v[234:237], v[40:43]
	v_mfma_f32_16x16x32_bf16 v[72:75], v[246:249], v[238:241], v[20:23]
	v_mfma_f32_16x16x32_bf16 v[20:23], v[250:253], v[234:237], v[44:47]
	v_mfma_f32_16x16x32_bf16 v[120:123], v[246:249], v[60:63], v[68:71]
	v_mfma_f32_16x16x32_bf16 v[68:71], v[146:149], v[238:241], v[20:23]
	s_waitcnt vmcnt(4) lgkmcnt(0)
	s_barrier
	s_nop 4
	ds_read_b128 v[20:23], v156 offset:49152
	ds_read_b128 v[24:27], v156 offset:50176
	ds_read_b128 v[36:39], v156 offset:51200
	ds_read_b128 v[222:225], v156 offset:52224
	ds_read_b128 v[226:229], v156 offset:53248
	ds_read_b128 v[230:233], v156 offset:54272
	ds_read_b128 v[234:237], v156 offset:55296
	ds_read_b128 v[238:241], v156 offset:56320
	s_add_u32 s14, s10, 0x80100
	s_addc_u32 s15, s11, 0
	s_mov_b32 m0, s37
	s_nop 0
	global_load_lds_dwordx4 v140, s[14:15]
	s_mov_b32 m0, s38
	s_nop 0
	global_load_lds_dwordx4 v153, s[14:15]
	s_waitcnt lgkmcnt(7)
	v_mfma_f32_16x16x32_bf16 v[28:31], v[12:15], v[20:23], v[158:161]
	s_waitcnt lgkmcnt(6)
	v_mfma_f32_16x16x32_bf16 v[64:67], v[16:19], v[24:27], v[28:31]
	v_mfma_f32_16x16x32_bf16 v[28:31], v[52:55], v[20:23], v[170:173]
	v_mfma_f32_16x16x32_bf16 v[60:63], v[56:59], v[24:27], v[28:31]
	s_waitcnt lgkmcnt(5)
	v_mfma_f32_16x16x32_bf16 v[28:31], v[12:15], v[36:39], v[174:177]
	s_waitcnt lgkmcnt(4)
	v_mfma_f32_16x16x32_bf16 v[48:51], v[16:19], v[222:225], v[28:31]
	v_mfma_f32_16x16x32_bf16 v[28:31], v[52:55], v[36:39], v[178:181]
	v_mfma_f32_16x16x32_bf16 v[44:47], v[56:59], v[222:225], v[28:31]
	s_waitcnt lgkmcnt(3)
	v_mfma_f32_16x16x32_bf16 v[28:31], v[12:15], v[226:229], v[182:185]
	s_waitcnt lgkmcnt(1)
	v_mfma_f32_16x16x32_bf16 v[4:7], v[12:15], v[234:237], v[4:7]
	v_mfma_f32_16x16x32_bf16 v[32:35], v[16:19], v[230:233], v[28:31]
	v_mfma_f32_16x16x32_bf16 v[28:31], v[52:55], v[226:229], v[186:189]
	s_waitcnt lgkmcnt(0)
	v_mfma_f32_16x16x32_bf16 v[16:19], v[16:19], v[238:241], v[4:7]
	v_mfma_f32_16x16x32_bf16 v[4:7], v[52:55], v[234:237], v[8:11]
	v_mfma_f32_16x16x32_bf16 v[28:31], v[56:59], v[230:233], v[28:31]
	v_mfma_f32_16x16x32_bf16 v[12:15], v[56:59], v[238:241], v[4:7]
	s_add_u32 s14, s20, 0x80100
	s_addc_u32 s15, s21, 0
	s_mov_b32 m0, s39
	s_nop 0
	global_load_lds_dwordx4 v139, s[14:15]
	s_mov_b32 m0, s40
	s_nop 0
	global_load_lds_dwordx4 v152, s[14:15]
	v_mfma_f32_16x16x32_bf16 v[4:7], v[242:245], v[20:23], v[190:193]
	s_mov_b32 s22, 2
	v_mfma_f32_16x16x32_bf16 v[56:59], v[246:249], v[24:27], v[4:7]
	v_mfma_f32_16x16x32_bf16 v[4:7], v[250:253], v[20:23], v[194:197]
	v_mfma_f32_16x16x32_bf16 v[52:55], v[146:149], v[24:27], v[4:7]
	v_mfma_f32_16x16x32_bf16 v[4:7], v[242:245], v[36:39], v[198:201]
	v_mfma_f32_16x16x32_bf16 v[40:43], v[246:249], v[222:225], v[4:7]
	v_mfma_f32_16x16x32_bf16 v[4:7], v[250:253], v[36:39], v[202:205]
	v_mfma_f32_16x16x32_bf16 v[36:39], v[146:149], v[222:225], v[4:7]
	v_mfma_f32_16x16x32_bf16 v[4:7], v[242:245], v[226:229], v[206:209]
	v_mfma_f32_16x16x32_bf16 v[24:27], v[246:249], v[230:233], v[4:7]
	v_mfma_f32_16x16x32_bf16 v[4:7], v[250:253], v[226:229], v[210:213]
	v_mfma_f32_16x16x32_bf16 v[20:23], v[146:149], v[230:233], v[4:7]
	v_mfma_f32_16x16x32_bf16 v[4:7], v[242:245], v[234:237], v[214:217]
	v_mfma_f32_16x16x32_bf16 v[8:11], v[250:253], v[234:237], v[218:221]
	v_mfma_f32_16x16x32_bf16 v[4:7], v[246:249], v[238:241], v[4:7]
	v_mfma_f32_16x16x32_bf16 v[8:11], v[146:149], v[238:241], v[8:11]

.LBB0_221:
	s_waitcnt vmcnt(2) lgkmcnt(0)
	s_barrier
	ds_read_b128 v[146:149], v132
	ds_read_b128 v[178:181], v156
	ds_read_b128 v[170:173], v132 offset:2048
	ds_read_b128 v[186:189], v156 offset:2048
	ds_read_b128 v[194:197], v156 offset:4096
	ds_read_b128 v[202:205], v156 offset:6144
	ds_read_b128 v[158:161], v132 offset:1024
	ds_read_b128 v[182:185], v156 offset:1024
	ds_read_b128 v[174:177], v132 offset:3072
	ds_read_b128 v[190:193], v156 offset:3072
	ds_read_b128 v[198:201], v156 offset:5120
	ds_read_b128 v[206:209], v156 offset:7168
	ds_read_b128 v[210:213], v133
	ds_read_b128 v[218:221], v133 offset:2048
	ds_read_b128 v[214:217], v133 offset:1024
	ds_read_b128 v[222:225], v133 offset:3072
	s_add_u32 s60, s10, s59
	s_addc_u32 s61, s11, 0
	s_add_u32 s24, s60, 0x80
	s_addc_u32 s25, s61, 0
	s_mov_b32 m0, s44
	s_nop 0
	global_load_lds_dwordx4 v140, s[24:25]
	s_mov_b32 m0, s48
	s_nop 0
	global_load_lds_dwordx4 v153, s[24:25]
	s_waitcnt lgkmcnt(14)
	v_mfma_f32_16x16x32_bf16 v[128:131], v[146:149], v[178:181], v[128:131]
	s_waitcnt lgkmcnt(13)
	v_mfma_f32_16x16x32_bf16 v[124:127], v[170:173], v[178:181], v[124:127]
	s_waitcnt lgkmcnt(12)
	v_mfma_f32_16x16x32_bf16 v[112:115], v[146:149], v[186:189], v[112:115]
	v_mfma_f32_16x16x32_bf16 v[108:111], v[170:173], v[186:189], v[108:111]
	s_waitcnt lgkmcnt(11)
	v_mfma_f32_16x16x32_bf16 v[96:99], v[146:149], v[194:197], v[96:99]
	v_mfma_f32_16x16x32_bf16 v[92:95], v[170:173], v[194:197], v[92:95]
	s_waitcnt lgkmcnt(10)
	v_mfma_f32_16x16x32_bf16 v[80:83], v[146:149], v[202:205], v[80:83]
	v_mfma_f32_16x16x32_bf16 v[76:79], v[170:173], v[202:205], v[76:79]
	s_waitcnt lgkmcnt(8)
	v_mfma_f32_16x16x32_bf16 v[128:131], v[158:161], v[182:185], v[128:131]
	s_waitcnt lgkmcnt(7)
	v_mfma_f32_16x16x32_bf16 v[124:127], v[174:177], v[182:185], v[124:127]
	s_waitcnt lgkmcnt(6)
	v_mfma_f32_16x16x32_bf16 v[112:115], v[158:161], v[190:193], v[112:115]
	v_mfma_f32_16x16x32_bf16 v[108:111], v[174:177], v[190:193], v[108:111]
	s_waitcnt lgkmcnt(5)
	v_mfma_f32_16x16x32_bf16 v[96:99], v[158:161], v[198:201], v[96:99]
	v_mfma_f32_16x16x32_bf16 v[92:95], v[174:177], v[198:201], v[92:95]
	s_waitcnt lgkmcnt(4)
	v_mfma_f32_16x16x32_bf16 v[80:83], v[158:161], v[206:209], v[80:83]
	v_mfma_f32_16x16x32_bf16 v[76:79], v[174:177], v[206:209], v[76:79]
	s_add_u32 s62, s20, s59
	s_addc_u32 s63, s21, 0
	s_add_u32 s24, s62, 0x80
	s_addc_u32 s25, s63, 0
	s_mov_b32 m0, s45
	s_nop 0
	global_load_lds_dwordx4 v139, s[24:25]
	s_mov_b32 m0, s49
	s_nop 0
	global_load_lds_dwordx4 v152, s[24:25]
	s_waitcnt lgkmcnt(3)
	v_mfma_f32_16x16x32_bf16 v[120:123], v[210:213], v[178:181], v[120:123]
	s_waitcnt lgkmcnt(2)
	v_mfma_f32_16x16x32_bf16 v[116:119], v[218:221], v[178:181], v[116:119]
	v_mfma_f32_16x16x32_bf16 v[104:107], v[210:213], v[186:189], v[104:107]
	v_mfma_f32_16x16x32_bf16 v[100:103], v[218:221], v[186:189], v[100:103]
	v_mfma_f32_16x16x32_bf16 v[88:91], v[210:213], v[194:197], v[88:91]
	v_mfma_f32_16x16x32_bf16 v[84:87], v[218:221], v[194:197], v[84:87]
	v_mfma_f32_16x16x32_bf16 v[72:75], v[210:213], v[202:205], v[72:75]
	v_mfma_f32_16x16x32_bf16 v[68:71], v[218:221], v[202:205], v[68:71]
	s_waitcnt lgkmcnt(1)
	v_mfma_f32_16x16x32_bf16 v[120:123], v[214:217], v[182:185], v[120:123]
	s_waitcnt lgkmcnt(0)
	v_mfma_f32_16x16x32_bf16 v[116:119], v[222:225], v[182:185], v[116:119]
	v_mfma_f32_16x16x32_bf16 v[104:107], v[214:217], v[190:193], v[104:107]
	v_mfma_f32_16x16x32_bf16 v[100:103], v[222:225], v[190:193], v[100:103]
	v_mfma_f32_16x16x32_bf16 v[88:91], v[214:217], v[198:201], v[88:91]
	v_mfma_f32_16x16x32_bf16 v[84:87], v[222:225], v[198:201], v[84:87]
	v_mfma_f32_16x16x32_bf16 v[72:75], v[214:217], v[206:209], v[72:75]
	v_mfma_f32_16x16x32_bf16 v[68:71], v[222:225], v[206:209], v[68:71]
	s_waitcnt vmcnt(4) lgkmcnt(0)
	s_barrier
	ds_read_b128 v[178:181], v156 offset:16384
	ds_read_b128 v[186:189], v156 offset:18432
	ds_read_b128 v[194:197], v156 offset:20480
	ds_read_b128 v[202:205], v156 offset:22528
	ds_read_b128 v[182:185], v156 offset:17408
	ds_read_b128 v[190:193], v156 offset:19456
	ds_read_b128 v[198:201], v156 offset:21504
	ds_read_b128 v[206:209], v156 offset:23552
	s_add_u32 s24, s60, 0x80080
	s_addc_u32 s25, s61, 0
	s_mov_b32 m0, s46
	s_nop 0
	global_load_lds_dwordx4 v140, s[24:25]
	s_mov_b32 m0, s50
	s_nop 0
	global_load_lds_dwordx4 v153, s[24:25]
	s_waitcnt lgkmcnt(7)
	v_mfma_f32_16x16x32_bf16 v[64:67], v[146:149], v[178:181], v[64:67]
	v_mfma_f32_16x16x32_bf16 v[60:63], v[170:173], v[178:181], v[60:63]
	s_waitcnt lgkmcnt(6)
	v_mfma_f32_16x16x32_bf16 v[48:51], v[146:149], v[186:189], v[48:51]
	v_mfma_f32_16x16x32_bf16 v[44:47], v[170:173], v[186:189], v[44:47]
	s_waitcnt lgkmcnt(5)
	v_mfma_f32_16x16x32_bf16 v[32:35], v[146:149], v[194:197], v[32:35]
	v_mfma_f32_16x16x32_bf16 v[28:31], v[170:173], v[194:197], v[28:31]
	s_waitcnt lgkmcnt(4)
	v_mfma_f32_16x16x32_bf16 v[16:19], v[146:149], v[202:205], v[16:19]
	v_mfma_f32_16x16x32_bf16 v[12:15], v[170:173], v[202:205], v[12:15]
	s_waitcnt lgkmcnt(3)
	v_mfma_f32_16x16x32_bf16 v[64:67], v[158:161], v[182:185], v[64:67]
	v_mfma_f32_16x16x32_bf16 v[60:63], v[174:177], v[182:185], v[60:63]
	s_waitcnt lgkmcnt(2)
	v_mfma_f32_16x16x32_bf16 v[48:51], v[158:161], v[190:193], v[48:51]
	v_mfma_f32_16x16x32_bf16 v[44:47], v[174:177], v[190:193], v[44:47]
	s_waitcnt lgkmcnt(1)
	v_mfma_f32_16x16x32_bf16 v[32:35], v[158:161], v[198:201], v[32:35]
	v_mfma_f32_16x16x32_bf16 v[28:31], v[174:177], v[198:201], v[28:31]
	s_waitcnt lgkmcnt(0)
	v_mfma_f32_16x16x32_bf16 v[16:19], v[158:161], v[206:209], v[16:19]
	v_mfma_f32_16x16x32_bf16 v[12:15], v[174:177], v[206:209], v[12:15]
	s_add_u32 s24, s62, 0x80080
	s_addc_u32 s25, s63, 0
	s_mov_b32 m0, s47
	s_nop 0
	global_load_lds_dwordx4 v139, s[24:25]
	s_mov_b32 m0, s51
	s_nop 0
	global_load_lds_dwordx4 v152, s[24:25]
	v_mfma_f32_16x16x32_bf16 v[56:59], v[210:213], v[178:181], v[56:59]
	s_add_u32 s24, s62, 0x100
	s_addc_u32 s25, s63, 0
	s_add_u32 s60, s60, 0x100
	v_mfma_f32_16x16x32_bf16 v[52:55], v[218:221], v[178:181], v[52:55]
	s_addc_u32 s61, s61, 0
	v_mfma_f32_16x16x32_bf16 v[40:43], v[210:213], v[186:189], v[40:43]
	v_mfma_f32_16x16x32_bf16 v[36:39], v[218:221], v[186:189], v[36:39]
	v_mfma_f32_16x16x32_bf16 v[24:27], v[210:213], v[194:197], v[24:27]
	v_mfma_f32_16x16x32_bf16 v[20:23], v[218:221], v[194:197], v[20:23]
	v_mfma_f32_16x16x32_bf16 v[4:7], v[210:213], v[202:205], v[4:7]
	v_mfma_f32_16x16x32_bf16 v[8:11], v[218:221], v[202:205], v[8:11]
	v_mfma_f32_16x16x32_bf16 v[56:59], v[214:217], v[182:185], v[56:59]
	v_mfma_f32_16x16x32_bf16 v[52:55], v[222:225], v[182:185], v[52:55]
	v_mfma_f32_16x16x32_bf16 v[40:43], v[214:217], v[190:193], v[40:43]
	v_mfma_f32_16x16x32_bf16 v[36:39], v[222:225], v[190:193], v[36:39]
	v_mfma_f32_16x16x32_bf16 v[24:27], v[214:217], v[198:201], v[24:27]
	v_mfma_f32_16x16x32_bf16 v[20:23], v[222:225], v[198:201], v[20:23]
	v_mfma_f32_16x16x32_bf16 v[4:7], v[214:217], v[206:209], v[4:7]
	v_mfma_f32_16x16x32_bf16 v[8:11], v[222:225], v[206:209], v[8:11]
	s_waitcnt vmcnt(2) lgkmcnt(0)
	s_barrier
; template <class Epi, class Sched>
; __device__ __forceinline__ void gemm_simple(PG8_LAS unsigned char* lds, const Gemm g, const Sched& S, const Epi& E, int wave_s) {
;     ...
;         for (; t < nt; t += 2) {
;             const bool last = (t == nt - 2);
;             PG8_TILE(0, cA + (size_t)(t + 1) * kstep, cB + (size_t)(t + 1) * kstep, true);
;             const char* a2 = last ? nA : cA + (size_t)(t + 2) * kstep; const char* b2 = last ? nB : cB + (size_t)(t + 2) * kstep;
;             PG8_TILE(1, a2, b2, (!last || has_next));
	ds_read_b128 v[146:149], v134
	ds_read_b128 v[178:181], v156 offset:32768
	ds_read_b128 v[170:173], v134 offset:2048
	ds_read_b128 v[186:189], v156 offset:34816
	ds_read_b128 v[194:197], v156 offset:36864
	ds_read_b128 v[202:205], v156 offset:38912
	ds_read_b128 v[158:161], v134 offset:1024
	ds_read_b128 v[182:185], v156 offset:33792
	ds_read_b128 v[174:177], v134 offset:3072
	ds_read_b128 v[190:193], v156 offset:35840
	ds_read_b128 v[198:201], v156 offset:37888
	ds_read_b128 v[206:209], v156 offset:39936
	ds_read_b128 v[210:213], v135
	ds_read_b128 v[218:221], v135 offset:2048
	ds_read_b128 v[214:217], v135 offset:1024
	ds_read_b128 v[222:225], v135 offset:3072
	s_cmp_eq_u32 s59, s22
	s_cselect_b32 s25, s13, s25
	s_cselect_b32 s24, s56, s24
	s_cselect_b32 s61, s5, s61
	s_cselect_b32 s60, s57, s60
	s_mov_b32 m0, s29
	s_nop 0
	global_load_lds_dwordx4 v140, s[60:61]
	s_mov_b32 m0, s35
	s_nop 0
	global_load_lds_dwordx4 v153, s[60:61]
	s_waitcnt lgkmcnt(14)
	v_mfma_f32_16x16x32_bf16 v[128:131], v[146:149], v[178:181], v[128:131]
	s_waitcnt lgkmcnt(13)
	v_mfma_f32_16x16x32_bf16 v[124:127], v[170:173], v[178:181], v[124:127]
	s_waitcnt lgkmcnt(12)
	v_mfma_f32_16x16x32_bf16 v[112:115], v[146:149], v[186:189], v[112:115]
	v_mfma_f32_16x16x32_bf16 v[108:111], v[170:173], v[186:189], v[108:111]
	s_waitcnt lgkmcnt(11)
	v_mfma_f32_16x16x32_bf16 v[96:99], v[146:149], v[194:197], v[96:99]
	v_mfma_f32_16x16x32_bf16 v[92:95], v[170:173], v[194:197], v[92:95]
	s_waitcnt lgkmcnt(10)
	v_mfma_f32_16x16x32_bf16 v[80:83], v[146:149], v[202:205], v[80:83]
	v_mfma_f32_16x16x32_bf16 v[76:79], v[170:173], v[202:205], v[76:79]
	s_waitcnt lgkmcnt(8)
	v_mfma_f32_16x16x32_bf16 v[128:131], v[158:161], v[182:185], v[128:131]
	s_waitcnt lgkmcnt(7)
	v_mfma_f32_16x16x32_bf16 v[124:127], v[174:177], v[182:185], v[124:127]
	s_waitcnt lgkmcnt(6)
	v_mfma_f32_16x16x32_bf16 v[112:115], v[158:161], v[190:193], v[112:115]
	v_mfma_f32_16x16x32_bf16 v[108:111], v[174:177], v[190:193], v[108:111]
	s_waitcnt lgkmcnt(5)
	v_mfma_f32_16x16x32_bf16 v[96:99], v[158:161], v[198:201], v[96:99]
	v_mfma_f32_16x16x32_bf16 v[92:95], v[174:177], v[198:201], v[92:95]
	s_waitcnt lgkmcnt(4)
	v_mfma_f32_16x16x32_bf16 v[80:83], v[158:161], v[206:209], v[80:83]
	v_mfma_f32_16x16x32_bf16 v[76:79], v[174:177], v[206:209], v[76:79]
	s_mov_b32 m0, s19
	s_nop 0
	global_load_lds_dwordx4 v139, s[24:25]
	s_mov_b32 m0, s36
	s_nop 0
	global_load_lds_dwordx4 v152, s[24:25]
	s_waitcnt lgkmcnt(3)
	v_mfma_f32_16x16x32_bf16 v[120:123], v[210:213], v[178:181], v[120:123]
	s_waitcnt lgkmcnt(2)
	v_mfma_f32_16x16x32_bf16 v[116:119], v[218:221], v[178:181], v[116:119]
	v_mfma_f32_16x16x32_bf16 v[104:107], v[210:213], v[186:189], v[104:107]
	v_mfma_f32_16x16x32_bf16 v[100:103], v[218:221], v[186:189], v[100:103]
	v_mfma_f32_16x16x32_bf16 v[88:91], v[210:213], v[194:197], v[88:91]
	v_mfma_f32_16x16x32_bf16 v[84:87], v[218:221], v[194:197], v[84:87]
	v_mfma_f32_16x16x32_bf16 v[72:75], v[210:213], v[202:205], v[72:75]
	v_mfma_f32_16x16x32_bf16 v[68:71], v[218:221], v[202:205], v[68:71]
	s_waitcnt lgkmcnt(1)
	v_mfma_f32_16x16x32_bf16 v[120:123], v[214:217], v[182:185], v[120:123]
	s_waitcnt lgkmcnt(0)
	v_mfma_f32_16x16x32_bf16 v[116:119], v[222:225], v[182:185], v[116:119]
	v_mfma_f32_16x16x32_bf16 v[104:107], v[214:217], v[190:193], v[104:107]
	v_mfma_f32_16x16x32_bf16 v[100:103], v[222:225], v[190:193], v[100:103]
	v_mfma_f32_16x16x32_bf16 v[88:91], v[214:217], v[198:201], v[88:91]
	v_mfma_f32_16x16x32_bf16 v[84:87], v[222:225], v[198:201], v[84:87]
	v_mfma_f32_16x16x32_bf16 v[72:75], v[214:217], v[206:209], v[72:75]
	v_mfma_f32_16x16x32_bf16 v[68:71], v[222:225], v[206:209], v[68:71]
	s_waitcnt vmcnt(4) lgkmcnt(0)
	s_barrier
; #define LAS __attribute__((address_space(3)))
; __device__ __forceinline__ void rstd_table(const float* ssq, LAS unsigned char* lds, const Unit& u, int tid, int par) {
;     if (tid < 256) { const f32x4* p = (const f32x4*)(ssq + (size_t)(u.pm * 256 + tid) * 32); f32x4 a = p[0];
; #pragma unroll
;         for (int i = 1; i < 8; ++i) a += p[i];
;         ((LAS float*)(lds + 131072 + par * 1024))[tid] = 1.0f / sqrtf(((a[0] + a[1]) + (a[2] + a[3])) * (1.0f / DM) + 1e-6f); }
	ds_read_b128 v[178:181], v156 offset:49152
	ds_read_b128 v[186:189], v156 offset:51200
	ds_read_b128 v[194:197], v156 offset:53248
	ds_read_b128 v[202:205], v156 offset:55296
	ds_read_b128 v[182:185], v156 offset:50176
	ds_read_b128 v[190:193], v156 offset:52224
	ds_read_b128 v[198:201], v156 offset:54272
	ds_read_b128 v[206:209], v156 offset:56320
	s_add_u32 s60, s60, 0x80000
	s_addc_u32 s61, s61, 0
	s_mov_b32 m0, s37
	s_nop 0
	global_load_lds_dwordx4 v140, s[60:61]
	s_mov_b32 m0, s38
	s_nop 0
	global_load_lds_dwordx4 v153, s[60:61]
	s_waitcnt lgkmcnt(7)
	v_mfma_f32_16x16x32_bf16 v[64:67], v[146:149], v[178:181], v[64:67]
	v_mfma_f32_16x16x32_bf16 v[60:63], v[170:173], v[178:181], v[60:63]
	s_waitcnt lgkmcnt(6)
	v_mfma_f32_16x16x32_bf16 v[48:51], v[146:149], v[186:189], v[48:51]
	v_mfma_f32_16x16x32_bf16 v[44:47], v[170:173], v[186:189], v[44:47]
	s_waitcnt lgkmcnt(5)
	v_mfma_f32_16x16x32_bf16 v[32:35], v[146:149], v[194:197], v[32:35]
	v_mfma_f32_16x16x32_bf16 v[28:31], v[170:173], v[194:197], v[28:31]
	s_waitcnt lgkmcnt(4)
	v_mfma_f32_16x16x32_bf16 v[16:19], v[146:149], v[202:205], v[16:19]
	v_mfma_f32_16x16x32_bf16 v[12:15], v[170:173], v[202:205], v[12:15]
	s_waitcnt lgkmcnt(3)
	v_mfma_f32_16x16x32_bf16 v[64:67], v[158:161], v[182:185], v[64:67]
	v_mfma_f32_16x16x32_bf16 v[60:63], v[174:177], v[182:185], v[60:63]
	s_waitcnt lgkmcnt(2)
	v_mfma_f32_16x16x32_bf16 v[48:51], v[158:161], v[190:193], v[48:51]
	v_mfma_f32_16x16x32_bf16 v[44:47], v[174:177], v[190:193], v[44:47]
	s_waitcnt lgkmcnt(1)
	v_mfma_f32_16x16x32_bf16 v[32:35], v[158:161], v[198:201], v[32:35]
	v_mfma_f32_16x16x32_bf16 v[28:31], v[174:177], v[198:201], v[28:31]
	s_waitcnt lgkmcnt(0)
	v_mfma_f32_16x16x32_bf16 v[16:19], v[158:161], v[206:209], v[16:19]
	v_mfma_f32_16x16x32_bf16 v[12:15], v[174:177], v[206:209], v[12:15]
	s_add_u32 s24, s24, 0x80000
	s_addc_u32 s25, s25, 0
	s_mov_b32 m0, s39
	s_nop 0
	global_load_lds_dwordx4 v139, s[24:25]
	s_mov_b32 m0, s40
	s_nop 0
	global_load_lds_dwordx4 v152, s[24:25]
	v_mfma_f32_16x16x32_bf16 v[56:59], v[210:213], v[178:181], v[56:59]
	s_add_i32 s58, s58, 2
	s_add_u32 s22, s22, 0xffffff00
	s_addc_u32 s23, s23, -1
	v_mfma_f32_16x16x32_bf16 v[52:55], v[218:221], v[178:181], v[52:55]
	s_add_u32 s20, s20, 0x100
	s_addc_u32 s21, s21, 0
	s_add_u32 s10, s10, 0x100
	v_mfma_f32_16x16x32_bf16 v[40:43], v[210:213], v[186:189], v[40:43]
	s_addc_u32 s11, s11, 0
	s_cmp_lt_u32 s58, 30
	v_mfma_f32_16x16x32_bf16 v[36:39], v[218:221], v[186:189], v[36:39]
	v_mfma_f32_16x16x32_bf16 v[24:27], v[210:213], v[194:197], v[24:27]
	v_mfma_f32_16x16x32_bf16 v[20:23], v[218:221], v[194:197], v[20:23]
	v_mfma_f32_16x16x32_bf16 v[4:7], v[210:213], v[202:205], v[4:7]
	v_mfma_f32_16x16x32_bf16 v[8:11], v[218:221], v[202:205], v[8:11]
	v_mfma_f32_16x16x32_bf16 v[56:59], v[214:217], v[182:185], v[56:59]
	v_mfma_f32_16x16x32_bf16 v[52:55], v[222:225], v[182:185], v[52:55]
	v_mfma_f32_16x16x32_bf16 v[40:43], v[214:217], v[190:193], v[40:43]
	v_mfma_f32_16x16x32_bf16 v[36:39], v[222:225], v[190:193], v[36:39]
	v_mfma_f32_16x16x32_bf16 v[24:27], v[214:217], v[198:201], v[24:27]
	v_mfma_f32_16x16x32_bf16 v[20:23], v[222:225], v[198:201], v[20:23]
	v_mfma_f32_16x16x32_bf16 v[4:7], v[214:217], v[206:209], v[4:7]
	v_mfma_f32_16x16x32_bf16 v[8:11], v[222:225], v[206:209], v[8:11]
	s_cbranch_scc1 .LBB0_221
	s_nor_b64 s[10:11], s[6:7], s[8:9]
	s_and_saveexec_b64 s[20:21], s[10:11]
	s_cbranch_execz .LBB0_211
	v_lshl_add_u32 v132, s12, 8, v138
	v_ashrrev_i32_e32 v133, 31, v132
	v_readlane_b32 s10, v255, 2
	v_lshlrev_b64 v[132:133], 7, v[132:133]
	v_readlane_b32 s11, v255, 3
	s_lshl_b32 s5, s53, 10
	s_and_b32 s5, s5, 0x400
	v_lshl_add_u64 v[136:137], s[10:11], 0, v[132:133]
	global_load_dwordx4 v[132:135], v[136:137], off offset:48
	global_load_dwordx4 v[146:149], v[136:137], off offset:32
	global_load_dwordx4 v[158:161], v[136:137], off
	global_load_dwordx4 v[170:173], v[136:137], off offset:16
	s_waitcnt vmcnt(0)
	v_pk_add_f32 v[142:143], v[160:161], v[172:173]
	v_pk_add_f32 v[144:145], v[158:159], v[170:171]
	v_pk_add_f32 v[142:143], v[142:143], v[148:149]
	v_pk_add_f32 v[144:145], v[144:145], v[146:147]
	v_pk_add_f32 v[142:143], v[142:143], v[134:135]
	v_pk_add_f32 v[144:145], v[144:145], v[132:133]
	global_load_dwordx4 v[132:135], v[136:137], off offset:112
	global_load_dwordx4 v[146:149], v[136:137], off offset:96
	global_load_dwordx4 v[158:161], v[136:137], off offset:80
	global_load_dwordx4 v[170:173], v[136:137], off offset:64
	s_waitcnt vmcnt(0)
	v_pk_add_f32 v[136:137], v[142:143], v[172:173]
	v_pk_add_f32 v[142:143], v[144:145], v[170:171]
	v_pk_add_f32 v[136:137], v[136:137], v[160:161]
	v_pk_add_f32 v[142:143], v[142:143], v[158:159]
	v_pk_add_f32 v[136:137], v[136:137], v[148:149]
	v_pk_add_f32 v[142:143], v[142:143], v[146:147]
	v_pk_add_f32 v[134:135], v[136:137], v[134:135]
	v_pk_add_f32 v[132:133], v[142:143], v[132:133]
	s_nop 0
	v_pk_mov_b32 v[136:137], v[132:133], v[134:135] op_sel:[1,0]
	v_mov_b32_e32 v133, v135
	v_pk_add_f32 v[132:133], v[136:137], v[132:133]
	s_nop 0
	v_add_f32_e32 v132, v132, v133
	v_fmamk_f32 v132, v132, 0x3a000000, v164
	v_cmp_gt_f32_e32 vcc, s69, v132
	v_mul_f32_e32 v133, 0x4f800000, v132
	s_nop 0
	v_cndmask_b32_e32 v132, v132, v133, vcc
	v_sqrt_f32_e32 v133, v132
	s_nop 0
	v_add_u32_e32 v134, -1, v133
	v_fma_f32 v135, -v134, v133, v132
	v_cmp_ge_f32_e64 s[10:11], 0, v135
	v_add_u32_e32 v135, 1, v133
	s_nop 0
	v_cndmask_b32_e64 v134, v133, v134, s[10:11]
	v_fma_f32 v133, -v135, v133, v132
	v_cmp_lt_f32_e64 s[10:11], 0, v133
	s_nop 1
	v_cndmask_b32_e64 v133, v134, v135, s[10:11]
	v_mul_f32_e32 v134, 0x37800000, v133
	v_cndmask_b32_e32 v133, v133, v134, vcc
	v_cmp_class_f32_e32 vcc, v132, v165
	s_nop 1
	v_cndmask_b32_e32 v132, v133, v132, vcc
	v_div_scale_f32 v133, s[10:11], v132, v132, 1.0
	v_rcp_f32_e32 v134, v133
	s_nop 0
	v_fma_f32 v135, -v133, v134, 1.0
	v_fmac_f32_e32 v134, v135, v134
	v_div_scale_f32 v135, vcc, 1.0, v132, 1.0
	v_mul_f32_e32 v136, v135, v134
	v_fma_f32 v137, -v133, v136, v135
	v_fmac_f32_e32 v136, v137, v134
	v_fma_f32 v133, -v133, v136, v135
	v_div_fmas_f32 v133, v133, v134, v136
	v_div_fixup_f32 v132, v133, v132, 1.0
	v_add_u32_e32 v133, s5, v154
	ds_write_b32 v133, v132
	s_branch .LBB0_211

; #define LAS __attribute__((address_space(3)))
; __device__ __forceinline__ void attn_mfma_phase(int wave_s, const bf16_t* Z, bf16_t* OG, float* LSE, LAS unsigned char* lds) {
;     ...
;     for (int item = bid; item < 3072; item += gdim) {
;         const int sub = item & 31, bgh = item >> 5, h = bgh & 3, g = (bgh >> 2) % 3, b = bgh / 12;
;         const int d = (g == 0) ? 1 : (g == 1) ? 4 : 16, L = SEQ / d, nqt = 32 / d, r = sub / nqt, qt = sub % nqt;
;         const int tile_start = 128 * qt - 64;
;         const bf16_t* zb = Z + (size_t)(b * SEQ + r) * N1 + g * 512 + h * 128;
;         for (int u = tid; u < 4096; u += NTHR) { const int rowl = u >> 4, c = u & 15, lk = tile_start + rowl;
;             u32x4 kv = (u32x4){0u, 0u, 0u, 0u}, vv = (u32x4){0u, 0u, 0u, 0u};
;             if (lk >= 0 && lk < L) { const bf16_t* rp = zb + (size_t)lk * d * N1 + c * 8; kv = *(const u32x4*)(rp + 1536); vv = *(const u32x4*)(rp + 3072); }
;             const int o = img_off(rowl, c); *(LAS u32x4*)(kimg + o) = kv; *(LAS u32x4*)(vimg + o) = vv; }
.LBB0_231:
	s_ashr_i32 s4, s35, 7
	s_mul_hi_i32 s6, s4, 0x55555556
	s_lshr_b32 s7, s6, 31
	s_ashr_i32 s5, s35, 5
	s_add_i32 s6, s6, s7
	s_and_b32 s17, s5, 3
	s_mul_i32 s6, s6, 3
	s_mul_hi_i32 s5, s5, 0x2aaaaaab
	s_sub_i32 s4, s4, s6
	s_lshr_b32 s6, s5, 31
	s_lshr_b32 s5, s5, 1
	s_and_b32 s10, s35, 31
	s_add_i32 s11, s5, s6
	s_cmp_eq_u32 s4, 0
	s_cselect_b64 s[6:7], -1, 0
	s_cmp_eq_u32 s4, 1
	s_cselect_b64 s[8:9], -1, 0
	s_and_b64 s[8:9], s[8:9], exec
	s_cselect_b32 s5, 2, 4
	s_and_b64 s[6:7], s[6:7], exec
	s_cselect_b32 s19, 0, s5
	s_lshr_b32 s6, 32, s19
	s_add_i32 s6, s6, -1
	s_sub_i32 s7, 5, s19
	s_and_b32 s6, s6, s10
	s_lshr_b32 s7, s10, s7
	s_lshl_b32 s20, s6, 7
	s_lshl_b32 s6, s11, 12
	s_or_b32 s84, s7, s6
	s_lshr_b32 s5, 0x1000, s19
	s_sub_i32 s18, s20, 64
	s_mul_i32 s7, s84, 0x3400
	s_mul_hi_i32 s6, s84, 0x3400
	s_add_u32 s8, s2, s7
	s_addc_u32 s9, s3, s6
	s_lshl_b32 s6, s4, 9
	s_ashr_i32 s7, s6, 31
	s_lshl_b64 s[6:7], s[6:7], 1
	s_add_u32 s6, s8, s6
	s_addc_u32 s7, s9, s7
	s_lshl_b32 s8, s17, 8
	s_add_u32 s6, s6, s8
	s_addc_u32 s7, s7, 0
	s_mov_b64 s[8:9], exec
	v_readlane_b32 s10, v255, 11
	v_readlane_b32 s11, v255, 12
	s_and_b64 s[10:11], s[8:9], s[10:11]
	s_mov_b64 exec, s[10:11]
	s_cbranch_execz .LBB0_236
	v_mov_b32_e32 v49, v141
	v_lshl_add_u64 v[8:9], s[6:7], 0, v[48:49]
	v_ashrrev_i32_e32 v234, 4, v56
	v_lshlrev_b32_e32 v236, 2, v234
	v_lshlrev_b32_e32 v235, 8, v234
	v_and_b32_e32 v236, 12, v236
	v_bfe_u32 v237, v234, 2, 2
	v_bitop3_b32 v237, v236, v57, v237 bitop3:0x36
	v_lshl_or_b32 v235, v237, 4, v235
	v_add_u32_e32 v235, 0, v235
	v_add_u32_e32 v236, 0x10000, v235
	s_add_i32 s21, s18, 0
	v_add_u32_e32 v140, s21, v234
	v_cmp_lt_i32_e32 vcc, -1, v140
	v_cmp_gt_i32_e64 s[86:87], s5, v140
	s_and_b64 vcc, vcc, s[86:87]
	v_mov_b64_e32 v[170:171], 0
	v_mov_b64_e32 v[172:173], 0
	v_mov_b64_e32 v[174:175], 0
	v_mov_b64_e32 v[176:177], 0
	s_and_saveexec_b64 s[86:87], vcc
	s_cbranch_execz .Lattn_ld_skip0
	v_lshlrev_b64 v[238:239], s19, v[140:141]
	v_mad_u64_u32 v[240:241], vcc, v238, s33, v[8:9]
	v_mad_u32_u24 v241, v239, s33, v241
	v_add_co_u32_e32 v242, vcc, 0x1000, v240
	s_nop 1
	v_addc_co_u32_e32 v243, vcc, 0, v241, vcc
	global_load_dwordx4 v[170:173], v[240:241], off offset:3072
	global_load_dwordx4 v[174:177], v[242:243], off offset:2048
.Lattn_ld_skip0:
	s_or_b64 exec, exec, s[86:87]
	s_add_i32 s21, s18, 32
	v_add_u32_e32 v140, s21, v234
	v_cmp_lt_i32_e32 vcc, -1, v140
	v_cmp_gt_i32_e64 s[86:87], s5, v140
	s_and_b64 vcc, vcc, s[86:87]
	v_mov_b64_e32 v[178:179], 0
	v_mov_b64_e32 v[180:181], 0
	v_mov_b64_e32 v[182:183], 0
	v_mov_b64_e32 v[184:185], 0
	s_and_saveexec_b64 s[86:87], vcc
	s_cbranch_execz .Lattn_ld_skip1
	v_lshlrev_b64 v[238:239], s19, v[140:141]
	v_mad_u64_u32 v[240:241], vcc, v238, s33, v[8:9]
	v_mad_u32_u24 v241, v239, s33, v241
	v_add_co_u32_e32 v242, vcc, 0x1000, v240
	s_nop 1
	v_addc_co_u32_e32 v243, vcc, 0, v241, vcc
	global_load_dwordx4 v[178:181], v[240:241], off offset:3072
	global_load_dwordx4 v[182:185], v[242:243], off offset:2048
.Lattn_ld_skip1:
	s_or_b64 exec, exec, s[86:87]
	s_add_i32 s21, s18, 64
	v_add_u32_e32 v140, s21, v234
	v_cmp_lt_i32_e32 vcc, -1, v140
	v_cmp_gt_i32_e64 s[86:87], s5, v140
	s_and_b64 vcc, vcc, s[86:87]
	v_mov_b64_e32 v[186:187], 0
	v_mov_b64_e32 v[188:189], 0
	v_mov_b64_e32 v[190:191], 0
	v_mov_b64_e32 v[192:193], 0
	s_and_saveexec_b64 s[86:87], vcc
	s_cbranch_execz .Lattn_ld_skip2
	v_lshlrev_b64 v[238:239], s19, v[140:141]
	v_mad_u64_u32 v[240:241], vcc, v238, s33, v[8:9]
	v_mad_u32_u24 v241, v239, s33, v241
	v_add_co_u32_e32 v242, vcc, 0x1000, v240
	s_nop 1
	v_addc_co_u32_e32 v243, vcc, 0, v241, vcc
	global_load_dwordx4 v[186:189], v[240:241], off offset:3072
	global_load_dwordx4 v[190:193], v[242:243], off offset:2048
; #define LAS __attribute__((address_space(3)))
; __device__ __forceinline__ void attn_mfma_phase(int wave_s, const bf16_t* Z, bf16_t* OG, float* LSE, LAS unsigned char* lds) {
;     ...
;         for (int u = tid; u < 4096; u += NTHR) { const int rowl = u >> 4, c = u & 15, lk = tile_start + rowl;
;             u32x4 kv = (u32x4){0u, 0u, 0u, 0u}, vv = (u32x4){0u, 0u, 0u, 0u};
;             if (lk >= 0 && lk < L) { const bf16_t* rp = zb + (size_t)lk * d * N1 + c * 8; kv = *(const u32x4*)(rp + 1536); vv = *(const u32x4*)(rp + 3072); }
;             const int o = img_off(rowl, c); *(LAS u32x4*)(kimg + o) = kv; *(LAS u32x4*)(vimg + o) = vv; }
.Lattn_ld_skip2:
	s_or_b64 exec, exec, s[86:87]
	s_add_i32 s21, s18, 96
	v_add_u32_e32 v140, s21, v234
	v_cmp_lt_i32_e32 vcc, -1, v140
	v_cmp_gt_i32_e64 s[86:87], s5, v140
	s_and_b64 vcc, vcc, s[86:87]
	v_mov_b64_e32 v[194:195], 0
	v_mov_b64_e32 v[196:197], 0
	v_mov_b64_e32 v[198:199], 0
	v_mov_b64_e32 v[200:201], 0
	s_and_saveexec_b64 s[86:87], vcc
	s_cbranch_execz .Lattn_ld_skip3
	v_lshlrev_b64 v[238:239], s19, v[140:141]
	v_mad_u64_u32 v[240:241], vcc, v238, s33, v[8:9]
	v_mad_u32_u24 v241, v239, s33, v241
	v_add_co_u32_e32 v242, vcc, 0x1000, v240
	s_nop 1
	v_addc_co_u32_e32 v243, vcc, 0, v241, vcc
	global_load_dwordx4 v[194:197], v[240:241], off offset:3072
	global_load_dwordx4 v[198:201], v[242:243], off offset:2048
.Lattn_ld_skip3:
	s_or_b64 exec, exec, s[86:87]
	s_add_i32 s21, s18, 128
	v_add_u32_e32 v140, s21, v234
	v_cmp_lt_i32_e32 vcc, -1, v140
	v_cmp_gt_i32_e64 s[86:87], s5, v140
	s_and_b64 vcc, vcc, s[86:87]
	v_mov_b64_e32 v[202:203], 0
	v_mov_b64_e32 v[204:205], 0
	v_mov_b64_e32 v[206:207], 0
	v_mov_b64_e32 v[208:209], 0
	s_and_saveexec_b64 s[86:87], vcc
	s_cbranch_execz .Lattn_ld_skip4
	v_lshlrev_b64 v[238:239], s19, v[140:141]
	v_mad_u64_u32 v[240:241], vcc, v238, s33, v[8:9]
	v_mad_u32_u24 v241, v239, s33, v241
	v_add_co_u32_e32 v242, vcc, 0x1000, v240
	s_nop 1
	v_addc_co_u32_e32 v243, vcc, 0, v241, vcc
	global_load_dwordx4 v[202:205], v[240:241], off offset:3072
	global_load_dwordx4 v[206:209], v[242:243], off offset:2048
.Lattn_ld_skip4:
	s_or_b64 exec, exec, s[86:87]
	s_add_i32 s21, s18, 160
	v_add_u32_e32 v140, s21, v234
	v_cmp_lt_i32_e32 vcc, -1, v140
	v_cmp_gt_i32_e64 s[86:87], s5, v140
	s_and_b64 vcc, vcc, s[86:87]
	v_mov_b64_e32 v[210:211], 0
	v_mov_b64_e32 v[212:213], 0
	v_mov_b64_e32 v[214:215], 0
	v_mov_b64_e32 v[216:217], 0
	s_and_saveexec_b64 s[86:87], vcc
	s_cbranch_execz .Lattn_ld_skip5
	v_lshlrev_b64 v[238:239], s19, v[140:141]
	v_mad_u64_u32 v[240:241], vcc, v238, s33, v[8:9]
	v_mad_u32_u24 v241, v239, s33, v241
	v_add_co_u32_e32 v242, vcc, 0x1000, v240
	s_nop 1
	v_addc_co_u32_e32 v243, vcc, 0, v241, vcc
	global_load_dwordx4 v[210:213], v[240:241], off offset:3072
	global_load_dwordx4 v[214:217], v[242:243], off offset:2048
.Lattn_ld_skip5:
	s_or_b64 exec, exec, s[86:87]
	s_add_i32 s21, s18, 192
	v_add_u32_e32 v140, s21, v234
	v_cmp_lt_i32_e32 vcc, -1, v140
	v_cmp_gt_i32_e64 s[86:87], s5, v140
	s_and_b64 vcc, vcc, s[86:87]
	v_mov_b64_e32 v[218:219], 0
	v_mov_b64_e32 v[220:221], 0
	v_mov_b64_e32 v[222:223], 0
	v_mov_b64_e32 v[224:225], 0
	s_and_saveexec_b64 s[86:87], vcc
	s_cbranch_execz .Lattn_ld_skip6
	v_lshlrev_b64 v[238:239], s19, v[140:141]
	v_mad_u64_u32 v[240:241], vcc, v238, s33, v[8:9]
	v_mad_u32_u24 v241, v239, s33, v241
	v_add_co_u32_e32 v242, vcc, 0x1000, v240
	s_nop 1
	v_addc_co_u32_e32 v243, vcc, 0, v241, vcc
	global_load_dwordx4 v[218:221], v[240:241], off offset:3072
	global_load_dwordx4 v[222:225], v[242:243], off offset:2048
.Lattn_ld_skip6:
	s_or_b64 exec, exec, s[86:87]
	s_add_i32 s21, s18, 224
	v_add_u32_e32 v140, s21, v234
	v_cmp_lt_i32_e32 vcc, -1, v140
	v_cmp_gt_i32_e64 s[86:87], s5, v140
	s_and_b64 vcc, vcc, s[86:87]
	v_mov_b64_e32 v[226:227], 0
	v_mov_b64_e32 v[228:229], 0
	v_mov_b64_e32 v[230:231], 0
	v_mov_b64_e32 v[232:233], 0
	s_and_saveexec_b64 s[86:87], vcc
	s_cbranch_execz .Lattn_ld_skip7
	v_lshlrev_b64 v[238:239], s19, v[140:141]
	v_mad_u64_u32 v[240:241], vcc, v238, s33, v[8:9]
	v_mad_u32_u24 v241, v239, s33, v241
	v_add_co_u32_e32 v242, vcc, 0x1000, v240
	s_nop 1
	v_addc_co_u32_e32 v243, vcc, 0, v241, vcc
	global_load_dwordx4 v[226:229], v[240:241], off offset:3072
	global_load_dwordx4 v[230:233], v[242:243], off offset:2048
.Lattn_ld_skip7:
	s_or_b64 exec, exec, s[86:87]
	s_waitcnt vmcnt(0)
	ds_write_b128 v235, v[170:173]
	ds_write_b128 v236, v[174:177]
	ds_write_b128 v235, v[178:181] offset:8192
	ds_write_b128 v236, v[182:185] offset:8192
	ds_write_b128 v235, v[186:189] offset:16384
	ds_write_b128 v236, v[190:193] offset:16384
	ds_write_b128 v235, v[194:197] offset:24576
	ds_write_b128 v236, v[198:201] offset:24576
	ds_write_b128 v235, v[202:205] offset:32768
	ds_write_b128 v236, v[206:209] offset:32768
	ds_write_b128 v235, v[210:213] offset:40960
	ds_write_b128 v236, v[214:217] offset:40960
	ds_write_b128 v235, v[218:221] offset:49152
	ds_write_b128 v236, v[222:225] offset:49152
	ds_write_b128 v235, v[226:229] offset:57344
	ds_write_b128 v236, v[230:233] offset:57344

; #define LAS __attribute__((address_space(3)))
; template <class Epi, class Sched>
; __device__ __forceinline__ void gemm_simple(PG8_LAS unsigned char* lds, const Gemm g, const Sched& S, const Epi& E, int wave_s) {
;     ...
;     for (int i = 0; i < 2; ++i) { int R, C; stage_rc(tid * 16 + i * 8192, R, C); const int Rb = Epi::PERM ? ((R & ~31) + perm32(R & 31)) : R;
;         voffA[i] = (unsigned)(R * K + C) * 2u; voffB[i] = (unsigned)(Rb * K + C) * 2u; }
;     const size_t kstep = (size_t)(BK * 2), hstep = (size_t)HALF * K * 2, tstep = 2 * hstep;
;     const unsigned ldsw = (unsigned)wid * 1024u; const unsigned lds_u = (unsigned)(__UINTPTR_TYPE__)lds;
;     const int aoff = lds_byte(wr * 64 + fr, fq * 8), boff = lds_byte(wc * 32 + fr, fq * 8);
; __device__ __forceinline__ void rstd_table(const float* ssq, LAS unsigned char* lds, const Unit& u, int tid, int par) {
;     if (tid < 256) { const f32x4* p = (const f32x4*)(ssq + (size_t)(u.pm * 256 + tid) * 32); f32x4 a = p[0];
; #pragma unroll
;         for (int i = 1; i < 8; ++i) a += p[i];
;         ((LAS float*)(lds + 131072 + par * 1024))[tid] = 1.0f / sqrtf(((a[0] + a[1]) + (a[2] + a[3])) * (1.0f / DM) + 1e-6f); }
.LBB0_261:
	s_andn2_b64 vcc, exec, s[4:5]
	s_cbranch_vccnz .LBB0_295
	v_bfe_i32 v3, v140, 27, 1
	v_lshlrev_b32_e32 v1, 4, v140
	v_lshrrev_b32_e32 v3, 22, v3
	v_add_u32_e32 v3, v1, v3
	v_and_b32_e32 v3, 0xfffffc00, v3
	v_sub_u32_e32 v3, v1, v3
	v_ashrrev_i32_e32 v2, 31, v140
	s_waitcnt lgkmcnt(0)
	v_lshrrev_b32_e32 v5, 4, v3
	v_lshrrev_b32_e32 v2, 26, v2
	v_bitop3_b32 v3, v5, v3, 32 bitop3:0x6c
	v_add_u32_e32 v2, v140, v2
	v_ashrrev_i32_e32 v6, 31, v3
	v_ashrrev_i32_e32 v2, 6, v2
	v_lshrrev_b32_e32 v6, 26, v6
	v_lshlrev_b32_e32 v5, 3, v2
	v_add_u32_e32 v6, v3, v6
	v_readlane_b32 s4, v254, 57
	v_and_b32_e32 v5, -16, v5
	v_ashrrev_i32_e32 v7, 6, v6
	v_and_b32_e32 v6, 0xc0, v6
	s_add_u32 s36, s4, 0x7a00000
	v_readlane_b32 s4, v254, 58
	v_add_u32_e32 v5, v7, v5
	v_sub_u32_e32 v3, v3, v6
	s_addc_u32 s37, s4, 0
	v_lshlrev_b32_e32 v2, 5, v2
	v_ashrrev_i16_sdwa v3, v166, sext(v3) dst_sel:DWORD dst_unused:UNUSED_PAD src0_sel:DWORD src1_sel:BYTE_0
	v_lshlrev_b32_e32 v6, 1, v5
	v_lshrrev_b32_e32 v8, 2, v5
	v_and_b32_e32 v7, 3, v7
	s_mov_b32 s4, 0xfffe0
	v_and_b32_e32 v2, 32, v2
	v_bfe_i32 v3, v3, 0, 16
	v_and_b32_e32 v6, 24, v6
	v_and_b32_e32 v8, 4, v8
	v_and_or_b32 v7, v5, s4, v7
	v_or3_b32 v6, v7, v8, v6
	v_add_lshl_u32 v2, v2, v3, 1
	v_add_u32_e32 v1, 0x2000, v1
	v_lshl_add_u32 v162, v5, 12, v2
	v_lshl_add_u32 v163, v6, 12, v2
	v_ashrrev_i32_e32 v2, 31, v1
	v_lshrrev_b32_e32 v2, 22, v2
	v_add_u32_e32 v2, v1, v2
	v_ashrrev_i32_e32 v2, 10, v2
	v_mul_i32_i24_e32 v3, 0x400, v2
	v_sub_u32_e32 v1, v1, v3
	v_lshrrev_b32_e32 v3, 4, v1
	v_bitop3_b32 v1, v3, v1, 32 bitop3:0x6c
	v_ashrrev_i32_e32 v5, 31, v1
	v_lshrrev_b32_e32 v5, 26, v5
	v_lshlrev_b32_e32 v3, 3, v2
	v_add_u32_e32 v5, v1, v5
	v_and_b32_e32 v3, -16, v3
	v_ashrrev_i32_e32 v6, 6, v5
	s_ashr_i32 s13, s12, 6
	v_add_u32_e32 v3, v6, v3
	v_and_b32_e32 v5, 0xc0, v5
	v_and_b32_e32 v6, 3, v6
	s_ashr_i32 s23, s22, 31
	s_ashr_i32 s21, s20, 31
	v_sub_u32_e32 v1, v1, v5
	v_and_or_b32 v6, v3, s4, v6
	s_lshl_b32 s8, s13, 10
	s_lshl_b64 s[4:5], s[22:23], 20
	s_lshl_b64 s[6:7], s[20:21], 20
	v_lshlrev_b32_e32 v2, 5, v2
	v_ashrrev_i16_sdwa v1, v166, sext(v1) dst_sel:DWORD dst_unused:UNUSED_PAD src0_sel:DWORD src1_sel:BYTE_0
	v_lshlrev_b32_e32 v5, 1, v3
	v_lshrrev_b32_e32 v7, 2, v3
	s_add_u32 s10, s36, s6
	v_and_b32_e32 v2, 32, v2
	v_bfe_i32 v1, v1, 0, 16
	v_and_b32_e32 v5, 24, v5
	v_and_b32_e32 v7, 4, v7
	s_addc_u32 s11, s37, s7
	s_waitcnt vmcnt(0) lgkmcnt(0)
	s_barrier
	s_add_i32 s23, s8, 0
	v_or3_b32 v5, v6, v7, v5
	v_add_lshl_u32 v1, v2, v1, 1
	s_add_i32 s38, s23, 0x10000
	s_mov_b32 m0, s38
	s_nop 0
	global_load_lds_dwordx4 v163, s[10:11]
	s_add_i32 s39, s23, 0x12000
	v_lshl_add_u32 v171, v5, 12, v1
	s_mov_b32 m0, s39
	s_nop 0
	global_load_lds_dwordx4 v171, s[10:11]
	s_add_u32 s24, s94, s4
	s_addc_u32 s25, s95, s5
	s_mov_b32 m0, s23
	s_nop 0
	global_load_lds_dwordx4 v162, s[24:25]
	v_lshl_add_u32 v170, v3, 12, v1
	s_add_i32 s40, s23, 0x2000
	s_mov_b32 m0, s40
	s_nop 0
	global_load_lds_dwordx4 v170, s[24:25]
	s_add_u32 s4, s10, 0x80000
	s_addc_u32 s5, s11, 0
	s_add_i32 s41, s23, 0x14000
	s_mov_b32 m0, s41
	s_nop 0
	global_load_lds_dwordx4 v163, s[4:5]
	s_add_i32 s42, s23, 0x16000
	s_mov_b32 m0, s42
	s_nop 0
	global_load_lds_dwordx4 v171, s[4:5]
	s_add_u32 s4, s24, 0x80000
	s_addc_u32 s5, s25, 0
	s_add_i32 s43, s23, 0x4000
	s_mov_b32 m0, s43
	s_nop 0
	global_load_lds_dwordx4 v162, s[4:5]
	s_add_i32 s44, s23, 0x6000
	s_mov_b32 m0, s44
	s_nop 0
	global_load_lds_dwordx4 v170, s[4:5]
	s_movk_i32 s4, 0xff
	v_cmp_lt_i32_e64 s[6:7], s4, v140
	s_movk_i32 s4, 0x100
	v_cmp_gt_i32_e32 vcc, s4, v140
	s_and_saveexec_b64 s[4:5], vcc
	s_cbranch_execz .LBB0_264
	v_lshl_add_u32 v2, s22, 8, v140
	v_ashrrev_i32_e32 v3, 31, v2
	v_readlane_b32 s8, v255, 2
	v_lshlrev_b64 v[2:3], 7, v[2:3]
	v_readlane_b32 s9, v255, 3
	s_nop 1
	v_lshl_add_u64 v[2:3], s[8:9], 0, v[2:3]
	global_load_dwordx4 v[6:9], v[2:3], off offset:48
	global_load_dwordx4 v[10:13], v[2:3], off offset:32
	global_load_dwordx4 v[14:17], v[2:3], off
	global_load_dwordx4 v[18:21], v[2:3], off offset:16
	s_waitcnt vmcnt(0)
	v_pk_add_f32 v[16:17], v[16:17], v[20:21]
	v_pk_add_f32 v[14:15], v[14:15], v[18:19]
	v_pk_add_f32 v[12:13], v[16:17], v[12:13]
	v_pk_add_f32 v[10:11], v[14:15], v[10:11]
	v_pk_add_f32 v[22:23], v[12:13], v[8:9]
	v_pk_add_f32 v[24:25], v[10:11], v[6:7]
	global_load_dwordx4 v[6:9], v[2:3], off offset:112
	global_load_dwordx4 v[10:13], v[2:3], off offset:96
	global_load_dwordx4 v[14:17], v[2:3], off offset:80
	global_load_dwordx4 v[18:21], v[2:3], off offset:64
	s_waitcnt vmcnt(0)
	v_pk_add_f32 v[2:3], v[22:23], v[20:21]
	v_pk_add_f32 v[18:19], v[24:25], v[18:19]
	v_pk_add_f32 v[2:3], v[2:3], v[16:17]
	v_pk_add_f32 v[14:15], v[18:19], v[14:15]
	v_pk_add_f32 v[2:3], v[2:3], v[12:13]
	v_pk_add_f32 v[10:11], v[14:15], v[10:11]
	v_pk_add_f32 v[2:3], v[2:3], v[8:9]
	v_pk_add_f32 v[6:7], v[10:11], v[6:7]
	s_nop 0
	v_pk_mov_b32 v[8:9], v[6:7], v[2:3] op_sel:[1,0]
	v_mov_b32_e32 v7, v3
	v_pk_add_f32 v[2:3], v[8:9], v[6:7]
	s_nop 0
	v_add_f32_e32 v1, v2, v3
	v_fmamk_f32 v1, v1, 0x3a000000, v164
	v_cmp_gt_f32_e32 vcc, s69, v1
	v_mul_f32_e32 v2, 0x4f800000, v1
	s_nop 0
	v_cndmask_b32_e32 v1, v1, v2, vcc
	v_sqrt_f32_e32 v2, v1
	s_nop 0
	v_add_u32_e32 v3, -1, v2
	v_fma_f32 v5, -v3, v2, v1
	v_cmp_ge_f32_e64 s[8:9], 0, v5
	v_add_u32_e32 v5, 1, v2
	s_nop 0
	v_cndmask_b32_e64 v3, v2, v3, s[8:9]
	v_fma_f32 v2, -v5, v2, v1
	v_cmp_lt_f32_e64 s[8:9], 0, v2
	s_nop 1
	v_cndmask_b32_e64 v2, v3, v5, s[8:9]
	v_mul_f32_e32 v3, 0x37800000, v2
	v_cndmask_b32_e32 v2, v2, v3, vcc
	v_cmp_class_f32_e32 vcc, v1, v165
	s_nop 1
	v_cndmask_b32_e32 v1, v2, v1, vcc
	v_div_scale_f32 v2, s[8:9], v1, v1, 1.0
	v_rcp_f32_e32 v3, v2
	s_nop 0
	v_fma_f32 v5, -v2, v3, 1.0
	v_fmac_f32_e32 v3, v5, v3
	v_div_scale_f32 v5, vcc, 1.0, v1, 1.0
	v_mul_f32_e32 v6, v5, v3
	v_fma_f32 v7, -v2, v6, v5
	v_fmac_f32_e32 v6, v7, v3
	v_fma_f32 v2, -v2, v6, v5
	v_div_fmas_f32 v2, v2, v3, v6
	v_div_fixup_f32 v1, v2, v1, 1.0
	v_lshl_add_u32 v2, v140, 2, 0
	v_add_u32_e32 v2, 0x20000, v2
	ds_write_b32 v2, v1

; template <class Epi, class Sched>
; __device__ __forceinline__ void gemm_simple(PG8_LAS unsigned char* lds, const Gemm g, const Sched& S, const Epi& E, int wave_s) {
;     ...
; #pragma unroll
;         for (int a = 0; a < 2; ++a)
; #pragma unroll
;             for (int b = 0; b < 2; ++b)
; #pragma unroll
;                 for (int m = 0; m < 4; ++m)
; #pragma unroll
;                     for (int n = 0; n < 2; ++n) acc[a][b][m][n] = (f32x4){zero_o, zero_o, zero_o, zero_o};
.LBB0_272:
	s_waitcnt lgkmcnt(0)
	v_mov_b64_e32 v[6:7], v[2:3]
	v_mov_b64_e32 v[10:11], v[2:3]
	v_mov_b64_e32 v[22:23], v[2:3]
	v_mov_b64_e32 v[26:27], v[2:3]
	v_mov_b64_e32 v[38:39], v[2:3]
	v_mov_b64_e32 v[42:43], v[2:3]
	v_mov_b64_e32 v[54:55], v[2:3]
	v_mov_b64_e32 v[58:59], v[2:3]
	v_mov_b64_e32 v[14:15], v[2:3]
	v_mov_b64_e32 v[18:19], v[2:3]
	v_mov_b64_e32 v[30:31], v[2:3]
	v_mov_b64_e32 v[34:35], v[2:3]
	v_mov_b64_e32 v[46:47], v[2:3]
	v_mov_b64_e32 v[50:51], v[2:3]
	v_mov_b64_e32 v[62:63], v[2:3]
	v_mov_b64_e32 v[66:67], v[2:3]
	v_mov_b64_e32 v[70:71], v[2:3]
	v_mov_b64_e32 v[74:75], v[2:3]
	v_mov_b64_e32 v[86:87], v[2:3]
	v_mov_b64_e32 v[90:91], v[2:3]
	v_mov_b64_e32 v[102:103], v[2:3]
	v_mov_b64_e32 v[106:107], v[2:3]
	v_mov_b64_e32 v[118:119], v[2:3]
	v_mov_b64_e32 v[122:123], v[2:3]
	v_mov_b64_e32 v[78:79], v[2:3]
	v_mov_b64_e32 v[82:83], v[2:3]
	v_mov_b64_e32 v[94:95], v[2:3]
	v_mov_b64_e32 v[98:99], v[2:3]
	v_mov_b64_e32 v[110:111], v[2:3]
	v_mov_b64_e32 v[114:115], v[2:3]
	v_mov_b64_e32 v[126:127], v[2:3]
	v_mov_b64_e32 v[130:131], v[2:3]
	s_mov_b32 s26, 0
	s_cmp_eq_u32 s21, 0
	v_add_u32_e32 v132, 0x10000, v173
	v_add_u32_e32 v133, 0x14000, v173
	v_add_u32_e32 v134, 0x18000, v173
	v_add_u32_e32 v135, 0x1c000, v173
	v_mov_b64_e32 v[4:5], v[0:1]
	v_mov_b64_e32 v[8:9], v[0:1]
	v_mov_b64_e32 v[20:21], v[0:1]
	v_mov_b64_e32 v[24:25], v[0:1]
	v_mov_b64_e32 v[36:37], v[0:1]
	v_mov_b64_e32 v[40:41], v[0:1]
	v_mov_b64_e32 v[52:53], v[0:1]
	v_mov_b64_e32 v[56:57], v[0:1]
	v_mov_b64_e32 v[12:13], v[0:1]
	v_mov_b64_e32 v[16:17], v[0:1]
	v_mov_b64_e32 v[28:29], v[0:1]
	v_mov_b64_e32 v[32:33], v[0:1]
	v_mov_b64_e32 v[44:45], v[0:1]
	v_mov_b64_e32 v[48:49], v[0:1]
	v_mov_b64_e32 v[60:61], v[0:1]
	v_mov_b64_e32 v[64:65], v[0:1]
	v_mov_b64_e32 v[68:69], v[0:1]
	v_mov_b64_e32 v[72:73], v[0:1]
	v_mov_b64_e32 v[84:85], v[0:1]
	v_mov_b64_e32 v[88:89], v[0:1]
	v_mov_b64_e32 v[100:101], v[0:1]
	v_mov_b64_e32 v[104:105], v[0:1]
	v_mov_b64_e32 v[116:117], v[0:1]
	v_mov_b64_e32 v[120:121], v[0:1]
	v_mov_b64_e32 v[76:77], v[0:1]
	v_mov_b64_e32 v[80:81], v[0:1]
	v_mov_b64_e32 v[92:93], v[0:1]
	v_mov_b64_e32 v[96:97], v[0:1]
	v_mov_b64_e32 v[108:109], v[0:1]
	v_mov_b64_e32 v[112:113], v[0:1]
	v_mov_b64_e32 v[124:125], v[0:1]
	v_mov_b64_e32 v[128:129], v[0:1]
	s_cbranch_scc1 .LBB0_274
	s_waitcnt vmcnt(18) lgkmcnt(0)
	s_barrier
	ds_read_b128 v[4:7], v132
	ds_read_b128 v[8:11], v132 offset:1024
	ds_read_b128 v[12:15], v132 offset:2048
	ds_read_b128 v[16:19], v132 offset:3072
	ds_read_b128 v[20:23], v174
	ds_read_b128 v[24:27], v174 offset:1024
	ds_read_b128 v[28:31], v174 offset:2048
	ds_read_b128 v[32:35], v174 offset:3072
	ds_read_b128 v[36:39], v174 offset:4096
	ds_read_b128 v[40:43], v174 offset:5120
	ds_read_b128 v[44:47], v174 offset:6144
	ds_read_b128 v[48:51], v174 offset:7168
	ds_read_b128 v[52:55], v133
	ds_read_b128 v[56:59], v133 offset:1024
	ds_read_b128 v[60:63], v133 offset:2048
	ds_read_b128 v[64:67], v133 offset:3072
	s_add_u32 s16, s10, 0x80
	s_addc_u32 s17, s11, 0
	s_mov_b32 m0, s49
	s_nop 0
	global_load_lds_dwordx4 v163, s[16:17]
	s_mov_b32 m0, s53
	s_nop 0
	global_load_lds_dwordx4 v171, s[16:17]
	s_waitcnt lgkmcnt(5)
	v_mfma_f32_16x16x32_bf16 v[92:95], v[4:7], v[44:47], v[0:3]
	v_mfma_f32_16x16x32_bf16 v[68:71], v[4:7], v[20:23], v[0:3]
	v_mfma_f32_16x16x32_bf16 v[72:75], v[12:15], v[20:23], v[0:3]
	v_mfma_f32_16x16x32_bf16 v[76:79], v[4:7], v[28:31], v[0:3]
	v_mfma_f32_16x16x32_bf16 v[80:83], v[12:15], v[28:31], v[0:3]
	v_mfma_f32_16x16x32_bf16 v[84:87], v[4:7], v[36:39], v[0:3]
	v_mfma_f32_16x16x32_bf16 v[88:91], v[12:15], v[36:39], v[0:3]
	s_waitcnt lgkmcnt(4)
	v_mfma_f32_16x16x32_bf16 v[100:103], v[8:11], v[48:51], v[92:95]
	v_mfma_f32_16x16x32_bf16 v[92:95], v[12:15], v[44:47], v[0:3]
	v_mfma_f32_16x16x32_bf16 v[68:71], v[8:11], v[24:27], v[68:71]
	v_mfma_f32_16x16x32_bf16 v[72:75], v[16:19], v[24:27], v[72:75]
	v_mfma_f32_16x16x32_bf16 v[76:79], v[8:11], v[32:35], v[76:79]
	v_mfma_f32_16x16x32_bf16 v[80:83], v[16:19], v[32:35], v[80:83]
	v_mfma_f32_16x16x32_bf16 v[84:87], v[8:11], v[40:43], v[84:87]
	v_mfma_f32_16x16x32_bf16 v[88:91], v[16:19], v[40:43], v[88:91]
	v_mfma_f32_16x16x32_bf16 v[104:107], v[16:19], v[48:51], v[92:95]
	s_add_u32 s16, s24, 0x80
	s_addc_u32 s17, s25, 0
	s_mov_b32 m0, s50
	s_nop 0
	global_load_lds_dwordx4 v162, s[16:17]
	s_mov_b32 m0, s54
	s_nop 0
	global_load_lds_dwordx4 v170, s[16:17]
	s_waitcnt lgkmcnt(3)
	v_mfma_f32_16x16x32_bf16 v[92:95], v[52:55], v[20:23], v[0:3]
	s_waitcnt lgkmcnt(1)
	v_mfma_f32_16x16x32_bf16 v[20:23], v[60:63], v[20:23], v[0:3]
	v_mfma_f32_16x16x32_bf16 v[116:119], v[56:59], v[24:27], v[92:95]
	s_waitcnt lgkmcnt(0)
	v_mfma_f32_16x16x32_bf16 v[20:23], v[64:67], v[24:27], v[20:23]
	v_mfma_f32_16x16x32_bf16 v[24:27], v[52:55], v[28:31], v[0:3]
	v_mfma_f32_16x16x32_bf16 v[28:31], v[60:63], v[28:31], v[0:3]
	v_mfma_f32_16x16x32_bf16 v[24:27], v[56:59], v[32:35], v[24:27]
	v_mfma_f32_16x16x32_bf16 v[28:31], v[64:67], v[32:35], v[28:31]
	v_mfma_f32_16x16x32_bf16 v[32:35], v[52:55], v[36:39], v[0:3]
	v_mfma_f32_16x16x32_bf16 v[36:39], v[60:63], v[36:39], v[0:3]
	v_mfma_f32_16x16x32_bf16 v[32:35], v[56:59], v[40:43], v[32:35]
	v_mfma_f32_16x16x32_bf16 v[36:39], v[64:67], v[40:43], v[36:39]
	v_mfma_f32_16x16x32_bf16 v[40:43], v[52:55], v[44:47], v[0:3]
	v_mfma_f32_16x16x32_bf16 v[44:47], v[60:63], v[44:47], v[0:3]
	v_mfma_f32_16x16x32_bf16 v[40:43], v[56:59], v[48:51], v[40:43]
	v_mfma_f32_16x16x32_bf16 v[44:47], v[64:67], v[48:51], v[44:47]
	s_waitcnt vmcnt(20) lgkmcnt(0)
	s_barrier
	ds_read_b128 v[48:51], v174 offset:16384
	ds_read_b128 v[92:95], v174 offset:17408
	ds_read_b128 v[96:99], v174 offset:18432
	ds_read_b128 v[108:111], v174 offset:19456
	ds_read_b128 v[112:115], v174 offset:20480
	ds_read_b128 v[120:123], v174 offset:21504
	ds_read_b128 v[124:127], v174 offset:22528
	ds_read_b128 v[128:131], v174 offset:23552
	s_add_u32 s16, s10, 0x80080
	s_addc_u32 s17, s11, 0
	s_mov_b32 m0, s51
	s_nop 0
	global_load_lds_dwordx4 v163, s[16:17]
	s_mov_b32 m0, s55
	s_nop 0
	global_load_lds_dwordx4 v171, s[16:17]
	s_waitcnt lgkmcnt(7)
	v_mfma_f32_16x16x32_bf16 v[136:139], v[4:7], v[48:51], v[0:3]
	s_waitcnt lgkmcnt(5)
	v_mfma_f32_16x16x32_bf16 v[146:149], v[4:7], v[96:99], v[0:3]
	s_waitcnt lgkmcnt(3)
	v_mfma_f32_16x16x32_bf16 v[156:159], v[4:7], v[112:115], v[0:3]
	s_waitcnt lgkmcnt(1)
	v_mfma_f32_16x16x32_bf16 v[4:7], v[4:7], v[124:127], v[0:3]
	v_mfma_f32_16x16x32_bf16 v[136:139], v[8:11], v[92:95], v[136:139]
	v_mfma_f32_16x16x32_bf16 v[146:149], v[8:11], v[108:111], v[146:149]
	v_mfma_f32_16x16x32_bf16 v[156:159], v[8:11], v[120:123], v[156:159]
	s_waitcnt lgkmcnt(0)
	v_mfma_f32_16x16x32_bf16 v[4:7], v[8:11], v[128:131], v[4:7]
	v_mfma_f32_16x16x32_bf16 v[8:11], v[12:15], v[124:127], v[0:3]
	v_mfma_f32_16x16x32_bf16 v[142:145], v[12:15], v[48:51], v[0:3]
	v_mfma_f32_16x16x32_bf16 v[152:155], v[12:15], v[96:99], v[0:3]
	v_mfma_f32_16x16x32_bf16 v[176:179], v[12:15], v[112:115], v[0:3]
	v_mfma_f32_16x16x32_bf16 v[8:11], v[16:19], v[128:131], v[8:11]
	v_mfma_f32_16x16x32_bf16 v[142:145], v[16:19], v[92:95], v[142:145]
	v_mfma_f32_16x16x32_bf16 v[152:155], v[16:19], v[108:111], v[152:155]
	v_mfma_f32_16x16x32_bf16 v[176:179], v[16:19], v[120:123], v[176:179]
	s_add_u32 s16, s24, 0x80080
	s_addc_u32 s17, s25, 0
	s_mov_b32 m0, s52
	s_nop 0
	global_load_lds_dwordx4 v162, s[16:17]
	s_mov_b32 m0, s56
	s_nop 0
	global_load_lds_dwordx4 v170, s[16:17]
	v_mfma_f32_16x16x32_bf16 v[12:15], v[52:55], v[48:51], v[0:3]
	v_mfma_f32_16x16x32_bf16 v[180:183], v[56:59], v[92:95], v[12:15]
	v_mfma_f32_16x16x32_bf16 v[12:15], v[60:63], v[48:51], v[0:3]
	v_mfma_f32_16x16x32_bf16 v[184:187], v[64:67], v[92:95], v[12:15]
	v_mfma_f32_16x16x32_bf16 v[12:15], v[52:55], v[96:99], v[0:3]
	v_mfma_f32_16x16x32_bf16 v[188:191], v[56:59], v[108:111], v[12:15]
	v_mfma_f32_16x16x32_bf16 v[12:15], v[60:63], v[96:99], v[0:3]
	v_mfma_f32_16x16x32_bf16 v[192:195], v[64:67], v[108:111], v[12:15]
	v_mfma_f32_16x16x32_bf16 v[12:15], v[52:55], v[112:115], v[0:3]
	v_mfma_f32_16x16x32_bf16 v[196:199], v[56:59], v[120:123], v[12:15]
	v_mfma_f32_16x16x32_bf16 v[12:15], v[60:63], v[112:115], v[0:3]
	v_mfma_f32_16x16x32_bf16 v[200:203], v[64:67], v[120:123], v[12:15]
	v_mfma_f32_16x16x32_bf16 v[12:15], v[52:55], v[124:127], v[0:3]
	v_mfma_f32_16x16x32_bf16 v[204:207], v[56:59], v[128:131], v[12:15]
	v_mfma_f32_16x16x32_bf16 v[12:15], v[60:63], v[124:127], v[0:3]
	v_mfma_f32_16x16x32_bf16 v[208:211], v[64:67], v[128:131], v[12:15]
	s_waitcnt vmcnt(2) lgkmcnt(0)
	s_barrier
	s_nop 5
	ds_read_b128 v[12:15], v134
	ds_read_b128 v[16:19], v134 offset:1024
	ds_read_b128 v[52:55], v134 offset:2048
	ds_read_b128 v[56:59], v134 offset:3072
	ds_read_b128 v[48:51], v174 offset:32768
	ds_read_b128 v[60:63], v174 offset:33792
	ds_read_b128 v[64:67], v174 offset:34816
	ds_read_b128 v[212:215], v174 offset:35840
	ds_read_b128 v[216:219], v174 offset:36864
	ds_read_b128 v[220:223], v174 offset:37888
	ds_read_b128 v[224:227], v174 offset:38912
	ds_read_b128 v[228:231], v174 offset:39936
	ds_read_b128 v[232:235], v135
	ds_read_b128 v[236:239], v135 offset:1024
	ds_read_b128 v[240:243], v135 offset:2048
	ds_read_b128 v[244:247], v135 offset:3072
	s_add_u32 s16, s10, 0x100
	s_addc_u32 s17, s11, 0
	s_mov_b32 m0, s38
	s_nop 0
	global_load_lds_dwordx4 v163, s[16:17]
	s_mov_b32 m0, s39
	s_nop 0
	global_load_lds_dwordx4 v171, s[16:17]
	s_waitcnt lgkmcnt(11)
	v_mfma_f32_16x16x32_bf16 v[68:71], v[12:15], v[48:51], v[68:71]
	s_waitcnt lgkmcnt(10)
	v_mfma_f32_16x16x32_bf16 v[128:131], v[16:19], v[60:63], v[68:71]
	v_mfma_f32_16x16x32_bf16 v[68:71], v[52:55], v[48:51], v[72:75]
	v_mfma_f32_16x16x32_bf16 v[124:127], v[56:59], v[60:63], v[68:71]
	s_waitcnt lgkmcnt(9)
	v_mfma_f32_16x16x32_bf16 v[68:71], v[12:15], v[64:67], v[76:79]
	s_waitcnt lgkmcnt(8)
	v_mfma_f32_16x16x32_bf16 v[112:115], v[16:19], v[212:215], v[68:71]
	v_mfma_f32_16x16x32_bf16 v[68:71], v[52:55], v[64:67], v[80:83]
	v_mfma_f32_16x16x32_bf16 v[108:111], v[56:59], v[212:215], v[68:71]
	s_waitcnt lgkmcnt(7)
	v_mfma_f32_16x16x32_bf16 v[68:71], v[12:15], v[216:219], v[84:87]
	s_waitcnt lgkmcnt(6)
	v_mfma_f32_16x16x32_bf16 v[96:99], v[16:19], v[220:223], v[68:71]
	v_mfma_f32_16x16x32_bf16 v[68:71], v[52:55], v[216:219], v[88:91]
	v_mfma_f32_16x16x32_bf16 v[92:95], v[56:59], v[220:223], v[68:71]
	s_waitcnt lgkmcnt(5)
	v_mfma_f32_16x16x32_bf16 v[68:71], v[12:15], v[224:227], v[100:103]
	s_waitcnt lgkmcnt(4)
	v_mfma_f32_16x16x32_bf16 v[80:83], v[16:19], v[228:231], v[68:71]
	v_mfma_f32_16x16x32_bf16 v[68:71], v[52:55], v[224:227], v[104:107]
	v_mfma_f32_16x16x32_bf16 v[76:79], v[56:59], v[228:231], v[68:71]
	s_add_u32 s16, s24, 0x100
	s_addc_u32 s17, s25, 0
	s_mov_b32 m0, s23
	s_nop 0
	global_load_lds_dwordx4 v162, s[16:17]
	s_mov_b32 m0, s40
	s_nop 0
	global_load_lds_dwordx4 v170, s[16:17]
	s_waitcnt lgkmcnt(1)
	v_mfma_f32_16x16x32_bf16 v[20:23], v[240:243], v[48:51], v[20:23]
	v_mfma_f32_16x16x32_bf16 v[68:71], v[232:235], v[48:51], v[116:119]
	s_waitcnt lgkmcnt(0)
	v_mfma_f32_16x16x32_bf16 v[116:119], v[244:247], v[60:63], v[20:23]
	v_mfma_f32_16x16x32_bf16 v[20:23], v[232:235], v[64:67], v[24:27]
	v_mfma_f32_16x16x32_bf16 v[104:107], v[236:239], v[212:215], v[20:23]
	v_mfma_f32_16x16x32_bf16 v[20:23], v[240:243], v[64:67], v[28:31]
	v_mfma_f32_16x16x32_bf16 v[100:103], v[244:247], v[212:215], v[20:23]
	v_mfma_f32_16x16x32_bf16 v[20:23], v[232:235], v[216:219], v[32:35]
	v_mfma_f32_16x16x32_bf16 v[88:91], v[236:239], v[220:223], v[20:23]
	v_mfma_f32_16x16x32_bf16 v[20:23], v[240:243], v[216:219], v[36:39]
	v_mfma_f32_16x16x32_bf16 v[84:87], v[244:247], v[220:223], v[20:23]
	v_mfma_f32_16x16x32_bf16 v[20:23], v[232:235], v[224:227], v[40:43]
	v_mfma_f32_16x16x32_bf16 v[72:75], v[236:239], v[228:231], v[20:23]
	v_mfma_f32_16x16x32_bf16 v[20:23], v[240:243], v[224:227], v[44:47]
	v_mfma_f32_16x16x32_bf16 v[120:123], v[236:239], v[60:63], v[68:71]
	v_mfma_f32_16x16x32_bf16 v[68:71], v[244:247], v[228:231], v[20:23]
	s_waitcnt vmcnt(4) lgkmcnt(0)
	s_barrier
	s_nop 4
	ds_read_b128 v[20:23], v174 offset:49152
	ds_read_b128 v[24:27], v174 offset:50176
	ds_read_b128 v[36:39], v174 offset:51200
	ds_read_b128 v[212:215], v174 offset:52224
	ds_read_b128 v[216:219], v174 offset:53248
	ds_read_b128 v[220:223], v174 offset:54272
	ds_read_b128 v[224:227], v174 offset:55296
	ds_read_b128 v[228:231], v174 offset:56320
	s_add_u32 s16, s10, 0x80100
	s_addc_u32 s17, s11, 0
	s_mov_b32 m0, s41
	s_nop 0
	global_load_lds_dwordx4 v163, s[16:17]
	s_mov_b32 m0, s42
	s_nop 0
	global_load_lds_dwordx4 v171, s[16:17]
	s_waitcnt lgkmcnt(7)
	v_mfma_f32_16x16x32_bf16 v[28:31], v[12:15], v[20:23], v[136:139]
	s_waitcnt lgkmcnt(6)
	v_mfma_f32_16x16x32_bf16 v[64:67], v[16:19], v[24:27], v[28:31]
	v_mfma_f32_16x16x32_bf16 v[28:31], v[52:55], v[20:23], v[142:145]
	v_mfma_f32_16x16x32_bf16 v[60:63], v[56:59], v[24:27], v[28:31]
	s_waitcnt lgkmcnt(5)
	v_mfma_f32_16x16x32_bf16 v[28:31], v[12:15], v[36:39], v[146:149]
	s_waitcnt lgkmcnt(4)
	v_mfma_f32_16x16x32_bf16 v[48:51], v[16:19], v[212:215], v[28:31]
	v_mfma_f32_16x16x32_bf16 v[28:31], v[52:55], v[36:39], v[152:155]
	v_mfma_f32_16x16x32_bf16 v[44:47], v[56:59], v[212:215], v[28:31]
	s_waitcnt lgkmcnt(3)
	v_mfma_f32_16x16x32_bf16 v[28:31], v[12:15], v[216:219], v[156:159]
	s_waitcnt lgkmcnt(1)
	v_mfma_f32_16x16x32_bf16 v[4:7], v[12:15], v[224:227], v[4:7]
	v_mfma_f32_16x16x32_bf16 v[32:35], v[16:19], v[220:223], v[28:31]
	v_mfma_f32_16x16x32_bf16 v[28:31], v[52:55], v[216:219], v[176:179]
	s_waitcnt lgkmcnt(0)
	v_mfma_f32_16x16x32_bf16 v[16:19], v[16:19], v[228:231], v[4:7]
	v_mfma_f32_16x16x32_bf16 v[4:7], v[52:55], v[224:227], v[8:11]
	v_mfma_f32_16x16x32_bf16 v[28:31], v[56:59], v[220:223], v[28:31]
	v_mfma_f32_16x16x32_bf16 v[12:15], v[56:59], v[228:231], v[4:7]
	s_add_u32 s16, s24, 0x80100
	s_addc_u32 s17, s25, 0
	s_mov_b32 m0, s43
	s_nop 0
	global_load_lds_dwordx4 v162, s[16:17]
	s_mov_b32 m0, s44
	s_nop 0
	global_load_lds_dwordx4 v170, s[16:17]
	v_mfma_f32_16x16x32_bf16 v[4:7], v[232:235], v[20:23], v[180:183]
	s_mov_b32 s26, 2
	v_mfma_f32_16x16x32_bf16 v[56:59], v[236:239], v[24:27], v[4:7]
	v_mfma_f32_16x16x32_bf16 v[4:7], v[240:243], v[20:23], v[184:187]
	v_mfma_f32_16x16x32_bf16 v[52:55], v[244:247], v[24:27], v[4:7]
	v_mfma_f32_16x16x32_bf16 v[4:7], v[232:235], v[36:39], v[188:191]
	v_mfma_f32_16x16x32_bf16 v[40:43], v[236:239], v[212:215], v[4:7]
	v_mfma_f32_16x16x32_bf16 v[4:7], v[240:243], v[36:39], v[192:195]
	v_mfma_f32_16x16x32_bf16 v[36:39], v[244:247], v[212:215], v[4:7]
	v_mfma_f32_16x16x32_bf16 v[4:7], v[232:235], v[216:219], v[196:199]
	v_mfma_f32_16x16x32_bf16 v[24:27], v[236:239], v[220:223], v[4:7]
	v_mfma_f32_16x16x32_bf16 v[4:7], v[240:243], v[216:219], v[200:203]
	v_mfma_f32_16x16x32_bf16 v[20:23], v[244:247], v[220:223], v[4:7]
	v_mfma_f32_16x16x32_bf16 v[4:7], v[232:235], v[224:227], v[204:207]
	v_mfma_f32_16x16x32_bf16 v[8:11], v[236:239], v[228:231], v[4:7]
	v_mfma_f32_16x16x32_bf16 v[4:7], v[240:243], v[224:227], v[208:211]
	v_mfma_f32_16x16x32_bf16 v[4:7], v[244:247], v[228:231], v[4:7]

.LBB0_275:
	s_waitcnt vmcnt(2) lgkmcnt(0)
	s_barrier
	ds_read_b128 v[136:139], v132
	ds_read_b128 v[156:159], v174
	ds_read_b128 v[146:149], v132 offset:2048
	ds_read_b128 v[180:183], v174 offset:2048
	ds_read_b128 v[188:191], v174 offset:4096
	ds_read_b128 v[196:199], v174 offset:6144
	ds_read_b128 v[142:145], v132 offset:1024
	ds_read_b128 v[176:179], v174 offset:1024
	ds_read_b128 v[152:155], v132 offset:3072
	ds_read_b128 v[184:187], v174 offset:3072
	ds_read_b128 v[192:195], v174 offset:5120
	ds_read_b128 v[200:203], v174 offset:7168
	ds_read_b128 v[204:207], v133
	ds_read_b128 v[212:215], v133 offset:2048
	ds_read_b128 v[208:211], v133 offset:1024
	ds_read_b128 v[216:219], v133 offset:3072
	s_add_u32 s63, s10, s62
	s_addc_u32 s64, s11, 0
	s_add_u32 s28, s63, 0x80
	s_addc_u32 s29, s64, 0
	s_mov_b32 m0, s49
	s_nop 0
	global_load_lds_dwordx4 v163, s[28:29]
	s_mov_b32 m0, s53
	s_nop 0
	global_load_lds_dwordx4 v171, s[28:29]
	s_waitcnt lgkmcnt(14)
	v_mfma_f32_16x16x32_bf16 v[128:131], v[136:139], v[156:159], v[128:131]
	s_waitcnt lgkmcnt(13)
	v_mfma_f32_16x16x32_bf16 v[124:127], v[146:149], v[156:159], v[124:127]
	s_waitcnt lgkmcnt(12)
	v_mfma_f32_16x16x32_bf16 v[112:115], v[136:139], v[180:183], v[112:115]
	v_mfma_f32_16x16x32_bf16 v[108:111], v[146:149], v[180:183], v[108:111]
	s_waitcnt lgkmcnt(11)
	v_mfma_f32_16x16x32_bf16 v[96:99], v[136:139], v[188:191], v[96:99]
	v_mfma_f32_16x16x32_bf16 v[92:95], v[146:149], v[188:191], v[92:95]
	s_waitcnt lgkmcnt(10)
	v_mfma_f32_16x16x32_bf16 v[80:83], v[136:139], v[196:199], v[80:83]
	v_mfma_f32_16x16x32_bf16 v[76:79], v[146:149], v[196:199], v[76:79]
	s_waitcnt lgkmcnt(8)
	v_mfma_f32_16x16x32_bf16 v[128:131], v[142:145], v[176:179], v[128:131]
	s_waitcnt lgkmcnt(7)
	v_mfma_f32_16x16x32_bf16 v[124:127], v[152:155], v[176:179], v[124:127]
	s_waitcnt lgkmcnt(6)
	v_mfma_f32_16x16x32_bf16 v[112:115], v[142:145], v[184:187], v[112:115]
	v_mfma_f32_16x16x32_bf16 v[108:111], v[152:155], v[184:187], v[108:111]
	s_waitcnt lgkmcnt(5)
	v_mfma_f32_16x16x32_bf16 v[96:99], v[142:145], v[192:195], v[96:99]
	v_mfma_f32_16x16x32_bf16 v[92:95], v[152:155], v[192:195], v[92:95]
	s_waitcnt lgkmcnt(4)
	v_mfma_f32_16x16x32_bf16 v[80:83], v[142:145], v[200:203], v[80:83]
	v_mfma_f32_16x16x32_bf16 v[76:79], v[152:155], v[200:203], v[76:79]
	s_add_u32 s65, s24, s62
	s_addc_u32 s66, s25, 0
	s_add_u32 s28, s65, 0x80
	s_addc_u32 s29, s66, 0
	s_mov_b32 m0, s50
	s_nop 0
	global_load_lds_dwordx4 v162, s[28:29]
	s_mov_b32 m0, s54
	s_nop 0
	global_load_lds_dwordx4 v170, s[28:29]
	s_waitcnt lgkmcnt(3)
	v_mfma_f32_16x16x32_bf16 v[120:123], v[204:207], v[156:159], v[120:123]
	s_waitcnt lgkmcnt(2)
	v_mfma_f32_16x16x32_bf16 v[116:119], v[212:215], v[156:159], v[116:119]
	v_mfma_f32_16x16x32_bf16 v[104:107], v[204:207], v[180:183], v[104:107]
	v_mfma_f32_16x16x32_bf16 v[100:103], v[212:215], v[180:183], v[100:103]
	v_mfma_f32_16x16x32_bf16 v[88:91], v[204:207], v[188:191], v[88:91]
	v_mfma_f32_16x16x32_bf16 v[84:87], v[212:215], v[188:191], v[84:87]
	v_mfma_f32_16x16x32_bf16 v[72:75], v[204:207], v[196:199], v[72:75]
	v_mfma_f32_16x16x32_bf16 v[68:71], v[212:215], v[196:199], v[68:71]
	s_waitcnt lgkmcnt(1)
	v_mfma_f32_16x16x32_bf16 v[120:123], v[208:211], v[176:179], v[120:123]
	s_waitcnt lgkmcnt(0)
	v_mfma_f32_16x16x32_bf16 v[116:119], v[216:219], v[176:179], v[116:119]
	v_mfma_f32_16x16x32_bf16 v[104:107], v[208:211], v[184:187], v[104:107]
	v_mfma_f32_16x16x32_bf16 v[100:103], v[216:219], v[184:187], v[100:103]
	v_mfma_f32_16x16x32_bf16 v[88:91], v[208:211], v[192:195], v[88:91]
	v_mfma_f32_16x16x32_bf16 v[84:87], v[216:219], v[192:195], v[84:87]
	v_mfma_f32_16x16x32_bf16 v[72:75], v[208:211], v[200:203], v[72:75]
	v_mfma_f32_16x16x32_bf16 v[68:71], v[216:219], v[200:203], v[68:71]
	s_waitcnt vmcnt(4) lgkmcnt(0)
	s_barrier
	ds_read_b128 v[156:159], v174 offset:16384
	ds_read_b128 v[180:183], v174 offset:18432
	ds_read_b128 v[188:191], v174 offset:20480
	ds_read_b128 v[196:199], v174 offset:22528
	ds_read_b128 v[176:179], v174 offset:17408
	ds_read_b128 v[184:187], v174 offset:19456
	ds_read_b128 v[192:195], v174 offset:21504
	ds_read_b128 v[200:203], v174 offset:23552
	s_add_u32 s28, s63, 0x80080
	s_addc_u32 s29, s64, 0
	s_mov_b32 m0, s51
	s_nop 0
	global_load_lds_dwordx4 v163, s[28:29]
	s_mov_b32 m0, s55
	s_nop 0
	global_load_lds_dwordx4 v171, s[28:29]
	s_waitcnt lgkmcnt(7)
	v_mfma_f32_16x16x32_bf16 v[64:67], v[136:139], v[156:159], v[64:67]
	v_mfma_f32_16x16x32_bf16 v[60:63], v[146:149], v[156:159], v[60:63]
	s_waitcnt lgkmcnt(6)
	v_mfma_f32_16x16x32_bf16 v[48:51], v[136:139], v[180:183], v[48:51]
	v_mfma_f32_16x16x32_bf16 v[44:47], v[146:149], v[180:183], v[44:47]
	s_waitcnt lgkmcnt(5)
	v_mfma_f32_16x16x32_bf16 v[32:35], v[136:139], v[188:191], v[32:35]
	v_mfma_f32_16x16x32_bf16 v[28:31], v[146:149], v[188:191], v[28:31]
	s_waitcnt lgkmcnt(4)
	v_mfma_f32_16x16x32_bf16 v[16:19], v[136:139], v[196:199], v[16:19]
	v_mfma_f32_16x16x32_bf16 v[12:15], v[146:149], v[196:199], v[12:15]
	s_waitcnt lgkmcnt(3)
	v_mfma_f32_16x16x32_bf16 v[64:67], v[142:145], v[176:179], v[64:67]
	v_mfma_f32_16x16x32_bf16 v[60:63], v[152:155], v[176:179], v[60:63]
	s_waitcnt lgkmcnt(2)
	v_mfma_f32_16x16x32_bf16 v[48:51], v[142:145], v[184:187], v[48:51]
	v_mfma_f32_16x16x32_bf16 v[44:47], v[152:155], v[184:187], v[44:47]
	s_waitcnt lgkmcnt(1)
	v_mfma_f32_16x16x32_bf16 v[32:35], v[142:145], v[192:195], v[32:35]
	v_mfma_f32_16x16x32_bf16 v[28:31], v[152:155], v[192:195], v[28:31]
	s_waitcnt lgkmcnt(0)
	v_mfma_f32_16x16x32_bf16 v[16:19], v[142:145], v[200:203], v[16:19]
	v_mfma_f32_16x16x32_bf16 v[12:15], v[152:155], v[200:203], v[12:15]
	s_add_u32 s28, s65, 0x80080
	s_addc_u32 s29, s66, 0
	s_mov_b32 m0, s52
	s_nop 0
	global_load_lds_dwordx4 v162, s[28:29]
	s_mov_b32 m0, s56
	s_nop 0
	global_load_lds_dwordx4 v170, s[28:29]
	v_mfma_f32_16x16x32_bf16 v[56:59], v[204:207], v[156:159], v[56:59]
	s_add_u32 s28, s65, 0x100
	s_addc_u32 s29, s66, 0
	s_add_u32 s63, s63, 0x100
	v_mfma_f32_16x16x32_bf16 v[52:55], v[212:215], v[156:159], v[52:55]
	s_addc_u32 s64, s64, 0
	v_mfma_f32_16x16x32_bf16 v[40:43], v[204:207], v[180:183], v[40:43]
	v_mfma_f32_16x16x32_bf16 v[36:39], v[212:215], v[180:183], v[36:39]
	v_mfma_f32_16x16x32_bf16 v[24:27], v[204:207], v[188:191], v[24:27]
	v_mfma_f32_16x16x32_bf16 v[20:23], v[212:215], v[188:191], v[20:23]
	v_mfma_f32_16x16x32_bf16 v[8:11], v[204:207], v[196:199], v[8:11]
	v_mfma_f32_16x16x32_bf16 v[4:7], v[212:215], v[196:199], v[4:7]
	v_mfma_f32_16x16x32_bf16 v[56:59], v[208:211], v[176:179], v[56:59]
	v_mfma_f32_16x16x32_bf16 v[52:55], v[216:219], v[176:179], v[52:55]
	v_mfma_f32_16x16x32_bf16 v[40:43], v[208:211], v[184:187], v[40:43]
	v_mfma_f32_16x16x32_bf16 v[36:39], v[216:219], v[184:187], v[36:39]
	v_mfma_f32_16x16x32_bf16 v[24:27], v[208:211], v[192:195], v[24:27]
	v_mfma_f32_16x16x32_bf16 v[20:23], v[216:219], v[192:195], v[20:23]
	v_mfma_f32_16x16x32_bf16 v[8:11], v[208:211], v[200:203], v[8:11]
	v_mfma_f32_16x16x32_bf16 v[4:7], v[216:219], v[200:203], v[4:7]
	s_waitcnt vmcnt(2) lgkmcnt(0)
	s_barrier
; template <class Epi, class Sched>
; __device__ __forceinline__ void gemm_simple(PG8_LAS unsigned char* lds, const Gemm g, const Sched& S, const Epi& E, int wave_s) {
;     ...
;             const char* a2 = last ? nA : cA + (size_t)(t + 2) * kstep; const char* b2 = last ? nB : cB + (size_t)(t + 2) * kstep;
;             PG8_TILE(1, a2, b2, (!last || has_next));
	ds_read_b128 v[136:139], v134
	ds_read_b128 v[156:159], v174 offset:32768
	ds_read_b128 v[146:149], v134 offset:2048
	ds_read_b128 v[180:183], v174 offset:34816
	ds_read_b128 v[188:191], v174 offset:36864
	ds_read_b128 v[196:199], v174 offset:38912
	ds_read_b128 v[142:145], v134 offset:1024
	ds_read_b128 v[176:179], v174 offset:33792
	ds_read_b128 v[152:155], v134 offset:3072
	ds_read_b128 v[184:187], v174 offset:35840
	ds_read_b128 v[192:195], v174 offset:37888
	ds_read_b128 v[200:203], v174 offset:39936
	ds_read_b128 v[204:207], v135
	ds_read_b128 v[212:215], v135 offset:2048
	ds_read_b128 v[208:211], v135 offset:1024
	ds_read_b128 v[216:219], v135 offset:3072
	s_cmp_eq_u32 s62, s26
	s_cselect_b32 s29, s15, s29
	s_cselect_b32 s28, s35, s28
	s_cselect_b32 s65, s13, s64
	s_cselect_b32 s64, s60, s63
	s_mov_b32 m0, s38
	s_nop 0
	global_load_lds_dwordx4 v163, s[64:65]
	s_mov_b32 m0, s39
	s_nop 0
	global_load_lds_dwordx4 v171, s[64:65]
	s_waitcnt lgkmcnt(14)
	v_mfma_f32_16x16x32_bf16 v[128:131], v[136:139], v[156:159], v[128:131]
	s_waitcnt lgkmcnt(13)
	v_mfma_f32_16x16x32_bf16 v[124:127], v[146:149], v[156:159], v[124:127]
	s_waitcnt lgkmcnt(12)
	v_mfma_f32_16x16x32_bf16 v[112:115], v[136:139], v[180:183], v[112:115]
	v_mfma_f32_16x16x32_bf16 v[108:111], v[146:149], v[180:183], v[108:111]
	s_waitcnt lgkmcnt(11)
	v_mfma_f32_16x16x32_bf16 v[96:99], v[136:139], v[188:191], v[96:99]
	v_mfma_f32_16x16x32_bf16 v[92:95], v[146:149], v[188:191], v[92:95]
	s_waitcnt lgkmcnt(10)
	v_mfma_f32_16x16x32_bf16 v[80:83], v[136:139], v[196:199], v[80:83]
	v_mfma_f32_16x16x32_bf16 v[76:79], v[146:149], v[196:199], v[76:79]
	s_waitcnt lgkmcnt(8)
	v_mfma_f32_16x16x32_bf16 v[128:131], v[142:145], v[176:179], v[128:131]
	s_waitcnt lgkmcnt(7)
	v_mfma_f32_16x16x32_bf16 v[124:127], v[152:155], v[176:179], v[124:127]
	s_waitcnt lgkmcnt(6)
	v_mfma_f32_16x16x32_bf16 v[112:115], v[142:145], v[184:187], v[112:115]
	v_mfma_f32_16x16x32_bf16 v[108:111], v[152:155], v[184:187], v[108:111]
	s_waitcnt lgkmcnt(5)
	v_mfma_f32_16x16x32_bf16 v[96:99], v[142:145], v[192:195], v[96:99]
	v_mfma_f32_16x16x32_bf16 v[92:95], v[152:155], v[192:195], v[92:95]
	s_waitcnt lgkmcnt(4)
	v_mfma_f32_16x16x32_bf16 v[80:83], v[142:145], v[200:203], v[80:83]
	v_mfma_f32_16x16x32_bf16 v[76:79], v[152:155], v[200:203], v[76:79]
	s_mov_b32 m0, s23
	s_nop 0
	global_load_lds_dwordx4 v162, s[28:29]
	s_mov_b32 m0, s40
	s_nop 0
	global_load_lds_dwordx4 v170, s[28:29]
	s_waitcnt lgkmcnt(3)
	v_mfma_f32_16x16x32_bf16 v[120:123], v[204:207], v[156:159], v[120:123]
	s_waitcnt lgkmcnt(2)
	v_mfma_f32_16x16x32_bf16 v[116:119], v[212:215], v[156:159], v[116:119]
	v_mfma_f32_16x16x32_bf16 v[104:107], v[204:207], v[180:183], v[104:107]
	v_mfma_f32_16x16x32_bf16 v[100:103], v[212:215], v[180:183], v[100:103]
	v_mfma_f32_16x16x32_bf16 v[88:91], v[204:207], v[188:191], v[88:91]
	v_mfma_f32_16x16x32_bf16 v[84:87], v[212:215], v[188:191], v[84:87]
	v_mfma_f32_16x16x32_bf16 v[72:75], v[204:207], v[196:199], v[72:75]
	v_mfma_f32_16x16x32_bf16 v[68:71], v[212:215], v[196:199], v[68:71]
	s_waitcnt lgkmcnt(1)
	v_mfma_f32_16x16x32_bf16 v[120:123], v[208:211], v[176:179], v[120:123]
	s_waitcnt lgkmcnt(0)
	v_mfma_f32_16x16x32_bf16 v[116:119], v[216:219], v[176:179], v[116:119]
	v_mfma_f32_16x16x32_bf16 v[104:107], v[208:211], v[184:187], v[104:107]
	v_mfma_f32_16x16x32_bf16 v[100:103], v[216:219], v[184:187], v[100:103]
	v_mfma_f32_16x16x32_bf16 v[88:91], v[208:211], v[192:195], v[88:91]
	v_mfma_f32_16x16x32_bf16 v[84:87], v[216:219], v[192:195], v[84:87]
	v_mfma_f32_16x16x32_bf16 v[72:75], v[208:211], v[200:203], v[72:75]
	v_mfma_f32_16x16x32_bf16 v[68:71], v[216:219], v[200:203], v[68:71]
	s_waitcnt vmcnt(4) lgkmcnt(0)
	s_barrier
; #define LAS __attribute__((address_space(3)))
; __device__ __forceinline__ void rstd_table(const float* ssq, LAS unsigned char* lds, const Unit& u, int tid, int par) {
;     if (tid < 256) { const f32x4* p = (const f32x4*)(ssq + (size_t)(u.pm * 256 + tid) * 32); f32x4 a = p[0];
; #pragma unroll
;         for (int i = 1; i < 8; ++i) a += p[i];
;         ((LAS float*)(lds + 131072 + par * 1024))[tid] = 1.0f / sqrtf(((a[0] + a[1]) + (a[2] + a[3])) * (1.0f / DM) + 1e-6f); }
	ds_read_b128 v[156:159], v174 offset:49152
	ds_read_b128 v[180:183], v174 offset:51200
	ds_read_b128 v[188:191], v174 offset:53248
	ds_read_b128 v[196:199], v174 offset:55296
	ds_read_b128 v[176:179], v174 offset:50176
	ds_read_b128 v[184:187], v174 offset:52224
	ds_read_b128 v[192:195], v174 offset:54272
	ds_read_b128 v[200:203], v174 offset:56320
	s_add_u32 s64, s64, 0x80000
	s_addc_u32 s65, s65, 0
	s_mov_b32 m0, s41
	s_nop 0
	global_load_lds_dwordx4 v163, s[64:65]
	s_mov_b32 m0, s42
	s_nop 0
	global_load_lds_dwordx4 v171, s[64:65]
	s_waitcnt lgkmcnt(7)
	v_mfma_f32_16x16x32_bf16 v[64:67], v[136:139], v[156:159], v[64:67]
	v_mfma_f32_16x16x32_bf16 v[60:63], v[146:149], v[156:159], v[60:63]
	s_waitcnt lgkmcnt(6)
	v_mfma_f32_16x16x32_bf16 v[48:51], v[136:139], v[180:183], v[48:51]
	v_mfma_f32_16x16x32_bf16 v[44:47], v[146:149], v[180:183], v[44:47]
	s_waitcnt lgkmcnt(5)
	v_mfma_f32_16x16x32_bf16 v[32:35], v[136:139], v[188:191], v[32:35]
	v_mfma_f32_16x16x32_bf16 v[28:31], v[146:149], v[188:191], v[28:31]
	s_waitcnt lgkmcnt(4)
	v_mfma_f32_16x16x32_bf16 v[16:19], v[136:139], v[196:199], v[16:19]
	v_mfma_f32_16x16x32_bf16 v[12:15], v[146:149], v[196:199], v[12:15]
	s_waitcnt lgkmcnt(3)
	v_mfma_f32_16x16x32_bf16 v[64:67], v[142:145], v[176:179], v[64:67]
	v_mfma_f32_16x16x32_bf16 v[60:63], v[152:155], v[176:179], v[60:63]
	s_waitcnt lgkmcnt(2)
	v_mfma_f32_16x16x32_bf16 v[48:51], v[142:145], v[184:187], v[48:51]
	v_mfma_f32_16x16x32_bf16 v[44:47], v[152:155], v[184:187], v[44:47]
	s_waitcnt lgkmcnt(1)
	v_mfma_f32_16x16x32_bf16 v[32:35], v[142:145], v[192:195], v[32:35]
	v_mfma_f32_16x16x32_bf16 v[28:31], v[152:155], v[192:195], v[28:31]
	s_waitcnt lgkmcnt(0)
	v_mfma_f32_16x16x32_bf16 v[16:19], v[142:145], v[200:203], v[16:19]
	v_mfma_f32_16x16x32_bf16 v[12:15], v[152:155], v[200:203], v[12:15]
	s_add_u32 s28, s28, 0x80000
	s_addc_u32 s29, s29, 0
	s_mov_b32 m0, s43
	s_nop 0
	global_load_lds_dwordx4 v162, s[28:29]
	s_mov_b32 m0, s44
	s_nop 0
	global_load_lds_dwordx4 v170, s[28:29]
	v_mfma_f32_16x16x32_bf16 v[56:59], v[204:207], v[156:159], v[56:59]
	s_add_i32 s61, s61, 2
	s_add_u32 s26, s26, 0xffffff00
	s_addc_u32 s27, s27, -1
	v_mfma_f32_16x16x32_bf16 v[52:55], v[212:215], v[156:159], v[52:55]
	s_add_u32 s24, s24, 0x100
	s_addc_u32 s25, s25, 0
	s_add_u32 s10, s10, 0x100
	v_mfma_f32_16x16x32_bf16 v[40:43], v[204:207], v[180:183], v[40:43]
	s_addc_u32 s11, s11, 0
	s_cmp_lt_u32 s61, 30
	v_mfma_f32_16x16x32_bf16 v[36:39], v[212:215], v[180:183], v[36:39]
	v_mfma_f32_16x16x32_bf16 v[24:27], v[204:207], v[188:191], v[24:27]
	v_mfma_f32_16x16x32_bf16 v[20:23], v[212:215], v[188:191], v[20:23]
	v_mfma_f32_16x16x32_bf16 v[8:11], v[204:207], v[196:199], v[8:11]
	v_mfma_f32_16x16x32_bf16 v[4:7], v[212:215], v[196:199], v[4:7]
	v_mfma_f32_16x16x32_bf16 v[56:59], v[208:211], v[176:179], v[56:59]
	v_mfma_f32_16x16x32_bf16 v[52:55], v[216:219], v[176:179], v[52:55]
	v_mfma_f32_16x16x32_bf16 v[40:43], v[208:211], v[184:187], v[40:43]
	v_mfma_f32_16x16x32_bf16 v[36:39], v[216:219], v[184:187], v[36:39]
	v_mfma_f32_16x16x32_bf16 v[24:27], v[208:211], v[192:195], v[24:27]
	v_mfma_f32_16x16x32_bf16 v[20:23], v[216:219], v[192:195], v[20:23]
	v_mfma_f32_16x16x32_bf16 v[8:11], v[208:211], v[200:203], v[8:11]
	v_mfma_f32_16x16x32_bf16 v[4:7], v[216:219], v[200:203], v[4:7]
	s_cbranch_scc1 .LBB0_275
	s_nor_b64 s[10:11], s[6:7], s[8:9]
	s_and_saveexec_b64 s[24:25], s[10:11]
	s_cbranch_execz .LBB0_278
	v_lshl_add_u32 v132, s14, 8, v140
	v_ashrrev_i32_e32 v133, 31, v132
	v_readlane_b32 s10, v255, 2
	v_lshlrev_b64 v[132:133], 7, v[132:133]
	v_readlane_b32 s11, v255, 3
	s_nop 1
	v_lshl_add_u64 v[152:153], s[10:11], 0, v[132:133]
	global_load_dwordx4 v[132:135], v[152:153], off offset:48
	global_load_dwordx4 v[136:139], v[152:153], off offset:32
	global_load_dwordx4 v[142:145], v[152:153], off
	global_load_dwordx4 v[146:149], v[152:153], off offset:16
	s_waitcnt vmcnt(0)
	v_pk_add_f32 v[144:145], v[144:145], v[148:149]
	v_pk_add_f32 v[142:143], v[142:143], v[146:147]
	v_pk_add_f32 v[138:139], v[144:145], v[138:139]
	v_pk_add_f32 v[136:137], v[142:143], v[136:137]
	v_pk_add_f32 v[154:155], v[138:139], v[134:135]
	v_pk_add_f32 v[156:157], v[136:137], v[132:133]
	global_load_dwordx4 v[132:135], v[152:153], off offset:112
	global_load_dwordx4 v[136:139], v[152:153], off offset:96
	global_load_dwordx4 v[142:145], v[152:153], off offset:80
	global_load_dwordx4 v[146:149], v[152:153], off offset:64
	s_waitcnt vmcnt(0)
	v_pk_add_f32 v[148:149], v[154:155], v[148:149]
	v_pk_add_f32 v[146:147], v[156:157], v[146:147]
	v_pk_add_f32 v[144:145], v[148:149], v[144:145]
	v_pk_add_f32 v[142:143], v[146:147], v[142:143]
	v_pk_add_f32 v[138:139], v[144:145], v[138:139]
	v_pk_add_f32 v[136:137], v[142:143], v[136:137]
	v_pk_add_f32 v[134:135], v[138:139], v[134:135]
	v_pk_add_f32 v[132:133], v[136:137], v[132:133]
	s_nop 0
	v_pk_mov_b32 v[136:137], v[132:133], v[134:135] op_sel:[1,0]
	v_mov_b32_e32 v133, v135
	v_pk_add_f32 v[132:133], v[136:137], v[132:133]
	s_nop 0
	v_add_f32_e32 v132, v132, v133
	v_fmamk_f32 v132, v132, 0x3a000000, v164
	v_cmp_gt_f32_e32 vcc, s69, v132
	v_mul_f32_e32 v133, 0x4f800000, v132
	s_nop 0
	v_cndmask_b32_e32 v132, v132, v133, vcc
	v_sqrt_f32_e32 v133, v132
	s_nop 0
	v_add_u32_e32 v134, -1, v133
	v_fma_f32 v135, -v134, v133, v132
	v_cmp_ge_f32_e64 s[10:11], 0, v135
	v_add_u32_e32 v135, 1, v133
	s_nop 0
	v_cndmask_b32_e64 v134, v133, v134, s[10:11]
	v_fma_f32 v133, -v135, v133, v132
	v_cmp_lt_f32_e64 s[10:11], 0, v133
	s_nop 1
	v_cndmask_b32_e64 v133, v134, v135, s[10:11]
	v_mul_f32_e32 v134, 0x37800000, v133
	v_cndmask_b32_e32 v133, v133, v134, vcc
	v_cmp_class_f32_e32 vcc, v132, v165
	s_nop 1
	v_cndmask_b32_e32 v132, v133, v132, vcc
	v_div_scale_f32 v133, s[10:11], v132, v132, 1.0
	v_rcp_f32_e32 v134, v133
	s_lshl_b32 s10, s59, 10
	s_and_b32 s10, s10, 0x400
	v_fma_f32 v135, -v133, v134, 1.0
	v_fmac_f32_e32 v134, v135, v134
	v_div_scale_f32 v135, vcc, 1.0, v132, 1.0
	v_mul_f32_e32 v136, v135, v134
	v_fma_f32 v137, -v133, v136, v135
	v_fmac_f32_e32 v136, v137, v134
	v_fma_f32 v133, -v133, v136, v135
	v_div_fmas_f32 v133, v133, v134, v136
	v_div_fixup_f32 v132, v133, v132, 1.0
	v_add_u32_e32 v133, s10, v172
	ds_write_b32 v133, v132

; #define PG8_LAS __attribute__((address_space(3)))
; #define LAS __attribute__((address_space(3)))
;     __host__ __device__ bool next(int i, Unit& u) const {
;     ...
;         int wgid = (int)L; { const int q = nwg / NXCD, r = nwg % NXCD, xcd = wgid % NXCD, off = wgid / NXCD; wgid = (xcd < r ? xcd * (q + 1) : r * (q + 1) + (xcd - r) * q) + off; }
;         const int nig = WGM * nN, gid = wgid / nig, fm = gid * WGM, gsz = (nM - fm) < WGM ? (nM - fm) : WGM;
;         u.pm = fm + ((wgid % nig) % gsz); u.pn = (wgid % nig) / gsz; return true;
;     }
; __device__ __forceinline__ unsigned cvt_pk_bf16(float lo, float hi) { unsigned r; asm volatile("v_cvt_pk_bf16_f32 %0, %1, %2" : "=v"(r) : "v"(lo), "v"(hi)); return r; }
; template <class Epi, class Sched>
; __device__ __forceinline__ void gemm_simple(PG8_LAS unsigned char* lds, const Gemm g, const Sched& S, const Epi& E, int wave_s) {
;     unsigned zz_o = 0u; asm volatile("" : "+v"(zz_o)); const int tid_o = wave_s * 64 + (int)__builtin_amdgcn_mbcnt_hi(~0u, __builtin_amdgcn_mbcnt_lo(~0u, zz_o));
;     float zero_o = 0.f; asm volatile("" : "+v"(zero_o));
;     const int tid = tid_o, wid = __builtin_amdgcn_readfirstlane(tid >> 6), lane = tid & 63, wr = wid >> 2, wc = wid & 3, fr = lane & 15, fq = lane >> 4;
;     const int K = g.K, nt = K / BK;
;     unsigned voffA[2], voffB[2];
; #pragma unroll
;     for (int i = 0; i < 2; ++i) { int R, C; stage_rc(tid * 16 + i * 8192, R, C); const int Rb = Epi::PERM ? ((R & ~31) + perm32(R & 31)) : R;
;         voffA[i] = (unsigned)(R * K + C) * 2u; voffB[i] = (unsigned)(Rb * K + C) * 2u; }
;     const size_t kstep = (size_t)(BK * 2), hstep = (size_t)HALF * K * 2, tstep = 2 * hstep;
;     const unsigned ldsw = (unsigned)wid * 1024u; const unsigned lds_u = (unsigned)(__UINTPTR_TYPE__)lds;
;     const int aoff = lds_byte(wr * 64 + fr, fq * 8), boff = lds_byte(wc * 32 + fr, fq * 8);
; __device__ __forceinline__ void rstd_table(const float* ssq, LAS unsigned char* lds, const Unit& u, int tid, int par) {
;     if (tid < 256) { const f32x4* p = (const f32x4*)(ssq + (size_t)(u.pm * 256 + tid) * 32); f32x4 a = p[0];
; #pragma unroll
;         for (int i = 1; i < 8; ++i) a += p[i];
;         ((LAS float*)(lds + 131072 + par * 1024))[tid] = 1.0f / sqrtf(((a[0] + a[1]) + (a[2] + a[3])) * (1.0f / DM) + 1e-6f); }
.LBB0_296:
	v_readlane_b32 s66, v254, 12
	s_and_b64 vcc, exec, s[14:15]
	v_readlane_b32 s67, v254, 13
	v_readlane_b32 s65, v254, 59
	s_cbranch_vccz .LBB0_318
	v_mov_b32_e32 v0, v141
	s_cmpk_gt_i32 s31, 0xcff
	v_mbcnt_lo_u32_b32 v0, -1, v0
	v_mbcnt_hi_u32_b32 v4, -1, v0
	v_add_u32_e32 v170, s75, v4
	v_mov_b32_e32 v0, v141
	v_readfirstlane_b32 s1, v170
	s_cbranch_scc1 .LBB0_318
	v_bfe_i32 v3, v170, 27, 1
	v_lshlrev_b32_e32 v1, 4, v170
	v_lshrrev_b32_e32 v3, 22, v3
	v_add_u32_e32 v3, v1, v3
	v_and_b32_e32 v3, 0xfffffc00, v3
	v_sub_u32_e32 v3, v1, v3
	v_ashrrev_i32_e32 v2, 31, v170
	s_waitcnt lgkmcnt(0)
	v_lshrrev_b32_e32 v5, 4, v3
	v_lshrrev_b32_e32 v2, 26, v2
	v_bitop3_b32 v3, v5, v3, 32 bitop3:0x6c
	v_add_u32_e32 v2, v170, v2
	v_ashrrev_i32_e32 v6, 31, v3
	v_ashrrev_i32_e32 v2, 6, v2
	v_lshrrev_b32_e32 v6, 26, v6
	v_lshlrev_b32_e32 v5, 3, v2
	v_add_u32_e32 v6, v3, v6
	v_and_b32_e32 v5, -16, v5
	v_ashrrev_i32_e32 v7, 6, v6
	v_and_b32_e32 v6, 0xc0, v6
	v_add_u32_e32 v5, v7, v5
	v_sub_u32_e32 v3, v3, v6
	v_lshlrev_b32_e32 v2, 5, v2
	v_ashrrev_i16_sdwa v3, v166, sext(v3) dst_sel:DWORD dst_unused:UNUSED_PAD src0_sel:DWORD src1_sel:BYTE_0
	v_lshlrev_b32_e32 v6, 1, v5
	v_lshrrev_b32_e32 v8, 2, v5
	v_and_b32_e32 v7, 3, v7
	s_mov_b32 s0, 0xfffe0
	v_and_b32_e32 v2, 32, v2
	v_bfe_i32 v3, v3, 0, 16
	v_and_b32_e32 v6, 24, v6
	v_and_b32_e32 v8, 4, v8
	v_and_or_b32 v7, v5, s0, v7
	v_or3_b32 v6, v7, v8, v6
	v_add_lshl_u32 v2, v2, v3, 1
	v_add_u32_e32 v1, 0x2000, v1
	v_lshl_add_u32 v171, v5, 12, v2
	v_lshl_add_u32 v172, v6, 12, v2
	v_ashrrev_i32_e32 v2, 31, v1
	v_lshrrev_b32_e32 v2, 22, v2
	v_add_u32_e32 v2, v1, v2
	v_ashrrev_i32_e32 v2, 10, v2
	v_mul_i32_i24_e32 v3, 0x400, v2
	v_sub_u32_e32 v1, v1, v3
	v_lshrrev_b32_e32 v3, 4, v1
	v_bitop3_b32 v1, v3, v1, 32 bitop3:0x6c
	v_ashrrev_i32_e32 v5, 31, v1
	v_lshrrev_b32_e32 v5, 26, v5
	v_lshlrev_b32_e32 v3, 3, v2
	v_add_u32_e32 v5, v1, v5
	v_and_b32_e32 v3, -16, v3
	v_ashrrev_i32_e32 v6, 6, v5
	v_add_u32_e32 v3, v6, v3
	v_and_b32_e32 v6, 3, v6
	s_ashr_i32 s26, s31, 31
	v_and_or_b32 v6, v3, s0, v6
	s_lshr_b32 s0, s26, 29
	s_add_i32 s0, s31, s0
	s_ashr_i32 s12, s1, 6
	s_ashr_i32 s4, s0, 3
	s_and_b32 s0, s0, -8
	s_lshl_b32 s8, s12, 10
	s_sub_i32 s0, s31, s0
	s_cmp_lt_i32 s0, 0
	s_movk_i32 s5, 0x1a1
	s_cselect_b32 s5, s5, 0x1a0
	s_mul_i32 s0, s0, s5
	s_add_i32 s0, s0, s4
	s_mul_hi_i32 s4, s0, 0x4ec4ec4f
	s_lshr_b32 s5, s4, 31
	s_ashr_i32 s4, s4, 5
	s_add_i32 s4, s4, s5
	s_lshl_b32 s5, s4, 2
	s_mulk_i32 s4, 0x68
	s_sub_i32 s4, s0, s4
	s_bfe_i32 s0, s4, 0x80000
	s_bfe_u32 s0, s0, 0x2000d
	s_add_i32 s6, s4, s0
	s_bfe_i32 s0, s6, 0x80000
	s_and_b32 s6, s6, 0xfc
	s_sub_i32 s4, s4, s6
	s_sext_i32_i16 s0, s0
	s_sext_i32_i8 s4, s4
	s_lshr_b32 s0, s0, 2
	s_add_i32 s18, s5, s4
	v_and_b32_e32 v5, 0xc0, v5
	s_ashr_i32 s19, s18, 31
	s_bfe_i64 s[6:7], s[0:1], 0x100000
	v_sub_u32_e32 v1, v1, v5
	s_lshl_b64 s[4:5], s[18:19], 20
	s_lshl_b64 s[6:7], s[6:7], 20
	v_readlane_b32 s68, v254, 57
	v_lshlrev_b32_e32 v2, 5, v2
	v_ashrrev_i16_sdwa v1, v166, sext(v1) dst_sel:DWORD dst_unused:UNUSED_PAD src0_sel:DWORD src1_sel:BYTE_0
	v_lshlrev_b32_e32 v5, 1, v3
	v_lshrrev_b32_e32 v7, 2, v3
	s_add_u32 s10, s68, s6
	v_readlane_b32 s70, v254, 58
	v_and_b32_e32 v2, 32, v2
	v_bfe_i32 v1, v1, 0, 16
	v_and_b32_e32 v5, 24, v5
	v_and_b32_e32 v7, 4, v7
	s_addc_u32 s11, s70, s7
	s_waitcnt vmcnt(0) lgkmcnt(0)
	s_barrier
	s_add_i32 s19, s8, 0
	v_or3_b32 v5, v6, v7, v5
	v_add_lshl_u32 v1, v2, v1, 1
	s_add_i32 s27, s19, 0x10000
	s_mov_b32 m0, s27
	s_nop 0
	global_load_lds_dwordx4 v172, s[10:11]
	s_add_i32 s28, s19, 0x12000
	v_lshl_add_u32 v174, v5, 12, v1
	s_mov_b32 m0, s28
	s_nop 0
	global_load_lds_dwordx4 v174, s[10:11]
	s_add_u32 s20, s94, s4
	s_addc_u32 s21, s95, s5
	s_mov_b32 m0, s19
	s_nop 0
	global_load_lds_dwordx4 v171, s[20:21]
	v_lshl_add_u32 v173, v3, 12, v1
	s_add_i32 s29, s19, 0x2000
	s_mov_b32 m0, s29
	s_nop 0
	global_load_lds_dwordx4 v173, s[20:21]
	s_add_u32 s4, s10, 0x80000
	s_addc_u32 s5, s11, 0
	s_add_i32 s36, s19, 0x14000
	s_mov_b32 m0, s36
	s_nop 0
	global_load_lds_dwordx4 v172, s[4:5]
	s_add_i32 s37, s19, 0x16000
	s_mov_b32 m0, s37
	s_nop 0
	global_load_lds_dwordx4 v174, s[4:5]
	s_add_u32 s4, s20, 0x80000
	s_addc_u32 s5, s21, 0
	s_add_i32 s38, s19, 0x4000
	s_mov_b32 m0, s38
	s_nop 0
	global_load_lds_dwordx4 v171, s[4:5]
	s_add_i32 s39, s19, 0x6000
	s_mov_b32 m0, s39
	s_nop 0
	global_load_lds_dwordx4 v173, s[4:5]
	s_movk_i32 s4, 0xff
	v_cmp_lt_i32_e64 s[6:7], s4, v170
	s_movk_i32 s4, 0x100
	v_cmp_gt_i32_e32 vcc, s4, v170
	s_and_saveexec_b64 s[4:5], vcc
	s_cbranch_execz .LBB0_300
	v_lshl_add_u32 v2, s18, 8, v170
	v_ashrrev_i32_e32 v3, 31, v2
	v_readlane_b32 s8, v255, 2
	v_lshlrev_b64 v[2:3], 7, v[2:3]
	v_readlane_b32 s9, v255, 3
	s_nop 1
	v_lshl_add_u64 v[2:3], s[8:9], 0, v[2:3]
	global_load_dwordx4 v[6:9], v[2:3], off
	global_load_dwordx4 v[10:13], v[2:3], off offset:16
	global_load_dwordx4 v[14:17], v[2:3], off offset:32
	global_load_dwordx4 v[18:21], v[2:3], off offset:48
	global_load_dwordx4 v[22:25], v[2:3], off offset:64
	global_load_dwordx4 v[26:29], v[2:3], off offset:80
	global_load_dwordx4 v[30:33], v[2:3], off offset:96
	global_load_dwordx4 v[34:37], v[2:3], off offset:112
	s_waitcnt vmcnt(6)
	v_pk_add_f32 v[2:3], v[8:9], v[12:13]
	v_pk_add_f32 v[6:7], v[6:7], v[10:11]
	s_waitcnt vmcnt(5)
	v_pk_add_f32 v[2:3], v[2:3], v[16:17]
	v_pk_add_f32 v[6:7], v[6:7], v[14:15]
	s_waitcnt vmcnt(4)
	v_pk_add_f32 v[2:3], v[2:3], v[20:21]
	v_pk_add_f32 v[6:7], v[6:7], v[18:19]
	s_waitcnt vmcnt(3)
	v_pk_add_f32 v[2:3], v[2:3], v[24:25]
	v_pk_add_f32 v[6:7], v[6:7], v[22:23]
	s_waitcnt vmcnt(2)
	v_pk_add_f32 v[2:3], v[2:3], v[28:29]
	v_pk_add_f32 v[6:7], v[6:7], v[26:27]
	s_waitcnt vmcnt(1)
	v_pk_add_f32 v[2:3], v[2:3], v[32:33]
	v_pk_add_f32 v[6:7], v[6:7], v[30:31]
	s_waitcnt vmcnt(0)
	v_pk_add_f32 v[2:3], v[2:3], v[36:37]
	v_pk_add_f32 v[6:7], v[6:7], v[34:35]
	s_nop 0
	v_pk_mov_b32 v[8:9], v[6:7], v[2:3] op_sel:[1,0]
	v_mov_b32_e32 v7, v3
	v_pk_add_f32 v[2:3], v[8:9], v[6:7]
	s_nop 0
	v_add_f32_e32 v1, v2, v3
	v_fmamk_f32 v1, v1, 0x3a000000, v164
	v_mul_f32_e32 v2, 0x4f800000, v1
	v_cmp_gt_f32_e32 vcc, s69, v1
	s_nop 1
	v_cndmask_b32_e32 v1, v1, v2, vcc
	v_sqrt_f32_e32 v2, v1
	s_nop 0
	v_add_u32_e32 v3, -1, v2
	v_add_u32_e32 v5, 1, v2
	v_fma_f32 v6, -v3, v2, v1
	v_fma_f32 v7, -v5, v2, v1
	v_cmp_ge_f32_e64 s[8:9], 0, v6
	s_nop 1
	v_cndmask_b32_e64 v2, v2, v3, s[8:9]
	v_cmp_lt_f32_e64 s[8:9], 0, v7
	s_nop 1
	v_cndmask_b32_e64 v2, v2, v5, s[8:9]
	v_mul_f32_e32 v3, 0x37800000, v2
	v_cndmask_b32_e32 v2, v2, v3, vcc
	v_cmp_class_f32_e32 vcc, v1, v165
	v_lshl_add_u32 v5, v170, 2, 0
	s_nop 0
	v_cndmask_b32_e32 v1, v2, v1, vcc
	v_div_scale_f32 v2, s[8:9], v1, v1, 1.0
	v_rcp_f32_e32 v3, v2
	v_div_scale_f32 v6, vcc, 1.0, v1, 1.0
	v_fma_f32 v7, -v2, v3, 1.0
	v_fmac_f32_e32 v3, v7, v3
	v_mul_f32_e32 v7, v6, v3
	v_fma_f32 v8, -v2, v7, v6
	v_fmac_f32_e32 v7, v8, v3
	v_fma_f32 v2, -v2, v7, v6
	v_div_fmas_f32 v2, v2, v3, v7
	v_div_fixup_f32 v1, v2, v1, 1.0
	v_add_u32_e32 v2, 0x20000, v5
	ds_write_b32 v2, v1

; template <class Epi, class Sched>
; __device__ __forceinline__ void gemm_simple(PG8_LAS unsigned char* lds, const Gemm g, const Sched& S, const Epi& E, int wave_s) {
;     ...
; #pragma unroll
;         for (int a = 0; a < 2; ++a)
; #pragma unroll
;             for (int b = 0; b < 2; ++b)
; #pragma unroll
;                 for (int m = 0; m < 4; ++m)
; #pragma unroll
;                     for (int n = 0; n < 2; ++n) acc[a][b][m][n] = (f32x4){zero_o, zero_o, zero_o, zero_o};
;         cur = nxt; cA = nA; cB = nB; ++ui;
.LBB0_304:
	v_mov_b64_e32 v[18:19], v[2:3]
	v_mov_b64_e32 v[14:15], v[2:3]
	v_mov_b64_e32 v[30:31], v[2:3]
	v_mov_b64_e32 v[34:35], v[2:3]
	v_mov_b64_e32 v[46:47], v[2:3]
	v_mov_b64_e32 v[50:51], v[2:3]
	v_mov_b64_e32 v[62:63], v[2:3]
	v_mov_b64_e32 v[66:67], v[2:3]
	v_mov_b64_e32 v[6:7], v[2:3]
	v_mov_b64_e32 v[10:11], v[2:3]
	v_mov_b64_e32 v[22:23], v[2:3]
	v_mov_b64_e32 v[26:27], v[2:3]
	v_mov_b64_e32 v[38:39], v[2:3]
	v_mov_b64_e32 v[42:43], v[2:3]
	v_mov_b64_e32 v[54:55], v[2:3]
	v_mov_b64_e32 v[58:59], v[2:3]
	v_mov_b64_e32 v[78:79], v[2:3]
	v_mov_b64_e32 v[82:83], v[2:3]
	v_mov_b64_e32 v[94:95], v[2:3]
	v_mov_b64_e32 v[98:99], v[2:3]
	v_mov_b64_e32 v[110:111], v[2:3]
	v_mov_b64_e32 v[114:115], v[2:3]
	v_mov_b64_e32 v[126:127], v[2:3]
	v_mov_b64_e32 v[130:131], v[2:3]
	v_mov_b64_e32 v[70:71], v[2:3]
	v_mov_b64_e32 v[74:75], v[2:3]
	v_mov_b64_e32 v[86:87], v[2:3]
	v_mov_b64_e32 v[90:91], v[2:3]
	v_mov_b64_e32 v[102:103], v[2:3]
	v_mov_b64_e32 v[106:107], v[2:3]
	v_mov_b64_e32 v[118:119], v[2:3]
	v_mov_b64_e32 v[122:123], v[2:3]
	s_mov_b32 s22, 0
	s_cmp_eq_u32 s55, 0
	v_add_u32_e32 v132, 0x10000, v176
	v_add_u32_e32 v133, 0x14000, v176
	v_add_u32_e32 v134, 0x18000, v176
	v_add_u32_e32 v135, 0x1c000, v176
	v_mov_b64_e32 v[16:17], v[0:1]
	v_mov_b64_e32 v[12:13], v[0:1]
	v_mov_b64_e32 v[28:29], v[0:1]
	v_mov_b64_e32 v[32:33], v[0:1]
	v_mov_b64_e32 v[44:45], v[0:1]
	v_mov_b64_e32 v[48:49], v[0:1]
	v_mov_b64_e32 v[60:61], v[0:1]
	v_mov_b64_e32 v[64:65], v[0:1]
	v_mov_b64_e32 v[4:5], v[0:1]
	v_mov_b64_e32 v[8:9], v[0:1]
	v_mov_b64_e32 v[20:21], v[0:1]
	v_mov_b64_e32 v[24:25], v[0:1]
	v_mov_b64_e32 v[36:37], v[0:1]
	v_mov_b64_e32 v[40:41], v[0:1]
	v_mov_b64_e32 v[52:53], v[0:1]
	v_mov_b64_e32 v[56:57], v[0:1]
	v_mov_b64_e32 v[76:77], v[0:1]
	v_mov_b64_e32 v[80:81], v[0:1]
	v_mov_b64_e32 v[92:93], v[0:1]
	v_mov_b64_e32 v[96:97], v[0:1]
	v_mov_b64_e32 v[108:109], v[0:1]
	v_mov_b64_e32 v[112:113], v[0:1]
	v_mov_b64_e32 v[124:125], v[0:1]
	v_mov_b64_e32 v[128:129], v[0:1]
	v_mov_b64_e32 v[68:69], v[0:1]
	v_mov_b64_e32 v[72:73], v[0:1]
	v_mov_b64_e32 v[84:85], v[0:1]
	v_mov_b64_e32 v[88:89], v[0:1]
	v_mov_b64_e32 v[100:101], v[0:1]
	v_mov_b64_e32 v[104:105], v[0:1]
	v_mov_b64_e32 v[116:117], v[0:1]
	v_mov_b64_e32 v[120:121], v[0:1]
	s_cbranch_scc1 .LBB0_306
	s_waitcnt vmcnt(18) lgkmcnt(0)
	s_barrier
	ds_read_b128 v[4:7], v132
	ds_read_b128 v[8:11], v132 offset:1024
	ds_read_b128 v[12:15], v132 offset:2048
	ds_read_b128 v[16:19], v132 offset:3072
	ds_read_b128 v[20:23], v177
	ds_read_b128 v[24:27], v177 offset:1024
	ds_read_b128 v[28:31], v177 offset:2048
	ds_read_b128 v[32:35], v177 offset:3072
	ds_read_b128 v[36:39], v177 offset:4096
	ds_read_b128 v[40:43], v177 offset:5120
	ds_read_b128 v[44:47], v177 offset:6144
	ds_read_b128 v[48:51], v177 offset:7168
	ds_read_b128 v[52:55], v133
	ds_read_b128 v[56:59], v133 offset:1024
	ds_read_b128 v[60:63], v133 offset:2048
	ds_read_b128 v[64:67], v133 offset:3072
	s_add_u32 s14, s10, 0x80
	s_addc_u32 s15, s11, 0
	s_mov_b32 m0, s43
	s_nop 0
	global_load_lds_dwordx4 v172, s[14:15]
	s_mov_b32 m0, s49
	s_nop 0
	global_load_lds_dwordx4 v174, s[14:15]
	s_waitcnt lgkmcnt(7)
	v_mfma_f32_16x16x32_bf16 v[88:91], v[12:15], v[36:39], v[0:3]
	s_waitcnt lgkmcnt(6)
	v_mfma_f32_16x16x32_bf16 v[92:95], v[16:19], v[40:43], v[88:91]
	s_waitcnt lgkmcnt(5)
	v_mfma_f32_16x16x32_bf16 v[88:91], v[4:7], v[44:47], v[0:3]
	v_mfma_f32_16x16x32_bf16 v[68:71], v[4:7], v[20:23], v[0:3]
	v_mfma_f32_16x16x32_bf16 v[72:75], v[12:15], v[20:23], v[0:3]
	v_mfma_f32_16x16x32_bf16 v[76:79], v[4:7], v[28:31], v[0:3]
	v_mfma_f32_16x16x32_bf16 v[80:83], v[12:15], v[28:31], v[0:3]
	v_mfma_f32_16x16x32_bf16 v[84:87], v[4:7], v[36:39], v[0:3]
	s_waitcnt lgkmcnt(4)
	v_mfma_f32_16x16x32_bf16 v[96:99], v[8:11], v[48:51], v[88:91]
	v_mfma_f32_16x16x32_bf16 v[88:91], v[12:15], v[44:47], v[0:3]
	v_mfma_f32_16x16x32_bf16 v[68:71], v[8:11], v[24:27], v[68:71]
	v_mfma_f32_16x16x32_bf16 v[72:75], v[16:19], v[24:27], v[72:75]
	v_mfma_f32_16x16x32_bf16 v[76:79], v[8:11], v[32:35], v[76:79]
	v_mfma_f32_16x16x32_bf16 v[80:83], v[16:19], v[32:35], v[80:83]
	v_mfma_f32_16x16x32_bf16 v[84:87], v[8:11], v[40:43], v[84:87]
	v_mfma_f32_16x16x32_bf16 v[108:111], v[16:19], v[48:51], v[88:91]
	s_add_u32 s14, s20, 0x80
	s_addc_u32 s15, s21, 0
	s_mov_b32 m0, s44
	s_nop 0
	global_load_lds_dwordx4 v171, s[14:15]
	s_mov_b32 m0, s50
	s_nop 0
	global_load_lds_dwordx4 v173, s[14:15]
	s_waitcnt lgkmcnt(3)
	v_mfma_f32_16x16x32_bf16 v[88:91], v[52:55], v[20:23], v[0:3]
	s_waitcnt lgkmcnt(1)
	v_mfma_f32_16x16x32_bf16 v[20:23], v[60:63], v[20:23], v[0:3]
	v_mfma_f32_16x16x32_bf16 v[112:115], v[56:59], v[24:27], v[88:91]
	s_waitcnt lgkmcnt(0)
	v_mfma_f32_16x16x32_bf16 v[20:23], v[64:67], v[24:27], v[20:23]
	v_mfma_f32_16x16x32_bf16 v[24:27], v[52:55], v[28:31], v[0:3]
	v_mfma_f32_16x16x32_bf16 v[28:31], v[60:63], v[28:31], v[0:3]
	v_mfma_f32_16x16x32_bf16 v[24:27], v[56:59], v[32:35], v[24:27]
	v_mfma_f32_16x16x32_bf16 v[28:31], v[64:67], v[32:35], v[28:31]
	v_mfma_f32_16x16x32_bf16 v[32:35], v[52:55], v[36:39], v[0:3]
	v_mfma_f32_16x16x32_bf16 v[36:39], v[60:63], v[36:39], v[0:3]
	v_mfma_f32_16x16x32_bf16 v[32:35], v[56:59], v[40:43], v[32:35]
	v_mfma_f32_16x16x32_bf16 v[36:39], v[64:67], v[40:43], v[36:39]
	v_mfma_f32_16x16x32_bf16 v[40:43], v[52:55], v[44:47], v[0:3]
	v_mfma_f32_16x16x32_bf16 v[44:47], v[60:63], v[44:47], v[0:3]
	v_mfma_f32_16x16x32_bf16 v[40:43], v[56:59], v[48:51], v[40:43]
	v_mfma_f32_16x16x32_bf16 v[44:47], v[64:67], v[48:51], v[44:47]
	s_waitcnt vmcnt(20) lgkmcnt(0)
	s_barrier
	ds_read_b128 v[48:51], v177 offset:16384
	ds_read_b128 v[88:91], v177 offset:17408
	ds_read_b128 v[100:103], v177 offset:18432
	ds_read_b128 v[104:107], v177 offset:19456
	ds_read_b128 v[116:119], v177 offset:20480
	ds_read_b128 v[120:123], v177 offset:21504
	ds_read_b128 v[124:127], v177 offset:22528
	ds_read_b128 v[128:131], v177 offset:23552
	s_add_u32 s14, s10, 0x80080
	s_addc_u32 s15, s11, 0
	s_mov_b32 m0, s45
	s_nop 0
	global_load_lds_dwordx4 v172, s[14:15]
	s_mov_b32 m0, s51
	s_nop 0
	global_load_lds_dwordx4 v174, s[14:15]
	s_waitcnt lgkmcnt(7)
	v_mfma_f32_16x16x32_bf16 v[136:139], v[4:7], v[48:51], v[0:3]
	s_waitcnt lgkmcnt(5)
	v_mfma_f32_16x16x32_bf16 v[156:159], v[4:7], v[100:103], v[0:3]
	s_waitcnt lgkmcnt(3)
	v_mfma_f32_16x16x32_bf16 v[178:181], v[4:7], v[116:119], v[0:3]
	s_waitcnt lgkmcnt(1)
	v_mfma_f32_16x16x32_bf16 v[4:7], v[4:7], v[124:127], v[0:3]
	v_mfma_f32_16x16x32_bf16 v[136:139], v[8:11], v[88:91], v[136:139]
	v_mfma_f32_16x16x32_bf16 v[156:159], v[8:11], v[104:107], v[156:159]
	v_mfma_f32_16x16x32_bf16 v[178:181], v[8:11], v[120:123], v[178:181]
	s_waitcnt lgkmcnt(0)
	v_mfma_f32_16x16x32_bf16 v[4:7], v[8:11], v[128:131], v[4:7]
	v_mfma_f32_16x16x32_bf16 v[8:11], v[12:15], v[124:127], v[0:3]
	v_mfma_f32_16x16x32_bf16 v[152:155], v[12:15], v[48:51], v[0:3]
	v_mfma_f32_16x16x32_bf16 v[160:163], v[12:15], v[100:103], v[0:3]
	v_mfma_f32_16x16x32_bf16 v[182:185], v[12:15], v[116:119], v[0:3]
	v_mfma_f32_16x16x32_bf16 v[12:15], v[16:19], v[128:131], v[8:11]
	v_mfma_f32_16x16x32_bf16 v[152:155], v[16:19], v[88:91], v[152:155]
	v_mfma_f32_16x16x32_bf16 v[160:163], v[16:19], v[104:107], v[160:163]
	v_mfma_f32_16x16x32_bf16 v[182:185], v[16:19], v[120:123], v[182:185]
	s_add_u32 s14, s20, 0x80080
	s_addc_u32 s15, s21, 0
	s_mov_b32 m0, s46
	s_nop 0
	global_load_lds_dwordx4 v171, s[14:15]
	s_mov_b32 m0, s52
	s_nop 0
	global_load_lds_dwordx4 v173, s[14:15]
	v_mfma_f32_16x16x32_bf16 v[8:11], v[52:55], v[48:51], v[0:3]
	v_mfma_f32_16x16x32_bf16 v[16:19], v[56:59], v[88:91], v[8:11]
	v_mfma_f32_16x16x32_bf16 v[8:11], v[60:63], v[48:51], v[0:3]
	v_mfma_f32_16x16x32_bf16 v[48:51], v[64:67], v[88:91], v[8:11]
	v_mfma_f32_16x16x32_bf16 v[8:11], v[52:55], v[100:103], v[0:3]
	v_mfma_f32_16x16x32_bf16 v[186:189], v[56:59], v[104:107], v[8:11]
	v_mfma_f32_16x16x32_bf16 v[8:11], v[60:63], v[100:103], v[0:3]
	v_mfma_f32_16x16x32_bf16 v[190:193], v[64:67], v[104:107], v[8:11]
	v_mfma_f32_16x16x32_bf16 v[8:11], v[52:55], v[116:119], v[0:3]
	v_mfma_f32_16x16x32_bf16 v[194:197], v[56:59], v[120:123], v[8:11]
	v_mfma_f32_16x16x32_bf16 v[8:11], v[60:63], v[116:119], v[0:3]
	v_mfma_f32_16x16x32_bf16 v[198:201], v[64:67], v[120:123], v[8:11]
	v_mfma_f32_16x16x32_bf16 v[8:11], v[52:55], v[124:127], v[0:3]
	v_mfma_f32_16x16x32_bf16 v[202:205], v[56:59], v[128:131], v[8:11]
	v_mfma_f32_16x16x32_bf16 v[8:11], v[60:63], v[124:127], v[0:3]
	v_mfma_f32_16x16x32_bf16 v[206:209], v[64:67], v[128:131], v[8:11]
	s_waitcnt vmcnt(2) lgkmcnt(0)
	s_barrier
	s_nop 5
	ds_read_b128 v[8:11], v134
	ds_read_b128 v[60:63], v134 offset:1024
	ds_read_b128 v[64:67], v134 offset:2048
	ds_read_b128 v[210:213], v134 offset:3072
	ds_read_b128 v[52:55], v177 offset:32768
	ds_read_b128 v[56:59], v177 offset:33792
	ds_read_b128 v[214:217], v177 offset:34816
	ds_read_b128 v[218:221], v177 offset:35840
	ds_read_b128 v[222:225], v177 offset:36864
	ds_read_b128 v[226:229], v177 offset:37888
	ds_read_b128 v[230:233], v177 offset:38912
	ds_read_b128 v[234:237], v177 offset:39936
	ds_read_b128 v[238:241], v135
	ds_read_b128 v[242:245], v135 offset:1024
	ds_read_b128 v[246:249], v135 offset:2048
	ds_read_b128 v[250:253], v135 offset:3072
	s_add_u32 s14, s10, 0x100
	s_addc_u32 s15, s11, 0
	s_mov_b32 m0, s27
	s_nop 0
	global_load_lds_dwordx4 v172, s[14:15]
	s_mov_b32 m0, s28
	s_nop 0
	global_load_lds_dwordx4 v174, s[14:15]
	s_waitcnt lgkmcnt(11)
	v_mfma_f32_16x16x32_bf16 v[68:71], v[8:11], v[52:55], v[68:71]
	s_waitcnt lgkmcnt(10)
	v_mfma_f32_16x16x32_bf16 v[120:123], v[60:63], v[56:59], v[68:71]
	v_mfma_f32_16x16x32_bf16 v[68:71], v[64:67], v[52:55], v[72:75]
	v_mfma_f32_16x16x32_bf16 v[116:119], v[210:213], v[56:59], v[68:71]
	s_waitcnt lgkmcnt(9)
	v_mfma_f32_16x16x32_bf16 v[68:71], v[8:11], v[214:217], v[76:79]
	s_waitcnt lgkmcnt(8)
	v_mfma_f32_16x16x32_bf16 v[104:107], v[60:63], v[218:221], v[68:71]
	v_mfma_f32_16x16x32_bf16 v[68:71], v[64:67], v[214:217], v[80:83]
	v_mfma_f32_16x16x32_bf16 v[100:103], v[210:213], v[218:221], v[68:71]
	s_waitcnt lgkmcnt(7)
	v_mfma_f32_16x16x32_bf16 v[68:71], v[8:11], v[222:225], v[84:87]
	s_waitcnt lgkmcnt(6)
	v_mfma_f32_16x16x32_bf16 v[88:91], v[60:63], v[226:229], v[68:71]
	v_mfma_f32_16x16x32_bf16 v[68:71], v[64:67], v[222:225], v[92:95]
	v_mfma_f32_16x16x32_bf16 v[84:87], v[210:213], v[226:229], v[68:71]
	s_waitcnt lgkmcnt(5)
	v_mfma_f32_16x16x32_bf16 v[68:71], v[8:11], v[230:233], v[96:99]
	s_waitcnt lgkmcnt(4)
	v_mfma_f32_16x16x32_bf16 v[72:75], v[60:63], v[234:237], v[68:71]
	v_mfma_f32_16x16x32_bf16 v[68:71], v[64:67], v[230:233], v[108:111]
	v_mfma_f32_16x16x32_bf16 v[68:71], v[210:213], v[234:237], v[68:71]
	s_add_u32 s14, s20, 0x100
	s_addc_u32 s15, s21, 0
	s_mov_b32 m0, s19
	s_nop 0
	global_load_lds_dwordx4 v171, s[14:15]
	s_mov_b32 m0, s29
	s_nop 0
	global_load_lds_dwordx4 v173, s[14:15]
	s_waitcnt lgkmcnt(1)
	v_mfma_f32_16x16x32_bf16 v[20:23], v[246:249], v[52:55], v[20:23]
	s_waitcnt lgkmcnt(0)
	v_mfma_f32_16x16x32_bf16 v[124:127], v[250:253], v[56:59], v[20:23]
	v_mfma_f32_16x16x32_bf16 v[20:23], v[238:241], v[214:217], v[24:27]
	v_mfma_f32_16x16x32_bf16 v[76:79], v[238:241], v[52:55], v[112:115]
	v_mfma_f32_16x16x32_bf16 v[112:115], v[242:245], v[218:221], v[20:23]
	v_mfma_f32_16x16x32_bf16 v[20:23], v[246:249], v[214:217], v[28:31]
	v_mfma_f32_16x16x32_bf16 v[108:111], v[250:253], v[218:221], v[20:23]
	v_mfma_f32_16x16x32_bf16 v[20:23], v[238:241], v[222:225], v[32:35]
	v_mfma_f32_16x16x32_bf16 v[96:99], v[242:245], v[226:229], v[20:23]
	v_mfma_f32_16x16x32_bf16 v[20:23], v[246:249], v[222:225], v[36:39]
	v_mfma_f32_16x16x32_bf16 v[92:95], v[250:253], v[226:229], v[20:23]
	v_mfma_f32_16x16x32_bf16 v[20:23], v[238:241], v[230:233], v[40:43]
	v_mfma_f32_16x16x32_bf16 v[80:83], v[242:245], v[234:237], v[20:23]
	v_mfma_f32_16x16x32_bf16 v[20:23], v[246:249], v[230:233], v[44:47]
	v_mfma_f32_16x16x32_bf16 v[128:131], v[242:245], v[56:59], v[76:79]
	v_mfma_f32_16x16x32_bf16 v[76:79], v[250:253], v[234:237], v[20:23]
	s_waitcnt vmcnt(4) lgkmcnt(0)
	s_barrier
; template <class Epi, class Sched>
; __device__ __forceinline__ void gemm_simple(PG8_LAS unsigned char* lds, const Gemm g, const Sched& S, const Epi& E, int wave_s) {
;     ...
;             PG8_TILE_W(1, cA + 2 * kstep, cB + 2 * kstep, "2", "4");
;             t = 2;
	ds_read_b128 v[28:31], v177 offset:49152
	ds_read_b128 v[32:35], v177 offset:50176
	ds_read_b128 v[44:47], v177 offset:51200
	ds_read_b128 v[214:217], v177 offset:52224
	ds_read_b128 v[218:221], v177 offset:53248
	ds_read_b128 v[222:225], v177 offset:54272
	ds_read_b128 v[226:229], v177 offset:55296
	ds_read_b128 v[230:233], v177 offset:56320
	s_add_u32 s14, s10, 0x80100
	s_addc_u32 s15, s11, 0
	s_mov_b32 m0, s36
	s_nop 0
	global_load_lds_dwordx4 v172, s[14:15]
	s_mov_b32 m0, s37
	s_nop 0
	global_load_lds_dwordx4 v174, s[14:15]
	s_waitcnt lgkmcnt(7)
	v_mfma_f32_16x16x32_bf16 v[20:23], v[8:11], v[28:31], v[136:139]
	s_waitcnt lgkmcnt(6)
	v_mfma_f32_16x16x32_bf16 v[56:59], v[60:63], v[32:35], v[20:23]
	v_mfma_f32_16x16x32_bf16 v[20:23], v[64:67], v[28:31], v[152:155]
	v_mfma_f32_16x16x32_bf16 v[52:55], v[210:213], v[32:35], v[20:23]
	s_waitcnt lgkmcnt(5)
	v_mfma_f32_16x16x32_bf16 v[20:23], v[8:11], v[44:47], v[156:159]
	s_waitcnt lgkmcnt(4)
	v_mfma_f32_16x16x32_bf16 v[40:43], v[60:63], v[214:217], v[20:23]
	v_mfma_f32_16x16x32_bf16 v[20:23], v[64:67], v[44:47], v[160:163]
	v_mfma_f32_16x16x32_bf16 v[36:39], v[210:213], v[214:217], v[20:23]
	s_waitcnt lgkmcnt(3)
	v_mfma_f32_16x16x32_bf16 v[20:23], v[8:11], v[218:221], v[178:181]
	s_waitcnt lgkmcnt(1)
	v_mfma_f32_16x16x32_bf16 v[4:7], v[8:11], v[226:229], v[4:7]
	v_mfma_f32_16x16x32_bf16 v[24:27], v[60:63], v[222:225], v[20:23]
	v_mfma_f32_16x16x32_bf16 v[20:23], v[64:67], v[218:221], v[182:185]
	s_waitcnt lgkmcnt(0)
	v_mfma_f32_16x16x32_bf16 v[8:11], v[60:63], v[230:233], v[4:7]
	v_mfma_f32_16x16x32_bf16 v[4:7], v[64:67], v[226:229], v[12:15]
	v_mfma_f32_16x16x32_bf16 v[20:23], v[210:213], v[222:225], v[20:23]
	v_mfma_f32_16x16x32_bf16 v[4:7], v[210:213], v[230:233], v[4:7]
	s_add_u32 s14, s20, 0x80100
	s_addc_u32 s15, s21, 0
	s_mov_b32 m0, s38
	s_nop 0
	global_load_lds_dwordx4 v171, s[14:15]
	s_mov_b32 m0, s39
	s_nop 0
	global_load_lds_dwordx4 v173, s[14:15]
	v_mfma_f32_16x16x32_bf16 v[12:15], v[238:241], v[28:31], v[16:19]
	s_mov_b32 s22, 2
	v_mfma_f32_16x16x32_bf16 v[64:67], v[242:245], v[32:35], v[12:15]
	v_mfma_f32_16x16x32_bf16 v[12:15], v[246:249], v[28:31], v[48:51]
	v_mfma_f32_16x16x32_bf16 v[60:63], v[250:253], v[32:35], v[12:15]
	v_mfma_f32_16x16x32_bf16 v[12:15], v[238:241], v[44:47], v[186:189]
	v_mfma_f32_16x16x32_bf16 v[48:51], v[242:245], v[214:217], v[12:15]
	v_mfma_f32_16x16x32_bf16 v[12:15], v[246:249], v[44:47], v[190:193]
	v_mfma_f32_16x16x32_bf16 v[44:47], v[250:253], v[214:217], v[12:15]
	v_mfma_f32_16x16x32_bf16 v[12:15], v[238:241], v[218:221], v[194:197]
	v_mfma_f32_16x16x32_bf16 v[32:35], v[242:245], v[222:225], v[12:15]
	v_mfma_f32_16x16x32_bf16 v[12:15], v[246:249], v[218:221], v[198:201]
	v_mfma_f32_16x16x32_bf16 v[28:31], v[250:253], v[222:225], v[12:15]
	v_mfma_f32_16x16x32_bf16 v[12:15], v[238:241], v[226:229], v[202:205]
	v_mfma_f32_16x16x32_bf16 v[16:19], v[246:249], v[226:229], v[206:209]
	v_mfma_f32_16x16x32_bf16 v[12:15], v[242:245], v[230:233], v[12:15]
	v_mfma_f32_16x16x32_bf16 v[16:19], v[250:253], v[230:233], v[16:19]

.LBB0_307:
	s_waitcnt vmcnt(2) lgkmcnt(0)
	s_barrier
	ds_read_b128 v[136:139], v132
	ds_read_b128 v[178:181], v177
	ds_read_b128 v[156:159], v132 offset:2048
	ds_read_b128 v[186:189], v177 offset:2048
	ds_read_b128 v[194:197], v177 offset:4096
	ds_read_b128 v[202:205], v177 offset:6144
	ds_read_b128 v[152:155], v132 offset:1024
	ds_read_b128 v[182:185], v177 offset:1024
	ds_read_b128 v[160:163], v132 offset:3072
	ds_read_b128 v[190:193], v177 offset:3072
	ds_read_b128 v[198:201], v177 offset:5120
	ds_read_b128 v[206:209], v177 offset:7168
	ds_read_b128 v[210:213], v133
	ds_read_b128 v[218:221], v133 offset:2048
	ds_read_b128 v[214:217], v133 offset:1024
	ds_read_b128 v[222:225], v133 offset:3072
	s_add_u32 s60, s10, s59
	s_addc_u32 s61, s11, 0
	s_add_u32 s24, s60, 0x80
	s_addc_u32 s25, s61, 0
	s_mov_b32 m0, s43
	s_nop 0
	global_load_lds_dwordx4 v172, s[24:25]
	s_mov_b32 m0, s49
	s_nop 0
	global_load_lds_dwordx4 v174, s[24:25]
	s_waitcnt lgkmcnt(14)
	v_mfma_f32_16x16x32_bf16 v[120:123], v[136:139], v[178:181], v[120:123]
	s_waitcnt lgkmcnt(13)
	v_mfma_f32_16x16x32_bf16 v[116:119], v[156:159], v[178:181], v[116:119]
	s_waitcnt lgkmcnt(12)
	v_mfma_f32_16x16x32_bf16 v[104:107], v[136:139], v[186:189], v[104:107]
	v_mfma_f32_16x16x32_bf16 v[100:103], v[156:159], v[186:189], v[100:103]
	s_waitcnt lgkmcnt(11)
	v_mfma_f32_16x16x32_bf16 v[88:91], v[136:139], v[194:197], v[88:91]
	v_mfma_f32_16x16x32_bf16 v[84:87], v[156:159], v[194:197], v[84:87]
	s_waitcnt lgkmcnt(10)
	v_mfma_f32_16x16x32_bf16 v[72:75], v[136:139], v[202:205], v[72:75]
	v_mfma_f32_16x16x32_bf16 v[68:71], v[156:159], v[202:205], v[68:71]
	s_waitcnt lgkmcnt(8)
	v_mfma_f32_16x16x32_bf16 v[120:123], v[152:155], v[182:185], v[120:123]
	s_waitcnt lgkmcnt(7)
	v_mfma_f32_16x16x32_bf16 v[116:119], v[160:163], v[182:185], v[116:119]
	s_waitcnt lgkmcnt(6)
	v_mfma_f32_16x16x32_bf16 v[104:107], v[152:155], v[190:193], v[104:107]
	v_mfma_f32_16x16x32_bf16 v[100:103], v[160:163], v[190:193], v[100:103]
	s_waitcnt lgkmcnt(5)
	v_mfma_f32_16x16x32_bf16 v[88:91], v[152:155], v[198:201], v[88:91]
	v_mfma_f32_16x16x32_bf16 v[84:87], v[160:163], v[198:201], v[84:87]
	s_waitcnt lgkmcnt(4)
	v_mfma_f32_16x16x32_bf16 v[72:75], v[152:155], v[206:209], v[72:75]
	v_mfma_f32_16x16x32_bf16 v[68:71], v[160:163], v[206:209], v[68:71]
	s_add_u32 s62, s20, s59
	s_addc_u32 s63, s21, 0
	s_add_u32 s24, s62, 0x80
	s_addc_u32 s25, s63, 0
	s_mov_b32 m0, s44
	s_nop 0
	global_load_lds_dwordx4 v171, s[24:25]
	s_mov_b32 m0, s50
	s_nop 0
	global_load_lds_dwordx4 v173, s[24:25]
	s_waitcnt lgkmcnt(3)
	v_mfma_f32_16x16x32_bf16 v[128:131], v[210:213], v[178:181], v[128:131]
	s_waitcnt lgkmcnt(2)
	v_mfma_f32_16x16x32_bf16 v[124:127], v[218:221], v[178:181], v[124:127]
	v_mfma_f32_16x16x32_bf16 v[112:115], v[210:213], v[186:189], v[112:115]
	v_mfma_f32_16x16x32_bf16 v[108:111], v[218:221], v[186:189], v[108:111]
	v_mfma_f32_16x16x32_bf16 v[96:99], v[210:213], v[194:197], v[96:99]
	v_mfma_f32_16x16x32_bf16 v[92:95], v[218:221], v[194:197], v[92:95]
	v_mfma_f32_16x16x32_bf16 v[80:83], v[210:213], v[202:205], v[80:83]
	v_mfma_f32_16x16x32_bf16 v[76:79], v[218:221], v[202:205], v[76:79]
	s_waitcnt lgkmcnt(1)
	v_mfma_f32_16x16x32_bf16 v[128:131], v[214:217], v[182:185], v[128:131]
	s_waitcnt lgkmcnt(0)
	v_mfma_f32_16x16x32_bf16 v[124:127], v[222:225], v[182:185], v[124:127]
	v_mfma_f32_16x16x32_bf16 v[112:115], v[214:217], v[190:193], v[112:115]
	v_mfma_f32_16x16x32_bf16 v[108:111], v[222:225], v[190:193], v[108:111]
	v_mfma_f32_16x16x32_bf16 v[96:99], v[214:217], v[198:201], v[96:99]
	v_mfma_f32_16x16x32_bf16 v[92:95], v[222:225], v[198:201], v[92:95]
	v_mfma_f32_16x16x32_bf16 v[80:83], v[214:217], v[206:209], v[80:83]
	v_mfma_f32_16x16x32_bf16 v[76:79], v[222:225], v[206:209], v[76:79]
	s_waitcnt vmcnt(4) lgkmcnt(0)
	s_barrier
	ds_read_b128 v[178:181], v177 offset:16384
	ds_read_b128 v[186:189], v177 offset:18432
	ds_read_b128 v[194:197], v177 offset:20480
	ds_read_b128 v[202:205], v177 offset:22528
	ds_read_b128 v[182:185], v177 offset:17408
	ds_read_b128 v[190:193], v177 offset:19456
	ds_read_b128 v[198:201], v177 offset:21504
	ds_read_b128 v[206:209], v177 offset:23552
	s_add_u32 s24, s60, 0x80080
	s_addc_u32 s25, s61, 0
	s_mov_b32 m0, s45
	s_nop 0
	global_load_lds_dwordx4 v172, s[24:25]
	s_mov_b32 m0, s51
	s_nop 0
	global_load_lds_dwordx4 v174, s[24:25]
	s_waitcnt lgkmcnt(7)
	v_mfma_f32_16x16x32_bf16 v[56:59], v[136:139], v[178:181], v[56:59]
	v_mfma_f32_16x16x32_bf16 v[52:55], v[156:159], v[178:181], v[52:55]
	s_waitcnt lgkmcnt(6)
	v_mfma_f32_16x16x32_bf16 v[40:43], v[136:139], v[186:189], v[40:43]
	v_mfma_f32_16x16x32_bf16 v[36:39], v[156:159], v[186:189], v[36:39]
	s_waitcnt lgkmcnt(5)
	v_mfma_f32_16x16x32_bf16 v[24:27], v[136:139], v[194:197], v[24:27]
	v_mfma_f32_16x16x32_bf16 v[20:23], v[156:159], v[194:197], v[20:23]
	s_waitcnt lgkmcnt(4)
	v_mfma_f32_16x16x32_bf16 v[8:11], v[136:139], v[202:205], v[8:11]
	v_mfma_f32_16x16x32_bf16 v[4:7], v[156:159], v[202:205], v[4:7]
	s_waitcnt lgkmcnt(3)
	v_mfma_f32_16x16x32_bf16 v[56:59], v[152:155], v[182:185], v[56:59]
	v_mfma_f32_16x16x32_bf16 v[52:55], v[160:163], v[182:185], v[52:55]
	s_waitcnt lgkmcnt(2)
	v_mfma_f32_16x16x32_bf16 v[40:43], v[152:155], v[190:193], v[40:43]
	v_mfma_f32_16x16x32_bf16 v[36:39], v[160:163], v[190:193], v[36:39]
	s_waitcnt lgkmcnt(1)
	v_mfma_f32_16x16x32_bf16 v[24:27], v[152:155], v[198:201], v[24:27]
	v_mfma_f32_16x16x32_bf16 v[20:23], v[160:163], v[198:201], v[20:23]
	s_waitcnt lgkmcnt(0)
	v_mfma_f32_16x16x32_bf16 v[8:11], v[152:155], v[206:209], v[8:11]
	v_mfma_f32_16x16x32_bf16 v[4:7], v[160:163], v[206:209], v[4:7]
	s_add_u32 s24, s62, 0x80080
	s_addc_u32 s25, s63, 0
	s_mov_b32 m0, s46
	s_nop 0
	global_load_lds_dwordx4 v171, s[24:25]
	s_mov_b32 m0, s52
	s_nop 0
	global_load_lds_dwordx4 v173, s[24:25]
	v_mfma_f32_16x16x32_bf16 v[64:67], v[210:213], v[178:181], v[64:67]
	s_add_u32 s24, s62, 0x100
	s_addc_u32 s25, s63, 0
	s_add_u32 s60, s60, 0x100
	v_mfma_f32_16x16x32_bf16 v[60:63], v[218:221], v[178:181], v[60:63]
	s_addc_u32 s61, s61, 0
	v_mfma_f32_16x16x32_bf16 v[48:51], v[210:213], v[186:189], v[48:51]
	v_mfma_f32_16x16x32_bf16 v[44:47], v[218:221], v[186:189], v[44:47]
	v_mfma_f32_16x16x32_bf16 v[32:35], v[210:213], v[194:197], v[32:35]
	v_mfma_f32_16x16x32_bf16 v[28:31], v[218:221], v[194:197], v[28:31]
	v_mfma_f32_16x16x32_bf16 v[12:15], v[210:213], v[202:205], v[12:15]
	v_mfma_f32_16x16x32_bf16 v[16:19], v[218:221], v[202:205], v[16:19]
	v_mfma_f32_16x16x32_bf16 v[64:67], v[214:217], v[182:185], v[64:67]
	v_mfma_f32_16x16x32_bf16 v[60:63], v[222:225], v[182:185], v[60:63]
	v_mfma_f32_16x16x32_bf16 v[48:51], v[214:217], v[190:193], v[48:51]
	v_mfma_f32_16x16x32_bf16 v[44:47], v[222:225], v[190:193], v[44:47]
	v_mfma_f32_16x16x32_bf16 v[32:35], v[214:217], v[198:201], v[32:35]
	v_mfma_f32_16x16x32_bf16 v[28:31], v[222:225], v[198:201], v[28:31]
	v_mfma_f32_16x16x32_bf16 v[12:15], v[214:217], v[206:209], v[12:15]
	v_mfma_f32_16x16x32_bf16 v[16:19], v[222:225], v[206:209], v[16:19]
	s_waitcnt vmcnt(2) lgkmcnt(0)
	s_barrier
; template <class Epi, class Sched>
; __device__ __forceinline__ void gemm_simple(PG8_LAS unsigned char* lds, const Gemm g, const Sched& S, const Epi& E, int wave_s) {
;     ...
;             const char* a2 = last ? nA : cA + (size_t)(t + 2) * kstep; const char* b2 = last ? nB : cB + (size_t)(t + 2) * kstep;
;             PG8_TILE(1, a2, b2, (!last || has_next));
	ds_read_b128 v[136:139], v134
	ds_read_b128 v[178:181], v177 offset:32768
	ds_read_b128 v[156:159], v134 offset:2048
	ds_read_b128 v[186:189], v177 offset:34816
	ds_read_b128 v[194:197], v177 offset:36864
	ds_read_b128 v[202:205], v177 offset:38912
	ds_read_b128 v[152:155], v134 offset:1024
	ds_read_b128 v[182:185], v177 offset:33792
	ds_read_b128 v[160:163], v134 offset:3072
	ds_read_b128 v[190:193], v177 offset:35840
	ds_read_b128 v[198:201], v177 offset:37888
	ds_read_b128 v[206:209], v177 offset:39936
	ds_read_b128 v[210:213], v135
	ds_read_b128 v[218:221], v135 offset:2048
	ds_read_b128 v[214:217], v135 offset:1024
	ds_read_b128 v[222:225], v135 offset:3072
	s_cmp_eq_u32 s59, s22
	s_cselect_b32 s25, s13, s25
	s_cselect_b32 s24, s56, s24
	s_cselect_b32 s61, s5, s61
	s_cselect_b32 s60, s57, s60
	s_mov_b32 m0, s27
	s_nop 0
	global_load_lds_dwordx4 v172, s[60:61]
	s_mov_b32 m0, s28
	s_nop 0
	global_load_lds_dwordx4 v174, s[60:61]
	s_waitcnt lgkmcnt(14)
	v_mfma_f32_16x16x32_bf16 v[120:123], v[136:139], v[178:181], v[120:123]
	s_waitcnt lgkmcnt(13)
	v_mfma_f32_16x16x32_bf16 v[116:119], v[156:159], v[178:181], v[116:119]
	s_waitcnt lgkmcnt(12)
	v_mfma_f32_16x16x32_bf16 v[104:107], v[136:139], v[186:189], v[104:107]
	v_mfma_f32_16x16x32_bf16 v[100:103], v[156:159], v[186:189], v[100:103]
	s_waitcnt lgkmcnt(11)
	v_mfma_f32_16x16x32_bf16 v[88:91], v[136:139], v[194:197], v[88:91]
	v_mfma_f32_16x16x32_bf16 v[84:87], v[156:159], v[194:197], v[84:87]
	s_waitcnt lgkmcnt(10)
	v_mfma_f32_16x16x32_bf16 v[72:75], v[136:139], v[202:205], v[72:75]
	v_mfma_f32_16x16x32_bf16 v[68:71], v[156:159], v[202:205], v[68:71]
	s_waitcnt lgkmcnt(8)
	v_mfma_f32_16x16x32_bf16 v[120:123], v[152:155], v[182:185], v[120:123]
	s_waitcnt lgkmcnt(7)
	v_mfma_f32_16x16x32_bf16 v[116:119], v[160:163], v[182:185], v[116:119]
	s_waitcnt lgkmcnt(6)
	v_mfma_f32_16x16x32_bf16 v[104:107], v[152:155], v[190:193], v[104:107]
	v_mfma_f32_16x16x32_bf16 v[100:103], v[160:163], v[190:193], v[100:103]
	s_waitcnt lgkmcnt(5)
	v_mfma_f32_16x16x32_bf16 v[88:91], v[152:155], v[198:201], v[88:91]
	v_mfma_f32_16x16x32_bf16 v[84:87], v[160:163], v[198:201], v[84:87]
	s_waitcnt lgkmcnt(4)
	v_mfma_f32_16x16x32_bf16 v[72:75], v[152:155], v[206:209], v[72:75]
	v_mfma_f32_16x16x32_bf16 v[68:71], v[160:163], v[206:209], v[68:71]
	s_mov_b32 m0, s19
	s_nop 0
	global_load_lds_dwordx4 v171, s[24:25]
	s_mov_b32 m0, s29
	s_nop 0
	global_load_lds_dwordx4 v173, s[24:25]
	s_waitcnt lgkmcnt(3)
	v_mfma_f32_16x16x32_bf16 v[128:131], v[210:213], v[178:181], v[128:131]
	s_waitcnt lgkmcnt(2)
	v_mfma_f32_16x16x32_bf16 v[124:127], v[218:221], v[178:181], v[124:127]
	v_mfma_f32_16x16x32_bf16 v[112:115], v[210:213], v[186:189], v[112:115]
	v_mfma_f32_16x16x32_bf16 v[108:111], v[218:221], v[186:189], v[108:111]
	v_mfma_f32_16x16x32_bf16 v[96:99], v[210:213], v[194:197], v[96:99]
	v_mfma_f32_16x16x32_bf16 v[92:95], v[218:221], v[194:197], v[92:95]
	v_mfma_f32_16x16x32_bf16 v[80:83], v[210:213], v[202:205], v[80:83]
	v_mfma_f32_16x16x32_bf16 v[76:79], v[218:221], v[202:205], v[76:79]
	s_waitcnt lgkmcnt(1)
	v_mfma_f32_16x16x32_bf16 v[128:131], v[214:217], v[182:185], v[128:131]
	s_waitcnt lgkmcnt(0)
	v_mfma_f32_16x16x32_bf16 v[124:127], v[222:225], v[182:185], v[124:127]
	v_mfma_f32_16x16x32_bf16 v[112:115], v[214:217], v[190:193], v[112:115]
	v_mfma_f32_16x16x32_bf16 v[108:111], v[222:225], v[190:193], v[108:111]
	v_mfma_f32_16x16x32_bf16 v[96:99], v[214:217], v[198:201], v[96:99]
	v_mfma_f32_16x16x32_bf16 v[92:95], v[222:225], v[198:201], v[92:95]
	v_mfma_f32_16x16x32_bf16 v[80:83], v[214:217], v[206:209], v[80:83]
	v_mfma_f32_16x16x32_bf16 v[76:79], v[222:225], v[206:209], v[76:79]
	s_waitcnt vmcnt(4) lgkmcnt(0)
	s_barrier
; #define LAS __attribute__((address_space(3)))
; __device__ __forceinline__ void rstd_table(const float* ssq, LAS unsigned char* lds, const Unit& u, int tid, int par) {
;     if (tid < 256) { const f32x4* p = (const f32x4*)(ssq + (size_t)(u.pm * 256 + tid) * 32); f32x4 a = p[0];
; #pragma unroll
;         for (int i = 1; i < 8; ++i) a += p[i];
;         ((LAS float*)(lds + 131072 + par * 1024))[tid] = 1.0f / sqrtf(((a[0] + a[1]) + (a[2] + a[3])) * (1.0f / DM) + 1e-6f); }
	ds_read_b128 v[178:181], v177 offset:49152
	ds_read_b128 v[186:189], v177 offset:51200
	ds_read_b128 v[194:197], v177 offset:53248
	ds_read_b128 v[202:205], v177 offset:55296
	ds_read_b128 v[182:185], v177 offset:50176
	ds_read_b128 v[190:193], v177 offset:52224
	ds_read_b128 v[198:201], v177 offset:54272
	ds_read_b128 v[206:209], v177 offset:56320
	s_add_u32 s60, s60, 0x80000
	s_addc_u32 s61, s61, 0
	s_mov_b32 m0, s36
	s_nop 0
	global_load_lds_dwordx4 v172, s[60:61]
	s_mov_b32 m0, s37
	s_nop 0
	global_load_lds_dwordx4 v174, s[60:61]
	s_waitcnt lgkmcnt(7)
	v_mfma_f32_16x16x32_bf16 v[56:59], v[136:139], v[178:181], v[56:59]
	v_mfma_f32_16x16x32_bf16 v[52:55], v[156:159], v[178:181], v[52:55]
	s_waitcnt lgkmcnt(6)
	v_mfma_f32_16x16x32_bf16 v[40:43], v[136:139], v[186:189], v[40:43]
	v_mfma_f32_16x16x32_bf16 v[36:39], v[156:159], v[186:189], v[36:39]
	s_waitcnt lgkmcnt(5)
	v_mfma_f32_16x16x32_bf16 v[24:27], v[136:139], v[194:197], v[24:27]
	v_mfma_f32_16x16x32_bf16 v[20:23], v[156:159], v[194:197], v[20:23]
	s_waitcnt lgkmcnt(4)
	v_mfma_f32_16x16x32_bf16 v[8:11], v[136:139], v[202:205], v[8:11]
	v_mfma_f32_16x16x32_bf16 v[4:7], v[156:159], v[202:205], v[4:7]
	s_waitcnt lgkmcnt(3)
	v_mfma_f32_16x16x32_bf16 v[56:59], v[152:155], v[182:185], v[56:59]
	v_mfma_f32_16x16x32_bf16 v[52:55], v[160:163], v[182:185], v[52:55]
	s_waitcnt lgkmcnt(2)
	v_mfma_f32_16x16x32_bf16 v[40:43], v[152:155], v[190:193], v[40:43]
	v_mfma_f32_16x16x32_bf16 v[36:39], v[160:163], v[190:193], v[36:39]
	s_waitcnt lgkmcnt(1)
	v_mfma_f32_16x16x32_bf16 v[24:27], v[152:155], v[198:201], v[24:27]
	v_mfma_f32_16x16x32_bf16 v[20:23], v[160:163], v[198:201], v[20:23]
	s_waitcnt lgkmcnt(0)
	v_mfma_f32_16x16x32_bf16 v[8:11], v[152:155], v[206:209], v[8:11]
	v_mfma_f32_16x16x32_bf16 v[4:7], v[160:163], v[206:209], v[4:7]
	s_add_u32 s24, s24, 0x80000
	s_addc_u32 s25, s25, 0
	s_mov_b32 m0, s38
	s_nop 0
	global_load_lds_dwordx4 v171, s[24:25]
	s_mov_b32 m0, s39
	s_nop 0
	global_load_lds_dwordx4 v173, s[24:25]
	v_mfma_f32_16x16x32_bf16 v[64:67], v[210:213], v[178:181], v[64:67]
	s_add_i32 s58, s58, 2
	s_add_u32 s22, s22, 0xffffff00
	s_addc_u32 s23, s23, -1
	v_mfma_f32_16x16x32_bf16 v[60:63], v[218:221], v[178:181], v[60:63]
	s_add_u32 s20, s20, 0x100
	s_addc_u32 s21, s21, 0
	s_add_u32 s10, s10, 0x100
	v_mfma_f32_16x16x32_bf16 v[48:51], v[210:213], v[186:189], v[48:51]
	s_addc_u32 s11, s11, 0
	s_cmp_lt_u32 s58, 30
	v_mfma_f32_16x16x32_bf16 v[44:47], v[218:221], v[186:189], v[44:47]
	v_mfma_f32_16x16x32_bf16 v[32:35], v[210:213], v[194:197], v[32:35]
	v_mfma_f32_16x16x32_bf16 v[28:31], v[218:221], v[194:197], v[28:31]
	v_mfma_f32_16x16x32_bf16 v[12:15], v[210:213], v[202:205], v[12:15]
	v_mfma_f32_16x16x32_bf16 v[16:19], v[218:221], v[202:205], v[16:19]
	v_mfma_f32_16x16x32_bf16 v[64:67], v[214:217], v[182:185], v[64:67]
	v_mfma_f32_16x16x32_bf16 v[60:63], v[222:225], v[182:185], v[60:63]
	v_mfma_f32_16x16x32_bf16 v[48:51], v[214:217], v[190:193], v[48:51]
	v_mfma_f32_16x16x32_bf16 v[44:47], v[222:225], v[190:193], v[44:47]
	v_mfma_f32_16x16x32_bf16 v[32:35], v[214:217], v[198:201], v[32:35]
	v_mfma_f32_16x16x32_bf16 v[28:31], v[222:225], v[198:201], v[28:31]
	v_mfma_f32_16x16x32_bf16 v[12:15], v[214:217], v[206:209], v[12:15]
	v_mfma_f32_16x16x32_bf16 v[16:19], v[222:225], v[206:209], v[16:19]
	s_cbranch_scc1 .LBB0_307
	s_nor_b64 s[10:11], s[6:7], s[8:9]
	s_and_saveexec_b64 s[20:21], s[10:11]
	s_cbranch_execz .LBB0_310
	v_lshl_add_u32 v132, s12, 8, v170
	v_ashrrev_i32_e32 v133, 31, v132
	v_readlane_b32 s10, v255, 2
	v_lshlrev_b64 v[132:133], 7, v[132:133]
	v_readlane_b32 s11, v255, 3
	s_lshl_b32 s5, s54, 10
	s_and_b32 s5, s5, 0x400
	v_lshl_add_u64 v[142:143], s[10:11], 0, v[132:133]
	global_load_dwordx4 v[132:135], v[142:143], off offset:48
	global_load_dwordx4 v[136:139], v[142:143], off offset:32
	global_load_dwordx4 v[152:155], v[142:143], off
	global_load_dwordx4 v[156:159], v[142:143], off offset:16
	s_waitcnt vmcnt(0)
	v_pk_add_f32 v[144:145], v[154:155], v[158:159]
	v_pk_add_f32 v[146:147], v[152:153], v[156:157]
	v_pk_add_f32 v[138:139], v[144:145], v[138:139]
	v_pk_add_f32 v[136:137], v[146:147], v[136:137]
	v_pk_add_f32 v[144:145], v[138:139], v[134:135]
	v_pk_add_f32 v[146:147], v[136:137], v[132:133]
	global_load_dwordx4 v[132:135], v[142:143], off offset:112
	global_load_dwordx4 v[136:139], v[142:143], off offset:96
	global_load_dwordx4 v[152:155], v[142:143], off offset:80
	global_load_dwordx4 v[156:159], v[142:143], off offset:64
	s_waitcnt vmcnt(0)
	v_pk_add_f32 v[142:143], v[144:145], v[158:159]
	v_pk_add_f32 v[144:145], v[146:147], v[156:157]
	v_pk_add_f32 v[142:143], v[142:143], v[154:155]
	v_pk_add_f32 v[144:145], v[144:145], v[152:153]
	v_pk_add_f32 v[138:139], v[142:143], v[138:139]
	v_pk_add_f32 v[136:137], v[144:145], v[136:137]
	v_pk_add_f32 v[134:135], v[138:139], v[134:135]
	v_pk_add_f32 v[132:133], v[136:137], v[132:133]
	s_nop 0
	v_pk_mov_b32 v[136:137], v[132:133], v[134:135] op_sel:[1,0]
	v_mov_b32_e32 v133, v135
	v_pk_add_f32 v[132:133], v[136:137], v[132:133]
	s_nop 0
	v_add_f32_e32 v132, v132, v133
	v_fmamk_f32 v132, v132, 0x3a000000, v164
	v_cmp_gt_f32_e32 vcc, s69, v132
	v_mul_f32_e32 v133, 0x4f800000, v132
	s_nop 0
	v_cndmask_b32_e32 v132, v132, v133, vcc
	v_sqrt_f32_e32 v133, v132
	s_nop 0
	v_add_u32_e32 v134, -1, v133
	v_fma_f32 v135, -v134, v133, v132
	v_cmp_ge_f32_e64 s[10:11], 0, v135
	v_add_u32_e32 v135, 1, v133
	s_nop 0
	v_cndmask_b32_e64 v134, v133, v134, s[10:11]
	v_fma_f32 v133, -v135, v133, v132
	v_cmp_lt_f32_e64 s[10:11], 0, v133
	s_nop 1
	v_cndmask_b32_e64 v133, v134, v135, s[10:11]
	v_mul_f32_e32 v134, 0x37800000, v133
	v_cndmask_b32_e32 v133, v133, v134, vcc
	v_cmp_class_f32_e32 vcc, v132, v165
	s_nop 1
	v_cndmask_b32_e32 v132, v133, v132, vcc
	v_div_scale_f32 v133, s[10:11], v132, v132, 1.0
	v_rcp_f32_e32 v134, v133
	s_nop 0
	v_fma_f32 v135, -v133, v134, 1.0
	v_fmac_f32_e32 v134, v135, v134
	v_div_scale_f32 v135, vcc, 1.0, v132, 1.0
	v_mul_f32_e32 v136, v135, v134
	v_fma_f32 v137, -v133, v136, v135
	v_fmac_f32_e32 v136, v137, v134
	v_fma_f32 v133, -v133, v136, v135
	v_div_fmas_f32 v133, v133, v134, v136
	v_div_fixup_f32 v132, v133, v132, 1.0
	v_add_u32_e32 v133, s5, v175
	ds_write_b32 v133, v132
